# v36 recipe + saddr-form K-loop DMA loads
# speedup vs baseline: 1.0060x; 1.0033x over previous
.Lpeel_13:
	v_add_u32_e32 v250, 0x18000, v147
	ds_read_b128 v[152:155], v149
	ds_read_b128 v[156:159], v149 offset:1024
	s_add_i32 s37, s25, 2
	s_add_u32 s40, s38, 0xfff80080
	s_addc_u32 s41, s39, -1
	s_cmp_eq_u32 s36, s25
	s_cselect_b32 s43, s27, s41
	s_cselect_b32 s42, s26, s40
	s_cselect_b32 s41, s29, s23
	s_cselect_b32 s40, s28, s21
	s_add_i32 m0, s35, 0xc000
	global_load_lds_dwordx4 v140, s[38:39]
	s_add_i32 m0, s35, 0xe000
	s_nop 0
	global_load_lds_dwordx4 v142, s[38:39]
	s_waitcnt vmcnt(8)
	s_waitcnt lgkmcnt(0)
	s_barrier
	s_setprio 1
	s_waitcnt lgkmcnt(0)
	v_mfma_f32_16x16x32_bf16 v[126:129], v[152:155], v[184:187], 0
	v_mfma_f32_16x16x32_bf16 v[122:125], v[160:163], v[184:187], 0
	v_mfma_f32_16x16x32_bf16 v[110:113], v[152:155], v[196:199], 0
	v_mfma_f32_16x16x32_bf16 v[106:109], v[160:163], v[196:199], 0
	v_mfma_f32_16x16x32_bf16 v[94:97], v[152:155], v[204:207], 0
	v_mfma_f32_16x16x32_bf16 v[90:93], v[160:163], v[204:207], 0
	v_mfma_f32_16x16x32_bf16 v[78:81], v[152:155], v[212:215], 0
	v_mfma_f32_16x16x32_bf16 v[74:77], v[160:163], v[212:215], 0
	v_mfma_f32_16x16x32_bf16 v[126:129], v[156:159], v[188:191], v[126:129]
	v_mfma_f32_16x16x32_bf16 v[122:125], v[164:167], v[188:191], v[122:125]
	v_mfma_f32_16x16x32_bf16 v[110:113], v[156:159], v[200:203], v[110:113]
	v_mfma_f32_16x16x32_bf16 v[106:109], v[164:167], v[200:203], v[106:109]
	v_mfma_f32_16x16x32_bf16 v[94:97], v[156:159], v[208:211], v[94:97]
	v_mfma_f32_16x16x32_bf16 v[90:93], v[164:167], v[208:211], v[90:93]
	v_mfma_f32_16x16x32_bf16 v[78:81], v[156:159], v[216:219], v[78:81]
	v_mfma_f32_16x16x32_bf16 v[74:77], v[164:167], v[216:219], v[74:77]
	v_mfma_f32_16x16x32_bf16 v[118:121], v[168:171], v[184:187], 0
	v_mfma_f32_16x16x32_bf16 v[114:117], v[176:179], v[184:187], 0
	v_mfma_f32_16x16x32_bf16 v[102:105], v[168:171], v[196:199], 0
	v_mfma_f32_16x16x32_bf16 v[98:101], v[176:179], v[196:199], 0
	v_mfma_f32_16x16x32_bf16 v[86:89], v[168:171], v[204:207], 0
	v_mfma_f32_16x16x32_bf16 v[82:85], v[176:179], v[204:207], 0
	v_mfma_f32_16x16x32_bf16 v[70:73], v[168:171], v[212:215], 0
	v_mfma_f32_16x16x32_bf16 v[66:69], v[176:179], v[212:215], 0
	v_mfma_f32_16x16x32_bf16 v[118:121], v[172:175], v[188:191], v[118:121]
	v_mfma_f32_16x16x32_bf16 v[114:117], v[180:183], v[188:191], v[114:117]
	v_mfma_f32_16x16x32_bf16 v[102:105], v[172:175], v[200:203], v[102:105]
	v_mfma_f32_16x16x32_bf16 v[98:101], v[180:183], v[200:203], v[98:101]
	v_mfma_f32_16x16x32_bf16 v[86:89], v[172:175], v[208:211], v[86:89]
	v_mfma_f32_16x16x32_bf16 v[82:85], v[180:183], v[208:211], v[82:85]
	v_mfma_f32_16x16x32_bf16 v[70:73], v[172:175], v[216:219], v[70:73]
	s_barrier
	v_mfma_f32_16x16x32_bf16 v[66:69], v[180:183], v[216:219], v[66:69]
	s_setprio 2
	s_add_i32 s25, s54, s33
	v_lshl_add_u64 v[144:145], s[40:41], 0, v[132:133]
	s_mov_b32 m0, s25
	ds_read_b128 v[184:187], v151 offset:16384
	ds_read_b128 v[188:191], v151 offset:17408
	ds_read_b128 v[196:199], v151 offset:18432
	ds_read_b128 v[200:203], v151 offset:19456
	ds_read_b128 v[204:207], v151 offset:20480
	ds_read_b128 v[208:211], v151 offset:21504
	ds_read_b128 v[212:215], v151 offset:22528
	ds_read_b128 v[216:219], v151 offset:23552
	global_load_lds_dwordx4 v132, s[40:41]
	s_add_i32 m0, s25, 0x2000
	s_add_u32 s44, s40, 0x80000
	v_lshl_add_u64 v[192:193], s[40:41], 0, v[136:137]
	s_addc_u32 s45, s41, 0
	s_add_i32 s25, s55, s33
	global_load_lds_dwordx4 v136, s[40:41]
	s_mov_b32 m0, s25
	v_lshl_add_u64 v[222:223], s[42:43], 0, v[134:135]
	global_load_lds_dwordx4 v132, s[44:45]
	s_add_i32 m0, s25, 0x2000
	s_nop 0
	global_load_lds_dwordx4 v136, s[44:45]
	v_lshl_add_u64 v[220:221], s[42:43], 0, v[130:131]
	s_mov_b32 m0, s35
	s_nop 0
	global_load_lds_dwordx4 v130, s[42:43]
	s_mov_b32 m0, s47
	s_nop 0
	global_load_lds_dwordx4 v134, s[42:43]
	s_waitcnt vmcnt(8)
	s_waitcnt lgkmcnt(0)
	s_barrier
	s_setprio 1
	s_waitcnt lgkmcnt(0)
	v_mfma_f32_16x16x32_bf16 v[62:65], v[152:155], v[184:187], 0
	v_mfma_f32_16x16x32_bf16 v[58:61], v[160:163], v[184:187], 0
	v_mfma_f32_16x16x32_bf16 v[46:49], v[152:155], v[196:199], 0
	v_mfma_f32_16x16x32_bf16 v[42:45], v[160:163], v[196:199], 0
	v_mfma_f32_16x16x32_bf16 v[30:33], v[152:155], v[204:207], 0
	v_mfma_f32_16x16x32_bf16 v[26:29], v[160:163], v[204:207], 0
	v_mfma_f32_16x16x32_bf16 v[14:17], v[152:155], v[212:215], 0
	v_mfma_f32_16x16x32_bf16 v[10:13], v[160:163], v[212:215], 0
	v_mfma_f32_16x16x32_bf16 v[62:65], v[156:159], v[188:191], v[62:65]
	v_mfma_f32_16x16x32_bf16 v[58:61], v[164:167], v[188:191], v[58:61]
	v_mfma_f32_16x16x32_bf16 v[46:49], v[156:159], v[200:203], v[46:49]
	v_mfma_f32_16x16x32_bf16 v[42:45], v[164:167], v[200:203], v[42:45]
	v_mfma_f32_16x16x32_bf16 v[30:33], v[156:159], v[208:211], v[30:33]
	v_mfma_f32_16x16x32_bf16 v[26:29], v[164:167], v[208:211], v[26:29]
	v_mfma_f32_16x16x32_bf16 v[14:17], v[156:159], v[216:219], v[14:17]
	v_mfma_f32_16x16x32_bf16 v[10:13], v[164:167], v[216:219], v[10:13]
	v_mfma_f32_16x16x32_bf16 v[54:57], v[168:171], v[184:187], 0
	v_mfma_f32_16x16x32_bf16 v[50:53], v[176:179], v[184:187], 0
	v_mfma_f32_16x16x32_bf16 v[38:41], v[168:171], v[196:199], 0
	v_mfma_f32_16x16x32_bf16 v[34:37], v[176:179], v[196:199], 0
	v_mfma_f32_16x16x32_bf16 v[22:25], v[168:171], v[204:207], 0
	v_mfma_f32_16x16x32_bf16 v[18:21], v[176:179], v[204:207], 0
	v_mfma_f32_16x16x32_bf16 v[6:9], v[168:171], v[212:215], 0
	v_mfma_f32_16x16x32_bf16 v[2:5], v[176:179], v[212:215], 0
	v_mfma_f32_16x16x32_bf16 v[54:57], v[172:175], v[188:191], v[54:57]
	v_mfma_f32_16x16x32_bf16 v[50:53], v[180:183], v[188:191], v[50:53]
	v_mfma_f32_16x16x32_bf16 v[38:41], v[172:175], v[200:203], v[38:41]
	v_mfma_f32_16x16x32_bf16 v[34:37], v[180:183], v[200:203], v[34:37]
	v_mfma_f32_16x16x32_bf16 v[22:25], v[172:175], v[208:211], v[22:25]
	v_mfma_f32_16x16x32_bf16 v[18:21], v[180:183], v[208:211], v[18:21]
	v_mfma_f32_16x16x32_bf16 v[6:9], v[172:175], v[216:219], v[6:9]
	s_barrier
	v_mfma_f32_16x16x32_bf16 v[2:5], v[180:183], v[216:219], v[2:5]
	s_setprio 2
	s_add_i32 s25, 0, 0x18000
	s_add_i32 s44, 0, 0x1c000
	ds_read_b128 v[152:155], v250
	ds_read_b128 v[156:159], v250 offset:1024
	ds_read_b128 v[160:163], v250 offset:2048
	ds_read_b128 v[164:167], v250 offset:3072
	ds_read_b128 v[168:171], v250 offset:16384
	ds_read_b128 v[172:175], v250 offset:17408
	ds_read_b128 v[176:179], v250 offset:18432
	ds_read_b128 v[180:183], v250 offset:19456
	s_add_u32 s42, s42, 0x80000
	s_addc_u32 s43, s43, 0
	s_mov_b32 m0, s48
	ds_read_b128 v[184:187], v151 offset:32768
	ds_read_b128 v[188:191], v151 offset:33792
	ds_read_b128 v[196:199], v151 offset:34816
	ds_read_b128 v[200:203], v151 offset:35840
	ds_read_b128 v[204:207], v151 offset:36864
	ds_read_b128 v[208:211], v151 offset:37888
	ds_read_b128 v[212:215], v151 offset:38912
	ds_read_b128 v[216:219], v151 offset:39936
	global_load_lds_dwordx4 v130, s[42:43]
	v_lshl_add_u64 v[224:225], s[42:43], 0, v[134:135]
	s_mov_b32 m0, s49
	s_nop 0
	global_load_lds_dwordx4 v134, s[42:43]
	s_waitcnt vmcnt(8)
	s_waitcnt lgkmcnt(0)
	s_barrier
	s_setprio 1
	s_waitcnt lgkmcnt(0)
	v_mfma_f32_16x16x32_bf16 v[126:129], v[152:155], v[184:187], v[126:129]
	v_mfma_f32_16x16x32_bf16 v[122:125], v[160:163], v[184:187], v[122:125]
	v_mfma_f32_16x16x32_bf16 v[110:113], v[152:155], v[196:199], v[110:113]
	v_mfma_f32_16x16x32_bf16 v[106:109], v[160:163], v[196:199], v[106:109]
	v_mfma_f32_16x16x32_bf16 v[94:97], v[152:155], v[204:207], v[94:97]
	v_mfma_f32_16x16x32_bf16 v[90:93], v[160:163], v[204:207], v[90:93]
	v_mfma_f32_16x16x32_bf16 v[78:81], v[152:155], v[212:215], v[78:81]
	v_mfma_f32_16x16x32_bf16 v[74:77], v[160:163], v[212:215], v[74:77]
	v_mfma_f32_16x16x32_bf16 v[126:129], v[156:159], v[188:191], v[126:129]
	v_mfma_f32_16x16x32_bf16 v[122:125], v[164:167], v[188:191], v[122:125]
	v_mfma_f32_16x16x32_bf16 v[110:113], v[156:159], v[200:203], v[110:113]
	v_mfma_f32_16x16x32_bf16 v[106:109], v[164:167], v[200:203], v[106:109]
	v_mfma_f32_16x16x32_bf16 v[94:97], v[156:159], v[208:211], v[94:97]
	v_mfma_f32_16x16x32_bf16 v[90:93], v[164:167], v[208:211], v[90:93]
	v_mfma_f32_16x16x32_bf16 v[78:81], v[156:159], v[216:219], v[78:81]
	v_mfma_f32_16x16x32_bf16 v[74:77], v[164:167], v[216:219], v[74:77]
	v_mfma_f32_16x16x32_bf16 v[118:121], v[168:171], v[184:187], v[118:121]
	v_mfma_f32_16x16x32_bf16 v[114:117], v[176:179], v[184:187], v[114:117]
	v_mfma_f32_16x16x32_bf16 v[102:105], v[168:171], v[196:199], v[102:105]
	v_mfma_f32_16x16x32_bf16 v[98:101], v[176:179], v[196:199], v[98:101]
	v_mfma_f32_16x16x32_bf16 v[86:89], v[168:171], v[204:207], v[86:89]
	v_mfma_f32_16x16x32_bf16 v[82:85], v[176:179], v[204:207], v[82:85]
	v_mfma_f32_16x16x32_bf16 v[70:73], v[168:171], v[212:215], v[70:73]
	v_mfma_f32_16x16x32_bf16 v[66:69], v[176:179], v[212:215], v[66:69]
	v_mfma_f32_16x16x32_bf16 v[118:121], v[172:175], v[188:191], v[118:121]
	v_mfma_f32_16x16x32_bf16 v[114:117], v[180:183], v[188:191], v[114:117]
	v_mfma_f32_16x16x32_bf16 v[102:105], v[172:175], v[200:203], v[102:105]
	v_mfma_f32_16x16x32_bf16 v[98:101], v[180:183], v[200:203], v[98:101]
	v_mfma_f32_16x16x32_bf16 v[86:89], v[172:175], v[208:211], v[86:89]
	v_mfma_f32_16x16x32_bf16 v[82:85], v[180:183], v[208:211], v[82:85]
	v_mfma_f32_16x16x32_bf16 v[70:73], v[172:175], v[216:219], v[70:73]
	s_barrier
	v_mfma_f32_16x16x32_bf16 v[66:69], v[180:183], v[216:219], v[66:69]
	s_setprio 2
	s_add_i32 s25, s25, s33
	v_lshl_add_u64 v[144:145], v[144:145], 0, s[16:17]
	s_mov_b32 m0, s25
	ds_read_b128 v[184:187], v151 offset:49152
	ds_read_b128 v[188:191], v151 offset:50176
	ds_read_b128 v[196:199], v151 offset:51200
	ds_read_b128 v[200:203], v151 offset:52224
	ds_read_b128 v[204:207], v151 offset:53248
	ds_read_b128 v[208:211], v151 offset:54272
	ds_read_b128 v[212:215], v151 offset:55296
	ds_read_b128 v[216:219], v151 offset:56320
	global_load_lds_dwordx4 v[144:145], off
	s_add_i32 m0, s25, 0x2000
	s_add_u32 s40, s40, 0x80080
	v_lshl_add_u64 v[144:145], v[192:193], 0, s[16:17]
	s_addc_u32 s41, s41, 0
	s_add_i32 s25, s44, s33
	global_load_lds_dwordx4 v[144:145], off
	s_mov_b32 m0, s25
	s_nop 0
	global_load_lds_dwordx4 v132, s[40:41]
	s_add_i32 m0, s25, 0x2000
	s_nop 0
	global_load_lds_dwordx4 v136, s[40:41]
	v_lshl_add_u64 v[144:145], v[220:221], 0, s[16:17]
	s_mov_b32 m0, s50
	s_nop 0
	global_load_lds_dwordx4 v[144:145], off
	v_lshl_add_u64 v[144:145], v[222:223], 0, s[16:17]
	s_mov_b32 m0, s51
	s_nop 0
	global_load_lds_dwordx4 v[144:145], off
	s_waitcnt vmcnt(8)
	s_waitcnt lgkmcnt(0)
	s_barrier
	s_setprio 1
	s_waitcnt lgkmcnt(0)
	v_mfma_f32_16x16x32_bf16 v[62:65], v[152:155], v[184:187], v[62:65]
	v_mfma_f32_16x16x32_bf16 v[58:61], v[160:163], v[184:187], v[58:61]
	v_mfma_f32_16x16x32_bf16 v[46:49], v[152:155], v[196:199], v[46:49]
	v_mfma_f32_16x16x32_bf16 v[42:45], v[160:163], v[196:199], v[42:45]
	v_mfma_f32_16x16x32_bf16 v[30:33], v[152:155], v[204:207], v[30:33]
	v_mfma_f32_16x16x32_bf16 v[26:29], v[160:163], v[204:207], v[26:29]
	v_mfma_f32_16x16x32_bf16 v[14:17], v[152:155], v[212:215], v[14:17]
	v_mfma_f32_16x16x32_bf16 v[10:13], v[160:163], v[212:215], v[10:13]
	v_mfma_f32_16x16x32_bf16 v[62:65], v[156:159], v[188:191], v[62:65]
	v_mfma_f32_16x16x32_bf16 v[58:61], v[164:167], v[188:191], v[58:61]
	v_mfma_f32_16x16x32_bf16 v[46:49], v[156:159], v[200:203], v[46:49]
	v_mfma_f32_16x16x32_bf16 v[42:45], v[164:167], v[200:203], v[42:45]
	v_mfma_f32_16x16x32_bf16 v[30:33], v[156:159], v[208:211], v[30:33]
	v_mfma_f32_16x16x32_bf16 v[26:29], v[164:167], v[208:211], v[26:29]
	v_mfma_f32_16x16x32_bf16 v[14:17], v[156:159], v[216:219], v[14:17]
	v_mfma_f32_16x16x32_bf16 v[10:13], v[164:167], v[216:219], v[10:13]
	v_mfma_f32_16x16x32_bf16 v[54:57], v[168:171], v[184:187], v[54:57]
	v_mfma_f32_16x16x32_bf16 v[50:53], v[176:179], v[184:187], v[50:53]
	v_mfma_f32_16x16x32_bf16 v[38:41], v[168:171], v[196:199], v[38:41]
	v_mfma_f32_16x16x32_bf16 v[34:37], v[176:179], v[196:199], v[34:37]
	v_mfma_f32_16x16x32_bf16 v[22:25], v[168:171], v[204:207], v[22:25]
	v_mfma_f32_16x16x32_bf16 v[18:21], v[176:179], v[204:207], v[18:21]
	v_mfma_f32_16x16x32_bf16 v[6:9], v[168:171], v[212:215], v[6:9]
	v_mfma_f32_16x16x32_bf16 v[2:5], v[176:179], v[212:215], v[2:5]
	v_mfma_f32_16x16x32_bf16 v[54:57], v[172:175], v[188:191], v[54:57]
	v_mfma_f32_16x16x32_bf16 v[50:53], v[180:183], v[188:191], v[50:53]
	v_mfma_f32_16x16x32_bf16 v[38:41], v[172:175], v[200:203], v[38:41]
	v_mfma_f32_16x16x32_bf16 v[34:37], v[180:183], v[200:203], v[34:37]
	v_mfma_f32_16x16x32_bf16 v[22:25], v[172:175], v[208:211], v[22:25]
	v_mfma_f32_16x16x32_bf16 v[18:21], v[180:183], v[208:211], v[18:21]
	v_mfma_f32_16x16x32_bf16 v[6:9], v[172:175], v[216:219], v[6:9]
	s_barrier
	v_mfma_f32_16x16x32_bf16 v[2:5], v[180:183], v[216:219], v[2:5]
	s_setprio 2
	s_add_u32 s38, s38, 0x100
	s_addc_u32 s39, s39, 0
	s_add_u32 s21, s21, 0x100
	s_addc_u32 s23, s23, 0
	s_cmp_ge_i32 s37, s62
	s_mov_b32 s25, s37
	s_cbranch_scc0 .LBB0_221
	s_branch .Lpeeldone_13
.LBB0_221:
	ds_read_b128 v[152:155], v149
	ds_read_b128 v[156:159], v149 offset:1024
	ds_read_b128 v[160:163], v149 offset:2048
	ds_read_b128 v[164:167], v149 offset:3072
	ds_read_b128 v[168:171], v150
	ds_read_b128 v[172:175], v150 offset:1024
	ds_read_b128 v[176:179], v150 offset:2048
	ds_read_b128 v[180:183], v150 offset:3072
	s_add_i32 s37, s25, 2
	s_add_u32 s40, s38, 0xfff80080
	s_addc_u32 s41, s39, -1
	s_cmp_eq_u32 s36, s25
	s_cselect_b32 s43, s27, s41
	s_cselect_b32 s42, s26, s40
	s_cselect_b32 s41, s29, s23
	s_cselect_b32 s40, s28, s21
	s_add_i32 m0, s35, 0xc000
	ds_read_b128 v[184:187], v151
	ds_read_b128 v[188:191], v151 offset:1024
	ds_read_b128 v[196:199], v151 offset:2048
	ds_read_b128 v[200:203], v151 offset:3072
	ds_read_b128 v[204:207], v151 offset:4096
	ds_read_b128 v[208:211], v151 offset:5120
	ds_read_b128 v[212:215], v151 offset:6144
	ds_read_b128 v[216:219], v151 offset:7168
	global_load_lds_dwordx4 v140, s[38:39]
	s_add_i32 m0, s35, 0xe000
	s_nop 0
	global_load_lds_dwordx4 v142, s[38:39]
	s_waitcnt vmcnt(8)
	s_waitcnt lgkmcnt(0)
	s_barrier
	s_setprio 1
	s_waitcnt lgkmcnt(0)
	v_mfma_f32_16x16x32_bf16 v[126:129], v[152:155], v[184:187], v[126:129]
	v_mfma_f32_16x16x32_bf16 v[122:125], v[160:163], v[184:187], v[122:125]
	v_mfma_f32_16x16x32_bf16 v[110:113], v[152:155], v[196:199], v[110:113]
	v_mfma_f32_16x16x32_bf16 v[106:109], v[160:163], v[196:199], v[106:109]
	v_mfma_f32_16x16x32_bf16 v[94:97], v[152:155], v[204:207], v[94:97]
	v_mfma_f32_16x16x32_bf16 v[90:93], v[160:163], v[204:207], v[90:93]
	v_mfma_f32_16x16x32_bf16 v[78:81], v[152:155], v[212:215], v[78:81]
	v_mfma_f32_16x16x32_bf16 v[74:77], v[160:163], v[212:215], v[74:77]
	v_mfma_f32_16x16x32_bf16 v[126:129], v[156:159], v[188:191], v[126:129]
	v_mfma_f32_16x16x32_bf16 v[122:125], v[164:167], v[188:191], v[122:125]
	v_mfma_f32_16x16x32_bf16 v[110:113], v[156:159], v[200:203], v[110:113]
	v_mfma_f32_16x16x32_bf16 v[106:109], v[164:167], v[200:203], v[106:109]
	v_mfma_f32_16x16x32_bf16 v[94:97], v[156:159], v[208:211], v[94:97]
	v_mfma_f32_16x16x32_bf16 v[90:93], v[164:167], v[208:211], v[90:93]
	v_mfma_f32_16x16x32_bf16 v[78:81], v[156:159], v[216:219], v[78:81]
	v_mfma_f32_16x16x32_bf16 v[74:77], v[164:167], v[216:219], v[74:77]
	v_mfma_f32_16x16x32_bf16 v[118:121], v[168:171], v[184:187], v[118:121]
	v_mfma_f32_16x16x32_bf16 v[114:117], v[176:179], v[184:187], v[114:117]
	v_mfma_f32_16x16x32_bf16 v[102:105], v[168:171], v[196:199], v[102:105]
	v_mfma_f32_16x16x32_bf16 v[98:101], v[176:179], v[196:199], v[98:101]
	v_mfma_f32_16x16x32_bf16 v[86:89], v[168:171], v[204:207], v[86:89]
	v_mfma_f32_16x16x32_bf16 v[82:85], v[176:179], v[204:207], v[82:85]
	v_mfma_f32_16x16x32_bf16 v[70:73], v[168:171], v[212:215], v[70:73]
	v_mfma_f32_16x16x32_bf16 v[66:69], v[176:179], v[212:215], v[66:69]
	v_mfma_f32_16x16x32_bf16 v[118:121], v[172:175], v[188:191], v[118:121]
	v_mfma_f32_16x16x32_bf16 v[114:117], v[180:183], v[188:191], v[114:117]
	v_mfma_f32_16x16x32_bf16 v[102:105], v[172:175], v[200:203], v[102:105]
	v_mfma_f32_16x16x32_bf16 v[98:101], v[180:183], v[200:203], v[98:101]
	v_mfma_f32_16x16x32_bf16 v[86:89], v[172:175], v[208:211], v[86:89]
	v_mfma_f32_16x16x32_bf16 v[82:85], v[180:183], v[208:211], v[82:85]
	v_mfma_f32_16x16x32_bf16 v[70:73], v[172:175], v[216:219], v[70:73]
	s_barrier
	v_mfma_f32_16x16x32_bf16 v[66:69], v[180:183], v[216:219], v[66:69]
	s_setprio 2
	s_add_i32 s25, s54, s33
	v_lshl_add_u64 v[144:145], s[40:41], 0, v[132:133]
	s_mov_b32 m0, s25
	ds_read_b128 v[184:187], v151 offset:16384
	ds_read_b128 v[188:191], v151 offset:17408
	ds_read_b128 v[196:199], v151 offset:18432
	ds_read_b128 v[200:203], v151 offset:19456
	ds_read_b128 v[204:207], v151 offset:20480
	ds_read_b128 v[208:211], v151 offset:21504
	ds_read_b128 v[212:215], v151 offset:22528
	ds_read_b128 v[216:219], v151 offset:23552
	global_load_lds_dwordx4 v132, s[40:41]
	s_add_i32 m0, s25, 0x2000
	s_add_u32 s44, s40, 0x80000
	v_lshl_add_u64 v[192:193], s[40:41], 0, v[136:137]
	s_addc_u32 s45, s41, 0
	s_add_i32 s25, s55, s33
	global_load_lds_dwordx4 v136, s[40:41]
	s_mov_b32 m0, s25
	v_lshl_add_u64 v[222:223], s[42:43], 0, v[134:135]
	global_load_lds_dwordx4 v132, s[44:45]
	s_add_i32 m0, s25, 0x2000
	s_nop 0
	global_load_lds_dwordx4 v136, s[44:45]
	v_lshl_add_u64 v[220:221], s[42:43], 0, v[130:131]
	s_mov_b32 m0, s35
	s_nop 0
	global_load_lds_dwordx4 v130, s[42:43]
	s_mov_b32 m0, s47
	s_nop 0
	global_load_lds_dwordx4 v134, s[42:43]
	s_waitcnt vmcnt(8)
	s_waitcnt lgkmcnt(0)
	s_barrier
	s_setprio 1
	s_waitcnt lgkmcnt(0)
	v_mfma_f32_16x16x32_bf16 v[62:65], v[152:155], v[184:187], v[62:65]
	v_mfma_f32_16x16x32_bf16 v[58:61], v[160:163], v[184:187], v[58:61]
	v_mfma_f32_16x16x32_bf16 v[46:49], v[152:155], v[196:199], v[46:49]
	v_mfma_f32_16x16x32_bf16 v[42:45], v[160:163], v[196:199], v[42:45]
	v_mfma_f32_16x16x32_bf16 v[30:33], v[152:155], v[204:207], v[30:33]
	v_mfma_f32_16x16x32_bf16 v[26:29], v[160:163], v[204:207], v[26:29]
	v_mfma_f32_16x16x32_bf16 v[14:17], v[152:155], v[212:215], v[14:17]
	v_mfma_f32_16x16x32_bf16 v[10:13], v[160:163], v[212:215], v[10:13]
	v_mfma_f32_16x16x32_bf16 v[62:65], v[156:159], v[188:191], v[62:65]
	v_mfma_f32_16x16x32_bf16 v[58:61], v[164:167], v[188:191], v[58:61]
	v_mfma_f32_16x16x32_bf16 v[46:49], v[156:159], v[200:203], v[46:49]
	v_mfma_f32_16x16x32_bf16 v[42:45], v[164:167], v[200:203], v[42:45]
	v_mfma_f32_16x16x32_bf16 v[30:33], v[156:159], v[208:211], v[30:33]
	v_mfma_f32_16x16x32_bf16 v[26:29], v[164:167], v[208:211], v[26:29]
	v_mfma_f32_16x16x32_bf16 v[14:17], v[156:159], v[216:219], v[14:17]
	v_mfma_f32_16x16x32_bf16 v[10:13], v[164:167], v[216:219], v[10:13]
	v_mfma_f32_16x16x32_bf16 v[54:57], v[168:171], v[184:187], v[54:57]
	v_mfma_f32_16x16x32_bf16 v[50:53], v[176:179], v[184:187], v[50:53]
	v_mfma_f32_16x16x32_bf16 v[38:41], v[168:171], v[196:199], v[38:41]
	v_mfma_f32_16x16x32_bf16 v[34:37], v[176:179], v[196:199], v[34:37]
	v_mfma_f32_16x16x32_bf16 v[22:25], v[168:171], v[204:207], v[22:25]
	v_mfma_f32_16x16x32_bf16 v[18:21], v[176:179], v[204:207], v[18:21]
	v_mfma_f32_16x16x32_bf16 v[6:9], v[168:171], v[212:215], v[6:9]
	v_mfma_f32_16x16x32_bf16 v[2:5], v[176:179], v[212:215], v[2:5]
	v_mfma_f32_16x16x32_bf16 v[54:57], v[172:175], v[188:191], v[54:57]
	v_mfma_f32_16x16x32_bf16 v[50:53], v[180:183], v[188:191], v[50:53]
	v_mfma_f32_16x16x32_bf16 v[38:41], v[172:175], v[200:203], v[38:41]
	v_mfma_f32_16x16x32_bf16 v[34:37], v[180:183], v[200:203], v[34:37]
	v_mfma_f32_16x16x32_bf16 v[22:25], v[172:175], v[208:211], v[22:25]
	v_mfma_f32_16x16x32_bf16 v[18:21], v[180:183], v[208:211], v[18:21]
	v_mfma_f32_16x16x32_bf16 v[6:9], v[172:175], v[216:219], v[6:9]
	s_barrier
	v_mfma_f32_16x16x32_bf16 v[2:5], v[180:183], v[216:219], v[2:5]
	s_setprio 2
	s_add_i32 s25, 0, 0x18000
	s_add_i32 s44, 0, 0x1c000
	ds_read_b128 v[152:155], v250
	ds_read_b128 v[156:159], v250 offset:1024
	ds_read_b128 v[160:163], v250 offset:2048
	ds_read_b128 v[164:167], v250 offset:3072
	ds_read_b128 v[168:171], v250 offset:16384
	ds_read_b128 v[172:175], v250 offset:17408
	ds_read_b128 v[176:179], v250 offset:18432
	ds_read_b128 v[180:183], v250 offset:19456
	s_add_u32 s42, s42, 0x80000
	s_addc_u32 s43, s43, 0
	s_mov_b32 m0, s48
	ds_read_b128 v[184:187], v151 offset:32768
	ds_read_b128 v[188:191], v151 offset:33792
	ds_read_b128 v[196:199], v151 offset:34816
	ds_read_b128 v[200:203], v151 offset:35840
	ds_read_b128 v[204:207], v151 offset:36864
	ds_read_b128 v[208:211], v151 offset:37888
	ds_read_b128 v[212:215], v151 offset:38912
	ds_read_b128 v[216:219], v151 offset:39936
	global_load_lds_dwordx4 v130, s[42:43]
	v_lshl_add_u64 v[224:225], s[42:43], 0, v[134:135]
	s_mov_b32 m0, s49
	s_nop 0
	global_load_lds_dwordx4 v134, s[42:43]
	s_waitcnt vmcnt(8)
	s_waitcnt lgkmcnt(0)
	s_barrier
	s_setprio 1
	s_waitcnt lgkmcnt(0)
	v_mfma_f32_16x16x32_bf16 v[126:129], v[152:155], v[184:187], v[126:129]
	v_mfma_f32_16x16x32_bf16 v[122:125], v[160:163], v[184:187], v[122:125]
	v_mfma_f32_16x16x32_bf16 v[110:113], v[152:155], v[196:199], v[110:113]
	v_mfma_f32_16x16x32_bf16 v[106:109], v[160:163], v[196:199], v[106:109]
	v_mfma_f32_16x16x32_bf16 v[94:97], v[152:155], v[204:207], v[94:97]
	v_mfma_f32_16x16x32_bf16 v[90:93], v[160:163], v[204:207], v[90:93]
	v_mfma_f32_16x16x32_bf16 v[78:81], v[152:155], v[212:215], v[78:81]
	v_mfma_f32_16x16x32_bf16 v[74:77], v[160:163], v[212:215], v[74:77]
	v_mfma_f32_16x16x32_bf16 v[126:129], v[156:159], v[188:191], v[126:129]
	v_mfma_f32_16x16x32_bf16 v[122:125], v[164:167], v[188:191], v[122:125]
	v_mfma_f32_16x16x32_bf16 v[110:113], v[156:159], v[200:203], v[110:113]
	v_mfma_f32_16x16x32_bf16 v[106:109], v[164:167], v[200:203], v[106:109]
	v_mfma_f32_16x16x32_bf16 v[94:97], v[156:159], v[208:211], v[94:97]
	v_mfma_f32_16x16x32_bf16 v[90:93], v[164:167], v[208:211], v[90:93]
	v_mfma_f32_16x16x32_bf16 v[78:81], v[156:159], v[216:219], v[78:81]
	v_mfma_f32_16x16x32_bf16 v[74:77], v[164:167], v[216:219], v[74:77]
	v_mfma_f32_16x16x32_bf16 v[118:121], v[168:171], v[184:187], v[118:121]
	v_mfma_f32_16x16x32_bf16 v[114:117], v[176:179], v[184:187], v[114:117]
	v_mfma_f32_16x16x32_bf16 v[102:105], v[168:171], v[196:199], v[102:105]
	v_mfma_f32_16x16x32_bf16 v[98:101], v[176:179], v[196:199], v[98:101]
	v_mfma_f32_16x16x32_bf16 v[86:89], v[168:171], v[204:207], v[86:89]
	v_mfma_f32_16x16x32_bf16 v[82:85], v[176:179], v[204:207], v[82:85]
	v_mfma_f32_16x16x32_bf16 v[70:73], v[168:171], v[212:215], v[70:73]
	v_mfma_f32_16x16x32_bf16 v[66:69], v[176:179], v[212:215], v[66:69]
	v_mfma_f32_16x16x32_bf16 v[118:121], v[172:175], v[188:191], v[118:121]
	v_mfma_f32_16x16x32_bf16 v[114:117], v[180:183], v[188:191], v[114:117]
	v_mfma_f32_16x16x32_bf16 v[102:105], v[172:175], v[200:203], v[102:105]
	v_mfma_f32_16x16x32_bf16 v[98:101], v[180:183], v[200:203], v[98:101]
	v_mfma_f32_16x16x32_bf16 v[86:89], v[172:175], v[208:211], v[86:89]
	v_mfma_f32_16x16x32_bf16 v[82:85], v[180:183], v[208:211], v[82:85]
	v_mfma_f32_16x16x32_bf16 v[70:73], v[172:175], v[216:219], v[70:73]
	s_barrier
	v_mfma_f32_16x16x32_bf16 v[66:69], v[180:183], v[216:219], v[66:69]
	s_setprio 2
	s_add_i32 s25, s25, s33
	v_lshl_add_u64 v[144:145], v[144:145], 0, s[16:17]
	s_mov_b32 m0, s25
	ds_read_b128 v[184:187], v151 offset:49152
	ds_read_b128 v[188:191], v151 offset:50176
	ds_read_b128 v[196:199], v151 offset:51200
	ds_read_b128 v[200:203], v151 offset:52224
	ds_read_b128 v[204:207], v151 offset:53248
	ds_read_b128 v[208:211], v151 offset:54272
	ds_read_b128 v[212:215], v151 offset:55296
	ds_read_b128 v[216:219], v151 offset:56320
	global_load_lds_dwordx4 v[144:145], off
	s_add_i32 m0, s25, 0x2000
	s_add_u32 s40, s40, 0x80080
	v_lshl_add_u64 v[144:145], v[192:193], 0, s[16:17]
	s_addc_u32 s41, s41, 0
	s_add_i32 s25, s44, s33
	global_load_lds_dwordx4 v[144:145], off
	s_mov_b32 m0, s25
	s_nop 0
	global_load_lds_dwordx4 v132, s[40:41]
	s_add_i32 m0, s25, 0x2000
	s_nop 0
	global_load_lds_dwordx4 v136, s[40:41]
	v_lshl_add_u64 v[144:145], v[220:221], 0, s[16:17]
	s_mov_b32 m0, s50
	s_nop 0
	global_load_lds_dwordx4 v[144:145], off
	v_lshl_add_u64 v[144:145], v[222:223], 0, s[16:17]
	s_mov_b32 m0, s51
	s_nop 0
	global_load_lds_dwordx4 v[144:145], off
	s_waitcnt vmcnt(8)
	s_waitcnt lgkmcnt(0)
	s_barrier
	s_setprio 1
	s_waitcnt lgkmcnt(0)
	v_mfma_f32_16x16x32_bf16 v[62:65], v[152:155], v[184:187], v[62:65]
	v_mfma_f32_16x16x32_bf16 v[58:61], v[160:163], v[184:187], v[58:61]
	v_mfma_f32_16x16x32_bf16 v[46:49], v[152:155], v[196:199], v[46:49]
	v_mfma_f32_16x16x32_bf16 v[42:45], v[160:163], v[196:199], v[42:45]
	v_mfma_f32_16x16x32_bf16 v[30:33], v[152:155], v[204:207], v[30:33]
	v_mfma_f32_16x16x32_bf16 v[26:29], v[160:163], v[204:207], v[26:29]
	v_mfma_f32_16x16x32_bf16 v[14:17], v[152:155], v[212:215], v[14:17]
	v_mfma_f32_16x16x32_bf16 v[10:13], v[160:163], v[212:215], v[10:13]
	v_mfma_f32_16x16x32_bf16 v[62:65], v[156:159], v[188:191], v[62:65]
	v_mfma_f32_16x16x32_bf16 v[58:61], v[164:167], v[188:191], v[58:61]
	v_mfma_f32_16x16x32_bf16 v[46:49], v[156:159], v[200:203], v[46:49]
	v_mfma_f32_16x16x32_bf16 v[42:45], v[164:167], v[200:203], v[42:45]
	v_mfma_f32_16x16x32_bf16 v[30:33], v[156:159], v[208:211], v[30:33]
	v_mfma_f32_16x16x32_bf16 v[26:29], v[164:167], v[208:211], v[26:29]
	v_mfma_f32_16x16x32_bf16 v[14:17], v[156:159], v[216:219], v[14:17]
	v_mfma_f32_16x16x32_bf16 v[10:13], v[164:167], v[216:219], v[10:13]
	v_mfma_f32_16x16x32_bf16 v[54:57], v[168:171], v[184:187], v[54:57]
	v_mfma_f32_16x16x32_bf16 v[50:53], v[176:179], v[184:187], v[50:53]
	v_mfma_f32_16x16x32_bf16 v[38:41], v[168:171], v[196:199], v[38:41]
	v_mfma_f32_16x16x32_bf16 v[34:37], v[176:179], v[196:199], v[34:37]
	v_mfma_f32_16x16x32_bf16 v[22:25], v[168:171], v[204:207], v[22:25]
	v_mfma_f32_16x16x32_bf16 v[18:21], v[176:179], v[204:207], v[18:21]
	v_mfma_f32_16x16x32_bf16 v[6:9], v[168:171], v[212:215], v[6:9]
	v_mfma_f32_16x16x32_bf16 v[2:5], v[176:179], v[212:215], v[2:5]
	v_mfma_f32_16x16x32_bf16 v[54:57], v[172:175], v[188:191], v[54:57]
	v_mfma_f32_16x16x32_bf16 v[50:53], v[180:183], v[188:191], v[50:53]
	v_mfma_f32_16x16x32_bf16 v[38:41], v[172:175], v[200:203], v[38:41]
	v_mfma_f32_16x16x32_bf16 v[34:37], v[180:183], v[200:203], v[34:37]
	v_mfma_f32_16x16x32_bf16 v[22:25], v[172:175], v[208:211], v[22:25]
	v_mfma_f32_16x16x32_bf16 v[18:21], v[180:183], v[208:211], v[18:21]
	v_mfma_f32_16x16x32_bf16 v[6:9], v[172:175], v[216:219], v[6:9]
	s_barrier
	v_mfma_f32_16x16x32_bf16 v[2:5], v[180:183], v[216:219], v[2:5]
	s_setprio 2
	s_add_u32 s38, s38, 0x100
	s_addc_u32 s39, s39, 0
	s_add_u32 s21, s21, 0x100
	s_addc_u32 s23, s23, 0
	s_cmp_ge_i32 s37, s62
	s_mov_b32 s25, s37
	s_cbranch_scc0 .LBB0_221

.Lpeel_12:
	v_add_u32_e32 v250, 0x18000, v213
	ds_read_b128 v[130:133], v215
	ds_read_b128 v[134:137], v215 offset:1024
	ds_read_b128 v[138:141], v215 offset:2048
	ds_read_b128 v[142:145], v215 offset:3072
	ds_read_b128 v[146:149], v216
	ds_read_b128 v[150:153], v216 offset:1024
	ds_read_b128 v[154:157], v216 offset:2048
	ds_read_b128 v[158:161], v216 offset:3072
	s_add_i32 s38, s34, 2
	s_add_u32 s35, s30, 0xffea0080
	s_addc_u32 s36, s31, -1
	s_cmp_eq_u32 s28, s34
	s_cselect_b32 s34, s26, s23
	s_cselect_b32 s37, s25, s36
	s_cselect_b32 s36, s24, s35
	s_cselect_b32 s35, s27, s29
	s_add_i32 m0, s40, 0xc000
	ds_read_b128 v[162:165], v217
	ds_read_b128 v[166:169], v217 offset:1024
	ds_read_b128 v[170:173], v217 offset:2048
	ds_read_b128 v[174:177], v217 offset:3072
	ds_read_b128 v[196:199], v217 offset:4096
	ds_read_b128 v[200:203], v217 offset:5120
	ds_read_b128 v[204:207], v217 offset:6144
	ds_read_b128 v[208:211], v217 offset:7168
	global_load_lds_dwordx4 v188, s[30:31]
	s_add_i32 m0, s40, 0xe000
	s_nop 0
	global_load_lds_dwordx4 v190, s[30:31]
	s_waitcnt vmcnt(8)
	s_waitcnt lgkmcnt(0)
	s_barrier
	s_setprio 1
	s_waitcnt lgkmcnt(0)
	v_mfma_f32_16x16x32_bf16 v[126:129], v[130:133], v[162:165], 0
	v_mfma_f32_16x16x32_bf16 v[122:125], v[138:141], v[162:165], 0
	v_mfma_f32_16x16x32_bf16 v[118:121], v[130:133], v[170:173], 0
	v_mfma_f32_16x16x32_bf16 v[114:117], v[138:141], v[170:173], 0
	v_mfma_f32_16x16x32_bf16 v[94:97], v[130:133], v[196:199], 0
	v_mfma_f32_16x16x32_bf16 v[90:93], v[138:141], v[196:199], 0
	v_mfma_f32_16x16x32_bf16 v[86:89], v[130:133], v[204:207], 0
	v_mfma_f32_16x16x32_bf16 v[82:85], v[138:141], v[204:207], 0
	v_mfma_f32_16x16x32_bf16 v[126:129], v[134:137], v[166:169], v[126:129]
	v_mfma_f32_16x16x32_bf16 v[122:125], v[142:145], v[166:169], v[122:125]
	v_mfma_f32_16x16x32_bf16 v[118:121], v[134:137], v[174:177], v[118:121]
	v_mfma_f32_16x16x32_bf16 v[114:117], v[142:145], v[174:177], v[114:117]
	v_mfma_f32_16x16x32_bf16 v[94:97], v[134:137], v[200:203], v[94:97]
	v_mfma_f32_16x16x32_bf16 v[90:93], v[142:145], v[200:203], v[90:93]
	v_mfma_f32_16x16x32_bf16 v[86:89], v[134:137], v[208:211], v[86:89]
	v_mfma_f32_16x16x32_bf16 v[82:85], v[142:145], v[208:211], v[82:85]
	v_mfma_f32_16x16x32_bf16 v[110:113], v[146:149], v[162:165], 0
	v_mfma_f32_16x16x32_bf16 v[106:109], v[154:157], v[162:165], 0
	v_mfma_f32_16x16x32_bf16 v[102:105], v[146:149], v[170:173], 0
	v_mfma_f32_16x16x32_bf16 v[98:101], v[154:157], v[170:173], 0
	v_mfma_f32_16x16x32_bf16 v[78:81], v[146:149], v[196:199], 0
	v_mfma_f32_16x16x32_bf16 v[74:77], v[154:157], v[196:199], 0
	v_mfma_f32_16x16x32_bf16 v[70:73], v[146:149], v[204:207], 0
	v_mfma_f32_16x16x32_bf16 v[66:69], v[154:157], v[204:207], 0
	v_mfma_f32_16x16x32_bf16 v[110:113], v[150:153], v[166:169], v[110:113]
	v_mfma_f32_16x16x32_bf16 v[106:109], v[158:161], v[166:169], v[106:109]
	v_mfma_f32_16x16x32_bf16 v[102:105], v[150:153], v[174:177], v[102:105]
	v_mfma_f32_16x16x32_bf16 v[98:101], v[158:161], v[174:177], v[98:101]
	v_mfma_f32_16x16x32_bf16 v[78:81], v[150:153], v[200:203], v[78:81]
	v_mfma_f32_16x16x32_bf16 v[74:77], v[158:161], v[200:203], v[74:77]
	v_mfma_f32_16x16x32_bf16 v[70:73], v[150:153], v[208:211], v[70:73]
	s_barrier
	v_mfma_f32_16x16x32_bf16 v[66:69], v[158:161], v[208:211], v[66:69]
	s_setprio 2
	s_add_i32 s39, s53, s33
	v_lshl_add_u64 v[192:193], s[34:35], 0, v[180:181]
	s_mov_b32 m0, s39
	ds_read_b128 v[162:165], v217 offset:16384
	ds_read_b128 v[166:169], v217 offset:17408
	ds_read_b128 v[170:173], v217 offset:18432
	ds_read_b128 v[174:177], v217 offset:19456
	ds_read_b128 v[196:199], v217 offset:20480
	ds_read_b128 v[200:203], v217 offset:21504
	ds_read_b128 v[204:207], v217 offset:22528
	ds_read_b128 v[208:211], v217 offset:23552
	global_load_lds_dwordx4 v180, s[34:35]
	s_add_i32 m0, s39, 0x2000
	s_add_u32 s62, s34, 0x160000
	v_lshl_add_u64 v[218:219], s[34:35], 0, v[184:185]
	s_addc_u32 s63, s35, 0
	s_add_i32 s39, s54, s33
	global_load_lds_dwordx4 v184, s[34:35]
	s_mov_b32 m0, s39
	v_lshl_add_u64 v[222:223], s[36:37], 0, v[182:183]
	global_load_lds_dwordx4 v180, s[62:63]
	s_add_i32 m0, s39, 0x2000
	s_nop 0
	global_load_lds_dwordx4 v184, s[62:63]
	v_lshl_add_u64 v[220:221], s[36:37], 0, v[178:179]
	s_mov_b32 m0, s40
	s_nop 0
	global_load_lds_dwordx4 v178, s[36:37]
	s_mov_b32 m0, s41
	s_nop 0
	global_load_lds_dwordx4 v182, s[36:37]
	s_waitcnt vmcnt(8)
	s_waitcnt lgkmcnt(0)
	s_barrier
	s_setprio 1
	s_waitcnt lgkmcnt(0)
	v_mfma_f32_16x16x32_bf16 v[62:65], v[130:133], v[162:165], 0
	v_mfma_f32_16x16x32_bf16 v[58:61], v[138:141], v[162:165], 0
	v_mfma_f32_16x16x32_bf16 v[54:57], v[130:133], v[170:173], 0
	v_mfma_f32_16x16x32_bf16 v[50:53], v[138:141], v[170:173], 0
	v_mfma_f32_16x16x32_bf16 v[30:33], v[130:133], v[196:199], 0
	v_mfma_f32_16x16x32_bf16 v[26:29], v[138:141], v[196:199], 0
	v_mfma_f32_16x16x32_bf16 v[22:25], v[130:133], v[204:207], 0
	v_mfma_f32_16x16x32_bf16 v[18:21], v[138:141], v[204:207], 0
	v_mfma_f32_16x16x32_bf16 v[62:65], v[134:137], v[166:169], v[62:65]
	v_mfma_f32_16x16x32_bf16 v[58:61], v[142:145], v[166:169], v[58:61]
	v_mfma_f32_16x16x32_bf16 v[54:57], v[134:137], v[174:177], v[54:57]
	v_mfma_f32_16x16x32_bf16 v[50:53], v[142:145], v[174:177], v[50:53]
	v_mfma_f32_16x16x32_bf16 v[30:33], v[134:137], v[200:203], v[30:33]
	v_mfma_f32_16x16x32_bf16 v[26:29], v[142:145], v[200:203], v[26:29]
	v_mfma_f32_16x16x32_bf16 v[22:25], v[134:137], v[208:211], v[22:25]
	v_mfma_f32_16x16x32_bf16 v[18:21], v[142:145], v[208:211], v[18:21]
	v_mfma_f32_16x16x32_bf16 v[46:49], v[146:149], v[162:165], 0
	v_mfma_f32_16x16x32_bf16 v[42:45], v[154:157], v[162:165], 0
	v_mfma_f32_16x16x32_bf16 v[38:41], v[146:149], v[170:173], 0
	v_mfma_f32_16x16x32_bf16 v[34:37], v[154:157], v[170:173], 0
	v_mfma_f32_16x16x32_bf16 v[14:17], v[146:149], v[196:199], 0
	v_mfma_f32_16x16x32_bf16 v[10:13], v[154:157], v[196:199], 0
	v_mfma_f32_16x16x32_bf16 v[6:9], v[146:149], v[204:207], 0
	v_mfma_f32_16x16x32_bf16 v[2:5], v[154:157], v[204:207], 0
	v_mfma_f32_16x16x32_bf16 v[46:49], v[150:153], v[166:169], v[46:49]
	v_mfma_f32_16x16x32_bf16 v[42:45], v[158:161], v[166:169], v[42:45]
	v_mfma_f32_16x16x32_bf16 v[38:41], v[150:153], v[174:177], v[38:41]
	v_mfma_f32_16x16x32_bf16 v[34:37], v[158:161], v[174:177], v[34:37]
	v_mfma_f32_16x16x32_bf16 v[14:17], v[150:153], v[200:203], v[14:17]
	v_mfma_f32_16x16x32_bf16 v[10:13], v[158:161], v[200:203], v[10:13]
	v_mfma_f32_16x16x32_bf16 v[6:9], v[150:153], v[208:211], v[6:9]
	s_barrier
	v_mfma_f32_16x16x32_bf16 v[2:5], v[158:161], v[208:211], v[2:5]
	s_setprio 2
	s_add_i32 s39, 0, 0x18000
	s_add_i32 s62, 0, 0x1c000
	ds_read_b128 v[130:133], v250
	ds_read_b128 v[134:137], v250 offset:1024
	ds_read_b128 v[138:141], v250 offset:2048
	ds_read_b128 v[142:145], v250 offset:3072
	ds_read_b128 v[146:149], v250 offset:16384
	ds_read_b128 v[150:153], v250 offset:17408
	ds_read_b128 v[154:157], v250 offset:18432
	ds_read_b128 v[158:161], v250 offset:19456
	s_add_u32 s36, s36, 0x160000
	s_addc_u32 s37, s37, 0
	s_mov_b32 m0, s42
	ds_read_b128 v[162:165], v217 offset:32768
	ds_read_b128 v[166:169], v217 offset:33792
	ds_read_b128 v[170:173], v217 offset:34816
	ds_read_b128 v[174:177], v217 offset:35840
	ds_read_b128 v[196:199], v217 offset:36864
	ds_read_b128 v[200:203], v217 offset:37888
	ds_read_b128 v[204:207], v217 offset:38912
	ds_read_b128 v[208:211], v217 offset:39936
	global_load_lds_dwordx4 v178, s[36:37]
	v_lshl_add_u64 v[224:225], s[36:37], 0, v[182:183]
	s_mov_b32 m0, s43
	s_nop 0
	global_load_lds_dwordx4 v182, s[36:37]
	s_waitcnt vmcnt(8)
	s_waitcnt lgkmcnt(0)
	s_barrier
	s_setprio 1
	s_waitcnt lgkmcnt(0)
	v_mfma_f32_16x16x32_bf16 v[126:129], v[130:133], v[162:165], v[126:129]
	v_mfma_f32_16x16x32_bf16 v[122:125], v[138:141], v[162:165], v[122:125]
	v_mfma_f32_16x16x32_bf16 v[118:121], v[130:133], v[170:173], v[118:121]
	v_mfma_f32_16x16x32_bf16 v[114:117], v[138:141], v[170:173], v[114:117]
	v_mfma_f32_16x16x32_bf16 v[94:97], v[130:133], v[196:199], v[94:97]
	v_mfma_f32_16x16x32_bf16 v[90:93], v[138:141], v[196:199], v[90:93]
	v_mfma_f32_16x16x32_bf16 v[86:89], v[130:133], v[204:207], v[86:89]
	v_mfma_f32_16x16x32_bf16 v[82:85], v[138:141], v[204:207], v[82:85]
	v_mfma_f32_16x16x32_bf16 v[126:129], v[134:137], v[166:169], v[126:129]
	v_mfma_f32_16x16x32_bf16 v[122:125], v[142:145], v[166:169], v[122:125]
	v_mfma_f32_16x16x32_bf16 v[118:121], v[134:137], v[174:177], v[118:121]
	v_mfma_f32_16x16x32_bf16 v[114:117], v[142:145], v[174:177], v[114:117]
	v_mfma_f32_16x16x32_bf16 v[94:97], v[134:137], v[200:203], v[94:97]
	v_mfma_f32_16x16x32_bf16 v[90:93], v[142:145], v[200:203], v[90:93]
	v_mfma_f32_16x16x32_bf16 v[86:89], v[134:137], v[208:211], v[86:89]
	v_mfma_f32_16x16x32_bf16 v[82:85], v[142:145], v[208:211], v[82:85]
	v_mfma_f32_16x16x32_bf16 v[110:113], v[146:149], v[162:165], v[110:113]
	v_mfma_f32_16x16x32_bf16 v[106:109], v[154:157], v[162:165], v[106:109]
	v_mfma_f32_16x16x32_bf16 v[102:105], v[146:149], v[170:173], v[102:105]
	v_mfma_f32_16x16x32_bf16 v[98:101], v[154:157], v[170:173], v[98:101]
	v_mfma_f32_16x16x32_bf16 v[78:81], v[146:149], v[196:199], v[78:81]
	v_mfma_f32_16x16x32_bf16 v[74:77], v[154:157], v[196:199], v[74:77]
	v_mfma_f32_16x16x32_bf16 v[70:73], v[146:149], v[204:207], v[70:73]
	v_mfma_f32_16x16x32_bf16 v[66:69], v[154:157], v[204:207], v[66:69]
	v_mfma_f32_16x16x32_bf16 v[110:113], v[150:153], v[166:169], v[110:113]
	v_mfma_f32_16x16x32_bf16 v[106:109], v[158:161], v[166:169], v[106:109]
	v_mfma_f32_16x16x32_bf16 v[102:105], v[150:153], v[174:177], v[102:105]
	v_mfma_f32_16x16x32_bf16 v[98:101], v[158:161], v[174:177], v[98:101]
	v_mfma_f32_16x16x32_bf16 v[78:81], v[150:153], v[200:203], v[78:81]
	v_mfma_f32_16x16x32_bf16 v[74:77], v[158:161], v[200:203], v[74:77]
	v_mfma_f32_16x16x32_bf16 v[70:73], v[150:153], v[208:211], v[70:73]
	s_barrier
	v_mfma_f32_16x16x32_bf16 v[66:69], v[158:161], v[208:211], v[66:69]
	s_setprio 2
	s_add_i32 s36, s39, s33
	v_lshl_add_u64 v[192:193], v[192:193], 0, s[18:19]
	s_mov_b32 m0, s36
	ds_read_b128 v[162:165], v217 offset:49152
	ds_read_b128 v[166:169], v217 offset:50176
	ds_read_b128 v[170:173], v217 offset:51200
	ds_read_b128 v[174:177], v217 offset:52224
	ds_read_b128 v[196:199], v217 offset:53248
	ds_read_b128 v[200:203], v217 offset:54272
	ds_read_b128 v[204:207], v217 offset:55296
	ds_read_b128 v[208:211], v217 offset:56320
	global_load_lds_dwordx4 v[192:193], off
	s_add_i32 m0, s36, 0x2000
	s_add_u32 s34, s34, 0x160080
	v_lshl_add_u64 v[192:193], v[218:219], 0, s[18:19]
	s_addc_u32 s35, s35, 0
	s_add_i32 s36, s62, s33
	global_load_lds_dwordx4 v[192:193], off
	s_mov_b32 m0, s36
	s_nop 0
	global_load_lds_dwordx4 v180, s[34:35]
	s_add_i32 m0, s36, 0x2000
	s_nop 0
	global_load_lds_dwordx4 v184, s[34:35]
	v_lshl_add_u64 v[192:193], v[220:221], 0, s[18:19]
	s_mov_b32 m0, s46
	s_nop 0
	global_load_lds_dwordx4 v[192:193], off
	v_lshl_add_u64 v[192:193], v[222:223], 0, s[18:19]
	s_mov_b32 m0, s47
	s_nop 0
	global_load_lds_dwordx4 v[192:193], off
	s_waitcnt vmcnt(8)
	s_waitcnt lgkmcnt(0)
	s_barrier
	s_setprio 1
	s_waitcnt lgkmcnt(0)
	v_mfma_f32_16x16x32_bf16 v[62:65], v[130:133], v[162:165], v[62:65]
	v_mfma_f32_16x16x32_bf16 v[58:61], v[138:141], v[162:165], v[58:61]
	v_mfma_f32_16x16x32_bf16 v[54:57], v[130:133], v[170:173], v[54:57]
	v_mfma_f32_16x16x32_bf16 v[50:53], v[138:141], v[170:173], v[50:53]
	v_mfma_f32_16x16x32_bf16 v[30:33], v[130:133], v[196:199], v[30:33]
	v_mfma_f32_16x16x32_bf16 v[26:29], v[138:141], v[196:199], v[26:29]
	v_mfma_f32_16x16x32_bf16 v[22:25], v[130:133], v[204:207], v[22:25]
	v_mfma_f32_16x16x32_bf16 v[18:21], v[138:141], v[204:207], v[18:21]
	v_mfma_f32_16x16x32_bf16 v[62:65], v[134:137], v[166:169], v[62:65]
	v_mfma_f32_16x16x32_bf16 v[58:61], v[142:145], v[166:169], v[58:61]
	v_mfma_f32_16x16x32_bf16 v[54:57], v[134:137], v[174:177], v[54:57]
	v_mfma_f32_16x16x32_bf16 v[50:53], v[142:145], v[174:177], v[50:53]
	v_mfma_f32_16x16x32_bf16 v[30:33], v[134:137], v[200:203], v[30:33]
	v_mfma_f32_16x16x32_bf16 v[26:29], v[142:145], v[200:203], v[26:29]
	v_mfma_f32_16x16x32_bf16 v[22:25], v[134:137], v[208:211], v[22:25]
	v_mfma_f32_16x16x32_bf16 v[18:21], v[142:145], v[208:211], v[18:21]
	v_mfma_f32_16x16x32_bf16 v[46:49], v[146:149], v[162:165], v[46:49]
	v_mfma_f32_16x16x32_bf16 v[42:45], v[154:157], v[162:165], v[42:45]
	v_mfma_f32_16x16x32_bf16 v[38:41], v[146:149], v[170:173], v[38:41]
	v_mfma_f32_16x16x32_bf16 v[34:37], v[154:157], v[170:173], v[34:37]
	v_mfma_f32_16x16x32_bf16 v[14:17], v[146:149], v[196:199], v[14:17]
	v_mfma_f32_16x16x32_bf16 v[10:13], v[154:157], v[196:199], v[10:13]
	v_mfma_f32_16x16x32_bf16 v[6:9], v[146:149], v[204:207], v[6:9]
	v_mfma_f32_16x16x32_bf16 v[2:5], v[154:157], v[204:207], v[2:5]
	v_mfma_f32_16x16x32_bf16 v[46:49], v[150:153], v[166:169], v[46:49]
	v_mfma_f32_16x16x32_bf16 v[42:45], v[158:161], v[166:169], v[42:45]
	v_mfma_f32_16x16x32_bf16 v[38:41], v[150:153], v[174:177], v[38:41]
	v_mfma_f32_16x16x32_bf16 v[34:37], v[158:161], v[174:177], v[34:37]
	v_mfma_f32_16x16x32_bf16 v[14:17], v[150:153], v[200:203], v[14:17]
	v_mfma_f32_16x16x32_bf16 v[10:13], v[158:161], v[200:203], v[10:13]
	v_mfma_f32_16x16x32_bf16 v[6:9], v[150:153], v[208:211], v[6:9]
	s_barrier
	v_mfma_f32_16x16x32_bf16 v[2:5], v[158:161], v[208:211], v[2:5]
	s_setprio 2
	s_add_u32 s30, s30, 0x100
	s_addc_u32 s31, s31, 0
	s_add_u32 s23, s23, 0x100
	s_addc_u32 s29, s29, 0
	s_cmp_ge_i32 s38, s61
	s_mov_b32 s34, s38
	s_cbranch_scc0 .LBB0_357
	s_branch .Lpeeldone_12
.LBB0_357:
	ds_read_b128 v[130:133], v215
	ds_read_b128 v[134:137], v215 offset:1024
	ds_read_b128 v[138:141], v215 offset:2048
	ds_read_b128 v[142:145], v215 offset:3072
	ds_read_b128 v[146:149], v216
	ds_read_b128 v[150:153], v216 offset:1024
	ds_read_b128 v[154:157], v216 offset:2048
	ds_read_b128 v[158:161], v216 offset:3072
	s_add_i32 s38, s34, 2
	s_add_u32 s35, s30, 0xffea0080
	s_addc_u32 s36, s31, -1
	s_cmp_eq_u32 s28, s34
	s_cselect_b32 s34, s26, s23
	s_cselect_b32 s37, s25, s36
	s_cselect_b32 s36, s24, s35
	s_cselect_b32 s35, s27, s29
	s_add_i32 m0, s40, 0xc000
	ds_read_b128 v[162:165], v217
	ds_read_b128 v[166:169], v217 offset:1024
	ds_read_b128 v[170:173], v217 offset:2048
	ds_read_b128 v[174:177], v217 offset:3072
	ds_read_b128 v[196:199], v217 offset:4096
	ds_read_b128 v[200:203], v217 offset:5120
	ds_read_b128 v[204:207], v217 offset:6144
	ds_read_b128 v[208:211], v217 offset:7168
	global_load_lds_dwordx4 v188, s[30:31]
	s_add_i32 m0, s40, 0xe000
	s_nop 0
	global_load_lds_dwordx4 v190, s[30:31]
	s_waitcnt vmcnt(8)
	s_waitcnt lgkmcnt(0)
	s_barrier
	s_setprio 1
	s_waitcnt lgkmcnt(0)
	v_mfma_f32_16x16x32_bf16 v[126:129], v[130:133], v[162:165], v[126:129]
	v_mfma_f32_16x16x32_bf16 v[122:125], v[138:141], v[162:165], v[122:125]
	v_mfma_f32_16x16x32_bf16 v[118:121], v[130:133], v[170:173], v[118:121]
	v_mfma_f32_16x16x32_bf16 v[114:117], v[138:141], v[170:173], v[114:117]
	v_mfma_f32_16x16x32_bf16 v[94:97], v[130:133], v[196:199], v[94:97]
	v_mfma_f32_16x16x32_bf16 v[90:93], v[138:141], v[196:199], v[90:93]
	v_mfma_f32_16x16x32_bf16 v[86:89], v[130:133], v[204:207], v[86:89]
	v_mfma_f32_16x16x32_bf16 v[82:85], v[138:141], v[204:207], v[82:85]
	v_mfma_f32_16x16x32_bf16 v[126:129], v[134:137], v[166:169], v[126:129]
	v_mfma_f32_16x16x32_bf16 v[122:125], v[142:145], v[166:169], v[122:125]
	v_mfma_f32_16x16x32_bf16 v[118:121], v[134:137], v[174:177], v[118:121]
	v_mfma_f32_16x16x32_bf16 v[114:117], v[142:145], v[174:177], v[114:117]
	v_mfma_f32_16x16x32_bf16 v[94:97], v[134:137], v[200:203], v[94:97]
	v_mfma_f32_16x16x32_bf16 v[90:93], v[142:145], v[200:203], v[90:93]
	v_mfma_f32_16x16x32_bf16 v[86:89], v[134:137], v[208:211], v[86:89]
	v_mfma_f32_16x16x32_bf16 v[82:85], v[142:145], v[208:211], v[82:85]
	v_mfma_f32_16x16x32_bf16 v[110:113], v[146:149], v[162:165], v[110:113]
	v_mfma_f32_16x16x32_bf16 v[106:109], v[154:157], v[162:165], v[106:109]
	v_mfma_f32_16x16x32_bf16 v[102:105], v[146:149], v[170:173], v[102:105]
	v_mfma_f32_16x16x32_bf16 v[98:101], v[154:157], v[170:173], v[98:101]
	v_mfma_f32_16x16x32_bf16 v[78:81], v[146:149], v[196:199], v[78:81]
	v_mfma_f32_16x16x32_bf16 v[74:77], v[154:157], v[196:199], v[74:77]
	v_mfma_f32_16x16x32_bf16 v[70:73], v[146:149], v[204:207], v[70:73]
	v_mfma_f32_16x16x32_bf16 v[66:69], v[154:157], v[204:207], v[66:69]
	v_mfma_f32_16x16x32_bf16 v[110:113], v[150:153], v[166:169], v[110:113]
	v_mfma_f32_16x16x32_bf16 v[106:109], v[158:161], v[166:169], v[106:109]
	v_mfma_f32_16x16x32_bf16 v[102:105], v[150:153], v[174:177], v[102:105]
	v_mfma_f32_16x16x32_bf16 v[98:101], v[158:161], v[174:177], v[98:101]
	v_mfma_f32_16x16x32_bf16 v[78:81], v[150:153], v[200:203], v[78:81]
	v_mfma_f32_16x16x32_bf16 v[74:77], v[158:161], v[200:203], v[74:77]
	v_mfma_f32_16x16x32_bf16 v[70:73], v[150:153], v[208:211], v[70:73]
	s_barrier
	v_mfma_f32_16x16x32_bf16 v[66:69], v[158:161], v[208:211], v[66:69]
	s_setprio 2
	s_add_i32 s39, s53, s33
	v_lshl_add_u64 v[192:193], s[34:35], 0, v[180:181]
	s_mov_b32 m0, s39
	ds_read_b128 v[162:165], v217 offset:16384
	ds_read_b128 v[166:169], v217 offset:17408
	ds_read_b128 v[170:173], v217 offset:18432
	ds_read_b128 v[174:177], v217 offset:19456
	ds_read_b128 v[196:199], v217 offset:20480
	ds_read_b128 v[200:203], v217 offset:21504
	ds_read_b128 v[204:207], v217 offset:22528
	ds_read_b128 v[208:211], v217 offset:23552
	global_load_lds_dwordx4 v180, s[34:35]
	s_add_i32 m0, s39, 0x2000
	s_add_u32 s62, s34, 0x160000
	v_lshl_add_u64 v[218:219], s[34:35], 0, v[184:185]
	s_addc_u32 s63, s35, 0
	s_add_i32 s39, s54, s33
	global_load_lds_dwordx4 v184, s[34:35]
	s_mov_b32 m0, s39
	v_lshl_add_u64 v[222:223], s[36:37], 0, v[182:183]
	global_load_lds_dwordx4 v180, s[62:63]
	s_add_i32 m0, s39, 0x2000
	s_nop 0
	global_load_lds_dwordx4 v184, s[62:63]
	v_lshl_add_u64 v[220:221], s[36:37], 0, v[178:179]
	s_mov_b32 m0, s40
	s_nop 0
	global_load_lds_dwordx4 v178, s[36:37]
	s_mov_b32 m0, s41
	s_nop 0
	global_load_lds_dwordx4 v182, s[36:37]
	s_waitcnt vmcnt(8)
	s_waitcnt lgkmcnt(0)
	s_barrier
	s_setprio 1
	s_waitcnt lgkmcnt(0)
	v_mfma_f32_16x16x32_bf16 v[62:65], v[130:133], v[162:165], v[62:65]
	v_mfma_f32_16x16x32_bf16 v[58:61], v[138:141], v[162:165], v[58:61]
	v_mfma_f32_16x16x32_bf16 v[54:57], v[130:133], v[170:173], v[54:57]
	v_mfma_f32_16x16x32_bf16 v[50:53], v[138:141], v[170:173], v[50:53]
	v_mfma_f32_16x16x32_bf16 v[30:33], v[130:133], v[196:199], v[30:33]
	v_mfma_f32_16x16x32_bf16 v[26:29], v[138:141], v[196:199], v[26:29]
	v_mfma_f32_16x16x32_bf16 v[22:25], v[130:133], v[204:207], v[22:25]
	v_mfma_f32_16x16x32_bf16 v[18:21], v[138:141], v[204:207], v[18:21]
	v_mfma_f32_16x16x32_bf16 v[62:65], v[134:137], v[166:169], v[62:65]
	v_mfma_f32_16x16x32_bf16 v[58:61], v[142:145], v[166:169], v[58:61]
	v_mfma_f32_16x16x32_bf16 v[54:57], v[134:137], v[174:177], v[54:57]
	v_mfma_f32_16x16x32_bf16 v[50:53], v[142:145], v[174:177], v[50:53]
	v_mfma_f32_16x16x32_bf16 v[30:33], v[134:137], v[200:203], v[30:33]
	v_mfma_f32_16x16x32_bf16 v[26:29], v[142:145], v[200:203], v[26:29]
	v_mfma_f32_16x16x32_bf16 v[22:25], v[134:137], v[208:211], v[22:25]
	v_mfma_f32_16x16x32_bf16 v[18:21], v[142:145], v[208:211], v[18:21]
	v_mfma_f32_16x16x32_bf16 v[46:49], v[146:149], v[162:165], v[46:49]
	v_mfma_f32_16x16x32_bf16 v[42:45], v[154:157], v[162:165], v[42:45]
	v_mfma_f32_16x16x32_bf16 v[38:41], v[146:149], v[170:173], v[38:41]
	v_mfma_f32_16x16x32_bf16 v[34:37], v[154:157], v[170:173], v[34:37]
	v_mfma_f32_16x16x32_bf16 v[14:17], v[146:149], v[196:199], v[14:17]
	v_mfma_f32_16x16x32_bf16 v[10:13], v[154:157], v[196:199], v[10:13]
	v_mfma_f32_16x16x32_bf16 v[6:9], v[146:149], v[204:207], v[6:9]
	v_mfma_f32_16x16x32_bf16 v[2:5], v[154:157], v[204:207], v[2:5]
	v_mfma_f32_16x16x32_bf16 v[46:49], v[150:153], v[166:169], v[46:49]
	v_mfma_f32_16x16x32_bf16 v[42:45], v[158:161], v[166:169], v[42:45]
	v_mfma_f32_16x16x32_bf16 v[38:41], v[150:153], v[174:177], v[38:41]
	v_mfma_f32_16x16x32_bf16 v[34:37], v[158:161], v[174:177], v[34:37]
	v_mfma_f32_16x16x32_bf16 v[14:17], v[150:153], v[200:203], v[14:17]
	v_mfma_f32_16x16x32_bf16 v[10:13], v[158:161], v[200:203], v[10:13]
	v_mfma_f32_16x16x32_bf16 v[6:9], v[150:153], v[208:211], v[6:9]
	s_barrier
	v_mfma_f32_16x16x32_bf16 v[2:5], v[158:161], v[208:211], v[2:5]
	s_setprio 2
	s_add_i32 s39, 0, 0x18000
	s_add_i32 s62, 0, 0x1c000
	ds_read_b128 v[130:133], v250
	ds_read_b128 v[134:137], v250 offset:1024
	ds_read_b128 v[138:141], v250 offset:2048
	ds_read_b128 v[142:145], v250 offset:3072
	ds_read_b128 v[146:149], v250 offset:16384
	ds_read_b128 v[150:153], v250 offset:17408
	ds_read_b128 v[154:157], v250 offset:18432
	ds_read_b128 v[158:161], v250 offset:19456
	s_add_u32 s36, s36, 0x160000
	s_addc_u32 s37, s37, 0
	s_mov_b32 m0, s42
	ds_read_b128 v[162:165], v217 offset:32768
	ds_read_b128 v[166:169], v217 offset:33792
	ds_read_b128 v[170:173], v217 offset:34816
	ds_read_b128 v[174:177], v217 offset:35840
	ds_read_b128 v[196:199], v217 offset:36864
	ds_read_b128 v[200:203], v217 offset:37888
	ds_read_b128 v[204:207], v217 offset:38912
	ds_read_b128 v[208:211], v217 offset:39936
	global_load_lds_dwordx4 v178, s[36:37]
	v_lshl_add_u64 v[224:225], s[36:37], 0, v[182:183]
	s_mov_b32 m0, s43
	s_nop 0
	global_load_lds_dwordx4 v182, s[36:37]
	s_waitcnt vmcnt(8)
	s_waitcnt lgkmcnt(0)
	s_barrier
	s_setprio 1
	s_waitcnt lgkmcnt(0)
	v_mfma_f32_16x16x32_bf16 v[126:129], v[130:133], v[162:165], v[126:129]
	v_mfma_f32_16x16x32_bf16 v[122:125], v[138:141], v[162:165], v[122:125]
	v_mfma_f32_16x16x32_bf16 v[118:121], v[130:133], v[170:173], v[118:121]
	v_mfma_f32_16x16x32_bf16 v[114:117], v[138:141], v[170:173], v[114:117]
	v_mfma_f32_16x16x32_bf16 v[94:97], v[130:133], v[196:199], v[94:97]
	v_mfma_f32_16x16x32_bf16 v[90:93], v[138:141], v[196:199], v[90:93]
	v_mfma_f32_16x16x32_bf16 v[86:89], v[130:133], v[204:207], v[86:89]
	v_mfma_f32_16x16x32_bf16 v[82:85], v[138:141], v[204:207], v[82:85]
	v_mfma_f32_16x16x32_bf16 v[126:129], v[134:137], v[166:169], v[126:129]
	v_mfma_f32_16x16x32_bf16 v[122:125], v[142:145], v[166:169], v[122:125]
	v_mfma_f32_16x16x32_bf16 v[118:121], v[134:137], v[174:177], v[118:121]
	v_mfma_f32_16x16x32_bf16 v[114:117], v[142:145], v[174:177], v[114:117]
	v_mfma_f32_16x16x32_bf16 v[94:97], v[134:137], v[200:203], v[94:97]
	v_mfma_f32_16x16x32_bf16 v[90:93], v[142:145], v[200:203], v[90:93]
	v_mfma_f32_16x16x32_bf16 v[86:89], v[134:137], v[208:211], v[86:89]
	v_mfma_f32_16x16x32_bf16 v[82:85], v[142:145], v[208:211], v[82:85]
	v_mfma_f32_16x16x32_bf16 v[110:113], v[146:149], v[162:165], v[110:113]
	v_mfma_f32_16x16x32_bf16 v[106:109], v[154:157], v[162:165], v[106:109]
	v_mfma_f32_16x16x32_bf16 v[102:105], v[146:149], v[170:173], v[102:105]
	v_mfma_f32_16x16x32_bf16 v[98:101], v[154:157], v[170:173], v[98:101]
	v_mfma_f32_16x16x32_bf16 v[78:81], v[146:149], v[196:199], v[78:81]
	v_mfma_f32_16x16x32_bf16 v[74:77], v[154:157], v[196:199], v[74:77]
	v_mfma_f32_16x16x32_bf16 v[70:73], v[146:149], v[204:207], v[70:73]
	v_mfma_f32_16x16x32_bf16 v[66:69], v[154:157], v[204:207], v[66:69]
	v_mfma_f32_16x16x32_bf16 v[110:113], v[150:153], v[166:169], v[110:113]
	v_mfma_f32_16x16x32_bf16 v[106:109], v[158:161], v[166:169], v[106:109]
	v_mfma_f32_16x16x32_bf16 v[102:105], v[150:153], v[174:177], v[102:105]
	v_mfma_f32_16x16x32_bf16 v[98:101], v[158:161], v[174:177], v[98:101]
	v_mfma_f32_16x16x32_bf16 v[78:81], v[150:153], v[200:203], v[78:81]
	v_mfma_f32_16x16x32_bf16 v[74:77], v[158:161], v[200:203], v[74:77]
	v_mfma_f32_16x16x32_bf16 v[70:73], v[150:153], v[208:211], v[70:73]
	s_barrier
	v_mfma_f32_16x16x32_bf16 v[66:69], v[158:161], v[208:211], v[66:69]
	s_setprio 2
	s_add_i32 s36, s39, s33
	v_lshl_add_u64 v[192:193], v[192:193], 0, s[18:19]
	s_mov_b32 m0, s36
	ds_read_b128 v[162:165], v217 offset:49152
	ds_read_b128 v[166:169], v217 offset:50176
	ds_read_b128 v[170:173], v217 offset:51200
	ds_read_b128 v[174:177], v217 offset:52224
	ds_read_b128 v[196:199], v217 offset:53248
	ds_read_b128 v[200:203], v217 offset:54272
	ds_read_b128 v[204:207], v217 offset:55296
	ds_read_b128 v[208:211], v217 offset:56320
	global_load_lds_dwordx4 v[192:193], off
	s_add_i32 m0, s36, 0x2000
	s_add_u32 s34, s34, 0x160080
	v_lshl_add_u64 v[192:193], v[218:219], 0, s[18:19]
	s_addc_u32 s35, s35, 0
	s_add_i32 s36, s62, s33
	global_load_lds_dwordx4 v[192:193], off
	s_mov_b32 m0, s36
	s_nop 0
	global_load_lds_dwordx4 v180, s[34:35]
	s_add_i32 m0, s36, 0x2000
	s_nop 0
	global_load_lds_dwordx4 v184, s[34:35]
	v_lshl_add_u64 v[192:193], v[220:221], 0, s[18:19]
	s_mov_b32 m0, s46
	s_nop 0
	global_load_lds_dwordx4 v[192:193], off
	v_lshl_add_u64 v[192:193], v[222:223], 0, s[18:19]
	s_mov_b32 m0, s47
	s_nop 0
	global_load_lds_dwordx4 v[192:193], off
	s_waitcnt vmcnt(8)
	s_waitcnt lgkmcnt(0)
	s_barrier
	s_setprio 1
	s_waitcnt lgkmcnt(0)
	v_mfma_f32_16x16x32_bf16 v[62:65], v[130:133], v[162:165], v[62:65]
	v_mfma_f32_16x16x32_bf16 v[58:61], v[138:141], v[162:165], v[58:61]
	v_mfma_f32_16x16x32_bf16 v[54:57], v[130:133], v[170:173], v[54:57]
	v_mfma_f32_16x16x32_bf16 v[50:53], v[138:141], v[170:173], v[50:53]
	v_mfma_f32_16x16x32_bf16 v[30:33], v[130:133], v[196:199], v[30:33]
	v_mfma_f32_16x16x32_bf16 v[26:29], v[138:141], v[196:199], v[26:29]
	v_mfma_f32_16x16x32_bf16 v[22:25], v[130:133], v[204:207], v[22:25]
	v_mfma_f32_16x16x32_bf16 v[18:21], v[138:141], v[204:207], v[18:21]
	v_mfma_f32_16x16x32_bf16 v[62:65], v[134:137], v[166:169], v[62:65]
	v_mfma_f32_16x16x32_bf16 v[58:61], v[142:145], v[166:169], v[58:61]
	v_mfma_f32_16x16x32_bf16 v[54:57], v[134:137], v[174:177], v[54:57]
	v_mfma_f32_16x16x32_bf16 v[50:53], v[142:145], v[174:177], v[50:53]
	v_mfma_f32_16x16x32_bf16 v[30:33], v[134:137], v[200:203], v[30:33]
	v_mfma_f32_16x16x32_bf16 v[26:29], v[142:145], v[200:203], v[26:29]
	v_mfma_f32_16x16x32_bf16 v[22:25], v[134:137], v[208:211], v[22:25]
	v_mfma_f32_16x16x32_bf16 v[18:21], v[142:145], v[208:211], v[18:21]
	v_mfma_f32_16x16x32_bf16 v[46:49], v[146:149], v[162:165], v[46:49]
	v_mfma_f32_16x16x32_bf16 v[42:45], v[154:157], v[162:165], v[42:45]
	v_mfma_f32_16x16x32_bf16 v[38:41], v[146:149], v[170:173], v[38:41]
	v_mfma_f32_16x16x32_bf16 v[34:37], v[154:157], v[170:173], v[34:37]
	v_mfma_f32_16x16x32_bf16 v[14:17], v[146:149], v[196:199], v[14:17]
	v_mfma_f32_16x16x32_bf16 v[10:13], v[154:157], v[196:199], v[10:13]
	v_mfma_f32_16x16x32_bf16 v[6:9], v[146:149], v[204:207], v[6:9]
	v_mfma_f32_16x16x32_bf16 v[2:5], v[154:157], v[204:207], v[2:5]
	v_mfma_f32_16x16x32_bf16 v[46:49], v[150:153], v[166:169], v[46:49]
	v_mfma_f32_16x16x32_bf16 v[42:45], v[158:161], v[166:169], v[42:45]
	v_mfma_f32_16x16x32_bf16 v[38:41], v[150:153], v[174:177], v[38:41]
	v_mfma_f32_16x16x32_bf16 v[34:37], v[158:161], v[174:177], v[34:37]
	v_mfma_f32_16x16x32_bf16 v[14:17], v[150:153], v[200:203], v[14:17]
	v_mfma_f32_16x16x32_bf16 v[10:13], v[158:161], v[200:203], v[10:13]
	v_mfma_f32_16x16x32_bf16 v[6:9], v[150:153], v[208:211], v[6:9]
	s_barrier
	v_mfma_f32_16x16x32_bf16 v[2:5], v[158:161], v[208:211], v[2:5]
	s_setprio 2
	s_add_u32 s30, s30, 0x100
	s_addc_u32 s31, s31, 0
	s_add_u32 s23, s23, 0x100
	s_addc_u32 s29, s29, 0
	s_cmp_ge_i32 s38, s61
	s_mov_b32 s34, s38
	s_cbranch_scc0 .LBB0_357

.Lpeel_11:
	v_add_u32_e32 v250, 0x18000, v143
	ds_read_b128 v[148:151], v145
	ds_read_b128 v[152:155], v145 offset:1024
	s_add_u32 s36, s34, 0xfff80080
	s_addc_u32 s37, s35, -1
	s_cmp_eq_u32 s58, 28
	s_cselect_b32 s39, s21, s37
	s_cselect_b32 s38, s54, s36
	s_cselect_b32 s37, s23, s57
	s_cselect_b32 s36, s55, s56
	s_add_i32 m0, s27, 0xc000
	global_load_lds_dwordx4 v138, s[34:35]
	s_add_i32 m0, s27, 0xe000
	s_nop 0
	global_load_lds_dwordx4 v140, s[34:35]
	s_waitcnt vmcnt(8)
	s_waitcnt lgkmcnt(0)
	s_barrier
	s_setprio 1
	s_waitcnt lgkmcnt(0)
	v_mfma_f32_16x16x32_bf16 v[126:129], v[148:151], v[180:183], 0
	v_mfma_f32_16x16x32_bf16 v[122:125], v[156:159], v[180:183], 0
	v_mfma_f32_16x16x32_bf16 v[118:121], v[148:151], v[188:191], 0
	v_mfma_f32_16x16x32_bf16 v[114:117], v[156:159], v[188:191], 0
	v_mfma_f32_16x16x32_bf16 v[102:105], v[148:151], v[200:203], 0
	v_mfma_f32_16x16x32_bf16 v[98:101], v[156:159], v[200:203], 0
	v_mfma_f32_16x16x32_bf16 v[86:89], v[148:151], v[208:211], 0
	v_mfma_f32_16x16x32_bf16 v[82:85], v[156:159], v[208:211], 0
	v_mfma_f32_16x16x32_bf16 v[126:129], v[152:155], v[184:187], v[126:129]
	v_mfma_f32_16x16x32_bf16 v[122:125], v[160:163], v[184:187], v[122:125]
	v_mfma_f32_16x16x32_bf16 v[118:121], v[152:155], v[196:199], v[118:121]
	v_mfma_f32_16x16x32_bf16 v[114:117], v[160:163], v[196:199], v[114:117]
	v_mfma_f32_16x16x32_bf16 v[102:105], v[152:155], v[204:207], v[102:105]
	v_mfma_f32_16x16x32_bf16 v[98:101], v[160:163], v[204:207], v[98:101]
	v_mfma_f32_16x16x32_bf16 v[86:89], v[152:155], v[212:215], v[86:89]
	v_mfma_f32_16x16x32_bf16 v[82:85], v[160:163], v[212:215], v[82:85]
	v_mfma_f32_16x16x32_bf16 v[110:113], v[164:167], v[180:183], 0
	v_mfma_f32_16x16x32_bf16 v[106:109], v[172:175], v[180:183], 0
	v_mfma_f32_16x16x32_bf16 v[94:97], v[164:167], v[188:191], 0
	v_mfma_f32_16x16x32_bf16 v[90:93], v[172:175], v[188:191], 0
	v_mfma_f32_16x16x32_bf16 v[78:81], v[164:167], v[200:203], 0
	v_mfma_f32_16x16x32_bf16 v[74:77], v[172:175], v[200:203], 0
	v_mfma_f32_16x16x32_bf16 v[70:73], v[164:167], v[208:211], 0
	v_mfma_f32_16x16x32_bf16 v[66:69], v[172:175], v[208:211], 0
	v_mfma_f32_16x16x32_bf16 v[110:113], v[168:171], v[184:187], v[110:113]
	v_mfma_f32_16x16x32_bf16 v[106:109], v[176:179], v[184:187], v[106:109]
	v_mfma_f32_16x16x32_bf16 v[94:97], v[168:171], v[196:199], v[94:97]
	v_mfma_f32_16x16x32_bf16 v[90:93], v[176:179], v[196:199], v[90:93]
	v_mfma_f32_16x16x32_bf16 v[78:81], v[168:171], v[204:207], v[78:81]
	v_mfma_f32_16x16x32_bf16 v[74:77], v[176:179], v[204:207], v[74:77]
	v_mfma_f32_16x16x32_bf16 v[70:73], v[168:171], v[212:215], v[70:73]
	s_barrier
	v_mfma_f32_16x16x32_bf16 v[66:69], v[176:179], v[212:215], v[66:69]
	s_setprio 2
	s_add_i32 s59, s47, s33
	v_lshl_add_u64 v[192:193], s[36:37], 0, v[134:135]
	s_mov_b32 m0, s59
	ds_read_b128 v[180:183], v147 offset:16384
	ds_read_b128 v[184:187], v147 offset:17408
	ds_read_b128 v[188:191], v147 offset:18432
	ds_read_b128 v[196:199], v147 offset:19456
	ds_read_b128 v[200:203], v147 offset:20480
	ds_read_b128 v[204:207], v147 offset:21504
	ds_read_b128 v[208:211], v147 offset:22528
	ds_read_b128 v[212:215], v147 offset:23552
	global_load_lds_dwordx4 v134, s[36:37]
	s_add_i32 m0, s59, 0x2000
	s_add_u32 s60, s36, 0x80000
	v_lshl_add_u64 v[216:217], s[36:37], 0, v[130:131]
	s_addc_u32 s61, s37, 0
	s_add_i32 s59, s48, s33
	global_load_lds_dwordx4 v130, s[36:37]
	s_mov_b32 m0, s59
	v_lshl_add_u64 v[220:221], s[38:39], 0, v[132:133]
	global_load_lds_dwordx4 v134, s[60:61]
	s_add_i32 m0, s59, 0x2000
	s_nop 0
	global_load_lds_dwordx4 v130, s[60:61]
	v_lshl_add_u64 v[218:219], s[38:39], 0, v[136:137]
	s_mov_b32 m0, s27
	s_nop 0
	global_load_lds_dwordx4 v136, s[38:39]
	s_mov_b32 m0, s41
	s_nop 0
	global_load_lds_dwordx4 v132, s[38:39]
	s_waitcnt vmcnt(8)
	s_waitcnt lgkmcnt(0)
	s_barrier
	s_setprio 1
	s_waitcnt lgkmcnt(0)
	v_mfma_f32_16x16x32_bf16 v[62:65], v[148:151], v[180:183], 0
	v_mfma_f32_16x16x32_bf16 v[58:61], v[156:159], v[180:183], 0
	v_mfma_f32_16x16x32_bf16 v[54:57], v[148:151], v[188:191], 0
	v_mfma_f32_16x16x32_bf16 v[50:53], v[156:159], v[188:191], 0
	v_mfma_f32_16x16x32_bf16 v[38:41], v[148:151], v[200:203], 0
	v_mfma_f32_16x16x32_bf16 v[34:37], v[156:159], v[200:203], 0
	v_mfma_f32_16x16x32_bf16 v[22:25], v[148:151], v[208:211], 0
	v_mfma_f32_16x16x32_bf16 v[18:21], v[156:159], v[208:211], 0
	v_mfma_f32_16x16x32_bf16 v[62:65], v[152:155], v[184:187], v[62:65]
	v_mfma_f32_16x16x32_bf16 v[58:61], v[160:163], v[184:187], v[58:61]
	v_mfma_f32_16x16x32_bf16 v[54:57], v[152:155], v[196:199], v[54:57]
	v_mfma_f32_16x16x32_bf16 v[50:53], v[160:163], v[196:199], v[50:53]
	v_mfma_f32_16x16x32_bf16 v[38:41], v[152:155], v[204:207], v[38:41]
	v_mfma_f32_16x16x32_bf16 v[34:37], v[160:163], v[204:207], v[34:37]
	v_mfma_f32_16x16x32_bf16 v[22:25], v[152:155], v[212:215], v[22:25]
	v_mfma_f32_16x16x32_bf16 v[18:21], v[160:163], v[212:215], v[18:21]
	v_mfma_f32_16x16x32_bf16 v[46:49], v[164:167], v[180:183], 0
	v_mfma_f32_16x16x32_bf16 v[42:45], v[172:175], v[180:183], 0
	v_mfma_f32_16x16x32_bf16 v[30:33], v[164:167], v[188:191], 0
	v_mfma_f32_16x16x32_bf16 v[26:29], v[172:175], v[188:191], 0
	v_mfma_f32_16x16x32_bf16 v[14:17], v[164:167], v[200:203], 0
	v_mfma_f32_16x16x32_bf16 v[10:13], v[172:175], v[200:203], 0
	v_mfma_f32_16x16x32_bf16 v[6:9], v[164:167], v[208:211], 0
	v_mfma_f32_16x16x32_bf16 v[2:5], v[172:175], v[208:211], 0
	v_mfma_f32_16x16x32_bf16 v[46:49], v[168:171], v[184:187], v[46:49]
	v_mfma_f32_16x16x32_bf16 v[42:45], v[176:179], v[184:187], v[42:45]
	v_mfma_f32_16x16x32_bf16 v[30:33], v[168:171], v[196:199], v[30:33]
	v_mfma_f32_16x16x32_bf16 v[26:29], v[176:179], v[196:199], v[26:29]
	v_mfma_f32_16x16x32_bf16 v[14:17], v[168:171], v[204:207], v[14:17]
	v_mfma_f32_16x16x32_bf16 v[10:13], v[176:179], v[204:207], v[10:13]
	v_mfma_f32_16x16x32_bf16 v[6:9], v[168:171], v[212:215], v[6:9]
	s_barrier
	v_mfma_f32_16x16x32_bf16 v[2:5], v[176:179], v[212:215], v[2:5]
	s_setprio 2
	s_add_i32 s59, 0, 0x18000
	s_add_i32 s60, 0, 0x1c000
	ds_read_b128 v[148:151], v250
	ds_read_b128 v[152:155], v250 offset:1024
	ds_read_b128 v[156:159], v250 offset:2048
	ds_read_b128 v[160:163], v250 offset:3072
	ds_read_b128 v[164:167], v250 offset:16384
	ds_read_b128 v[168:171], v250 offset:17408
	ds_read_b128 v[172:175], v250 offset:18432
	ds_read_b128 v[176:179], v250 offset:19456
	s_add_u32 s38, s38, 0x80000
	s_addc_u32 s39, s39, 0
	s_mov_b32 m0, s42
	ds_read_b128 v[180:183], v147 offset:32768
	ds_read_b128 v[184:187], v147 offset:33792
	ds_read_b128 v[188:191], v147 offset:34816
	ds_read_b128 v[196:199], v147 offset:35840
	ds_read_b128 v[200:203], v147 offset:36864
	ds_read_b128 v[204:207], v147 offset:37888
	ds_read_b128 v[208:211], v147 offset:38912
	ds_read_b128 v[212:215], v147 offset:39936
	global_load_lds_dwordx4 v136, s[38:39]
	v_lshl_add_u64 v[222:223], s[38:39], 0, v[132:133]
	s_mov_b32 m0, s43
	s_nop 0
	global_load_lds_dwordx4 v132, s[38:39]
	s_waitcnt vmcnt(8)
	s_waitcnt lgkmcnt(0)
	s_barrier
	s_setprio 1
	s_waitcnt lgkmcnt(0)
	v_mfma_f32_16x16x32_bf16 v[126:129], v[148:151], v[180:183], v[126:129]
	v_mfma_f32_16x16x32_bf16 v[122:125], v[156:159], v[180:183], v[122:125]
	v_mfma_f32_16x16x32_bf16 v[118:121], v[148:151], v[188:191], v[118:121]
	v_mfma_f32_16x16x32_bf16 v[114:117], v[156:159], v[188:191], v[114:117]
	v_mfma_f32_16x16x32_bf16 v[102:105], v[148:151], v[200:203], v[102:105]
	v_mfma_f32_16x16x32_bf16 v[98:101], v[156:159], v[200:203], v[98:101]
	v_mfma_f32_16x16x32_bf16 v[86:89], v[148:151], v[208:211], v[86:89]
	v_mfma_f32_16x16x32_bf16 v[82:85], v[156:159], v[208:211], v[82:85]
	v_mfma_f32_16x16x32_bf16 v[126:129], v[152:155], v[184:187], v[126:129]
	v_mfma_f32_16x16x32_bf16 v[122:125], v[160:163], v[184:187], v[122:125]
	v_mfma_f32_16x16x32_bf16 v[118:121], v[152:155], v[196:199], v[118:121]
	v_mfma_f32_16x16x32_bf16 v[114:117], v[160:163], v[196:199], v[114:117]
	v_mfma_f32_16x16x32_bf16 v[102:105], v[152:155], v[204:207], v[102:105]
	v_mfma_f32_16x16x32_bf16 v[98:101], v[160:163], v[204:207], v[98:101]
	v_mfma_f32_16x16x32_bf16 v[86:89], v[152:155], v[212:215], v[86:89]
	v_mfma_f32_16x16x32_bf16 v[82:85], v[160:163], v[212:215], v[82:85]
	v_mfma_f32_16x16x32_bf16 v[110:113], v[164:167], v[180:183], v[110:113]
	v_mfma_f32_16x16x32_bf16 v[106:109], v[172:175], v[180:183], v[106:109]
	v_mfma_f32_16x16x32_bf16 v[94:97], v[164:167], v[188:191], v[94:97]
	v_mfma_f32_16x16x32_bf16 v[90:93], v[172:175], v[188:191], v[90:93]
	v_mfma_f32_16x16x32_bf16 v[78:81], v[164:167], v[200:203], v[78:81]
	v_mfma_f32_16x16x32_bf16 v[74:77], v[172:175], v[200:203], v[74:77]
	v_mfma_f32_16x16x32_bf16 v[70:73], v[164:167], v[208:211], v[70:73]
	v_mfma_f32_16x16x32_bf16 v[66:69], v[172:175], v[208:211], v[66:69]
	v_mfma_f32_16x16x32_bf16 v[110:113], v[168:171], v[184:187], v[110:113]
	v_mfma_f32_16x16x32_bf16 v[106:109], v[176:179], v[184:187], v[106:109]
	v_mfma_f32_16x16x32_bf16 v[94:97], v[168:171], v[196:199], v[94:97]
	v_mfma_f32_16x16x32_bf16 v[90:93], v[176:179], v[196:199], v[90:93]
	v_mfma_f32_16x16x32_bf16 v[78:81], v[168:171], v[204:207], v[78:81]
	v_mfma_f32_16x16x32_bf16 v[74:77], v[176:179], v[204:207], v[74:77]
	v_mfma_f32_16x16x32_bf16 v[70:73], v[168:171], v[212:215], v[70:73]
	s_barrier
	v_mfma_f32_16x16x32_bf16 v[66:69], v[176:179], v[212:215], v[66:69]
	s_setprio 2
	s_add_i32 s38, s59, s33
	v_lshl_add_u64 v[192:193], v[192:193], 0, s[6:7]
	s_mov_b32 m0, s38
	ds_read_b128 v[180:183], v147 offset:49152
	ds_read_b128 v[184:187], v147 offset:50176
	ds_read_b128 v[188:191], v147 offset:51200
	ds_read_b128 v[196:199], v147 offset:52224
	ds_read_b128 v[200:203], v147 offset:53248
	ds_read_b128 v[204:207], v147 offset:54272
	ds_read_b128 v[208:211], v147 offset:55296
	ds_read_b128 v[212:215], v147 offset:56320
	global_load_lds_dwordx4 v[192:193], off
	s_add_i32 m0, s38, 0x2000
	s_add_u32 s36, s36, 0x80080
	v_lshl_add_u64 v[192:193], v[216:217], 0, s[6:7]
	s_addc_u32 s37, s37, 0
	s_add_i32 s38, s60, s33
	global_load_lds_dwordx4 v[192:193], off
	s_mov_b32 m0, s38
	s_nop 0
	global_load_lds_dwordx4 v134, s[36:37]
	s_add_i32 m0, s38, 0x2000
	s_nop 0
	global_load_lds_dwordx4 v130, s[36:37]
	v_lshl_add_u64 v[192:193], v[218:219], 0, s[6:7]
	s_mov_b32 m0, s45
	s_nop 0
	global_load_lds_dwordx4 v[192:193], off
	v_lshl_add_u64 v[192:193], v[220:221], 0, s[6:7]
	s_mov_b32 m0, s46
	s_nop 0
	global_load_lds_dwordx4 v[192:193], off
	s_waitcnt vmcnt(8)
	s_waitcnt lgkmcnt(0)
	s_barrier
	s_setprio 1
	s_waitcnt lgkmcnt(0)
	v_mfma_f32_16x16x32_bf16 v[62:65], v[148:151], v[180:183], v[62:65]
	v_mfma_f32_16x16x32_bf16 v[58:61], v[156:159], v[180:183], v[58:61]
	v_mfma_f32_16x16x32_bf16 v[54:57], v[148:151], v[188:191], v[54:57]
	v_mfma_f32_16x16x32_bf16 v[50:53], v[156:159], v[188:191], v[50:53]
	v_mfma_f32_16x16x32_bf16 v[38:41], v[148:151], v[200:203], v[38:41]
	v_mfma_f32_16x16x32_bf16 v[34:37], v[156:159], v[200:203], v[34:37]
	v_mfma_f32_16x16x32_bf16 v[22:25], v[148:151], v[208:211], v[22:25]
	v_mfma_f32_16x16x32_bf16 v[18:21], v[156:159], v[208:211], v[18:21]
	v_mfma_f32_16x16x32_bf16 v[62:65], v[152:155], v[184:187], v[62:65]
	v_mfma_f32_16x16x32_bf16 v[58:61], v[160:163], v[184:187], v[58:61]
	v_mfma_f32_16x16x32_bf16 v[54:57], v[152:155], v[196:199], v[54:57]
	v_mfma_f32_16x16x32_bf16 v[50:53], v[160:163], v[196:199], v[50:53]
	v_mfma_f32_16x16x32_bf16 v[38:41], v[152:155], v[204:207], v[38:41]
	v_mfma_f32_16x16x32_bf16 v[34:37], v[160:163], v[204:207], v[34:37]
	v_mfma_f32_16x16x32_bf16 v[22:25], v[152:155], v[212:215], v[22:25]
	v_mfma_f32_16x16x32_bf16 v[18:21], v[160:163], v[212:215], v[18:21]
	v_mfma_f32_16x16x32_bf16 v[46:49], v[164:167], v[180:183], v[46:49]
	v_mfma_f32_16x16x32_bf16 v[42:45], v[172:175], v[180:183], v[42:45]
	v_mfma_f32_16x16x32_bf16 v[30:33], v[164:167], v[188:191], v[30:33]
	v_mfma_f32_16x16x32_bf16 v[26:29], v[172:175], v[188:191], v[26:29]
	v_mfma_f32_16x16x32_bf16 v[14:17], v[164:167], v[200:203], v[14:17]
	v_mfma_f32_16x16x32_bf16 v[10:13], v[172:175], v[200:203], v[10:13]
	v_mfma_f32_16x16x32_bf16 v[6:9], v[164:167], v[208:211], v[6:9]
	v_mfma_f32_16x16x32_bf16 v[2:5], v[172:175], v[208:211], v[2:5]
	v_mfma_f32_16x16x32_bf16 v[46:49], v[168:171], v[184:187], v[46:49]
	v_mfma_f32_16x16x32_bf16 v[42:45], v[176:179], v[184:187], v[42:45]
	v_mfma_f32_16x16x32_bf16 v[30:33], v[168:171], v[196:199], v[30:33]
	v_mfma_f32_16x16x32_bf16 v[26:29], v[176:179], v[196:199], v[26:29]
	v_mfma_f32_16x16x32_bf16 v[14:17], v[168:171], v[204:207], v[14:17]
	v_mfma_f32_16x16x32_bf16 v[10:13], v[176:179], v[204:207], v[10:13]
	v_mfma_f32_16x16x32_bf16 v[6:9], v[168:171], v[212:215], v[6:9]
	s_barrier
	v_mfma_f32_16x16x32_bf16 v[2:5], v[176:179], v[212:215], v[2:5]
	s_setprio 2
	s_add_i32 s58, s58, 2
	s_add_u32 s34, s34, 0x100
	s_addc_u32 s35, s35, 0
	s_add_u32 s56, s56, 0x100
	s_addc_u32 s57, s57, 0
	s_cmp_gt_u32 s58, 29
	s_cbranch_scc0 .LBB0_541
	s_branch .Lpeeldone_11
.LBB0_541:
	ds_read_b128 v[148:151], v145
	ds_read_b128 v[152:155], v145 offset:1024
	ds_read_b128 v[156:159], v145 offset:2048
	ds_read_b128 v[160:163], v145 offset:3072
	ds_read_b128 v[164:167], v146
	ds_read_b128 v[168:171], v146 offset:1024
	ds_read_b128 v[172:175], v146 offset:2048
	ds_read_b128 v[176:179], v146 offset:3072
	s_add_u32 s36, s34, 0xfff80080
	s_addc_u32 s37, s35, -1
	s_cmp_eq_u32 s58, 28
	s_cselect_b32 s39, s21, s37
	s_cselect_b32 s38, s54, s36
	s_cselect_b32 s37, s23, s57
	s_cselect_b32 s36, s55, s56
	s_add_i32 m0, s27, 0xc000
	ds_read_b128 v[180:183], v147
	ds_read_b128 v[184:187], v147 offset:1024
	ds_read_b128 v[188:191], v147 offset:2048
	ds_read_b128 v[196:199], v147 offset:3072
	ds_read_b128 v[200:203], v147 offset:4096
	ds_read_b128 v[204:207], v147 offset:5120
	ds_read_b128 v[208:211], v147 offset:6144
	ds_read_b128 v[212:215], v147 offset:7168
	global_load_lds_dwordx4 v138, s[34:35]
	s_add_i32 m0, s27, 0xe000
	s_nop 0
	global_load_lds_dwordx4 v140, s[34:35]
	s_waitcnt vmcnt(8)
	s_waitcnt lgkmcnt(0)
	s_barrier
	s_setprio 1
	s_waitcnt lgkmcnt(0)
	v_mfma_f32_16x16x32_bf16 v[126:129], v[148:151], v[180:183], v[126:129]
	v_mfma_f32_16x16x32_bf16 v[122:125], v[156:159], v[180:183], v[122:125]
	v_mfma_f32_16x16x32_bf16 v[118:121], v[148:151], v[188:191], v[118:121]
	v_mfma_f32_16x16x32_bf16 v[114:117], v[156:159], v[188:191], v[114:117]
	v_mfma_f32_16x16x32_bf16 v[102:105], v[148:151], v[200:203], v[102:105]
	v_mfma_f32_16x16x32_bf16 v[98:101], v[156:159], v[200:203], v[98:101]
	v_mfma_f32_16x16x32_bf16 v[86:89], v[148:151], v[208:211], v[86:89]
	v_mfma_f32_16x16x32_bf16 v[82:85], v[156:159], v[208:211], v[82:85]
	v_mfma_f32_16x16x32_bf16 v[126:129], v[152:155], v[184:187], v[126:129]
	v_mfma_f32_16x16x32_bf16 v[122:125], v[160:163], v[184:187], v[122:125]
	v_mfma_f32_16x16x32_bf16 v[118:121], v[152:155], v[196:199], v[118:121]
	v_mfma_f32_16x16x32_bf16 v[114:117], v[160:163], v[196:199], v[114:117]
	v_mfma_f32_16x16x32_bf16 v[102:105], v[152:155], v[204:207], v[102:105]
	v_mfma_f32_16x16x32_bf16 v[98:101], v[160:163], v[204:207], v[98:101]
	v_mfma_f32_16x16x32_bf16 v[86:89], v[152:155], v[212:215], v[86:89]
	v_mfma_f32_16x16x32_bf16 v[82:85], v[160:163], v[212:215], v[82:85]
	v_mfma_f32_16x16x32_bf16 v[110:113], v[164:167], v[180:183], v[110:113]
	v_mfma_f32_16x16x32_bf16 v[106:109], v[172:175], v[180:183], v[106:109]
	v_mfma_f32_16x16x32_bf16 v[94:97], v[164:167], v[188:191], v[94:97]
	v_mfma_f32_16x16x32_bf16 v[90:93], v[172:175], v[188:191], v[90:93]
	v_mfma_f32_16x16x32_bf16 v[78:81], v[164:167], v[200:203], v[78:81]
	v_mfma_f32_16x16x32_bf16 v[74:77], v[172:175], v[200:203], v[74:77]
	v_mfma_f32_16x16x32_bf16 v[70:73], v[164:167], v[208:211], v[70:73]
	v_mfma_f32_16x16x32_bf16 v[66:69], v[172:175], v[208:211], v[66:69]
	v_mfma_f32_16x16x32_bf16 v[110:113], v[168:171], v[184:187], v[110:113]
	v_mfma_f32_16x16x32_bf16 v[106:109], v[176:179], v[184:187], v[106:109]
	v_mfma_f32_16x16x32_bf16 v[94:97], v[168:171], v[196:199], v[94:97]
	v_mfma_f32_16x16x32_bf16 v[90:93], v[176:179], v[196:199], v[90:93]
	v_mfma_f32_16x16x32_bf16 v[78:81], v[168:171], v[204:207], v[78:81]
	v_mfma_f32_16x16x32_bf16 v[74:77], v[176:179], v[204:207], v[74:77]
	v_mfma_f32_16x16x32_bf16 v[70:73], v[168:171], v[212:215], v[70:73]
	s_barrier
	v_mfma_f32_16x16x32_bf16 v[66:69], v[176:179], v[212:215], v[66:69]
	s_setprio 2
	s_add_i32 s59, s47, s33
	v_lshl_add_u64 v[192:193], s[36:37], 0, v[134:135]
	s_mov_b32 m0, s59
	ds_read_b128 v[180:183], v147 offset:16384
	ds_read_b128 v[184:187], v147 offset:17408
	ds_read_b128 v[188:191], v147 offset:18432
	ds_read_b128 v[196:199], v147 offset:19456
	ds_read_b128 v[200:203], v147 offset:20480
	ds_read_b128 v[204:207], v147 offset:21504
	ds_read_b128 v[208:211], v147 offset:22528
	ds_read_b128 v[212:215], v147 offset:23552
	global_load_lds_dwordx4 v134, s[36:37]
	s_add_i32 m0, s59, 0x2000
	s_add_u32 s60, s36, 0x80000
	v_lshl_add_u64 v[216:217], s[36:37], 0, v[130:131]
	s_addc_u32 s61, s37, 0
	s_add_i32 s59, s48, s33
	global_load_lds_dwordx4 v130, s[36:37]
	s_mov_b32 m0, s59
	v_lshl_add_u64 v[220:221], s[38:39], 0, v[132:133]
	global_load_lds_dwordx4 v134, s[60:61]
	s_add_i32 m0, s59, 0x2000
	s_nop 0
	global_load_lds_dwordx4 v130, s[60:61]
	v_lshl_add_u64 v[218:219], s[38:39], 0, v[136:137]
	s_mov_b32 m0, s27
	s_nop 0
	global_load_lds_dwordx4 v136, s[38:39]
	s_mov_b32 m0, s41
	s_nop 0
	global_load_lds_dwordx4 v132, s[38:39]
	s_waitcnt vmcnt(8)
	s_waitcnt lgkmcnt(0)
	s_barrier
	s_setprio 1
	s_waitcnt lgkmcnt(0)
	v_mfma_f32_16x16x32_bf16 v[62:65], v[148:151], v[180:183], v[62:65]
	v_mfma_f32_16x16x32_bf16 v[58:61], v[156:159], v[180:183], v[58:61]
	v_mfma_f32_16x16x32_bf16 v[54:57], v[148:151], v[188:191], v[54:57]
	v_mfma_f32_16x16x32_bf16 v[50:53], v[156:159], v[188:191], v[50:53]
	v_mfma_f32_16x16x32_bf16 v[38:41], v[148:151], v[200:203], v[38:41]
	v_mfma_f32_16x16x32_bf16 v[34:37], v[156:159], v[200:203], v[34:37]
	v_mfma_f32_16x16x32_bf16 v[22:25], v[148:151], v[208:211], v[22:25]
	v_mfma_f32_16x16x32_bf16 v[18:21], v[156:159], v[208:211], v[18:21]
	v_mfma_f32_16x16x32_bf16 v[62:65], v[152:155], v[184:187], v[62:65]
	v_mfma_f32_16x16x32_bf16 v[58:61], v[160:163], v[184:187], v[58:61]
	v_mfma_f32_16x16x32_bf16 v[54:57], v[152:155], v[196:199], v[54:57]
	v_mfma_f32_16x16x32_bf16 v[50:53], v[160:163], v[196:199], v[50:53]
	v_mfma_f32_16x16x32_bf16 v[38:41], v[152:155], v[204:207], v[38:41]
	v_mfma_f32_16x16x32_bf16 v[34:37], v[160:163], v[204:207], v[34:37]
	v_mfma_f32_16x16x32_bf16 v[22:25], v[152:155], v[212:215], v[22:25]
	v_mfma_f32_16x16x32_bf16 v[18:21], v[160:163], v[212:215], v[18:21]
	v_mfma_f32_16x16x32_bf16 v[46:49], v[164:167], v[180:183], v[46:49]
	v_mfma_f32_16x16x32_bf16 v[42:45], v[172:175], v[180:183], v[42:45]
	v_mfma_f32_16x16x32_bf16 v[30:33], v[164:167], v[188:191], v[30:33]
	v_mfma_f32_16x16x32_bf16 v[26:29], v[172:175], v[188:191], v[26:29]
	v_mfma_f32_16x16x32_bf16 v[14:17], v[164:167], v[200:203], v[14:17]
	v_mfma_f32_16x16x32_bf16 v[10:13], v[172:175], v[200:203], v[10:13]
	v_mfma_f32_16x16x32_bf16 v[6:9], v[164:167], v[208:211], v[6:9]
	v_mfma_f32_16x16x32_bf16 v[2:5], v[172:175], v[208:211], v[2:5]
	v_mfma_f32_16x16x32_bf16 v[46:49], v[168:171], v[184:187], v[46:49]
	v_mfma_f32_16x16x32_bf16 v[42:45], v[176:179], v[184:187], v[42:45]
	v_mfma_f32_16x16x32_bf16 v[30:33], v[168:171], v[196:199], v[30:33]
	v_mfma_f32_16x16x32_bf16 v[26:29], v[176:179], v[196:199], v[26:29]
	v_mfma_f32_16x16x32_bf16 v[14:17], v[168:171], v[204:207], v[14:17]
	v_mfma_f32_16x16x32_bf16 v[10:13], v[176:179], v[204:207], v[10:13]
	v_mfma_f32_16x16x32_bf16 v[6:9], v[168:171], v[212:215], v[6:9]
	s_barrier
	v_mfma_f32_16x16x32_bf16 v[2:5], v[176:179], v[212:215], v[2:5]
	s_setprio 2
	s_add_i32 s59, 0, 0x18000
	s_add_i32 s60, 0, 0x1c000
	ds_read_b128 v[148:151], v250
	ds_read_b128 v[152:155], v250 offset:1024
	ds_read_b128 v[156:159], v250 offset:2048
	ds_read_b128 v[160:163], v250 offset:3072
	ds_read_b128 v[164:167], v250 offset:16384
	ds_read_b128 v[168:171], v250 offset:17408
	ds_read_b128 v[172:175], v250 offset:18432
	ds_read_b128 v[176:179], v250 offset:19456
	s_add_u32 s38, s38, 0x80000
	s_addc_u32 s39, s39, 0
	s_mov_b32 m0, s42
	ds_read_b128 v[180:183], v147 offset:32768
	ds_read_b128 v[184:187], v147 offset:33792
	ds_read_b128 v[188:191], v147 offset:34816
	ds_read_b128 v[196:199], v147 offset:35840
	ds_read_b128 v[200:203], v147 offset:36864
	ds_read_b128 v[204:207], v147 offset:37888
	ds_read_b128 v[208:211], v147 offset:38912
	ds_read_b128 v[212:215], v147 offset:39936
	global_load_lds_dwordx4 v136, s[38:39]
	v_lshl_add_u64 v[222:223], s[38:39], 0, v[132:133]
	s_mov_b32 m0, s43
	s_nop 0
	global_load_lds_dwordx4 v132, s[38:39]
	s_waitcnt vmcnt(8)
	s_waitcnt lgkmcnt(0)
	s_barrier
	s_setprio 1
	s_waitcnt lgkmcnt(0)
	v_mfma_f32_16x16x32_bf16 v[126:129], v[148:151], v[180:183], v[126:129]
	v_mfma_f32_16x16x32_bf16 v[122:125], v[156:159], v[180:183], v[122:125]
	v_mfma_f32_16x16x32_bf16 v[118:121], v[148:151], v[188:191], v[118:121]
	v_mfma_f32_16x16x32_bf16 v[114:117], v[156:159], v[188:191], v[114:117]
	v_mfma_f32_16x16x32_bf16 v[102:105], v[148:151], v[200:203], v[102:105]
	v_mfma_f32_16x16x32_bf16 v[98:101], v[156:159], v[200:203], v[98:101]
	v_mfma_f32_16x16x32_bf16 v[86:89], v[148:151], v[208:211], v[86:89]
	v_mfma_f32_16x16x32_bf16 v[82:85], v[156:159], v[208:211], v[82:85]
	v_mfma_f32_16x16x32_bf16 v[126:129], v[152:155], v[184:187], v[126:129]
	v_mfma_f32_16x16x32_bf16 v[122:125], v[160:163], v[184:187], v[122:125]
	v_mfma_f32_16x16x32_bf16 v[118:121], v[152:155], v[196:199], v[118:121]
	v_mfma_f32_16x16x32_bf16 v[114:117], v[160:163], v[196:199], v[114:117]
	v_mfma_f32_16x16x32_bf16 v[102:105], v[152:155], v[204:207], v[102:105]
	v_mfma_f32_16x16x32_bf16 v[98:101], v[160:163], v[204:207], v[98:101]
	v_mfma_f32_16x16x32_bf16 v[86:89], v[152:155], v[212:215], v[86:89]
	v_mfma_f32_16x16x32_bf16 v[82:85], v[160:163], v[212:215], v[82:85]
	v_mfma_f32_16x16x32_bf16 v[110:113], v[164:167], v[180:183], v[110:113]
	v_mfma_f32_16x16x32_bf16 v[106:109], v[172:175], v[180:183], v[106:109]
	v_mfma_f32_16x16x32_bf16 v[94:97], v[164:167], v[188:191], v[94:97]
	v_mfma_f32_16x16x32_bf16 v[90:93], v[172:175], v[188:191], v[90:93]
	v_mfma_f32_16x16x32_bf16 v[78:81], v[164:167], v[200:203], v[78:81]
	v_mfma_f32_16x16x32_bf16 v[74:77], v[172:175], v[200:203], v[74:77]
	v_mfma_f32_16x16x32_bf16 v[70:73], v[164:167], v[208:211], v[70:73]
	v_mfma_f32_16x16x32_bf16 v[66:69], v[172:175], v[208:211], v[66:69]
	v_mfma_f32_16x16x32_bf16 v[110:113], v[168:171], v[184:187], v[110:113]
	v_mfma_f32_16x16x32_bf16 v[106:109], v[176:179], v[184:187], v[106:109]
	v_mfma_f32_16x16x32_bf16 v[94:97], v[168:171], v[196:199], v[94:97]
	v_mfma_f32_16x16x32_bf16 v[90:93], v[176:179], v[196:199], v[90:93]
	v_mfma_f32_16x16x32_bf16 v[78:81], v[168:171], v[204:207], v[78:81]
	v_mfma_f32_16x16x32_bf16 v[74:77], v[176:179], v[204:207], v[74:77]
	v_mfma_f32_16x16x32_bf16 v[70:73], v[168:171], v[212:215], v[70:73]
	s_barrier
	v_mfma_f32_16x16x32_bf16 v[66:69], v[176:179], v[212:215], v[66:69]
	s_setprio 2
	s_add_i32 s38, s59, s33
	v_lshl_add_u64 v[192:193], v[192:193], 0, s[6:7]
	s_mov_b32 m0, s38
	ds_read_b128 v[180:183], v147 offset:49152
	ds_read_b128 v[184:187], v147 offset:50176
	ds_read_b128 v[188:191], v147 offset:51200
	ds_read_b128 v[196:199], v147 offset:52224
	ds_read_b128 v[200:203], v147 offset:53248
	ds_read_b128 v[204:207], v147 offset:54272
	ds_read_b128 v[208:211], v147 offset:55296
	ds_read_b128 v[212:215], v147 offset:56320
	global_load_lds_dwordx4 v[192:193], off
	s_add_i32 m0, s38, 0x2000
	s_add_u32 s36, s36, 0x80080
	v_lshl_add_u64 v[192:193], v[216:217], 0, s[6:7]
	s_addc_u32 s37, s37, 0
	s_add_i32 s38, s60, s33
	global_load_lds_dwordx4 v[192:193], off
	s_mov_b32 m0, s38
	s_nop 0
	global_load_lds_dwordx4 v134, s[36:37]
	s_add_i32 m0, s38, 0x2000
	s_nop 0
	global_load_lds_dwordx4 v130, s[36:37]
	v_lshl_add_u64 v[192:193], v[218:219], 0, s[6:7]
	s_mov_b32 m0, s45
	s_nop 0
	global_load_lds_dwordx4 v[192:193], off
	v_lshl_add_u64 v[192:193], v[220:221], 0, s[6:7]
	s_mov_b32 m0, s46
	s_nop 0
	global_load_lds_dwordx4 v[192:193], off
	s_waitcnt vmcnt(8)
	s_waitcnt lgkmcnt(0)
	s_barrier
	s_setprio 1
	s_waitcnt lgkmcnt(0)
	v_mfma_f32_16x16x32_bf16 v[62:65], v[148:151], v[180:183], v[62:65]
	v_mfma_f32_16x16x32_bf16 v[58:61], v[156:159], v[180:183], v[58:61]
	v_mfma_f32_16x16x32_bf16 v[54:57], v[148:151], v[188:191], v[54:57]
	v_mfma_f32_16x16x32_bf16 v[50:53], v[156:159], v[188:191], v[50:53]
	v_mfma_f32_16x16x32_bf16 v[38:41], v[148:151], v[200:203], v[38:41]
	v_mfma_f32_16x16x32_bf16 v[34:37], v[156:159], v[200:203], v[34:37]
	v_mfma_f32_16x16x32_bf16 v[22:25], v[148:151], v[208:211], v[22:25]
	v_mfma_f32_16x16x32_bf16 v[18:21], v[156:159], v[208:211], v[18:21]
	v_mfma_f32_16x16x32_bf16 v[62:65], v[152:155], v[184:187], v[62:65]
	v_mfma_f32_16x16x32_bf16 v[58:61], v[160:163], v[184:187], v[58:61]
	v_mfma_f32_16x16x32_bf16 v[54:57], v[152:155], v[196:199], v[54:57]
	v_mfma_f32_16x16x32_bf16 v[50:53], v[160:163], v[196:199], v[50:53]
	v_mfma_f32_16x16x32_bf16 v[38:41], v[152:155], v[204:207], v[38:41]
	v_mfma_f32_16x16x32_bf16 v[34:37], v[160:163], v[204:207], v[34:37]
	v_mfma_f32_16x16x32_bf16 v[22:25], v[152:155], v[212:215], v[22:25]
	v_mfma_f32_16x16x32_bf16 v[18:21], v[160:163], v[212:215], v[18:21]
	v_mfma_f32_16x16x32_bf16 v[46:49], v[164:167], v[180:183], v[46:49]
	v_mfma_f32_16x16x32_bf16 v[42:45], v[172:175], v[180:183], v[42:45]
	v_mfma_f32_16x16x32_bf16 v[30:33], v[164:167], v[188:191], v[30:33]
	v_mfma_f32_16x16x32_bf16 v[26:29], v[172:175], v[188:191], v[26:29]
	v_mfma_f32_16x16x32_bf16 v[14:17], v[164:167], v[200:203], v[14:17]
	v_mfma_f32_16x16x32_bf16 v[10:13], v[172:175], v[200:203], v[10:13]
	v_mfma_f32_16x16x32_bf16 v[6:9], v[164:167], v[208:211], v[6:9]
	v_mfma_f32_16x16x32_bf16 v[2:5], v[172:175], v[208:211], v[2:5]
	v_mfma_f32_16x16x32_bf16 v[46:49], v[168:171], v[184:187], v[46:49]
	v_mfma_f32_16x16x32_bf16 v[42:45], v[176:179], v[184:187], v[42:45]
	v_mfma_f32_16x16x32_bf16 v[30:33], v[168:171], v[196:199], v[30:33]
	v_mfma_f32_16x16x32_bf16 v[26:29], v[176:179], v[196:199], v[26:29]
	v_mfma_f32_16x16x32_bf16 v[14:17], v[168:171], v[204:207], v[14:17]
	v_mfma_f32_16x16x32_bf16 v[10:13], v[176:179], v[204:207], v[10:13]
	v_mfma_f32_16x16x32_bf16 v[6:9], v[168:171], v[212:215], v[6:9]
	s_barrier
	v_mfma_f32_16x16x32_bf16 v[2:5], v[176:179], v[212:215], v[2:5]
	s_setprio 2
	s_add_i32 s58, s58, 2
	s_add_u32 s34, s34, 0x100
	s_addc_u32 s35, s35, 0
	s_add_u32 s56, s56, 0x100
	s_addc_u32 s57, s57, 0
	s_cmp_gt_u32 s58, 29
	s_cbranch_scc0 .LBB0_541

.Lpeel_10:
	v_add_u32_e32 v250, 0x18000, v145
	ds_read_b128 v[150:153], v147
	ds_read_b128 v[154:157], v147 offset:1024
	s_add_u32 s28, s26, 0xfffe0080
	s_addc_u32 s29, s27, -1
	s_cmp_eq_u32 s50, 4
	s_cselect_b32 s31, s13, s29
	s_cselect_b32 s30, s46, s28
	s_cselect_b32 s29, s17, s49
	s_cselect_b32 s28, s47, s48
	s_add_i32 m0, s36, 0xc000
	global_load_lds_dwordx4 v138, s[26:27]
	s_add_i32 m0, s36, 0xe000
	s_nop 0
	global_load_lds_dwordx4 v140, s[26:27]
	s_waitcnt vmcnt(8)
	s_waitcnt lgkmcnt(0)
	s_barrier
	s_setprio 1
	s_waitcnt lgkmcnt(0)
	v_mfma_f32_16x16x32_bf16 v[126:129], v[150:153], v[182:185], 0
	v_mfma_f32_16x16x32_bf16 v[122:125], v[158:161], v[182:185], 0
	v_mfma_f32_16x16x32_bf16 v[118:121], v[150:153], v[190:193], 0
	v_mfma_f32_16x16x32_bf16 v[114:117], v[158:161], v[190:193], 0
	v_mfma_f32_16x16x32_bf16 v[102:105], v[150:153], v[210:213], 0
	v_mfma_f32_16x16x32_bf16 v[98:101], v[158:161], v[210:213], 0
	v_mfma_f32_16x16x32_bf16 v[86:89], v[150:153], v[218:221], 0
	v_mfma_f32_16x16x32_bf16 v[82:85], v[158:161], v[218:221], 0
	v_mfma_f32_16x16x32_bf16 v[126:129], v[154:157], v[186:189], v[126:129]
	v_mfma_f32_16x16x32_bf16 v[122:125], v[162:165], v[186:189], v[122:125]
	v_mfma_f32_16x16x32_bf16 v[118:121], v[154:157], v[198:201], v[118:121]
	v_mfma_f32_16x16x32_bf16 v[114:117], v[162:165], v[198:201], v[114:117]
	v_mfma_f32_16x16x32_bf16 v[102:105], v[154:157], v[214:217], v[102:105]
	v_mfma_f32_16x16x32_bf16 v[98:101], v[162:165], v[214:217], v[98:101]
	v_mfma_f32_16x16x32_bf16 v[86:89], v[154:157], v[222:225], v[86:89]
	v_mfma_f32_16x16x32_bf16 v[82:85], v[162:165], v[222:225], v[82:85]
	v_mfma_f32_16x16x32_bf16 v[110:113], v[166:169], v[182:185], 0
	v_mfma_f32_16x16x32_bf16 v[106:109], v[174:177], v[182:185], 0
	v_mfma_f32_16x16x32_bf16 v[94:97], v[166:169], v[190:193], 0
	v_mfma_f32_16x16x32_bf16 v[90:93], v[174:177], v[190:193], 0
	v_mfma_f32_16x16x32_bf16 v[78:81], v[166:169], v[210:213], 0
	v_mfma_f32_16x16x32_bf16 v[74:77], v[174:177], v[210:213], 0
	v_mfma_f32_16x16x32_bf16 v[70:73], v[166:169], v[218:221], 0
	v_mfma_f32_16x16x32_bf16 v[66:69], v[174:177], v[218:221], 0
	v_mfma_f32_16x16x32_bf16 v[110:113], v[170:173], v[186:189], v[110:113]
	v_mfma_f32_16x16x32_bf16 v[106:109], v[178:181], v[186:189], v[106:109]
	v_mfma_f32_16x16x32_bf16 v[94:97], v[170:173], v[198:201], v[94:97]
	v_mfma_f32_16x16x32_bf16 v[90:93], v[178:181], v[198:201], v[90:93]
	v_mfma_f32_16x16x32_bf16 v[78:81], v[170:173], v[214:217], v[78:81]
	v_mfma_f32_16x16x32_bf16 v[74:77], v[178:181], v[214:217], v[74:77]
	v_mfma_f32_16x16x32_bf16 v[70:73], v[170:173], v[222:225], v[70:73]
	s_barrier
	v_mfma_f32_16x16x32_bf16 v[66:69], v[178:181], v[222:225], v[66:69]
	s_setprio 2
	s_add_i32 s51, s43, s35
	v_lshl_add_u64 v[202:203], s[28:29], 0, v[132:133]
	s_mov_b32 m0, s51
	ds_read_b128 v[182:185], v149 offset:16384
	ds_read_b128 v[186:189], v149 offset:17408
	ds_read_b128 v[190:193], v149 offset:18432
	ds_read_b128 v[198:201], v149 offset:19456
	ds_read_b128 v[210:213], v149 offset:20480
	ds_read_b128 v[214:217], v149 offset:21504
	ds_read_b128 v[218:221], v149 offset:22528
	ds_read_b128 v[222:225], v149 offset:23552
	global_load_lds_dwordx4 v132, s[28:29]
	s_add_i32 m0, s51, 0x2000
	s_add_u32 s52, s28, 0x20000
	v_lshl_add_u64 v[206:207], s[28:29], 0, v[134:135]
	s_addc_u32 s53, s29, 0
	s_add_i32 s51, s44, s35
	global_load_lds_dwordx4 v134, s[28:29]
	s_mov_b32 m0, s51
	v_lshl_add_u64 v[228:229], s[30:31], 0, v[136:137]
	global_load_lds_dwordx4 v132, s[52:53]
	s_add_i32 m0, s51, 0x2000
	s_nop 0
	global_load_lds_dwordx4 v134, s[52:53]
	v_lshl_add_u64 v[226:227], s[30:31], 0, v[130:131]
	s_mov_b32 m0, s36
	s_nop 0
	global_load_lds_dwordx4 v130, s[30:31]
	s_mov_b32 m0, s37
	s_nop 0
	global_load_lds_dwordx4 v136, s[30:31]
	s_waitcnt vmcnt(8)
	s_waitcnt lgkmcnt(0)
	s_barrier
	s_setprio 1
	s_waitcnt lgkmcnt(0)
	v_mfma_f32_16x16x32_bf16 v[62:65], v[150:153], v[182:185], 0
	v_mfma_f32_16x16x32_bf16 v[58:61], v[158:161], v[182:185], 0
	v_mfma_f32_16x16x32_bf16 v[54:57], v[150:153], v[190:193], 0
	v_mfma_f32_16x16x32_bf16 v[50:53], v[158:161], v[190:193], 0
	v_mfma_f32_16x16x32_bf16 v[38:41], v[150:153], v[210:213], 0
	v_mfma_f32_16x16x32_bf16 v[34:37], v[158:161], v[210:213], 0
	v_mfma_f32_16x16x32_bf16 v[22:25], v[150:153], v[218:221], 0
	v_mfma_f32_16x16x32_bf16 v[18:21], v[158:161], v[218:221], 0
	v_mfma_f32_16x16x32_bf16 v[62:65], v[154:157], v[186:189], v[62:65]
	v_mfma_f32_16x16x32_bf16 v[58:61], v[162:165], v[186:189], v[58:61]
	v_mfma_f32_16x16x32_bf16 v[54:57], v[154:157], v[198:201], v[54:57]
	v_mfma_f32_16x16x32_bf16 v[50:53], v[162:165], v[198:201], v[50:53]
	v_mfma_f32_16x16x32_bf16 v[38:41], v[154:157], v[214:217], v[38:41]
	v_mfma_f32_16x16x32_bf16 v[34:37], v[162:165], v[214:217], v[34:37]
	v_mfma_f32_16x16x32_bf16 v[22:25], v[154:157], v[222:225], v[22:25]
	v_mfma_f32_16x16x32_bf16 v[18:21], v[162:165], v[222:225], v[18:21]
	v_mfma_f32_16x16x32_bf16 v[46:49], v[166:169], v[182:185], 0
	v_mfma_f32_16x16x32_bf16 v[42:45], v[174:177], v[182:185], 0
	v_mfma_f32_16x16x32_bf16 v[30:33], v[166:169], v[190:193], 0
	v_mfma_f32_16x16x32_bf16 v[26:29], v[174:177], v[190:193], 0
	v_mfma_f32_16x16x32_bf16 v[14:17], v[166:169], v[210:213], 0
	v_mfma_f32_16x16x32_bf16 v[10:13], v[174:177], v[210:213], 0
	v_mfma_f32_16x16x32_bf16 v[6:9], v[166:169], v[218:221], 0
	v_mfma_f32_16x16x32_bf16 v[2:5], v[174:177], v[218:221], 0
	v_mfma_f32_16x16x32_bf16 v[46:49], v[170:173], v[186:189], v[46:49]
	v_mfma_f32_16x16x32_bf16 v[42:45], v[178:181], v[186:189], v[42:45]
	v_mfma_f32_16x16x32_bf16 v[30:33], v[170:173], v[198:201], v[30:33]
	v_mfma_f32_16x16x32_bf16 v[26:29], v[178:181], v[198:201], v[26:29]
	v_mfma_f32_16x16x32_bf16 v[14:17], v[170:173], v[214:217], v[14:17]
	v_mfma_f32_16x16x32_bf16 v[10:13], v[178:181], v[214:217], v[10:13]
	v_mfma_f32_16x16x32_bf16 v[6:9], v[170:173], v[222:225], v[6:9]
	s_barrier
	v_mfma_f32_16x16x32_bf16 v[2:5], v[178:181], v[222:225], v[2:5]
	s_setprio 2
	s_add_i32 s51, 0, 0x18000
	s_add_i32 s52, 0, 0x1c000
	ds_read_b128 v[150:153], v250
	ds_read_b128 v[154:157], v250 offset:1024
	ds_read_b128 v[158:161], v250 offset:2048
	ds_read_b128 v[162:165], v250 offset:3072
	ds_read_b128 v[166:169], v250 offset:16384
	ds_read_b128 v[170:173], v250 offset:17408
	ds_read_b128 v[174:177], v250 offset:18432
	ds_read_b128 v[178:181], v250 offset:19456
	s_add_u32 s30, s30, 0x20000
	s_addc_u32 s31, s31, 0
	s_mov_b32 m0, s38
	ds_read_b128 v[182:185], v149 offset:32768
	ds_read_b128 v[186:189], v149 offset:33792
	ds_read_b128 v[190:193], v149 offset:34816
	ds_read_b128 v[198:201], v149 offset:35840
	ds_read_b128 v[210:213], v149 offset:36864
	ds_read_b128 v[214:217], v149 offset:37888
	ds_read_b128 v[218:221], v149 offset:38912
	ds_read_b128 v[222:225], v149 offset:39936
	global_load_lds_dwordx4 v130, s[30:31]
	v_lshl_add_u64 v[230:231], s[30:31], 0, v[136:137]
	s_mov_b32 m0, s39
	s_nop 0
	global_load_lds_dwordx4 v136, s[30:31]
	s_waitcnt vmcnt(8)
	s_waitcnt lgkmcnt(0)
	s_barrier
	s_setprio 1
	s_waitcnt lgkmcnt(0)
	v_mfma_f32_16x16x32_bf16 v[126:129], v[150:153], v[182:185], v[126:129]
	v_mfma_f32_16x16x32_bf16 v[122:125], v[158:161], v[182:185], v[122:125]
	v_mfma_f32_16x16x32_bf16 v[118:121], v[150:153], v[190:193], v[118:121]
	v_mfma_f32_16x16x32_bf16 v[114:117], v[158:161], v[190:193], v[114:117]
	v_mfma_f32_16x16x32_bf16 v[102:105], v[150:153], v[210:213], v[102:105]
	v_mfma_f32_16x16x32_bf16 v[98:101], v[158:161], v[210:213], v[98:101]
	v_mfma_f32_16x16x32_bf16 v[86:89], v[150:153], v[218:221], v[86:89]
	v_mfma_f32_16x16x32_bf16 v[82:85], v[158:161], v[218:221], v[82:85]
	v_mfma_f32_16x16x32_bf16 v[126:129], v[154:157], v[186:189], v[126:129]
	v_mfma_f32_16x16x32_bf16 v[122:125], v[162:165], v[186:189], v[122:125]
	v_mfma_f32_16x16x32_bf16 v[118:121], v[154:157], v[198:201], v[118:121]
	v_mfma_f32_16x16x32_bf16 v[114:117], v[162:165], v[198:201], v[114:117]
	v_mfma_f32_16x16x32_bf16 v[102:105], v[154:157], v[214:217], v[102:105]
	v_mfma_f32_16x16x32_bf16 v[98:101], v[162:165], v[214:217], v[98:101]
	v_mfma_f32_16x16x32_bf16 v[86:89], v[154:157], v[222:225], v[86:89]
	v_mfma_f32_16x16x32_bf16 v[82:85], v[162:165], v[222:225], v[82:85]
	v_mfma_f32_16x16x32_bf16 v[110:113], v[166:169], v[182:185], v[110:113]
	v_mfma_f32_16x16x32_bf16 v[106:109], v[174:177], v[182:185], v[106:109]
	v_mfma_f32_16x16x32_bf16 v[94:97], v[166:169], v[190:193], v[94:97]
	v_mfma_f32_16x16x32_bf16 v[90:93], v[174:177], v[190:193], v[90:93]
	v_mfma_f32_16x16x32_bf16 v[78:81], v[166:169], v[210:213], v[78:81]
	v_mfma_f32_16x16x32_bf16 v[74:77], v[174:177], v[210:213], v[74:77]
	v_mfma_f32_16x16x32_bf16 v[70:73], v[166:169], v[218:221], v[70:73]
	v_mfma_f32_16x16x32_bf16 v[66:69], v[174:177], v[218:221], v[66:69]
	v_mfma_f32_16x16x32_bf16 v[110:113], v[170:173], v[186:189], v[110:113]
	v_mfma_f32_16x16x32_bf16 v[106:109], v[178:181], v[186:189], v[106:109]
	v_mfma_f32_16x16x32_bf16 v[94:97], v[170:173], v[198:201], v[94:97]
	v_mfma_f32_16x16x32_bf16 v[90:93], v[178:181], v[198:201], v[90:93]
	v_mfma_f32_16x16x32_bf16 v[78:81], v[170:173], v[214:217], v[78:81]
	v_mfma_f32_16x16x32_bf16 v[74:77], v[178:181], v[214:217], v[74:77]
	v_mfma_f32_16x16x32_bf16 v[70:73], v[170:173], v[222:225], v[70:73]
	s_barrier
	v_mfma_f32_16x16x32_bf16 v[66:69], v[178:181], v[222:225], v[66:69]
	s_setprio 2
	s_add_i32 s30, s51, s35
	v_lshl_add_u64 v[202:203], v[202:203], 0, s[8:9]
	s_mov_b32 m0, s30
	ds_read_b128 v[182:185], v149 offset:49152
	ds_read_b128 v[186:189], v149 offset:50176
	ds_read_b128 v[190:193], v149 offset:51200
	ds_read_b128 v[198:201], v149 offset:52224
	ds_read_b128 v[210:213], v149 offset:53248
	ds_read_b128 v[214:217], v149 offset:54272
	ds_read_b128 v[218:221], v149 offset:55296
	ds_read_b128 v[222:225], v149 offset:56320
	global_load_lds_dwordx4 v[202:203], off
	s_add_i32 m0, s30, 0x2000
	s_add_u32 s28, s28, 0x20080
	v_lshl_add_u64 v[202:203], v[206:207], 0, s[8:9]
	s_addc_u32 s29, s29, 0
	s_add_i32 s30, s52, s35
	global_load_lds_dwordx4 v[202:203], off
	s_mov_b32 m0, s30
	s_nop 0
	global_load_lds_dwordx4 v132, s[28:29]
	s_add_i32 m0, s30, 0x2000
	s_nop 0
	global_load_lds_dwordx4 v134, s[28:29]
	v_lshl_add_u64 v[202:203], v[226:227], 0, s[8:9]
	s_mov_b32 m0, s41
	s_nop 0
	global_load_lds_dwordx4 v[202:203], off
	v_lshl_add_u64 v[202:203], v[228:229], 0, s[8:9]
	s_mov_b32 m0, s42
	s_nop 0
	global_load_lds_dwordx4 v[202:203], off
	s_waitcnt vmcnt(8)
	s_waitcnt lgkmcnt(0)
	s_barrier
	s_setprio 1
	s_waitcnt lgkmcnt(0)
	v_mfma_f32_16x16x32_bf16 v[62:65], v[150:153], v[182:185], v[62:65]
	v_mfma_f32_16x16x32_bf16 v[58:61], v[158:161], v[182:185], v[58:61]
	v_mfma_f32_16x16x32_bf16 v[54:57], v[150:153], v[190:193], v[54:57]
	v_mfma_f32_16x16x32_bf16 v[50:53], v[158:161], v[190:193], v[50:53]
	v_mfma_f32_16x16x32_bf16 v[38:41], v[150:153], v[210:213], v[38:41]
	v_mfma_f32_16x16x32_bf16 v[34:37], v[158:161], v[210:213], v[34:37]
	v_mfma_f32_16x16x32_bf16 v[22:25], v[150:153], v[218:221], v[22:25]
	v_mfma_f32_16x16x32_bf16 v[18:21], v[158:161], v[218:221], v[18:21]
	v_mfma_f32_16x16x32_bf16 v[62:65], v[154:157], v[186:189], v[62:65]
	v_mfma_f32_16x16x32_bf16 v[58:61], v[162:165], v[186:189], v[58:61]
	v_mfma_f32_16x16x32_bf16 v[54:57], v[154:157], v[198:201], v[54:57]
	v_mfma_f32_16x16x32_bf16 v[50:53], v[162:165], v[198:201], v[50:53]
	v_mfma_f32_16x16x32_bf16 v[38:41], v[154:157], v[214:217], v[38:41]
	v_mfma_f32_16x16x32_bf16 v[34:37], v[162:165], v[214:217], v[34:37]
	v_mfma_f32_16x16x32_bf16 v[22:25], v[154:157], v[222:225], v[22:25]
	v_mfma_f32_16x16x32_bf16 v[18:21], v[162:165], v[222:225], v[18:21]
	v_mfma_f32_16x16x32_bf16 v[46:49], v[166:169], v[182:185], v[46:49]
	v_mfma_f32_16x16x32_bf16 v[42:45], v[174:177], v[182:185], v[42:45]
	v_mfma_f32_16x16x32_bf16 v[30:33], v[166:169], v[190:193], v[30:33]
	v_mfma_f32_16x16x32_bf16 v[26:29], v[174:177], v[190:193], v[26:29]
	v_mfma_f32_16x16x32_bf16 v[14:17], v[166:169], v[210:213], v[14:17]
	v_mfma_f32_16x16x32_bf16 v[10:13], v[174:177], v[210:213], v[10:13]
	v_mfma_f32_16x16x32_bf16 v[6:9], v[166:169], v[218:221], v[6:9]
	v_mfma_f32_16x16x32_bf16 v[2:5], v[174:177], v[218:221], v[2:5]
	v_mfma_f32_16x16x32_bf16 v[46:49], v[170:173], v[186:189], v[46:49]
	v_mfma_f32_16x16x32_bf16 v[42:45], v[178:181], v[186:189], v[42:45]
	v_mfma_f32_16x16x32_bf16 v[30:33], v[170:173], v[198:201], v[30:33]
	v_mfma_f32_16x16x32_bf16 v[26:29], v[178:181], v[198:201], v[26:29]
	v_mfma_f32_16x16x32_bf16 v[14:17], v[170:173], v[214:217], v[14:17]
	v_mfma_f32_16x16x32_bf16 v[10:13], v[178:181], v[214:217], v[10:13]
	v_mfma_f32_16x16x32_bf16 v[6:9], v[170:173], v[222:225], v[6:9]
	s_barrier
	v_mfma_f32_16x16x32_bf16 v[2:5], v[178:181], v[222:225], v[2:5]
	s_setprio 2
	s_add_i32 s50, s50, 2
	s_add_u32 s26, s26, 0x100
	s_addc_u32 s27, s27, 0
	s_add_u32 s48, s48, 0x100
	s_addc_u32 s49, s49, 0
	s_cmp_gt_u32 s50, 5
	s_cbranch_scc0 .LBB0_690
	s_branch .Lpeeldone_10
.LBB0_690:
	ds_read_b128 v[150:153], v147
	ds_read_b128 v[154:157], v147 offset:1024
	ds_read_b128 v[158:161], v147 offset:2048
	ds_read_b128 v[162:165], v147 offset:3072
	ds_read_b128 v[166:169], v148
	ds_read_b128 v[170:173], v148 offset:1024
	ds_read_b128 v[174:177], v148 offset:2048
	ds_read_b128 v[178:181], v148 offset:3072
	s_add_u32 s28, s26, 0xfffe0080
	s_addc_u32 s29, s27, -1
	s_cmp_eq_u32 s50, 4
	s_cselect_b32 s31, s13, s29
	s_cselect_b32 s30, s46, s28
	s_cselect_b32 s29, s17, s49
	s_cselect_b32 s28, s47, s48
	s_add_i32 m0, s36, 0xc000
	ds_read_b128 v[182:185], v149
	ds_read_b128 v[186:189], v149 offset:1024
	ds_read_b128 v[190:193], v149 offset:2048
	ds_read_b128 v[198:201], v149 offset:3072
	ds_read_b128 v[210:213], v149 offset:4096
	ds_read_b128 v[214:217], v149 offset:5120
	ds_read_b128 v[218:221], v149 offset:6144
	ds_read_b128 v[222:225], v149 offset:7168
	global_load_lds_dwordx4 v138, s[26:27]
	s_add_i32 m0, s36, 0xe000
	s_nop 0
	global_load_lds_dwordx4 v140, s[26:27]
	s_waitcnt vmcnt(8)
	s_waitcnt lgkmcnt(0)
	s_barrier
	s_setprio 1
	s_waitcnt lgkmcnt(0)
	v_mfma_f32_16x16x32_bf16 v[126:129], v[150:153], v[182:185], v[126:129]
	v_mfma_f32_16x16x32_bf16 v[122:125], v[158:161], v[182:185], v[122:125]
	v_mfma_f32_16x16x32_bf16 v[118:121], v[150:153], v[190:193], v[118:121]
	v_mfma_f32_16x16x32_bf16 v[114:117], v[158:161], v[190:193], v[114:117]
	v_mfma_f32_16x16x32_bf16 v[102:105], v[150:153], v[210:213], v[102:105]
	v_mfma_f32_16x16x32_bf16 v[98:101], v[158:161], v[210:213], v[98:101]
	v_mfma_f32_16x16x32_bf16 v[86:89], v[150:153], v[218:221], v[86:89]
	v_mfma_f32_16x16x32_bf16 v[82:85], v[158:161], v[218:221], v[82:85]
	v_mfma_f32_16x16x32_bf16 v[126:129], v[154:157], v[186:189], v[126:129]
	v_mfma_f32_16x16x32_bf16 v[122:125], v[162:165], v[186:189], v[122:125]
	v_mfma_f32_16x16x32_bf16 v[118:121], v[154:157], v[198:201], v[118:121]
	v_mfma_f32_16x16x32_bf16 v[114:117], v[162:165], v[198:201], v[114:117]
	v_mfma_f32_16x16x32_bf16 v[102:105], v[154:157], v[214:217], v[102:105]
	v_mfma_f32_16x16x32_bf16 v[98:101], v[162:165], v[214:217], v[98:101]
	v_mfma_f32_16x16x32_bf16 v[86:89], v[154:157], v[222:225], v[86:89]
	v_mfma_f32_16x16x32_bf16 v[82:85], v[162:165], v[222:225], v[82:85]
	v_mfma_f32_16x16x32_bf16 v[110:113], v[166:169], v[182:185], v[110:113]
	v_mfma_f32_16x16x32_bf16 v[106:109], v[174:177], v[182:185], v[106:109]
	v_mfma_f32_16x16x32_bf16 v[94:97], v[166:169], v[190:193], v[94:97]
	v_mfma_f32_16x16x32_bf16 v[90:93], v[174:177], v[190:193], v[90:93]
	v_mfma_f32_16x16x32_bf16 v[78:81], v[166:169], v[210:213], v[78:81]
	v_mfma_f32_16x16x32_bf16 v[74:77], v[174:177], v[210:213], v[74:77]
	v_mfma_f32_16x16x32_bf16 v[70:73], v[166:169], v[218:221], v[70:73]
	v_mfma_f32_16x16x32_bf16 v[66:69], v[174:177], v[218:221], v[66:69]
	v_mfma_f32_16x16x32_bf16 v[110:113], v[170:173], v[186:189], v[110:113]
	v_mfma_f32_16x16x32_bf16 v[106:109], v[178:181], v[186:189], v[106:109]
	v_mfma_f32_16x16x32_bf16 v[94:97], v[170:173], v[198:201], v[94:97]
	v_mfma_f32_16x16x32_bf16 v[90:93], v[178:181], v[198:201], v[90:93]
	v_mfma_f32_16x16x32_bf16 v[78:81], v[170:173], v[214:217], v[78:81]
	v_mfma_f32_16x16x32_bf16 v[74:77], v[178:181], v[214:217], v[74:77]
	v_mfma_f32_16x16x32_bf16 v[70:73], v[170:173], v[222:225], v[70:73]
	s_barrier
	v_mfma_f32_16x16x32_bf16 v[66:69], v[178:181], v[222:225], v[66:69]
	s_setprio 2
	s_add_i32 s51, s43, s35
	v_lshl_add_u64 v[202:203], s[28:29], 0, v[132:133]
	s_mov_b32 m0, s51
	ds_read_b128 v[182:185], v149 offset:16384
	ds_read_b128 v[186:189], v149 offset:17408
	ds_read_b128 v[190:193], v149 offset:18432
	ds_read_b128 v[198:201], v149 offset:19456
	ds_read_b128 v[210:213], v149 offset:20480
	ds_read_b128 v[214:217], v149 offset:21504
	ds_read_b128 v[218:221], v149 offset:22528
	ds_read_b128 v[222:225], v149 offset:23552
	global_load_lds_dwordx4 v132, s[28:29]
	s_add_i32 m0, s51, 0x2000
	s_add_u32 s52, s28, 0x20000
	v_lshl_add_u64 v[206:207], s[28:29], 0, v[134:135]
	s_addc_u32 s53, s29, 0
	s_add_i32 s51, s44, s35
	global_load_lds_dwordx4 v134, s[28:29]
	s_mov_b32 m0, s51
	v_lshl_add_u64 v[228:229], s[30:31], 0, v[136:137]
	global_load_lds_dwordx4 v132, s[52:53]
	s_add_i32 m0, s51, 0x2000
	s_nop 0
	global_load_lds_dwordx4 v134, s[52:53]
	v_lshl_add_u64 v[226:227], s[30:31], 0, v[130:131]
	s_mov_b32 m0, s36
	s_nop 0
	global_load_lds_dwordx4 v130, s[30:31]
	s_mov_b32 m0, s37
	s_nop 0
	global_load_lds_dwordx4 v136, s[30:31]
	s_waitcnt vmcnt(8)
	s_waitcnt lgkmcnt(0)
	s_barrier
	s_setprio 1
	s_waitcnt lgkmcnt(0)
	v_mfma_f32_16x16x32_bf16 v[62:65], v[150:153], v[182:185], v[62:65]
	v_mfma_f32_16x16x32_bf16 v[58:61], v[158:161], v[182:185], v[58:61]
	v_mfma_f32_16x16x32_bf16 v[54:57], v[150:153], v[190:193], v[54:57]
	v_mfma_f32_16x16x32_bf16 v[50:53], v[158:161], v[190:193], v[50:53]
	v_mfma_f32_16x16x32_bf16 v[38:41], v[150:153], v[210:213], v[38:41]
	v_mfma_f32_16x16x32_bf16 v[34:37], v[158:161], v[210:213], v[34:37]
	v_mfma_f32_16x16x32_bf16 v[22:25], v[150:153], v[218:221], v[22:25]
	v_mfma_f32_16x16x32_bf16 v[18:21], v[158:161], v[218:221], v[18:21]
	v_mfma_f32_16x16x32_bf16 v[62:65], v[154:157], v[186:189], v[62:65]
	v_mfma_f32_16x16x32_bf16 v[58:61], v[162:165], v[186:189], v[58:61]
	v_mfma_f32_16x16x32_bf16 v[54:57], v[154:157], v[198:201], v[54:57]
	v_mfma_f32_16x16x32_bf16 v[50:53], v[162:165], v[198:201], v[50:53]
	v_mfma_f32_16x16x32_bf16 v[38:41], v[154:157], v[214:217], v[38:41]
	v_mfma_f32_16x16x32_bf16 v[34:37], v[162:165], v[214:217], v[34:37]
	v_mfma_f32_16x16x32_bf16 v[22:25], v[154:157], v[222:225], v[22:25]
	v_mfma_f32_16x16x32_bf16 v[18:21], v[162:165], v[222:225], v[18:21]
	v_mfma_f32_16x16x32_bf16 v[46:49], v[166:169], v[182:185], v[46:49]
	v_mfma_f32_16x16x32_bf16 v[42:45], v[174:177], v[182:185], v[42:45]
	v_mfma_f32_16x16x32_bf16 v[30:33], v[166:169], v[190:193], v[30:33]
	v_mfma_f32_16x16x32_bf16 v[26:29], v[174:177], v[190:193], v[26:29]
	v_mfma_f32_16x16x32_bf16 v[14:17], v[166:169], v[210:213], v[14:17]
	v_mfma_f32_16x16x32_bf16 v[10:13], v[174:177], v[210:213], v[10:13]
	v_mfma_f32_16x16x32_bf16 v[6:9], v[166:169], v[218:221], v[6:9]
	v_mfma_f32_16x16x32_bf16 v[2:5], v[174:177], v[218:221], v[2:5]
	v_mfma_f32_16x16x32_bf16 v[46:49], v[170:173], v[186:189], v[46:49]
	v_mfma_f32_16x16x32_bf16 v[42:45], v[178:181], v[186:189], v[42:45]
	v_mfma_f32_16x16x32_bf16 v[30:33], v[170:173], v[198:201], v[30:33]
	v_mfma_f32_16x16x32_bf16 v[26:29], v[178:181], v[198:201], v[26:29]
	v_mfma_f32_16x16x32_bf16 v[14:17], v[170:173], v[214:217], v[14:17]
	v_mfma_f32_16x16x32_bf16 v[10:13], v[178:181], v[214:217], v[10:13]
	v_mfma_f32_16x16x32_bf16 v[6:9], v[170:173], v[222:225], v[6:9]
	s_barrier
	v_mfma_f32_16x16x32_bf16 v[2:5], v[178:181], v[222:225], v[2:5]
	s_setprio 2
	s_add_i32 s51, 0, 0x18000
	s_add_i32 s52, 0, 0x1c000
	ds_read_b128 v[150:153], v250
	ds_read_b128 v[154:157], v250 offset:1024
	ds_read_b128 v[158:161], v250 offset:2048
	ds_read_b128 v[162:165], v250 offset:3072
	ds_read_b128 v[166:169], v250 offset:16384
	ds_read_b128 v[170:173], v250 offset:17408
	ds_read_b128 v[174:177], v250 offset:18432
	ds_read_b128 v[178:181], v250 offset:19456
	s_add_u32 s30, s30, 0x20000
	s_addc_u32 s31, s31, 0
	s_mov_b32 m0, s38
	ds_read_b128 v[182:185], v149 offset:32768
	ds_read_b128 v[186:189], v149 offset:33792
	ds_read_b128 v[190:193], v149 offset:34816
	ds_read_b128 v[198:201], v149 offset:35840
	ds_read_b128 v[210:213], v149 offset:36864
	ds_read_b128 v[214:217], v149 offset:37888
	ds_read_b128 v[218:221], v149 offset:38912
	ds_read_b128 v[222:225], v149 offset:39936
	global_load_lds_dwordx4 v130, s[30:31]
	v_lshl_add_u64 v[230:231], s[30:31], 0, v[136:137]
	s_mov_b32 m0, s39
	s_nop 0
	global_load_lds_dwordx4 v136, s[30:31]
	s_waitcnt vmcnt(8)
	s_waitcnt lgkmcnt(0)
	s_barrier
	s_setprio 1
	s_waitcnt lgkmcnt(0)
	v_mfma_f32_16x16x32_bf16 v[126:129], v[150:153], v[182:185], v[126:129]
	v_mfma_f32_16x16x32_bf16 v[122:125], v[158:161], v[182:185], v[122:125]
	v_mfma_f32_16x16x32_bf16 v[118:121], v[150:153], v[190:193], v[118:121]
	v_mfma_f32_16x16x32_bf16 v[114:117], v[158:161], v[190:193], v[114:117]
	v_mfma_f32_16x16x32_bf16 v[102:105], v[150:153], v[210:213], v[102:105]
	v_mfma_f32_16x16x32_bf16 v[98:101], v[158:161], v[210:213], v[98:101]
	v_mfma_f32_16x16x32_bf16 v[86:89], v[150:153], v[218:221], v[86:89]
	v_mfma_f32_16x16x32_bf16 v[82:85], v[158:161], v[218:221], v[82:85]
	v_mfma_f32_16x16x32_bf16 v[126:129], v[154:157], v[186:189], v[126:129]
	v_mfma_f32_16x16x32_bf16 v[122:125], v[162:165], v[186:189], v[122:125]
	v_mfma_f32_16x16x32_bf16 v[118:121], v[154:157], v[198:201], v[118:121]
	v_mfma_f32_16x16x32_bf16 v[114:117], v[162:165], v[198:201], v[114:117]
	v_mfma_f32_16x16x32_bf16 v[102:105], v[154:157], v[214:217], v[102:105]
	v_mfma_f32_16x16x32_bf16 v[98:101], v[162:165], v[214:217], v[98:101]
	v_mfma_f32_16x16x32_bf16 v[86:89], v[154:157], v[222:225], v[86:89]
	v_mfma_f32_16x16x32_bf16 v[82:85], v[162:165], v[222:225], v[82:85]
	v_mfma_f32_16x16x32_bf16 v[110:113], v[166:169], v[182:185], v[110:113]
	v_mfma_f32_16x16x32_bf16 v[106:109], v[174:177], v[182:185], v[106:109]
	v_mfma_f32_16x16x32_bf16 v[94:97], v[166:169], v[190:193], v[94:97]
	v_mfma_f32_16x16x32_bf16 v[90:93], v[174:177], v[190:193], v[90:93]
	v_mfma_f32_16x16x32_bf16 v[78:81], v[166:169], v[210:213], v[78:81]
	v_mfma_f32_16x16x32_bf16 v[74:77], v[174:177], v[210:213], v[74:77]
	v_mfma_f32_16x16x32_bf16 v[70:73], v[166:169], v[218:221], v[70:73]
	v_mfma_f32_16x16x32_bf16 v[66:69], v[174:177], v[218:221], v[66:69]
	v_mfma_f32_16x16x32_bf16 v[110:113], v[170:173], v[186:189], v[110:113]
	v_mfma_f32_16x16x32_bf16 v[106:109], v[178:181], v[186:189], v[106:109]
	v_mfma_f32_16x16x32_bf16 v[94:97], v[170:173], v[198:201], v[94:97]
	v_mfma_f32_16x16x32_bf16 v[90:93], v[178:181], v[198:201], v[90:93]
	v_mfma_f32_16x16x32_bf16 v[78:81], v[170:173], v[214:217], v[78:81]
	v_mfma_f32_16x16x32_bf16 v[74:77], v[178:181], v[214:217], v[74:77]
	v_mfma_f32_16x16x32_bf16 v[70:73], v[170:173], v[222:225], v[70:73]
	s_barrier
	v_mfma_f32_16x16x32_bf16 v[66:69], v[178:181], v[222:225], v[66:69]
	s_setprio 2
	s_add_i32 s30, s51, s35
	v_lshl_add_u64 v[202:203], v[202:203], 0, s[8:9]
	s_mov_b32 m0, s30
	ds_read_b128 v[182:185], v149 offset:49152
	ds_read_b128 v[186:189], v149 offset:50176
	ds_read_b128 v[190:193], v149 offset:51200
	ds_read_b128 v[198:201], v149 offset:52224
	ds_read_b128 v[210:213], v149 offset:53248
	ds_read_b128 v[214:217], v149 offset:54272
	ds_read_b128 v[218:221], v149 offset:55296
	ds_read_b128 v[222:225], v149 offset:56320
	global_load_lds_dwordx4 v[202:203], off
	s_add_i32 m0, s30, 0x2000
	s_add_u32 s28, s28, 0x20080
	v_lshl_add_u64 v[202:203], v[206:207], 0, s[8:9]
	s_addc_u32 s29, s29, 0
	s_add_i32 s30, s52, s35
	global_load_lds_dwordx4 v[202:203], off
	s_mov_b32 m0, s30
	s_nop 0
	global_load_lds_dwordx4 v132, s[28:29]
	s_add_i32 m0, s30, 0x2000
	s_nop 0
	global_load_lds_dwordx4 v134, s[28:29]
	v_lshl_add_u64 v[202:203], v[226:227], 0, s[8:9]
	s_mov_b32 m0, s41
	s_nop 0
	global_load_lds_dwordx4 v[202:203], off
	v_lshl_add_u64 v[202:203], v[228:229], 0, s[8:9]
	s_mov_b32 m0, s42
	s_nop 0
	global_load_lds_dwordx4 v[202:203], off
	s_waitcnt vmcnt(8)
	s_waitcnt lgkmcnt(0)
	s_barrier
	s_setprio 1
	s_waitcnt lgkmcnt(0)
	v_mfma_f32_16x16x32_bf16 v[62:65], v[150:153], v[182:185], v[62:65]
	v_mfma_f32_16x16x32_bf16 v[58:61], v[158:161], v[182:185], v[58:61]
	v_mfma_f32_16x16x32_bf16 v[54:57], v[150:153], v[190:193], v[54:57]
	v_mfma_f32_16x16x32_bf16 v[50:53], v[158:161], v[190:193], v[50:53]
	v_mfma_f32_16x16x32_bf16 v[38:41], v[150:153], v[210:213], v[38:41]
	v_mfma_f32_16x16x32_bf16 v[34:37], v[158:161], v[210:213], v[34:37]
	v_mfma_f32_16x16x32_bf16 v[22:25], v[150:153], v[218:221], v[22:25]
	v_mfma_f32_16x16x32_bf16 v[18:21], v[158:161], v[218:221], v[18:21]
	v_mfma_f32_16x16x32_bf16 v[62:65], v[154:157], v[186:189], v[62:65]
	v_mfma_f32_16x16x32_bf16 v[58:61], v[162:165], v[186:189], v[58:61]
	v_mfma_f32_16x16x32_bf16 v[54:57], v[154:157], v[198:201], v[54:57]
	v_mfma_f32_16x16x32_bf16 v[50:53], v[162:165], v[198:201], v[50:53]
	v_mfma_f32_16x16x32_bf16 v[38:41], v[154:157], v[214:217], v[38:41]
	v_mfma_f32_16x16x32_bf16 v[34:37], v[162:165], v[214:217], v[34:37]
	v_mfma_f32_16x16x32_bf16 v[22:25], v[154:157], v[222:225], v[22:25]
	v_mfma_f32_16x16x32_bf16 v[18:21], v[162:165], v[222:225], v[18:21]
	v_mfma_f32_16x16x32_bf16 v[46:49], v[166:169], v[182:185], v[46:49]
	v_mfma_f32_16x16x32_bf16 v[42:45], v[174:177], v[182:185], v[42:45]
	v_mfma_f32_16x16x32_bf16 v[30:33], v[166:169], v[190:193], v[30:33]
	v_mfma_f32_16x16x32_bf16 v[26:29], v[174:177], v[190:193], v[26:29]
	v_mfma_f32_16x16x32_bf16 v[14:17], v[166:169], v[210:213], v[14:17]
	v_mfma_f32_16x16x32_bf16 v[10:13], v[174:177], v[210:213], v[10:13]
	v_mfma_f32_16x16x32_bf16 v[6:9], v[166:169], v[218:221], v[6:9]
	v_mfma_f32_16x16x32_bf16 v[2:5], v[174:177], v[218:221], v[2:5]
	v_mfma_f32_16x16x32_bf16 v[46:49], v[170:173], v[186:189], v[46:49]
	v_mfma_f32_16x16x32_bf16 v[42:45], v[178:181], v[186:189], v[42:45]
	v_mfma_f32_16x16x32_bf16 v[30:33], v[170:173], v[198:201], v[30:33]
	v_mfma_f32_16x16x32_bf16 v[26:29], v[178:181], v[198:201], v[26:29]
	v_mfma_f32_16x16x32_bf16 v[14:17], v[170:173], v[214:217], v[14:17]
	v_mfma_f32_16x16x32_bf16 v[10:13], v[178:181], v[214:217], v[10:13]
	v_mfma_f32_16x16x32_bf16 v[6:9], v[170:173], v[222:225], v[6:9]
	s_barrier
	v_mfma_f32_16x16x32_bf16 v[2:5], v[178:181], v[222:225], v[2:5]
	s_setprio 2
	s_add_i32 s50, s50, 2
	s_add_u32 s26, s26, 0x100
	s_addc_u32 s27, s27, 0
	s_add_u32 s48, s48, 0x100
	s_addc_u32 s49, s49, 0
	s_cmp_gt_u32 s50, 5
	s_cbranch_scc0 .LBB0_690

.Lpeel_9:
	v_add_u32_e32 v250, 0x18000, v139
	ds_read_b128 v[144:147], v140
	ds_read_b128 v[148:151], v140 offset:1024
	s_add_u32 s36, s34, 0xfffe0080
	s_addc_u32 s37, s35, -1
	s_cmp_eq_u32 s59, 4
	s_cselect_b32 s39, s21, s37
	s_cselect_b32 s38, s55, s36
	s_cselect_b32 s37, s25, s58
	s_cselect_b32 s36, s56, s57
	s_add_i32 m0, s27, 0xc000
	global_load_lds_dwordx4 v130, s[34:35]
	s_add_i32 m0, s27, 0xe000
	s_nop 0
	global_load_lds_dwordx4 v136, s[34:35]
	s_waitcnt vmcnt(8)
	s_waitcnt lgkmcnt(0)
	s_barrier
	s_setprio 1
	s_waitcnt lgkmcnt(0)
	v_mfma_f32_16x16x32_bf16 v[126:129], v[144:147], v[176:179], 0
	v_mfma_f32_16x16x32_bf16 v[122:125], v[152:155], v[176:179], 0
	v_mfma_f32_16x16x32_bf16 v[118:121], v[144:147], v[184:187], 0
	v_mfma_f32_16x16x32_bf16 v[114:117], v[152:155], v[184:187], 0
	v_mfma_f32_16x16x32_bf16 v[102:105], v[144:147], v[198:201], 0
	v_mfma_f32_16x16x32_bf16 v[98:101], v[152:155], v[198:201], 0
	v_mfma_f32_16x16x32_bf16 v[86:89], v[144:147], v[214:217], 0
	v_mfma_f32_16x16x32_bf16 v[82:85], v[152:155], v[214:217], 0
	v_mfma_f32_16x16x32_bf16 v[126:129], v[148:151], v[180:183], v[126:129]
	v_mfma_f32_16x16x32_bf16 v[122:125], v[156:159], v[180:183], v[122:125]
	v_mfma_f32_16x16x32_bf16 v[118:121], v[148:151], v[188:191], v[118:121]
	v_mfma_f32_16x16x32_bf16 v[114:117], v[156:159], v[188:191], v[114:117]
	v_mfma_f32_16x16x32_bf16 v[102:105], v[148:151], v[210:213], v[102:105]
	v_mfma_f32_16x16x32_bf16 v[98:101], v[156:159], v[210:213], v[98:101]
	v_mfma_f32_16x16x32_bf16 v[86:89], v[148:151], v[218:221], v[86:89]
	v_mfma_f32_16x16x32_bf16 v[82:85], v[156:159], v[218:221], v[82:85]
	v_mfma_f32_16x16x32_bf16 v[110:113], v[160:163], v[176:179], 0
	v_mfma_f32_16x16x32_bf16 v[106:109], v[168:171], v[176:179], 0
	v_mfma_f32_16x16x32_bf16 v[94:97], v[160:163], v[184:187], 0
	v_mfma_f32_16x16x32_bf16 v[90:93], v[168:171], v[184:187], 0
	v_mfma_f32_16x16x32_bf16 v[78:81], v[160:163], v[198:201], 0
	v_mfma_f32_16x16x32_bf16 v[74:77], v[168:171], v[198:201], 0
	v_mfma_f32_16x16x32_bf16 v[70:73], v[160:163], v[214:217], 0
	v_mfma_f32_16x16x32_bf16 v[66:69], v[168:171], v[214:217], 0
	v_mfma_f32_16x16x32_bf16 v[110:113], v[164:167], v[180:183], v[110:113]
	v_mfma_f32_16x16x32_bf16 v[106:109], v[172:175], v[180:183], v[106:109]
	v_mfma_f32_16x16x32_bf16 v[94:97], v[164:167], v[188:191], v[94:97]
	v_mfma_f32_16x16x32_bf16 v[90:93], v[172:175], v[188:191], v[90:93]
	v_mfma_f32_16x16x32_bf16 v[78:81], v[164:167], v[210:213], v[78:81]
	v_mfma_f32_16x16x32_bf16 v[74:77], v[172:175], v[210:213], v[74:77]
	v_mfma_f32_16x16x32_bf16 v[70:73], v[164:167], v[218:221], v[70:73]
	s_barrier
	v_mfma_f32_16x16x32_bf16 v[66:69], v[172:175], v[218:221], v[66:69]
	s_setprio 2
	s_add_i32 s60, s48, s41
	v_lshl_add_u64 v[192:193], s[36:37], 0, v[132:133]
	s_mov_b32 m0, s60
	ds_read_b128 v[176:179], v142 offset:16384
	ds_read_b128 v[180:183], v142 offset:17408
	ds_read_b128 v[184:187], v142 offset:18432
	ds_read_b128 v[188:191], v142 offset:19456
	ds_read_b128 v[198:201], v142 offset:20480
	ds_read_b128 v[210:213], v142 offset:21504
	ds_read_b128 v[214:217], v142 offset:22528
	ds_read_b128 v[218:221], v142 offset:23552
	global_load_lds_dwordx4 v132, s[36:37]
	s_add_i32 m0, s60, 0x2000
	s_add_u32 s60, s36, 0x20000
	v_lshl_add_u64 v[202:203], s[36:37], 0, v[134:135]
	s_addc_u32 s61, s37, 0
	s_add_i32 s62, s49, s41
	global_load_lds_dwordx4 v134, s[36:37]
	s_mov_b32 m0, s62
	v_lshl_add_u64 v[222:223], s[38:39], 0, v[136:137]
	global_load_lds_dwordx4 v132, s[60:61]
	s_add_i32 m0, s62, 0x2000
	s_nop 0
	global_load_lds_dwordx4 v134, s[60:61]
	v_lshl_add_u64 v[206:207], s[38:39], 0, v[130:131]
	s_mov_b32 m0, s27
	s_nop 0
	global_load_lds_dwordx4 v130, s[38:39]
	s_mov_b32 m0, s42
	s_nop 0
	global_load_lds_dwordx4 v136, s[38:39]
	s_waitcnt vmcnt(8)
	s_waitcnt lgkmcnt(0)
	s_barrier
	s_setprio 1
	s_waitcnt lgkmcnt(0)
	v_mfma_f32_16x16x32_bf16 v[62:65], v[144:147], v[176:179], 0
	v_mfma_f32_16x16x32_bf16 v[58:61], v[152:155], v[176:179], 0
	v_mfma_f32_16x16x32_bf16 v[54:57], v[144:147], v[184:187], 0
	v_mfma_f32_16x16x32_bf16 v[50:53], v[152:155], v[184:187], 0
	v_mfma_f32_16x16x32_bf16 v[38:41], v[144:147], v[198:201], 0
	v_mfma_f32_16x16x32_bf16 v[34:37], v[152:155], v[198:201], 0
	v_mfma_f32_16x16x32_bf16 v[22:25], v[144:147], v[214:217], 0
	v_mfma_f32_16x16x32_bf16 v[18:21], v[152:155], v[214:217], 0
	v_mfma_f32_16x16x32_bf16 v[62:65], v[148:151], v[180:183], v[62:65]
	v_mfma_f32_16x16x32_bf16 v[58:61], v[156:159], v[180:183], v[58:61]
	v_mfma_f32_16x16x32_bf16 v[54:57], v[148:151], v[188:191], v[54:57]
	v_mfma_f32_16x16x32_bf16 v[50:53], v[156:159], v[188:191], v[50:53]
	v_mfma_f32_16x16x32_bf16 v[38:41], v[148:151], v[210:213], v[38:41]
	v_mfma_f32_16x16x32_bf16 v[34:37], v[156:159], v[210:213], v[34:37]
	v_mfma_f32_16x16x32_bf16 v[22:25], v[148:151], v[218:221], v[22:25]
	v_mfma_f32_16x16x32_bf16 v[18:21], v[156:159], v[218:221], v[18:21]
	v_mfma_f32_16x16x32_bf16 v[46:49], v[160:163], v[176:179], 0
	v_mfma_f32_16x16x32_bf16 v[42:45], v[168:171], v[176:179], 0
	v_mfma_f32_16x16x32_bf16 v[30:33], v[160:163], v[184:187], 0
	v_mfma_f32_16x16x32_bf16 v[26:29], v[168:171], v[184:187], 0
	v_mfma_f32_16x16x32_bf16 v[14:17], v[160:163], v[198:201], 0
	v_mfma_f32_16x16x32_bf16 v[10:13], v[168:171], v[198:201], 0
	v_mfma_f32_16x16x32_bf16 v[6:9], v[160:163], v[214:217], 0
	v_mfma_f32_16x16x32_bf16 v[2:5], v[168:171], v[214:217], 0
	v_mfma_f32_16x16x32_bf16 v[46:49], v[164:167], v[180:183], v[46:49]
	v_mfma_f32_16x16x32_bf16 v[42:45], v[172:175], v[180:183], v[42:45]
	v_mfma_f32_16x16x32_bf16 v[30:33], v[164:167], v[188:191], v[30:33]
	v_mfma_f32_16x16x32_bf16 v[26:29], v[172:175], v[188:191], v[26:29]
	v_mfma_f32_16x16x32_bf16 v[14:17], v[164:167], v[210:213], v[14:17]
	v_mfma_f32_16x16x32_bf16 v[10:13], v[172:175], v[210:213], v[10:13]
	v_mfma_f32_16x16x32_bf16 v[6:9], v[164:167], v[218:221], v[6:9]
	s_barrier
	v_mfma_f32_16x16x32_bf16 v[2:5], v[172:175], v[218:221], v[2:5]
	s_setprio 2
	s_add_i32 s60, 0, 0x18000
	s_add_i32 s61, 0, 0x1c000
	ds_read_b128 v[144:147], v250
	ds_read_b128 v[148:151], v250 offset:1024
	ds_read_b128 v[152:155], v250 offset:2048
	ds_read_b128 v[156:159], v250 offset:3072
	ds_read_b128 v[160:163], v250 offset:16384
	ds_read_b128 v[164:167], v250 offset:17408
	ds_read_b128 v[168:171], v250 offset:18432
	ds_read_b128 v[172:175], v250 offset:19456
	v_add_u32_e32 v143, s61, v139
	s_add_u32 s38, s38, 0x20000
	s_addc_u32 s39, s39, 0
	s_mov_b32 m0, s43
	ds_read_b128 v[176:179], v142 offset:32768
	ds_read_b128 v[180:183], v142 offset:33792
	ds_read_b128 v[184:187], v142 offset:34816
	ds_read_b128 v[188:191], v142 offset:35840
	ds_read_b128 v[198:201], v142 offset:36864
	ds_read_b128 v[210:213], v142 offset:37888
	ds_read_b128 v[214:217], v142 offset:38912
	ds_read_b128 v[218:221], v142 offset:39936
	global_load_lds_dwordx4 v130, s[38:39]
	v_lshl_add_u64 v[224:225], s[38:39], 0, v[136:137]
	s_mov_b32 m0, s44
	s_nop 0
	global_load_lds_dwordx4 v136, s[38:39]
	s_waitcnt vmcnt(8)
	s_waitcnt lgkmcnt(0)
	s_barrier
	s_setprio 1
	s_waitcnt lgkmcnt(0)
	v_mfma_f32_16x16x32_bf16 v[126:129], v[144:147], v[176:179], v[126:129]
	v_mfma_f32_16x16x32_bf16 v[122:125], v[152:155], v[176:179], v[122:125]
	v_mfma_f32_16x16x32_bf16 v[118:121], v[144:147], v[184:187], v[118:121]
	v_mfma_f32_16x16x32_bf16 v[114:117], v[152:155], v[184:187], v[114:117]
	v_mfma_f32_16x16x32_bf16 v[102:105], v[144:147], v[198:201], v[102:105]
	v_mfma_f32_16x16x32_bf16 v[98:101], v[152:155], v[198:201], v[98:101]
	v_mfma_f32_16x16x32_bf16 v[86:89], v[144:147], v[214:217], v[86:89]
	v_mfma_f32_16x16x32_bf16 v[82:85], v[152:155], v[214:217], v[82:85]
	v_mfma_f32_16x16x32_bf16 v[126:129], v[148:151], v[180:183], v[126:129]
	v_mfma_f32_16x16x32_bf16 v[122:125], v[156:159], v[180:183], v[122:125]
	v_mfma_f32_16x16x32_bf16 v[118:121], v[148:151], v[188:191], v[118:121]
	v_mfma_f32_16x16x32_bf16 v[114:117], v[156:159], v[188:191], v[114:117]
	v_mfma_f32_16x16x32_bf16 v[102:105], v[148:151], v[210:213], v[102:105]
	v_mfma_f32_16x16x32_bf16 v[98:101], v[156:159], v[210:213], v[98:101]
	v_mfma_f32_16x16x32_bf16 v[86:89], v[148:151], v[218:221], v[86:89]
	v_mfma_f32_16x16x32_bf16 v[82:85], v[156:159], v[218:221], v[82:85]
	v_mfma_f32_16x16x32_bf16 v[110:113], v[160:163], v[176:179], v[110:113]
	v_mfma_f32_16x16x32_bf16 v[106:109], v[168:171], v[176:179], v[106:109]
	v_mfma_f32_16x16x32_bf16 v[94:97], v[160:163], v[184:187], v[94:97]
	v_mfma_f32_16x16x32_bf16 v[90:93], v[168:171], v[184:187], v[90:93]
	v_mfma_f32_16x16x32_bf16 v[78:81], v[160:163], v[198:201], v[78:81]
	v_mfma_f32_16x16x32_bf16 v[74:77], v[168:171], v[198:201], v[74:77]
	v_mfma_f32_16x16x32_bf16 v[70:73], v[160:163], v[214:217], v[70:73]
	v_mfma_f32_16x16x32_bf16 v[66:69], v[168:171], v[214:217], v[66:69]
	v_mfma_f32_16x16x32_bf16 v[110:113], v[164:167], v[180:183], v[110:113]
	v_mfma_f32_16x16x32_bf16 v[106:109], v[172:175], v[180:183], v[106:109]
	v_mfma_f32_16x16x32_bf16 v[94:97], v[164:167], v[188:191], v[94:97]
	v_mfma_f32_16x16x32_bf16 v[90:93], v[172:175], v[188:191], v[90:93]
	v_mfma_f32_16x16x32_bf16 v[78:81], v[164:167], v[210:213], v[78:81]
	v_mfma_f32_16x16x32_bf16 v[74:77], v[172:175], v[210:213], v[74:77]
	v_mfma_f32_16x16x32_bf16 v[70:73], v[164:167], v[218:221], v[70:73]
	s_barrier
	v_mfma_f32_16x16x32_bf16 v[66:69], v[172:175], v[218:221], v[66:69]
	s_setprio 2
	s_add_i32 s38, s60, s41
	v_lshl_add_u64 v[192:193], v[192:193], 0, s[6:7]
	s_mov_b32 m0, s38
	ds_read_b128 v[176:179], v142 offset:49152
	ds_read_b128 v[180:183], v142 offset:50176
	ds_read_b128 v[184:187], v142 offset:51200
	ds_read_b128 v[188:191], v142 offset:52224
	ds_read_b128 v[198:201], v142 offset:53248
	ds_read_b128 v[210:213], v142 offset:54272
	ds_read_b128 v[214:217], v142 offset:55296
	ds_read_b128 v[218:221], v142 offset:56320
	global_load_lds_dwordx4 v[192:193], off
	s_add_i32 m0, s38, 0x2000
	s_add_u32 s36, s36, 0x20080
	v_lshl_add_u64 v[192:193], v[202:203], 0, s[6:7]
	s_addc_u32 s37, s37, 0
	s_add_i32 s38, s61, s41
	global_load_lds_dwordx4 v[192:193], off
	s_mov_b32 m0, s38
	s_nop 0
	global_load_lds_dwordx4 v132, s[36:37]
	s_add_i32 m0, s38, 0x2000
	s_nop 0
	global_load_lds_dwordx4 v134, s[36:37]
	v_lshl_add_u64 v[192:193], v[206:207], 0, s[6:7]
	s_mov_b32 m0, s46
	s_nop 0
	global_load_lds_dwordx4 v[192:193], off
	v_lshl_add_u64 v[192:193], v[222:223], 0, s[6:7]
	s_mov_b32 m0, s47
	s_nop 0
	global_load_lds_dwordx4 v[192:193], off
	s_waitcnt vmcnt(8)
	s_waitcnt lgkmcnt(0)
	s_barrier
	s_setprio 1
	s_waitcnt lgkmcnt(0)
	v_mfma_f32_16x16x32_bf16 v[62:65], v[144:147], v[176:179], v[62:65]
	v_mfma_f32_16x16x32_bf16 v[58:61], v[152:155], v[176:179], v[58:61]
	v_mfma_f32_16x16x32_bf16 v[54:57], v[144:147], v[184:187], v[54:57]
	v_mfma_f32_16x16x32_bf16 v[50:53], v[152:155], v[184:187], v[50:53]
	v_mfma_f32_16x16x32_bf16 v[38:41], v[144:147], v[198:201], v[38:41]
	v_mfma_f32_16x16x32_bf16 v[34:37], v[152:155], v[198:201], v[34:37]
	v_mfma_f32_16x16x32_bf16 v[22:25], v[144:147], v[214:217], v[22:25]
	v_mfma_f32_16x16x32_bf16 v[18:21], v[152:155], v[214:217], v[18:21]
	v_mfma_f32_16x16x32_bf16 v[62:65], v[148:151], v[180:183], v[62:65]
	v_mfma_f32_16x16x32_bf16 v[58:61], v[156:159], v[180:183], v[58:61]
	v_mfma_f32_16x16x32_bf16 v[54:57], v[148:151], v[188:191], v[54:57]
	v_mfma_f32_16x16x32_bf16 v[50:53], v[156:159], v[188:191], v[50:53]
	v_mfma_f32_16x16x32_bf16 v[38:41], v[148:151], v[210:213], v[38:41]
	v_mfma_f32_16x16x32_bf16 v[34:37], v[156:159], v[210:213], v[34:37]
	v_mfma_f32_16x16x32_bf16 v[22:25], v[148:151], v[218:221], v[22:25]
	v_mfma_f32_16x16x32_bf16 v[18:21], v[156:159], v[218:221], v[18:21]
	v_mfma_f32_16x16x32_bf16 v[46:49], v[160:163], v[176:179], v[46:49]
	v_mfma_f32_16x16x32_bf16 v[42:45], v[168:171], v[176:179], v[42:45]
	v_mfma_f32_16x16x32_bf16 v[30:33], v[160:163], v[184:187], v[30:33]
	v_mfma_f32_16x16x32_bf16 v[26:29], v[168:171], v[184:187], v[26:29]
	v_mfma_f32_16x16x32_bf16 v[14:17], v[160:163], v[198:201], v[14:17]
	v_mfma_f32_16x16x32_bf16 v[10:13], v[168:171], v[198:201], v[10:13]
	v_mfma_f32_16x16x32_bf16 v[6:9], v[160:163], v[214:217], v[6:9]
	v_mfma_f32_16x16x32_bf16 v[2:5], v[168:171], v[214:217], v[2:5]
	v_mfma_f32_16x16x32_bf16 v[46:49], v[164:167], v[180:183], v[46:49]
	v_mfma_f32_16x16x32_bf16 v[42:45], v[172:175], v[180:183], v[42:45]
	v_mfma_f32_16x16x32_bf16 v[30:33], v[164:167], v[188:191], v[30:33]
	v_mfma_f32_16x16x32_bf16 v[26:29], v[172:175], v[188:191], v[26:29]
	v_mfma_f32_16x16x32_bf16 v[14:17], v[164:167], v[210:213], v[14:17]
	v_mfma_f32_16x16x32_bf16 v[10:13], v[172:175], v[210:213], v[10:13]
	v_mfma_f32_16x16x32_bf16 v[6:9], v[164:167], v[218:221], v[6:9]
	s_barrier
	v_mfma_f32_16x16x32_bf16 v[2:5], v[172:175], v[218:221], v[2:5]
	s_setprio 2
	s_add_i32 s59, s59, 2
	s_add_u32 s34, s34, 0x100
	s_addc_u32 s35, s35, 0
	s_add_u32 s57, s57, 0x100
	s_addc_u32 s58, s58, 0
	s_cmp_gt_u32 s59, 5
	s_cbranch_scc0 .LBB0_714
	s_branch .Lpeeldone_9
.LBB0_714:
	ds_read_b128 v[144:147], v140
	ds_read_b128 v[148:151], v140 offset:1024
	ds_read_b128 v[152:155], v140 offset:2048
	ds_read_b128 v[156:159], v140 offset:3072
	ds_read_b128 v[160:163], v141
	ds_read_b128 v[164:167], v141 offset:1024
	ds_read_b128 v[168:171], v141 offset:2048
	ds_read_b128 v[172:175], v141 offset:3072
	s_add_u32 s36, s34, 0xfffe0080
	s_addc_u32 s37, s35, -1
	s_cmp_eq_u32 s59, 4
	s_cselect_b32 s39, s21, s37
	s_cselect_b32 s38, s55, s36
	s_cselect_b32 s37, s25, s58
	s_cselect_b32 s36, s56, s57
	s_add_i32 m0, s27, 0xc000
	ds_read_b128 v[176:179], v142
	ds_read_b128 v[180:183], v142 offset:1024
	ds_read_b128 v[184:187], v142 offset:2048
	ds_read_b128 v[188:191], v142 offset:3072
	ds_read_b128 v[198:201], v142 offset:4096
	ds_read_b128 v[210:213], v142 offset:5120
	ds_read_b128 v[214:217], v142 offset:6144
	ds_read_b128 v[218:221], v142 offset:7168
	global_load_lds_dwordx4 v130, s[34:35]
	s_add_i32 m0, s27, 0xe000
	s_nop 0
	global_load_lds_dwordx4 v136, s[34:35]
	s_waitcnt vmcnt(8)
	s_waitcnt lgkmcnt(0)
	s_barrier
	s_setprio 1
	s_waitcnt lgkmcnt(0)
	v_mfma_f32_16x16x32_bf16 v[126:129], v[144:147], v[176:179], v[126:129]
	v_mfma_f32_16x16x32_bf16 v[122:125], v[152:155], v[176:179], v[122:125]
	v_mfma_f32_16x16x32_bf16 v[118:121], v[144:147], v[184:187], v[118:121]
	v_mfma_f32_16x16x32_bf16 v[114:117], v[152:155], v[184:187], v[114:117]
	v_mfma_f32_16x16x32_bf16 v[102:105], v[144:147], v[198:201], v[102:105]
	v_mfma_f32_16x16x32_bf16 v[98:101], v[152:155], v[198:201], v[98:101]
	v_mfma_f32_16x16x32_bf16 v[86:89], v[144:147], v[214:217], v[86:89]
	v_mfma_f32_16x16x32_bf16 v[82:85], v[152:155], v[214:217], v[82:85]
	v_mfma_f32_16x16x32_bf16 v[126:129], v[148:151], v[180:183], v[126:129]
	v_mfma_f32_16x16x32_bf16 v[122:125], v[156:159], v[180:183], v[122:125]
	v_mfma_f32_16x16x32_bf16 v[118:121], v[148:151], v[188:191], v[118:121]
	v_mfma_f32_16x16x32_bf16 v[114:117], v[156:159], v[188:191], v[114:117]
	v_mfma_f32_16x16x32_bf16 v[102:105], v[148:151], v[210:213], v[102:105]
	v_mfma_f32_16x16x32_bf16 v[98:101], v[156:159], v[210:213], v[98:101]
	v_mfma_f32_16x16x32_bf16 v[86:89], v[148:151], v[218:221], v[86:89]
	v_mfma_f32_16x16x32_bf16 v[82:85], v[156:159], v[218:221], v[82:85]
	v_mfma_f32_16x16x32_bf16 v[110:113], v[160:163], v[176:179], v[110:113]
	v_mfma_f32_16x16x32_bf16 v[106:109], v[168:171], v[176:179], v[106:109]
	v_mfma_f32_16x16x32_bf16 v[94:97], v[160:163], v[184:187], v[94:97]
	v_mfma_f32_16x16x32_bf16 v[90:93], v[168:171], v[184:187], v[90:93]
	v_mfma_f32_16x16x32_bf16 v[78:81], v[160:163], v[198:201], v[78:81]
	v_mfma_f32_16x16x32_bf16 v[74:77], v[168:171], v[198:201], v[74:77]
	v_mfma_f32_16x16x32_bf16 v[70:73], v[160:163], v[214:217], v[70:73]
	v_mfma_f32_16x16x32_bf16 v[66:69], v[168:171], v[214:217], v[66:69]
	v_mfma_f32_16x16x32_bf16 v[110:113], v[164:167], v[180:183], v[110:113]
	v_mfma_f32_16x16x32_bf16 v[106:109], v[172:175], v[180:183], v[106:109]
	v_mfma_f32_16x16x32_bf16 v[94:97], v[164:167], v[188:191], v[94:97]
	v_mfma_f32_16x16x32_bf16 v[90:93], v[172:175], v[188:191], v[90:93]
	v_mfma_f32_16x16x32_bf16 v[78:81], v[164:167], v[210:213], v[78:81]
	v_mfma_f32_16x16x32_bf16 v[74:77], v[172:175], v[210:213], v[74:77]
	v_mfma_f32_16x16x32_bf16 v[70:73], v[164:167], v[218:221], v[70:73]
	s_barrier
	v_mfma_f32_16x16x32_bf16 v[66:69], v[172:175], v[218:221], v[66:69]
	s_setprio 2
	s_add_i32 s60, s48, s41
	v_lshl_add_u64 v[192:193], s[36:37], 0, v[132:133]
	s_mov_b32 m0, s60
	ds_read_b128 v[176:179], v142 offset:16384
	ds_read_b128 v[180:183], v142 offset:17408
	ds_read_b128 v[184:187], v142 offset:18432
	ds_read_b128 v[188:191], v142 offset:19456
	ds_read_b128 v[198:201], v142 offset:20480
	ds_read_b128 v[210:213], v142 offset:21504
	ds_read_b128 v[214:217], v142 offset:22528
	ds_read_b128 v[218:221], v142 offset:23552
	global_load_lds_dwordx4 v132, s[36:37]
	s_add_i32 m0, s60, 0x2000
	s_add_u32 s60, s36, 0x20000
	v_lshl_add_u64 v[202:203], s[36:37], 0, v[134:135]
	s_addc_u32 s61, s37, 0
	s_add_i32 s62, s49, s41
	global_load_lds_dwordx4 v134, s[36:37]
	s_mov_b32 m0, s62
	v_lshl_add_u64 v[222:223], s[38:39], 0, v[136:137]
	global_load_lds_dwordx4 v132, s[60:61]
	s_add_i32 m0, s62, 0x2000
	s_nop 0
	global_load_lds_dwordx4 v134, s[60:61]
	v_lshl_add_u64 v[206:207], s[38:39], 0, v[130:131]
	s_mov_b32 m0, s27
	s_nop 0
	global_load_lds_dwordx4 v130, s[38:39]
	s_mov_b32 m0, s42
	s_nop 0
	global_load_lds_dwordx4 v136, s[38:39]
	s_waitcnt vmcnt(8)
	s_waitcnt lgkmcnt(0)
	s_barrier
	s_setprio 1
	s_waitcnt lgkmcnt(0)
	v_mfma_f32_16x16x32_bf16 v[62:65], v[144:147], v[176:179], v[62:65]
	v_mfma_f32_16x16x32_bf16 v[58:61], v[152:155], v[176:179], v[58:61]
	v_mfma_f32_16x16x32_bf16 v[54:57], v[144:147], v[184:187], v[54:57]
	v_mfma_f32_16x16x32_bf16 v[50:53], v[152:155], v[184:187], v[50:53]
	v_mfma_f32_16x16x32_bf16 v[38:41], v[144:147], v[198:201], v[38:41]
	v_mfma_f32_16x16x32_bf16 v[34:37], v[152:155], v[198:201], v[34:37]
	v_mfma_f32_16x16x32_bf16 v[22:25], v[144:147], v[214:217], v[22:25]
	v_mfma_f32_16x16x32_bf16 v[18:21], v[152:155], v[214:217], v[18:21]
	v_mfma_f32_16x16x32_bf16 v[62:65], v[148:151], v[180:183], v[62:65]
	v_mfma_f32_16x16x32_bf16 v[58:61], v[156:159], v[180:183], v[58:61]
	v_mfma_f32_16x16x32_bf16 v[54:57], v[148:151], v[188:191], v[54:57]
	v_mfma_f32_16x16x32_bf16 v[50:53], v[156:159], v[188:191], v[50:53]
	v_mfma_f32_16x16x32_bf16 v[38:41], v[148:151], v[210:213], v[38:41]
	v_mfma_f32_16x16x32_bf16 v[34:37], v[156:159], v[210:213], v[34:37]
	v_mfma_f32_16x16x32_bf16 v[22:25], v[148:151], v[218:221], v[22:25]
	v_mfma_f32_16x16x32_bf16 v[18:21], v[156:159], v[218:221], v[18:21]
	v_mfma_f32_16x16x32_bf16 v[46:49], v[160:163], v[176:179], v[46:49]
	v_mfma_f32_16x16x32_bf16 v[42:45], v[168:171], v[176:179], v[42:45]
	v_mfma_f32_16x16x32_bf16 v[30:33], v[160:163], v[184:187], v[30:33]
	v_mfma_f32_16x16x32_bf16 v[26:29], v[168:171], v[184:187], v[26:29]
	v_mfma_f32_16x16x32_bf16 v[14:17], v[160:163], v[198:201], v[14:17]
	v_mfma_f32_16x16x32_bf16 v[10:13], v[168:171], v[198:201], v[10:13]
	v_mfma_f32_16x16x32_bf16 v[6:9], v[160:163], v[214:217], v[6:9]
	v_mfma_f32_16x16x32_bf16 v[2:5], v[168:171], v[214:217], v[2:5]
	v_mfma_f32_16x16x32_bf16 v[46:49], v[164:167], v[180:183], v[46:49]
	v_mfma_f32_16x16x32_bf16 v[42:45], v[172:175], v[180:183], v[42:45]
	v_mfma_f32_16x16x32_bf16 v[30:33], v[164:167], v[188:191], v[30:33]
	v_mfma_f32_16x16x32_bf16 v[26:29], v[172:175], v[188:191], v[26:29]
	v_mfma_f32_16x16x32_bf16 v[14:17], v[164:167], v[210:213], v[14:17]
	v_mfma_f32_16x16x32_bf16 v[10:13], v[172:175], v[210:213], v[10:13]
	v_mfma_f32_16x16x32_bf16 v[6:9], v[164:167], v[218:221], v[6:9]
	s_barrier
	v_mfma_f32_16x16x32_bf16 v[2:5], v[172:175], v[218:221], v[2:5]
	s_setprio 2
	s_add_i32 s60, 0, 0x18000
	s_add_i32 s61, 0, 0x1c000
	ds_read_b128 v[144:147], v250
	ds_read_b128 v[148:151], v250 offset:1024
	ds_read_b128 v[152:155], v250 offset:2048
	ds_read_b128 v[156:159], v250 offset:3072
	ds_read_b128 v[160:163], v250 offset:16384
	ds_read_b128 v[164:167], v250 offset:17408
	ds_read_b128 v[168:171], v250 offset:18432
	ds_read_b128 v[172:175], v250 offset:19456
	v_add_u32_e32 v143, s61, v139
	s_add_u32 s38, s38, 0x20000
	s_addc_u32 s39, s39, 0
	s_mov_b32 m0, s43
	ds_read_b128 v[176:179], v142 offset:32768
	ds_read_b128 v[180:183], v142 offset:33792
	ds_read_b128 v[184:187], v142 offset:34816
	ds_read_b128 v[188:191], v142 offset:35840
	ds_read_b128 v[198:201], v142 offset:36864
	ds_read_b128 v[210:213], v142 offset:37888
	ds_read_b128 v[214:217], v142 offset:38912
	ds_read_b128 v[218:221], v142 offset:39936
	global_load_lds_dwordx4 v130, s[38:39]
	v_lshl_add_u64 v[224:225], s[38:39], 0, v[136:137]
	s_mov_b32 m0, s44
	s_nop 0
	global_load_lds_dwordx4 v136, s[38:39]
	s_waitcnt vmcnt(8)
	s_waitcnt lgkmcnt(0)
	s_barrier
	s_setprio 1
	s_waitcnt lgkmcnt(0)
	v_mfma_f32_16x16x32_bf16 v[126:129], v[144:147], v[176:179], v[126:129]
	v_mfma_f32_16x16x32_bf16 v[122:125], v[152:155], v[176:179], v[122:125]
	v_mfma_f32_16x16x32_bf16 v[118:121], v[144:147], v[184:187], v[118:121]
	v_mfma_f32_16x16x32_bf16 v[114:117], v[152:155], v[184:187], v[114:117]
	v_mfma_f32_16x16x32_bf16 v[102:105], v[144:147], v[198:201], v[102:105]
	v_mfma_f32_16x16x32_bf16 v[98:101], v[152:155], v[198:201], v[98:101]
	v_mfma_f32_16x16x32_bf16 v[86:89], v[144:147], v[214:217], v[86:89]
	v_mfma_f32_16x16x32_bf16 v[82:85], v[152:155], v[214:217], v[82:85]
	v_mfma_f32_16x16x32_bf16 v[126:129], v[148:151], v[180:183], v[126:129]
	v_mfma_f32_16x16x32_bf16 v[122:125], v[156:159], v[180:183], v[122:125]
	v_mfma_f32_16x16x32_bf16 v[118:121], v[148:151], v[188:191], v[118:121]
	v_mfma_f32_16x16x32_bf16 v[114:117], v[156:159], v[188:191], v[114:117]
	v_mfma_f32_16x16x32_bf16 v[102:105], v[148:151], v[210:213], v[102:105]
	v_mfma_f32_16x16x32_bf16 v[98:101], v[156:159], v[210:213], v[98:101]
	v_mfma_f32_16x16x32_bf16 v[86:89], v[148:151], v[218:221], v[86:89]
	v_mfma_f32_16x16x32_bf16 v[82:85], v[156:159], v[218:221], v[82:85]
	v_mfma_f32_16x16x32_bf16 v[110:113], v[160:163], v[176:179], v[110:113]
	v_mfma_f32_16x16x32_bf16 v[106:109], v[168:171], v[176:179], v[106:109]
	v_mfma_f32_16x16x32_bf16 v[94:97], v[160:163], v[184:187], v[94:97]
	v_mfma_f32_16x16x32_bf16 v[90:93], v[168:171], v[184:187], v[90:93]
	v_mfma_f32_16x16x32_bf16 v[78:81], v[160:163], v[198:201], v[78:81]
	v_mfma_f32_16x16x32_bf16 v[74:77], v[168:171], v[198:201], v[74:77]
	v_mfma_f32_16x16x32_bf16 v[70:73], v[160:163], v[214:217], v[70:73]
	v_mfma_f32_16x16x32_bf16 v[66:69], v[168:171], v[214:217], v[66:69]
	v_mfma_f32_16x16x32_bf16 v[110:113], v[164:167], v[180:183], v[110:113]
	v_mfma_f32_16x16x32_bf16 v[106:109], v[172:175], v[180:183], v[106:109]
	v_mfma_f32_16x16x32_bf16 v[94:97], v[164:167], v[188:191], v[94:97]
	v_mfma_f32_16x16x32_bf16 v[90:93], v[172:175], v[188:191], v[90:93]
	v_mfma_f32_16x16x32_bf16 v[78:81], v[164:167], v[210:213], v[78:81]
	v_mfma_f32_16x16x32_bf16 v[74:77], v[172:175], v[210:213], v[74:77]
	v_mfma_f32_16x16x32_bf16 v[70:73], v[164:167], v[218:221], v[70:73]
	s_barrier
	v_mfma_f32_16x16x32_bf16 v[66:69], v[172:175], v[218:221], v[66:69]
	s_setprio 2
	s_add_i32 s38, s60, s41
	v_lshl_add_u64 v[192:193], v[192:193], 0, s[6:7]
	s_mov_b32 m0, s38
	ds_read_b128 v[176:179], v142 offset:49152
	ds_read_b128 v[180:183], v142 offset:50176
	ds_read_b128 v[184:187], v142 offset:51200
	ds_read_b128 v[188:191], v142 offset:52224
	ds_read_b128 v[198:201], v142 offset:53248
	ds_read_b128 v[210:213], v142 offset:54272
	ds_read_b128 v[214:217], v142 offset:55296
	ds_read_b128 v[218:221], v142 offset:56320
	global_load_lds_dwordx4 v[192:193], off
	s_add_i32 m0, s38, 0x2000
	s_add_u32 s36, s36, 0x20080
	v_lshl_add_u64 v[192:193], v[202:203], 0, s[6:7]
	s_addc_u32 s37, s37, 0
	s_add_i32 s38, s61, s41
	global_load_lds_dwordx4 v[192:193], off
	s_mov_b32 m0, s38
	s_nop 0
	global_load_lds_dwordx4 v132, s[36:37]
	s_add_i32 m0, s38, 0x2000
	s_nop 0
	global_load_lds_dwordx4 v134, s[36:37]
	v_lshl_add_u64 v[192:193], v[206:207], 0, s[6:7]
	s_mov_b32 m0, s46
	s_nop 0
	global_load_lds_dwordx4 v[192:193], off
	v_lshl_add_u64 v[192:193], v[222:223], 0, s[6:7]
	s_mov_b32 m0, s47
	s_nop 0
	global_load_lds_dwordx4 v[192:193], off
	s_waitcnt vmcnt(8)
	s_waitcnt lgkmcnt(0)
	s_barrier
	s_setprio 1
	s_waitcnt lgkmcnt(0)
	v_mfma_f32_16x16x32_bf16 v[62:65], v[144:147], v[176:179], v[62:65]
	v_mfma_f32_16x16x32_bf16 v[58:61], v[152:155], v[176:179], v[58:61]
	v_mfma_f32_16x16x32_bf16 v[54:57], v[144:147], v[184:187], v[54:57]
	v_mfma_f32_16x16x32_bf16 v[50:53], v[152:155], v[184:187], v[50:53]
	v_mfma_f32_16x16x32_bf16 v[38:41], v[144:147], v[198:201], v[38:41]
	v_mfma_f32_16x16x32_bf16 v[34:37], v[152:155], v[198:201], v[34:37]
	v_mfma_f32_16x16x32_bf16 v[22:25], v[144:147], v[214:217], v[22:25]
	v_mfma_f32_16x16x32_bf16 v[18:21], v[152:155], v[214:217], v[18:21]
	v_mfma_f32_16x16x32_bf16 v[62:65], v[148:151], v[180:183], v[62:65]
	v_mfma_f32_16x16x32_bf16 v[58:61], v[156:159], v[180:183], v[58:61]
	v_mfma_f32_16x16x32_bf16 v[54:57], v[148:151], v[188:191], v[54:57]
	v_mfma_f32_16x16x32_bf16 v[50:53], v[156:159], v[188:191], v[50:53]
	v_mfma_f32_16x16x32_bf16 v[38:41], v[148:151], v[210:213], v[38:41]
	v_mfma_f32_16x16x32_bf16 v[34:37], v[156:159], v[210:213], v[34:37]
	v_mfma_f32_16x16x32_bf16 v[22:25], v[148:151], v[218:221], v[22:25]
	v_mfma_f32_16x16x32_bf16 v[18:21], v[156:159], v[218:221], v[18:21]
	v_mfma_f32_16x16x32_bf16 v[46:49], v[160:163], v[176:179], v[46:49]
	v_mfma_f32_16x16x32_bf16 v[42:45], v[168:171], v[176:179], v[42:45]
	v_mfma_f32_16x16x32_bf16 v[30:33], v[160:163], v[184:187], v[30:33]
	v_mfma_f32_16x16x32_bf16 v[26:29], v[168:171], v[184:187], v[26:29]
	v_mfma_f32_16x16x32_bf16 v[14:17], v[160:163], v[198:201], v[14:17]
	v_mfma_f32_16x16x32_bf16 v[10:13], v[168:171], v[198:201], v[10:13]
	v_mfma_f32_16x16x32_bf16 v[6:9], v[160:163], v[214:217], v[6:9]
	v_mfma_f32_16x16x32_bf16 v[2:5], v[168:171], v[214:217], v[2:5]
	v_mfma_f32_16x16x32_bf16 v[46:49], v[164:167], v[180:183], v[46:49]
	v_mfma_f32_16x16x32_bf16 v[42:45], v[172:175], v[180:183], v[42:45]
	v_mfma_f32_16x16x32_bf16 v[30:33], v[164:167], v[188:191], v[30:33]
	v_mfma_f32_16x16x32_bf16 v[26:29], v[172:175], v[188:191], v[26:29]
	v_mfma_f32_16x16x32_bf16 v[14:17], v[164:167], v[210:213], v[14:17]
	v_mfma_f32_16x16x32_bf16 v[10:13], v[172:175], v[210:213], v[10:13]
	v_mfma_f32_16x16x32_bf16 v[6:9], v[164:167], v[218:221], v[6:9]
	s_barrier
	v_mfma_f32_16x16x32_bf16 v[2:5], v[172:175], v[218:221], v[2:5]
	s_setprio 2
	s_add_i32 s59, s59, 2
	s_add_u32 s34, s34, 0x100
	s_addc_u32 s35, s35, 0
	s_add_u32 s57, s57, 0x100
	s_addc_u32 s58, s58, 0
	s_cmp_gt_u32 s59, 5
	s_cbranch_scc0 .LBB0_714

.Lpeel_8:
	v_add_u32_e32 v250, 0x18000, v168
	ds_read_b128 v[130:133], v170
	ds_read_b128 v[134:137], v170 offset:1024
	ds_read_b128 v[138:141], v170 offset:2048
	ds_read_b128 v[142:145], v170 offset:3072
	ds_read_b128 v[160:163], v171
	ds_read_b128 v[164:167], v171 offset:1024
	ds_read_b128 v[174:177], v171 offset:2048
	ds_read_b128 v[178:181], v171 offset:3072
	s_add_i32 s31, s21, 2
	s_add_u32 s36, s34, 0xfff80080
	s_addc_u32 s37, s35, -1
	s_cmp_eq_u32 s30, s21
	s_cselect_b32 s39, s23, s37
	s_cselect_b32 s38, s22, s36
	s_cselect_b32 s37, s25, s19
	s_cselect_b32 s36, s24, s17
	s_add_i32 m0, s27, 0xc000
	ds_read_b128 v[182:185], v172
	ds_read_b128 v[186:189], v172 offset:1024
	ds_read_b128 v[190:193], v172 offset:2048
	ds_read_b128 v[198:201], v172 offset:3072
	ds_read_b128 v[210:213], v172 offset:4096
	ds_read_b128 v[214:217], v172 offset:5120
	global_load_lds_dwordx4 v156, s[34:35]
	s_add_i32 m0, s27, 0xe000
	s_nop 0
	global_load_lds_dwordx4 v158, s[34:35]
	s_waitcnt vmcnt(8)
	s_waitcnt lgkmcnt(0)
	s_barrier
	s_setprio 1
	s_waitcnt lgkmcnt(0)
	v_mfma_f32_16x16x32_bf16 v[126:129], v[130:133], v[182:185], 0
	v_mfma_f32_16x16x32_bf16 v[122:125], v[138:141], v[182:185], 0
	v_mfma_f32_16x16x32_bf16 v[118:121], v[130:133], v[190:193], 0
	v_mfma_f32_16x16x32_bf16 v[110:113], v[138:141], v[190:193], 0
	v_mfma_f32_16x16x32_bf16 v[94:97], v[130:133], v[210:213], 0
	v_mfma_f32_16x16x32_bf16 v[90:93], v[138:141], v[210:213], 0
	v_mfma_f32_16x16x32_bf16 v[78:81], v[130:133], v[218:221], 0
	v_mfma_f32_16x16x32_bf16 v[74:77], v[138:141], v[218:221], 0
	v_mfma_f32_16x16x32_bf16 v[126:129], v[134:137], v[186:189], v[126:129]
	v_mfma_f32_16x16x32_bf16 v[122:125], v[142:145], v[186:189], v[122:125]
	v_mfma_f32_16x16x32_bf16 v[118:121], v[134:137], v[198:201], v[118:121]
	v_mfma_f32_16x16x32_bf16 v[110:113], v[142:145], v[198:201], v[110:113]
	v_mfma_f32_16x16x32_bf16 v[94:97], v[134:137], v[214:217], v[94:97]
	v_mfma_f32_16x16x32_bf16 v[90:93], v[142:145], v[214:217], v[90:93]
	v_mfma_f32_16x16x32_bf16 v[78:81], v[134:137], v[222:225], v[78:81]
	v_mfma_f32_16x16x32_bf16 v[74:77], v[142:145], v[222:225], v[74:77]
	v_mfma_f32_16x16x32_bf16 v[114:117], v[160:163], v[182:185], 0
	v_mfma_f32_16x16x32_bf16 v[106:109], v[174:177], v[182:185], 0
	v_mfma_f32_16x16x32_bf16 v[102:105], v[160:163], v[190:193], 0
	v_mfma_f32_16x16x32_bf16 v[98:101], v[174:177], v[190:193], 0
	v_mfma_f32_16x16x32_bf16 v[86:89], v[160:163], v[210:213], 0
	v_mfma_f32_16x16x32_bf16 v[82:85], v[174:177], v[210:213], 0
	v_mfma_f32_16x16x32_bf16 v[70:73], v[160:163], v[218:221], 0
	v_mfma_f32_16x16x32_bf16 v[66:69], v[174:177], v[218:221], 0
	v_mfma_f32_16x16x32_bf16 v[114:117], v[164:167], v[186:189], v[114:117]
	v_mfma_f32_16x16x32_bf16 v[106:109], v[178:181], v[186:189], v[106:109]
	v_mfma_f32_16x16x32_bf16 v[102:105], v[164:167], v[198:201], v[102:105]
	v_mfma_f32_16x16x32_bf16 v[98:101], v[178:181], v[198:201], v[98:101]
	v_mfma_f32_16x16x32_bf16 v[86:89], v[164:167], v[214:217], v[86:89]
	v_mfma_f32_16x16x32_bf16 v[82:85], v[178:181], v[214:217], v[82:85]
	v_mfma_f32_16x16x32_bf16 v[70:73], v[164:167], v[222:225], v[70:73]
	s_barrier
	v_mfma_f32_16x16x32_bf16 v[66:69], v[178:181], v[222:225], v[66:69]
	s_setprio 2
	s_add_i32 s21, s63, s33
	v_lshl_add_u64 v[202:203], s[36:37], 0, v[148:149]
	s_mov_b32 m0, s21
	ds_read_b128 v[182:185], v172 offset:16384
	ds_read_b128 v[186:189], v172 offset:17408
	ds_read_b128 v[190:193], v172 offset:18432
	ds_read_b128 v[198:201], v172 offset:19456
	ds_read_b128 v[210:213], v172 offset:20480
	ds_read_b128 v[214:217], v172 offset:21504
	ds_read_b128 v[218:221], v172 offset:22528
	ds_read_b128 v[222:225], v172 offset:23552
	global_load_lds_dwordx4 v148, s[36:37]
	s_add_i32 m0, s21, 0x2000
	s_add_u32 s40, s36, 0x80000
	v_lshl_add_u64 v[206:207], s[36:37], 0, v[152:153]
	s_addc_u32 s41, s37, 0
	s_add_i32 s21, s64, s33
	global_load_lds_dwordx4 v152, s[36:37]
	s_mov_b32 m0, s21
	v_lshl_add_u64 v[228:229], s[38:39], 0, v[150:151]
	global_load_lds_dwordx4 v148, s[40:41]
	s_add_i32 m0, s21, 0x2000
	s_nop 0
	global_load_lds_dwordx4 v152, s[40:41]
	v_lshl_add_u64 v[226:227], s[38:39], 0, v[146:147]
	s_mov_b32 m0, s27
	s_nop 0
	global_load_lds_dwordx4 v146, s[38:39]
	s_mov_b32 m0, s29
	s_nop 0
	global_load_lds_dwordx4 v150, s[38:39]
	s_waitcnt vmcnt(8)
	s_waitcnt lgkmcnt(0)
	s_barrier
	s_setprio 1
	s_waitcnt lgkmcnt(0)
	v_mfma_f32_16x16x32_bf16 v[62:65], v[130:133], v[182:185], 0
	v_mfma_f32_16x16x32_bf16 v[58:61], v[138:141], v[182:185], 0
	v_mfma_f32_16x16x32_bf16 v[46:49], v[130:133], v[190:193], 0
	v_mfma_f32_16x16x32_bf16 v[42:45], v[138:141], v[190:193], 0
	v_mfma_f32_16x16x32_bf16 v[30:33], v[130:133], v[210:213], 0
	v_mfma_f32_16x16x32_bf16 v[26:29], v[138:141], v[210:213], 0
	v_mfma_f32_16x16x32_bf16 v[14:17], v[130:133], v[218:221], 0
	v_mfma_f32_16x16x32_bf16 v[10:13], v[138:141], v[218:221], 0
	v_mfma_f32_16x16x32_bf16 v[62:65], v[134:137], v[186:189], v[62:65]
	v_mfma_f32_16x16x32_bf16 v[58:61], v[142:145], v[186:189], v[58:61]
	v_mfma_f32_16x16x32_bf16 v[46:49], v[134:137], v[198:201], v[46:49]
	v_mfma_f32_16x16x32_bf16 v[42:45], v[142:145], v[198:201], v[42:45]
	v_mfma_f32_16x16x32_bf16 v[30:33], v[134:137], v[214:217], v[30:33]
	v_mfma_f32_16x16x32_bf16 v[26:29], v[142:145], v[214:217], v[26:29]
	v_mfma_f32_16x16x32_bf16 v[14:17], v[134:137], v[222:225], v[14:17]
	v_mfma_f32_16x16x32_bf16 v[10:13], v[142:145], v[222:225], v[10:13]
	v_mfma_f32_16x16x32_bf16 v[54:57], v[160:163], v[182:185], 0
	v_mfma_f32_16x16x32_bf16 v[50:53], v[174:177], v[182:185], 0
	v_mfma_f32_16x16x32_bf16 v[38:41], v[160:163], v[190:193], 0
	v_mfma_f32_16x16x32_bf16 v[34:37], v[174:177], v[190:193], 0
	v_mfma_f32_16x16x32_bf16 v[22:25], v[160:163], v[210:213], 0
	v_mfma_f32_16x16x32_bf16 v[18:21], v[174:177], v[210:213], 0
	v_mfma_f32_16x16x32_bf16 v[6:9], v[160:163], v[218:221], 0
	v_mfma_f32_16x16x32_bf16 v[2:5], v[174:177], v[218:221], 0
	v_mfma_f32_16x16x32_bf16 v[54:57], v[164:167], v[186:189], v[54:57]
	v_mfma_f32_16x16x32_bf16 v[50:53], v[178:181], v[186:189], v[50:53]
	v_mfma_f32_16x16x32_bf16 v[38:41], v[164:167], v[198:201], v[38:41]
	v_mfma_f32_16x16x32_bf16 v[34:37], v[178:181], v[198:201], v[34:37]
	v_mfma_f32_16x16x32_bf16 v[22:25], v[164:167], v[214:217], v[22:25]
	v_mfma_f32_16x16x32_bf16 v[18:21], v[178:181], v[214:217], v[18:21]
	v_mfma_f32_16x16x32_bf16 v[6:9], v[164:167], v[222:225], v[6:9]
	s_barrier
	v_mfma_f32_16x16x32_bf16 v[2:5], v[178:181], v[222:225], v[2:5]
	s_setprio 2
	s_add_i32 s21, 0, 0x18000
	s_add_i32 s40, 0, 0x1c000
	ds_read_b128 v[130:133], v250
	ds_read_b128 v[134:137], v250 offset:1024
	ds_read_b128 v[138:141], v250 offset:2048
	ds_read_b128 v[142:145], v250 offset:3072
	ds_read_b128 v[160:163], v250 offset:16384
	ds_read_b128 v[164:167], v250 offset:17408
	ds_read_b128 v[174:177], v250 offset:18432
	ds_read_b128 v[178:181], v250 offset:19456
	v_add_u32_e32 v173, s40, v168
	s_add_u32 s38, s38, 0x80000
	s_addc_u32 s39, s39, 0
	s_mov_b32 m0, s42
	ds_read_b128 v[182:185], v172 offset:32768
	ds_read_b128 v[186:189], v172 offset:33792
	ds_read_b128 v[190:193], v172 offset:34816
	ds_read_b128 v[198:201], v172 offset:35840
	ds_read_b128 v[210:213], v172 offset:36864
	ds_read_b128 v[214:217], v172 offset:37888
	ds_read_b128 v[218:221], v172 offset:38912
	ds_read_b128 v[222:225], v172 offset:39936
	global_load_lds_dwordx4 v146, s[38:39]
	v_lshl_add_u64 v[230:231], s[38:39], 0, v[150:151]
	s_mov_b32 m0, s43
	s_nop 0
	global_load_lds_dwordx4 v150, s[38:39]
	s_waitcnt vmcnt(8)
	s_waitcnt lgkmcnt(0)
	s_barrier
	s_setprio 1
	s_waitcnt lgkmcnt(0)
	v_mfma_f32_16x16x32_bf16 v[126:129], v[130:133], v[182:185], v[126:129]
	v_mfma_f32_16x16x32_bf16 v[122:125], v[138:141], v[182:185], v[122:125]
	v_mfma_f32_16x16x32_bf16 v[118:121], v[130:133], v[190:193], v[118:121]
	v_mfma_f32_16x16x32_bf16 v[110:113], v[138:141], v[190:193], v[110:113]
	v_mfma_f32_16x16x32_bf16 v[94:97], v[130:133], v[210:213], v[94:97]
	v_mfma_f32_16x16x32_bf16 v[90:93], v[138:141], v[210:213], v[90:93]
	v_mfma_f32_16x16x32_bf16 v[78:81], v[130:133], v[218:221], v[78:81]
	v_mfma_f32_16x16x32_bf16 v[74:77], v[138:141], v[218:221], v[74:77]
	v_mfma_f32_16x16x32_bf16 v[126:129], v[134:137], v[186:189], v[126:129]
	v_mfma_f32_16x16x32_bf16 v[122:125], v[142:145], v[186:189], v[122:125]
	v_mfma_f32_16x16x32_bf16 v[118:121], v[134:137], v[198:201], v[118:121]
	v_mfma_f32_16x16x32_bf16 v[110:113], v[142:145], v[198:201], v[110:113]
	v_mfma_f32_16x16x32_bf16 v[94:97], v[134:137], v[214:217], v[94:97]
	v_mfma_f32_16x16x32_bf16 v[90:93], v[142:145], v[214:217], v[90:93]
	v_mfma_f32_16x16x32_bf16 v[78:81], v[134:137], v[222:225], v[78:81]
	v_mfma_f32_16x16x32_bf16 v[74:77], v[142:145], v[222:225], v[74:77]
	v_mfma_f32_16x16x32_bf16 v[114:117], v[160:163], v[182:185], v[114:117]
	v_mfma_f32_16x16x32_bf16 v[106:109], v[174:177], v[182:185], v[106:109]
	v_mfma_f32_16x16x32_bf16 v[102:105], v[160:163], v[190:193], v[102:105]
	v_mfma_f32_16x16x32_bf16 v[98:101], v[174:177], v[190:193], v[98:101]
	v_mfma_f32_16x16x32_bf16 v[86:89], v[160:163], v[210:213], v[86:89]
	v_mfma_f32_16x16x32_bf16 v[82:85], v[174:177], v[210:213], v[82:85]
	v_mfma_f32_16x16x32_bf16 v[70:73], v[160:163], v[218:221], v[70:73]
	v_mfma_f32_16x16x32_bf16 v[66:69], v[174:177], v[218:221], v[66:69]
	v_mfma_f32_16x16x32_bf16 v[114:117], v[164:167], v[186:189], v[114:117]
	v_mfma_f32_16x16x32_bf16 v[106:109], v[178:181], v[186:189], v[106:109]
	v_mfma_f32_16x16x32_bf16 v[102:105], v[164:167], v[198:201], v[102:105]
	v_mfma_f32_16x16x32_bf16 v[98:101], v[178:181], v[198:201], v[98:101]
	v_mfma_f32_16x16x32_bf16 v[86:89], v[164:167], v[214:217], v[86:89]
	v_mfma_f32_16x16x32_bf16 v[82:85], v[178:181], v[214:217], v[82:85]
	v_mfma_f32_16x16x32_bf16 v[70:73], v[164:167], v[222:225], v[70:73]
	s_barrier
	v_mfma_f32_16x16x32_bf16 v[66:69], v[178:181], v[222:225], v[66:69]
	s_setprio 2
	s_add_i32 s21, s21, s33
	v_lshl_add_u64 v[202:203], v[202:203], 0, s[12:13]
	s_mov_b32 m0, s21
	ds_read_b128 v[182:185], v172 offset:49152
	ds_read_b128 v[186:189], v172 offset:50176
	ds_read_b128 v[190:193], v172 offset:51200
	ds_read_b128 v[198:201], v172 offset:52224
	ds_read_b128 v[210:213], v172 offset:53248
	ds_read_b128 v[214:217], v172 offset:54272
	ds_read_b128 v[218:221], v172 offset:55296
	ds_read_b128 v[222:225], v172 offset:56320
	global_load_lds_dwordx4 v[202:203], off
	s_add_i32 m0, s21, 0x2000
	s_add_u32 s36, s36, 0x80080
	v_lshl_add_u64 v[202:203], v[206:207], 0, s[12:13]
	s_addc_u32 s37, s37, 0
	s_add_i32 s21, s40, s33
	global_load_lds_dwordx4 v[202:203], off
	s_mov_b32 m0, s21
	s_nop 0
	global_load_lds_dwordx4 v148, s[36:37]
	s_add_i32 m0, s21, 0x2000
	s_nop 0
	global_load_lds_dwordx4 v152, s[36:37]
	v_lshl_add_u64 v[202:203], v[226:227], 0, s[12:13]
	s_mov_b32 m0, s53
	s_nop 0
	global_load_lds_dwordx4 v[202:203], off
	v_lshl_add_u64 v[202:203], v[228:229], 0, s[12:13]
	s_mov_b32 m0, s54
	s_nop 0
	global_load_lds_dwordx4 v[202:203], off
	s_waitcnt vmcnt(8)
	s_waitcnt lgkmcnt(0)
	s_barrier
	s_setprio 1
	s_waitcnt lgkmcnt(0)
	v_mfma_f32_16x16x32_bf16 v[62:65], v[130:133], v[182:185], v[62:65]
	v_mfma_f32_16x16x32_bf16 v[58:61], v[138:141], v[182:185], v[58:61]
	v_mfma_f32_16x16x32_bf16 v[46:49], v[130:133], v[190:193], v[46:49]
	v_mfma_f32_16x16x32_bf16 v[42:45], v[138:141], v[190:193], v[42:45]
	v_mfma_f32_16x16x32_bf16 v[30:33], v[130:133], v[210:213], v[30:33]
	v_mfma_f32_16x16x32_bf16 v[26:29], v[138:141], v[210:213], v[26:29]
	v_mfma_f32_16x16x32_bf16 v[14:17], v[130:133], v[218:221], v[14:17]
	v_mfma_f32_16x16x32_bf16 v[10:13], v[138:141], v[218:221], v[10:13]
	v_mfma_f32_16x16x32_bf16 v[62:65], v[134:137], v[186:189], v[62:65]
	v_mfma_f32_16x16x32_bf16 v[58:61], v[142:145], v[186:189], v[58:61]
	v_mfma_f32_16x16x32_bf16 v[46:49], v[134:137], v[198:201], v[46:49]
	v_mfma_f32_16x16x32_bf16 v[42:45], v[142:145], v[198:201], v[42:45]
	v_mfma_f32_16x16x32_bf16 v[30:33], v[134:137], v[214:217], v[30:33]
	v_mfma_f32_16x16x32_bf16 v[26:29], v[142:145], v[214:217], v[26:29]
	v_mfma_f32_16x16x32_bf16 v[14:17], v[134:137], v[222:225], v[14:17]
	v_mfma_f32_16x16x32_bf16 v[10:13], v[142:145], v[222:225], v[10:13]
	v_mfma_f32_16x16x32_bf16 v[54:57], v[160:163], v[182:185], v[54:57]
	v_mfma_f32_16x16x32_bf16 v[50:53], v[174:177], v[182:185], v[50:53]
	v_mfma_f32_16x16x32_bf16 v[38:41], v[160:163], v[190:193], v[38:41]
	v_mfma_f32_16x16x32_bf16 v[34:37], v[174:177], v[190:193], v[34:37]
	v_mfma_f32_16x16x32_bf16 v[22:25], v[160:163], v[210:213], v[22:25]
	v_mfma_f32_16x16x32_bf16 v[18:21], v[174:177], v[210:213], v[18:21]
	v_mfma_f32_16x16x32_bf16 v[6:9], v[160:163], v[218:221], v[6:9]
	v_mfma_f32_16x16x32_bf16 v[2:5], v[174:177], v[218:221], v[2:5]
	v_mfma_f32_16x16x32_bf16 v[54:57], v[164:167], v[186:189], v[54:57]
	v_mfma_f32_16x16x32_bf16 v[50:53], v[178:181], v[186:189], v[50:53]
	v_mfma_f32_16x16x32_bf16 v[38:41], v[164:167], v[198:201], v[38:41]
	v_mfma_f32_16x16x32_bf16 v[34:37], v[178:181], v[198:201], v[34:37]
	v_mfma_f32_16x16x32_bf16 v[22:25], v[164:167], v[214:217], v[22:25]
	v_mfma_f32_16x16x32_bf16 v[18:21], v[178:181], v[214:217], v[18:21]
	v_mfma_f32_16x16x32_bf16 v[6:9], v[164:167], v[222:225], v[6:9]
	s_barrier
	v_mfma_f32_16x16x32_bf16 v[2:5], v[178:181], v[222:225], v[2:5]
	s_setprio 2
	s_add_u32 s34, s34, 0x100
	s_addc_u32 s35, s35, 0
	s_add_u32 s17, s17, 0x100
	s_addc_u32 s19, s19, 0
	s_cmp_ge_i32 s31, s69
	s_mov_b32 s21, s31
	s_cbranch_scc0 .LBB0_1122
	s_branch .Lpeeldone_8
.LBB0_1122:
	ds_read_b128 v[130:133], v170
	ds_read_b128 v[134:137], v170 offset:1024
	ds_read_b128 v[138:141], v170 offset:2048
	ds_read_b128 v[142:145], v170 offset:3072
	ds_read_b128 v[160:163], v171
	ds_read_b128 v[164:167], v171 offset:1024
	ds_read_b128 v[174:177], v171 offset:2048
	ds_read_b128 v[178:181], v171 offset:3072
	s_add_i32 s31, s21, 2
	s_add_u32 s36, s34, 0xfff80080
	s_addc_u32 s37, s35, -1
	s_cmp_eq_u32 s30, s21
	s_cselect_b32 s39, s23, s37
	s_cselect_b32 s38, s22, s36
	s_cselect_b32 s37, s25, s19
	s_cselect_b32 s36, s24, s17
	s_add_i32 m0, s27, 0xc000
	ds_read_b128 v[182:185], v172
	ds_read_b128 v[186:189], v172 offset:1024
	ds_read_b128 v[190:193], v172 offset:2048
	ds_read_b128 v[198:201], v172 offset:3072
	ds_read_b128 v[210:213], v172 offset:4096
	ds_read_b128 v[214:217], v172 offset:5120
	ds_read_b128 v[218:221], v172 offset:6144
	ds_read_b128 v[222:225], v172 offset:7168
	global_load_lds_dwordx4 v156, s[34:35]
	s_add_i32 m0, s27, 0xe000
	s_nop 0
	global_load_lds_dwordx4 v158, s[34:35]
	s_waitcnt vmcnt(8)
	s_waitcnt lgkmcnt(0)
	s_barrier
	s_setprio 1
	s_waitcnt lgkmcnt(0)
	v_mfma_f32_16x16x32_bf16 v[126:129], v[130:133], v[182:185], v[126:129]
	v_mfma_f32_16x16x32_bf16 v[122:125], v[138:141], v[182:185], v[122:125]
	v_mfma_f32_16x16x32_bf16 v[118:121], v[130:133], v[190:193], v[118:121]
	v_mfma_f32_16x16x32_bf16 v[110:113], v[138:141], v[190:193], v[110:113]
	v_mfma_f32_16x16x32_bf16 v[94:97], v[130:133], v[210:213], v[94:97]
	v_mfma_f32_16x16x32_bf16 v[90:93], v[138:141], v[210:213], v[90:93]
	v_mfma_f32_16x16x32_bf16 v[78:81], v[130:133], v[218:221], v[78:81]
	v_mfma_f32_16x16x32_bf16 v[74:77], v[138:141], v[218:221], v[74:77]
	v_mfma_f32_16x16x32_bf16 v[126:129], v[134:137], v[186:189], v[126:129]
	v_mfma_f32_16x16x32_bf16 v[122:125], v[142:145], v[186:189], v[122:125]
	v_mfma_f32_16x16x32_bf16 v[118:121], v[134:137], v[198:201], v[118:121]
	v_mfma_f32_16x16x32_bf16 v[110:113], v[142:145], v[198:201], v[110:113]
	v_mfma_f32_16x16x32_bf16 v[94:97], v[134:137], v[214:217], v[94:97]
	v_mfma_f32_16x16x32_bf16 v[90:93], v[142:145], v[214:217], v[90:93]
	v_mfma_f32_16x16x32_bf16 v[78:81], v[134:137], v[222:225], v[78:81]
	v_mfma_f32_16x16x32_bf16 v[74:77], v[142:145], v[222:225], v[74:77]
	v_mfma_f32_16x16x32_bf16 v[114:117], v[160:163], v[182:185], v[114:117]
	v_mfma_f32_16x16x32_bf16 v[106:109], v[174:177], v[182:185], v[106:109]
	v_mfma_f32_16x16x32_bf16 v[102:105], v[160:163], v[190:193], v[102:105]
	v_mfma_f32_16x16x32_bf16 v[98:101], v[174:177], v[190:193], v[98:101]
	v_mfma_f32_16x16x32_bf16 v[86:89], v[160:163], v[210:213], v[86:89]
	v_mfma_f32_16x16x32_bf16 v[82:85], v[174:177], v[210:213], v[82:85]
	v_mfma_f32_16x16x32_bf16 v[70:73], v[160:163], v[218:221], v[70:73]
	v_mfma_f32_16x16x32_bf16 v[66:69], v[174:177], v[218:221], v[66:69]
	v_mfma_f32_16x16x32_bf16 v[114:117], v[164:167], v[186:189], v[114:117]
	v_mfma_f32_16x16x32_bf16 v[106:109], v[178:181], v[186:189], v[106:109]
	v_mfma_f32_16x16x32_bf16 v[102:105], v[164:167], v[198:201], v[102:105]
	v_mfma_f32_16x16x32_bf16 v[98:101], v[178:181], v[198:201], v[98:101]
	v_mfma_f32_16x16x32_bf16 v[86:89], v[164:167], v[214:217], v[86:89]
	v_mfma_f32_16x16x32_bf16 v[82:85], v[178:181], v[214:217], v[82:85]
	v_mfma_f32_16x16x32_bf16 v[70:73], v[164:167], v[222:225], v[70:73]
	s_barrier
	v_mfma_f32_16x16x32_bf16 v[66:69], v[178:181], v[222:225], v[66:69]
	s_setprio 2
	s_add_i32 s21, s63, s33
	v_lshl_add_u64 v[202:203], s[36:37], 0, v[148:149]
	s_mov_b32 m0, s21
	ds_read_b128 v[182:185], v172 offset:16384
	ds_read_b128 v[186:189], v172 offset:17408
	ds_read_b128 v[190:193], v172 offset:18432
	ds_read_b128 v[198:201], v172 offset:19456
	ds_read_b128 v[210:213], v172 offset:20480
	ds_read_b128 v[214:217], v172 offset:21504
	ds_read_b128 v[218:221], v172 offset:22528
	ds_read_b128 v[222:225], v172 offset:23552
	global_load_lds_dwordx4 v148, s[36:37]
	s_add_i32 m0, s21, 0x2000
	s_add_u32 s40, s36, 0x80000
	v_lshl_add_u64 v[206:207], s[36:37], 0, v[152:153]
	s_addc_u32 s41, s37, 0
	s_add_i32 s21, s64, s33
	global_load_lds_dwordx4 v152, s[36:37]
	s_mov_b32 m0, s21
	v_lshl_add_u64 v[228:229], s[38:39], 0, v[150:151]
	global_load_lds_dwordx4 v148, s[40:41]
	s_add_i32 m0, s21, 0x2000
	s_nop 0
	global_load_lds_dwordx4 v152, s[40:41]
	v_lshl_add_u64 v[226:227], s[38:39], 0, v[146:147]
	s_mov_b32 m0, s27
	s_nop 0
	global_load_lds_dwordx4 v146, s[38:39]
	s_mov_b32 m0, s29
	s_nop 0
	global_load_lds_dwordx4 v150, s[38:39]
	s_waitcnt vmcnt(8)
	s_waitcnt lgkmcnt(0)
	s_barrier
	s_setprio 1
	s_waitcnt lgkmcnt(0)
	v_mfma_f32_16x16x32_bf16 v[62:65], v[130:133], v[182:185], v[62:65]
	v_mfma_f32_16x16x32_bf16 v[58:61], v[138:141], v[182:185], v[58:61]
	v_mfma_f32_16x16x32_bf16 v[46:49], v[130:133], v[190:193], v[46:49]
	v_mfma_f32_16x16x32_bf16 v[42:45], v[138:141], v[190:193], v[42:45]
	v_mfma_f32_16x16x32_bf16 v[30:33], v[130:133], v[210:213], v[30:33]
	v_mfma_f32_16x16x32_bf16 v[26:29], v[138:141], v[210:213], v[26:29]
	v_mfma_f32_16x16x32_bf16 v[14:17], v[130:133], v[218:221], v[14:17]
	v_mfma_f32_16x16x32_bf16 v[10:13], v[138:141], v[218:221], v[10:13]
	v_mfma_f32_16x16x32_bf16 v[62:65], v[134:137], v[186:189], v[62:65]
	v_mfma_f32_16x16x32_bf16 v[58:61], v[142:145], v[186:189], v[58:61]
	v_mfma_f32_16x16x32_bf16 v[46:49], v[134:137], v[198:201], v[46:49]
	v_mfma_f32_16x16x32_bf16 v[42:45], v[142:145], v[198:201], v[42:45]
	v_mfma_f32_16x16x32_bf16 v[30:33], v[134:137], v[214:217], v[30:33]
	v_mfma_f32_16x16x32_bf16 v[26:29], v[142:145], v[214:217], v[26:29]
	v_mfma_f32_16x16x32_bf16 v[14:17], v[134:137], v[222:225], v[14:17]
	v_mfma_f32_16x16x32_bf16 v[10:13], v[142:145], v[222:225], v[10:13]
	v_mfma_f32_16x16x32_bf16 v[54:57], v[160:163], v[182:185], v[54:57]
	v_mfma_f32_16x16x32_bf16 v[50:53], v[174:177], v[182:185], v[50:53]
	v_mfma_f32_16x16x32_bf16 v[38:41], v[160:163], v[190:193], v[38:41]
	v_mfma_f32_16x16x32_bf16 v[34:37], v[174:177], v[190:193], v[34:37]
	v_mfma_f32_16x16x32_bf16 v[22:25], v[160:163], v[210:213], v[22:25]
	v_mfma_f32_16x16x32_bf16 v[18:21], v[174:177], v[210:213], v[18:21]
	v_mfma_f32_16x16x32_bf16 v[6:9], v[160:163], v[218:221], v[6:9]
	v_mfma_f32_16x16x32_bf16 v[2:5], v[174:177], v[218:221], v[2:5]
	v_mfma_f32_16x16x32_bf16 v[54:57], v[164:167], v[186:189], v[54:57]
	v_mfma_f32_16x16x32_bf16 v[50:53], v[178:181], v[186:189], v[50:53]
	v_mfma_f32_16x16x32_bf16 v[38:41], v[164:167], v[198:201], v[38:41]
	v_mfma_f32_16x16x32_bf16 v[34:37], v[178:181], v[198:201], v[34:37]
	v_mfma_f32_16x16x32_bf16 v[22:25], v[164:167], v[214:217], v[22:25]
	v_mfma_f32_16x16x32_bf16 v[18:21], v[178:181], v[214:217], v[18:21]
	v_mfma_f32_16x16x32_bf16 v[6:9], v[164:167], v[222:225], v[6:9]
	s_barrier
	v_mfma_f32_16x16x32_bf16 v[2:5], v[178:181], v[222:225], v[2:5]
	s_setprio 2
	s_add_i32 s21, 0, 0x18000
	s_add_i32 s40, 0, 0x1c000
	ds_read_b128 v[130:133], v250
	ds_read_b128 v[134:137], v250 offset:1024
	ds_read_b128 v[138:141], v250 offset:2048
	ds_read_b128 v[142:145], v250 offset:3072
	ds_read_b128 v[160:163], v250 offset:16384
	ds_read_b128 v[164:167], v250 offset:17408
	ds_read_b128 v[174:177], v250 offset:18432
	ds_read_b128 v[178:181], v250 offset:19456
	v_add_u32_e32 v173, s40, v168
	s_add_u32 s38, s38, 0x80000
	s_addc_u32 s39, s39, 0
	s_mov_b32 m0, s42
	ds_read_b128 v[182:185], v172 offset:32768
	ds_read_b128 v[186:189], v172 offset:33792
	ds_read_b128 v[190:193], v172 offset:34816
	ds_read_b128 v[198:201], v172 offset:35840
	ds_read_b128 v[210:213], v172 offset:36864
	ds_read_b128 v[214:217], v172 offset:37888
	ds_read_b128 v[218:221], v172 offset:38912
	ds_read_b128 v[222:225], v172 offset:39936
	global_load_lds_dwordx4 v146, s[38:39]
	v_lshl_add_u64 v[230:231], s[38:39], 0, v[150:151]
	s_mov_b32 m0, s43
	s_nop 0
	global_load_lds_dwordx4 v150, s[38:39]
	s_waitcnt vmcnt(8)
	s_waitcnt lgkmcnt(0)
	s_barrier
	s_setprio 1
	s_waitcnt lgkmcnt(0)
	v_mfma_f32_16x16x32_bf16 v[126:129], v[130:133], v[182:185], v[126:129]
	v_mfma_f32_16x16x32_bf16 v[122:125], v[138:141], v[182:185], v[122:125]
	v_mfma_f32_16x16x32_bf16 v[118:121], v[130:133], v[190:193], v[118:121]
	v_mfma_f32_16x16x32_bf16 v[110:113], v[138:141], v[190:193], v[110:113]
	v_mfma_f32_16x16x32_bf16 v[94:97], v[130:133], v[210:213], v[94:97]
	v_mfma_f32_16x16x32_bf16 v[90:93], v[138:141], v[210:213], v[90:93]
	v_mfma_f32_16x16x32_bf16 v[78:81], v[130:133], v[218:221], v[78:81]
	v_mfma_f32_16x16x32_bf16 v[74:77], v[138:141], v[218:221], v[74:77]
	v_mfma_f32_16x16x32_bf16 v[126:129], v[134:137], v[186:189], v[126:129]
	v_mfma_f32_16x16x32_bf16 v[122:125], v[142:145], v[186:189], v[122:125]
	v_mfma_f32_16x16x32_bf16 v[118:121], v[134:137], v[198:201], v[118:121]
	v_mfma_f32_16x16x32_bf16 v[110:113], v[142:145], v[198:201], v[110:113]
	v_mfma_f32_16x16x32_bf16 v[94:97], v[134:137], v[214:217], v[94:97]
	v_mfma_f32_16x16x32_bf16 v[90:93], v[142:145], v[214:217], v[90:93]
	v_mfma_f32_16x16x32_bf16 v[78:81], v[134:137], v[222:225], v[78:81]
	v_mfma_f32_16x16x32_bf16 v[74:77], v[142:145], v[222:225], v[74:77]
	v_mfma_f32_16x16x32_bf16 v[114:117], v[160:163], v[182:185], v[114:117]
	v_mfma_f32_16x16x32_bf16 v[106:109], v[174:177], v[182:185], v[106:109]
	v_mfma_f32_16x16x32_bf16 v[102:105], v[160:163], v[190:193], v[102:105]
	v_mfma_f32_16x16x32_bf16 v[98:101], v[174:177], v[190:193], v[98:101]
	v_mfma_f32_16x16x32_bf16 v[86:89], v[160:163], v[210:213], v[86:89]
	v_mfma_f32_16x16x32_bf16 v[82:85], v[174:177], v[210:213], v[82:85]
	v_mfma_f32_16x16x32_bf16 v[70:73], v[160:163], v[218:221], v[70:73]
	v_mfma_f32_16x16x32_bf16 v[66:69], v[174:177], v[218:221], v[66:69]
	v_mfma_f32_16x16x32_bf16 v[114:117], v[164:167], v[186:189], v[114:117]
	v_mfma_f32_16x16x32_bf16 v[106:109], v[178:181], v[186:189], v[106:109]
	v_mfma_f32_16x16x32_bf16 v[102:105], v[164:167], v[198:201], v[102:105]
	v_mfma_f32_16x16x32_bf16 v[98:101], v[178:181], v[198:201], v[98:101]
	v_mfma_f32_16x16x32_bf16 v[86:89], v[164:167], v[214:217], v[86:89]
	v_mfma_f32_16x16x32_bf16 v[82:85], v[178:181], v[214:217], v[82:85]
	v_mfma_f32_16x16x32_bf16 v[70:73], v[164:167], v[222:225], v[70:73]
	s_barrier
	v_mfma_f32_16x16x32_bf16 v[66:69], v[178:181], v[222:225], v[66:69]
	s_setprio 2
	s_add_i32 s21, s21, s33
	v_lshl_add_u64 v[202:203], v[202:203], 0, s[12:13]
	s_mov_b32 m0, s21
	ds_read_b128 v[182:185], v172 offset:49152
	ds_read_b128 v[186:189], v172 offset:50176
	ds_read_b128 v[190:193], v172 offset:51200
	ds_read_b128 v[198:201], v172 offset:52224
	ds_read_b128 v[210:213], v172 offset:53248
	ds_read_b128 v[214:217], v172 offset:54272
	ds_read_b128 v[218:221], v172 offset:55296
	ds_read_b128 v[222:225], v172 offset:56320
	global_load_lds_dwordx4 v[202:203], off
	s_add_i32 m0, s21, 0x2000
	s_add_u32 s36, s36, 0x80080
	v_lshl_add_u64 v[202:203], v[206:207], 0, s[12:13]
	s_addc_u32 s37, s37, 0
	s_add_i32 s21, s40, s33
	global_load_lds_dwordx4 v[202:203], off
	s_mov_b32 m0, s21
	s_nop 0
	global_load_lds_dwordx4 v148, s[36:37]
	s_add_i32 m0, s21, 0x2000
	s_nop 0
	global_load_lds_dwordx4 v152, s[36:37]
	v_lshl_add_u64 v[202:203], v[226:227], 0, s[12:13]
	s_mov_b32 m0, s53
	s_nop 0
	global_load_lds_dwordx4 v[202:203], off
	v_lshl_add_u64 v[202:203], v[228:229], 0, s[12:13]
	s_mov_b32 m0, s54
	s_nop 0
	global_load_lds_dwordx4 v[202:203], off
	s_waitcnt vmcnt(8)
	s_waitcnt lgkmcnt(0)
	s_barrier
	s_setprio 1
	s_waitcnt lgkmcnt(0)
	v_mfma_f32_16x16x32_bf16 v[62:65], v[130:133], v[182:185], v[62:65]
	v_mfma_f32_16x16x32_bf16 v[58:61], v[138:141], v[182:185], v[58:61]
	v_mfma_f32_16x16x32_bf16 v[46:49], v[130:133], v[190:193], v[46:49]
	v_mfma_f32_16x16x32_bf16 v[42:45], v[138:141], v[190:193], v[42:45]
	v_mfma_f32_16x16x32_bf16 v[30:33], v[130:133], v[210:213], v[30:33]
	v_mfma_f32_16x16x32_bf16 v[26:29], v[138:141], v[210:213], v[26:29]
	v_mfma_f32_16x16x32_bf16 v[14:17], v[130:133], v[218:221], v[14:17]
	v_mfma_f32_16x16x32_bf16 v[10:13], v[138:141], v[218:221], v[10:13]
	v_mfma_f32_16x16x32_bf16 v[62:65], v[134:137], v[186:189], v[62:65]
	v_mfma_f32_16x16x32_bf16 v[58:61], v[142:145], v[186:189], v[58:61]
	v_mfma_f32_16x16x32_bf16 v[46:49], v[134:137], v[198:201], v[46:49]
	v_mfma_f32_16x16x32_bf16 v[42:45], v[142:145], v[198:201], v[42:45]
	v_mfma_f32_16x16x32_bf16 v[30:33], v[134:137], v[214:217], v[30:33]
	v_mfma_f32_16x16x32_bf16 v[26:29], v[142:145], v[214:217], v[26:29]
	v_mfma_f32_16x16x32_bf16 v[14:17], v[134:137], v[222:225], v[14:17]
	v_mfma_f32_16x16x32_bf16 v[10:13], v[142:145], v[222:225], v[10:13]
	v_mfma_f32_16x16x32_bf16 v[54:57], v[160:163], v[182:185], v[54:57]
	v_mfma_f32_16x16x32_bf16 v[50:53], v[174:177], v[182:185], v[50:53]
	v_mfma_f32_16x16x32_bf16 v[38:41], v[160:163], v[190:193], v[38:41]
	v_mfma_f32_16x16x32_bf16 v[34:37], v[174:177], v[190:193], v[34:37]
	v_mfma_f32_16x16x32_bf16 v[22:25], v[160:163], v[210:213], v[22:25]
	v_mfma_f32_16x16x32_bf16 v[18:21], v[174:177], v[210:213], v[18:21]
	v_mfma_f32_16x16x32_bf16 v[6:9], v[160:163], v[218:221], v[6:9]
	v_mfma_f32_16x16x32_bf16 v[2:5], v[174:177], v[218:221], v[2:5]
	v_mfma_f32_16x16x32_bf16 v[54:57], v[164:167], v[186:189], v[54:57]
	v_mfma_f32_16x16x32_bf16 v[50:53], v[178:181], v[186:189], v[50:53]
	v_mfma_f32_16x16x32_bf16 v[38:41], v[164:167], v[198:201], v[38:41]
	v_mfma_f32_16x16x32_bf16 v[34:37], v[178:181], v[198:201], v[34:37]
	v_mfma_f32_16x16x32_bf16 v[22:25], v[164:167], v[214:217], v[22:25]
	v_mfma_f32_16x16x32_bf16 v[18:21], v[178:181], v[214:217], v[18:21]
	v_mfma_f32_16x16x32_bf16 v[6:9], v[164:167], v[222:225], v[6:9]
	s_barrier
	v_mfma_f32_16x16x32_bf16 v[2:5], v[178:181], v[222:225], v[2:5]
	s_setprio 2
	s_add_u32 s34, s34, 0x100
	s_addc_u32 s35, s35, 0
	s_add_u32 s17, s17, 0x100
	s_addc_u32 s19, s19, 0
	s_cmp_ge_i32 s31, s69
	s_mov_b32 s21, s31
	s_cbranch_scc0 .LBB0_1122

.Lpeel_7:
	v_add_u32_e32 v250, 0x18000, v146
	ds_read_b128 v[152:155], v148
	ds_read_b128 v[156:159], v148 offset:1024
	s_add_i32 s29, s19, 2
	s_add_u32 s34, s30, 0xfff80080
	s_addc_u32 s35, s31, -1
	s_cmp_eq_u32 s28, s19
	s_cselect_b32 s37, s21, s35
	s_cselect_b32 s36, s20, s34
	s_cselect_b32 s35, s23, s17
	s_cselect_b32 s34, s22, s15
	s_add_i32 m0, s27, 0xc000
	global_load_lds_dwordx4 v140, s[30:31]
	s_add_i32 m0, s27, 0xe000
	s_nop 0
	global_load_lds_dwordx4 v142, s[30:31]
	s_waitcnt vmcnt(8)
	s_waitcnt lgkmcnt(0)
	s_barrier
	s_setprio 1
	s_waitcnt lgkmcnt(0)
	v_mfma_f32_16x16x32_bf16 v[126:129], v[152:155], v[184:187], 0
	v_mfma_f32_16x16x32_bf16 v[122:125], v[160:163], v[184:187], 0
	v_mfma_f32_16x16x32_bf16 v[110:113], v[152:155], v[198:201], 0
	v_mfma_f32_16x16x32_bf16 v[106:109], v[160:163], v[198:201], 0
	v_mfma_f32_16x16x32_bf16 v[94:97], v[152:155], v[214:217], 0
	v_mfma_f32_16x16x32_bf16 v[90:93], v[160:163], v[214:217], 0
	v_mfma_f32_16x16x32_bf16 v[78:81], v[152:155], v[222:225], 0
	v_mfma_f32_16x16x32_bf16 v[74:77], v[160:163], v[222:225], 0
	v_mfma_f32_16x16x32_bf16 v[126:129], v[156:159], v[188:191], v[126:129]
	v_mfma_f32_16x16x32_bf16 v[122:125], v[164:167], v[188:191], v[122:125]
	v_mfma_f32_16x16x32_bf16 v[110:113], v[156:159], v[210:213], v[110:113]
	v_mfma_f32_16x16x32_bf16 v[106:109], v[164:167], v[210:213], v[106:109]
	v_mfma_f32_16x16x32_bf16 v[94:97], v[156:159], v[218:221], v[94:97]
	v_mfma_f32_16x16x32_bf16 v[90:93], v[164:167], v[218:221], v[90:93]
	v_mfma_f32_16x16x32_bf16 v[78:81], v[156:159], v[226:229], v[78:81]
	v_mfma_f32_16x16x32_bf16 v[74:77], v[164:167], v[226:229], v[74:77]
	v_mfma_f32_16x16x32_bf16 v[118:121], v[168:171], v[184:187], 0
	v_mfma_f32_16x16x32_bf16 v[114:117], v[176:179], v[184:187], 0
	v_mfma_f32_16x16x32_bf16 v[102:105], v[168:171], v[198:201], 0
	v_mfma_f32_16x16x32_bf16 v[98:101], v[176:179], v[198:201], 0
	v_mfma_f32_16x16x32_bf16 v[86:89], v[168:171], v[214:217], 0
	v_mfma_f32_16x16x32_bf16 v[82:85], v[176:179], v[214:217], 0
	v_mfma_f32_16x16x32_bf16 v[70:73], v[168:171], v[222:225], 0
	v_mfma_f32_16x16x32_bf16 v[66:69], v[176:179], v[222:225], 0
	v_mfma_f32_16x16x32_bf16 v[118:121], v[172:175], v[188:191], v[118:121]
	v_mfma_f32_16x16x32_bf16 v[114:117], v[180:183], v[188:191], v[114:117]
	v_mfma_f32_16x16x32_bf16 v[102:105], v[172:175], v[210:213], v[102:105]
	v_mfma_f32_16x16x32_bf16 v[98:101], v[180:183], v[210:213], v[98:101]
	v_mfma_f32_16x16x32_bf16 v[86:89], v[172:175], v[218:221], v[86:89]
	v_mfma_f32_16x16x32_bf16 v[82:85], v[180:183], v[218:221], v[82:85]
	v_mfma_f32_16x16x32_bf16 v[70:73], v[172:175], v[226:229], v[70:73]
	s_barrier
	v_mfma_f32_16x16x32_bf16 v[66:69], v[180:183], v[226:229], v[66:69]
	s_setprio 2
	s_add_i32 s19, s60, s33
	v_lshl_add_u64 v[144:145], s[34:35], 0, v[132:133]
	s_mov_b32 m0, s19
	ds_read_b128 v[184:187], v150 offset:16384
	ds_read_b128 v[188:191], v150 offset:17408
	ds_read_b128 v[198:201], v150 offset:18432
	ds_read_b128 v[210:213], v150 offset:19456
	ds_read_b128 v[214:217], v150 offset:20480
	ds_read_b128 v[218:221], v150 offset:21504
	ds_read_b128 v[222:225], v150 offset:22528
	ds_read_b128 v[226:229], v150 offset:23552
	global_load_lds_dwordx4 v132, s[34:35]
	s_add_i32 m0, s19, 0x2000
	s_add_u32 s38, s34, 0x80000
	v_lshl_add_u64 v[192:193], s[34:35], 0, v[136:137]
	s_addc_u32 s39, s35, 0
	s_add_i32 s19, s61, s33
	global_load_lds_dwordx4 v136, s[34:35]
	s_mov_b32 m0, s19
	v_lshl_add_u64 v[206:207], s[36:37], 0, v[134:135]
	global_load_lds_dwordx4 v132, s[38:39]
	s_add_i32 m0, s19, 0x2000
	s_nop 0
	global_load_lds_dwordx4 v136, s[38:39]
	v_lshl_add_u64 v[202:203], s[36:37], 0, v[130:131]
	s_mov_b32 m0, s27
	s_nop 0
	global_load_lds_dwordx4 v130, s[36:37]
	s_mov_b32 m0, s41
	s_nop 0
	global_load_lds_dwordx4 v134, s[36:37]
	s_waitcnt vmcnt(8)
	s_waitcnt lgkmcnt(0)
	s_barrier
	s_setprio 1
	s_waitcnt lgkmcnt(0)
	v_mfma_f32_16x16x32_bf16 v[62:65], v[152:155], v[184:187], 0
	v_mfma_f32_16x16x32_bf16 v[58:61], v[160:163], v[184:187], 0
	v_mfma_f32_16x16x32_bf16 v[46:49], v[152:155], v[198:201], 0
	v_mfma_f32_16x16x32_bf16 v[42:45], v[160:163], v[198:201], 0
	v_mfma_f32_16x16x32_bf16 v[30:33], v[152:155], v[214:217], 0
	v_mfma_f32_16x16x32_bf16 v[26:29], v[160:163], v[214:217], 0
	v_mfma_f32_16x16x32_bf16 v[14:17], v[152:155], v[222:225], 0
	v_mfma_f32_16x16x32_bf16 v[10:13], v[160:163], v[222:225], 0
	v_mfma_f32_16x16x32_bf16 v[62:65], v[156:159], v[188:191], v[62:65]
	v_mfma_f32_16x16x32_bf16 v[58:61], v[164:167], v[188:191], v[58:61]
	v_mfma_f32_16x16x32_bf16 v[46:49], v[156:159], v[210:213], v[46:49]
	v_mfma_f32_16x16x32_bf16 v[42:45], v[164:167], v[210:213], v[42:45]
	v_mfma_f32_16x16x32_bf16 v[30:33], v[156:159], v[218:221], v[30:33]
	v_mfma_f32_16x16x32_bf16 v[26:29], v[164:167], v[218:221], v[26:29]
	v_mfma_f32_16x16x32_bf16 v[14:17], v[156:159], v[226:229], v[14:17]
	v_mfma_f32_16x16x32_bf16 v[10:13], v[164:167], v[226:229], v[10:13]
	v_mfma_f32_16x16x32_bf16 v[54:57], v[168:171], v[184:187], 0
	v_mfma_f32_16x16x32_bf16 v[50:53], v[176:179], v[184:187], 0
	v_mfma_f32_16x16x32_bf16 v[38:41], v[168:171], v[198:201], 0
	v_mfma_f32_16x16x32_bf16 v[34:37], v[176:179], v[198:201], 0
	v_mfma_f32_16x16x32_bf16 v[22:25], v[168:171], v[214:217], 0
	v_mfma_f32_16x16x32_bf16 v[18:21], v[176:179], v[214:217], 0
	v_mfma_f32_16x16x32_bf16 v[6:9], v[168:171], v[222:225], 0
	v_mfma_f32_16x16x32_bf16 v[2:5], v[176:179], v[222:225], 0
	v_mfma_f32_16x16x32_bf16 v[54:57], v[172:175], v[188:191], v[54:57]
	v_mfma_f32_16x16x32_bf16 v[50:53], v[180:183], v[188:191], v[50:53]
	v_mfma_f32_16x16x32_bf16 v[38:41], v[172:175], v[210:213], v[38:41]
	v_mfma_f32_16x16x32_bf16 v[34:37], v[180:183], v[210:213], v[34:37]
	v_mfma_f32_16x16x32_bf16 v[22:25], v[172:175], v[218:221], v[22:25]
	v_mfma_f32_16x16x32_bf16 v[18:21], v[180:183], v[218:221], v[18:21]
	v_mfma_f32_16x16x32_bf16 v[6:9], v[172:175], v[226:229], v[6:9]
	s_barrier
	v_mfma_f32_16x16x32_bf16 v[2:5], v[180:183], v[226:229], v[2:5]
	s_setprio 2
	s_add_i32 s19, 0, 0x18000
	s_add_i32 s38, 0, 0x1c000
	ds_read_b128 v[152:155], v250
	ds_read_b128 v[156:159], v250 offset:1024
	ds_read_b128 v[160:163], v250 offset:2048
	ds_read_b128 v[164:167], v250 offset:3072
	ds_read_b128 v[168:171], v250 offset:16384
	ds_read_b128 v[172:175], v250 offset:17408
	ds_read_b128 v[176:179], v250 offset:18432
	ds_read_b128 v[180:183], v250 offset:19456
	v_add_u32_e32 v151, s38, v146
	s_add_u32 s36, s36, 0x80000
	s_addc_u32 s37, s37, 0
	s_mov_b32 m0, s42
	ds_read_b128 v[184:187], v150 offset:32768
	ds_read_b128 v[188:191], v150 offset:33792
	ds_read_b128 v[198:201], v150 offset:34816
	ds_read_b128 v[210:213], v150 offset:35840
	ds_read_b128 v[214:217], v150 offset:36864
	ds_read_b128 v[218:221], v150 offset:37888
	ds_read_b128 v[222:225], v150 offset:38912
	ds_read_b128 v[226:229], v150 offset:39936
	global_load_lds_dwordx4 v130, s[36:37]
	v_lshl_add_u64 v[230:231], s[36:37], 0, v[134:135]
	s_mov_b32 m0, s43
	s_nop 0
	global_load_lds_dwordx4 v134, s[36:37]
	s_waitcnt vmcnt(8)
	s_waitcnt lgkmcnt(0)
	s_barrier
	s_setprio 1
	s_waitcnt lgkmcnt(0)
	v_mfma_f32_16x16x32_bf16 v[126:129], v[152:155], v[184:187], v[126:129]
	v_mfma_f32_16x16x32_bf16 v[122:125], v[160:163], v[184:187], v[122:125]
	v_mfma_f32_16x16x32_bf16 v[110:113], v[152:155], v[198:201], v[110:113]
	v_mfma_f32_16x16x32_bf16 v[106:109], v[160:163], v[198:201], v[106:109]
	v_mfma_f32_16x16x32_bf16 v[94:97], v[152:155], v[214:217], v[94:97]
	v_mfma_f32_16x16x32_bf16 v[90:93], v[160:163], v[214:217], v[90:93]
	v_mfma_f32_16x16x32_bf16 v[78:81], v[152:155], v[222:225], v[78:81]
	v_mfma_f32_16x16x32_bf16 v[74:77], v[160:163], v[222:225], v[74:77]
	v_mfma_f32_16x16x32_bf16 v[126:129], v[156:159], v[188:191], v[126:129]
	v_mfma_f32_16x16x32_bf16 v[122:125], v[164:167], v[188:191], v[122:125]
	v_mfma_f32_16x16x32_bf16 v[110:113], v[156:159], v[210:213], v[110:113]
	v_mfma_f32_16x16x32_bf16 v[106:109], v[164:167], v[210:213], v[106:109]
	v_mfma_f32_16x16x32_bf16 v[94:97], v[156:159], v[218:221], v[94:97]
	v_mfma_f32_16x16x32_bf16 v[90:93], v[164:167], v[218:221], v[90:93]
	v_mfma_f32_16x16x32_bf16 v[78:81], v[156:159], v[226:229], v[78:81]
	v_mfma_f32_16x16x32_bf16 v[74:77], v[164:167], v[226:229], v[74:77]
	v_mfma_f32_16x16x32_bf16 v[118:121], v[168:171], v[184:187], v[118:121]
	v_mfma_f32_16x16x32_bf16 v[114:117], v[176:179], v[184:187], v[114:117]
	v_mfma_f32_16x16x32_bf16 v[102:105], v[168:171], v[198:201], v[102:105]
	v_mfma_f32_16x16x32_bf16 v[98:101], v[176:179], v[198:201], v[98:101]
	v_mfma_f32_16x16x32_bf16 v[86:89], v[168:171], v[214:217], v[86:89]
	v_mfma_f32_16x16x32_bf16 v[82:85], v[176:179], v[214:217], v[82:85]
	v_mfma_f32_16x16x32_bf16 v[70:73], v[168:171], v[222:225], v[70:73]
	v_mfma_f32_16x16x32_bf16 v[66:69], v[176:179], v[222:225], v[66:69]
	v_mfma_f32_16x16x32_bf16 v[118:121], v[172:175], v[188:191], v[118:121]
	v_mfma_f32_16x16x32_bf16 v[114:117], v[180:183], v[188:191], v[114:117]
	v_mfma_f32_16x16x32_bf16 v[102:105], v[172:175], v[210:213], v[102:105]
	v_mfma_f32_16x16x32_bf16 v[98:101], v[180:183], v[210:213], v[98:101]
	v_mfma_f32_16x16x32_bf16 v[86:89], v[172:175], v[218:221], v[86:89]
	v_mfma_f32_16x16x32_bf16 v[82:85], v[180:183], v[218:221], v[82:85]
	v_mfma_f32_16x16x32_bf16 v[70:73], v[172:175], v[226:229], v[70:73]
	s_barrier
	v_mfma_f32_16x16x32_bf16 v[66:69], v[180:183], v[226:229], v[66:69]
	s_setprio 2
	s_add_i32 s19, s19, s33
	v_lshl_add_u64 v[144:145], v[144:145], 0, s[10:11]
	s_mov_b32 m0, s19
	ds_read_b128 v[184:187], v150 offset:49152
	ds_read_b128 v[188:191], v150 offset:50176
	ds_read_b128 v[198:201], v150 offset:51200
	ds_read_b128 v[210:213], v150 offset:52224
	ds_read_b128 v[214:217], v150 offset:53248
	ds_read_b128 v[218:221], v150 offset:54272
	ds_read_b128 v[222:225], v150 offset:55296
	ds_read_b128 v[226:229], v150 offset:56320
	global_load_lds_dwordx4 v[144:145], off
	s_add_i32 m0, s19, 0x2000
	s_add_u32 s34, s34, 0x80080
	v_lshl_add_u64 v[144:145], v[192:193], 0, s[10:11]
	s_addc_u32 s35, s35, 0
	s_add_i32 s19, s38, s33
	global_load_lds_dwordx4 v[144:145], off
	s_mov_b32 m0, s19
	s_nop 0
	global_load_lds_dwordx4 v132, s[34:35]
	s_add_i32 m0, s19, 0x2000
	s_nop 0
	global_load_lds_dwordx4 v136, s[34:35]
	v_lshl_add_u64 v[144:145], v[202:203], 0, s[10:11]
	s_mov_b32 m0, s51
	s_nop 0
	global_load_lds_dwordx4 v[144:145], off
	v_lshl_add_u64 v[144:145], v[206:207], 0, s[10:11]
	s_mov_b32 m0, s52
	s_nop 0
	global_load_lds_dwordx4 v[144:145], off
	s_waitcnt vmcnt(8)
	s_waitcnt lgkmcnt(0)
	s_barrier
	s_setprio 1
	s_waitcnt lgkmcnt(0)
	v_mfma_f32_16x16x32_bf16 v[62:65], v[152:155], v[184:187], v[62:65]
	v_mfma_f32_16x16x32_bf16 v[58:61], v[160:163], v[184:187], v[58:61]
	v_mfma_f32_16x16x32_bf16 v[46:49], v[152:155], v[198:201], v[46:49]
	v_mfma_f32_16x16x32_bf16 v[42:45], v[160:163], v[198:201], v[42:45]
	v_mfma_f32_16x16x32_bf16 v[30:33], v[152:155], v[214:217], v[30:33]
	v_mfma_f32_16x16x32_bf16 v[26:29], v[160:163], v[214:217], v[26:29]
	v_mfma_f32_16x16x32_bf16 v[14:17], v[152:155], v[222:225], v[14:17]
	v_mfma_f32_16x16x32_bf16 v[10:13], v[160:163], v[222:225], v[10:13]
	v_mfma_f32_16x16x32_bf16 v[62:65], v[156:159], v[188:191], v[62:65]
	v_mfma_f32_16x16x32_bf16 v[58:61], v[164:167], v[188:191], v[58:61]
	v_mfma_f32_16x16x32_bf16 v[46:49], v[156:159], v[210:213], v[46:49]
	v_mfma_f32_16x16x32_bf16 v[42:45], v[164:167], v[210:213], v[42:45]
	v_mfma_f32_16x16x32_bf16 v[30:33], v[156:159], v[218:221], v[30:33]
	v_mfma_f32_16x16x32_bf16 v[26:29], v[164:167], v[218:221], v[26:29]
	v_mfma_f32_16x16x32_bf16 v[14:17], v[156:159], v[226:229], v[14:17]
	v_mfma_f32_16x16x32_bf16 v[10:13], v[164:167], v[226:229], v[10:13]
	v_mfma_f32_16x16x32_bf16 v[54:57], v[168:171], v[184:187], v[54:57]
	v_mfma_f32_16x16x32_bf16 v[50:53], v[176:179], v[184:187], v[50:53]
	v_mfma_f32_16x16x32_bf16 v[38:41], v[168:171], v[198:201], v[38:41]
	v_mfma_f32_16x16x32_bf16 v[34:37], v[176:179], v[198:201], v[34:37]
	v_mfma_f32_16x16x32_bf16 v[22:25], v[168:171], v[214:217], v[22:25]
	v_mfma_f32_16x16x32_bf16 v[18:21], v[176:179], v[214:217], v[18:21]
	v_mfma_f32_16x16x32_bf16 v[6:9], v[168:171], v[222:225], v[6:9]
	v_mfma_f32_16x16x32_bf16 v[2:5], v[176:179], v[222:225], v[2:5]
	v_mfma_f32_16x16x32_bf16 v[54:57], v[172:175], v[188:191], v[54:57]
	v_mfma_f32_16x16x32_bf16 v[50:53], v[180:183], v[188:191], v[50:53]
	v_mfma_f32_16x16x32_bf16 v[38:41], v[172:175], v[210:213], v[38:41]
	v_mfma_f32_16x16x32_bf16 v[34:37], v[180:183], v[210:213], v[34:37]
	v_mfma_f32_16x16x32_bf16 v[22:25], v[172:175], v[218:221], v[22:25]
	v_mfma_f32_16x16x32_bf16 v[18:21], v[180:183], v[218:221], v[18:21]
	v_mfma_f32_16x16x32_bf16 v[6:9], v[172:175], v[226:229], v[6:9]
	s_barrier
	v_mfma_f32_16x16x32_bf16 v[2:5], v[180:183], v[226:229], v[2:5]
	s_setprio 2
	s_add_u32 s30, s30, 0x100
	s_addc_u32 s31, s31, 0
	s_add_u32 s15, s15, 0x100
	s_addc_u32 s17, s17, 0
	s_cmp_ge_i32 s29, s68
	s_mov_b32 s19, s29
	s_cbranch_scc0 .LBB0_1315
	s_branch .Lpeeldone_7
.LBB0_1315:
	ds_read_b128 v[152:155], v148
	ds_read_b128 v[156:159], v148 offset:1024
	ds_read_b128 v[160:163], v148 offset:2048
	ds_read_b128 v[164:167], v148 offset:3072
	ds_read_b128 v[168:171], v149
	ds_read_b128 v[172:175], v149 offset:1024
	ds_read_b128 v[176:179], v149 offset:2048
	ds_read_b128 v[180:183], v149 offset:3072
	s_add_i32 s29, s19, 2
	s_add_u32 s34, s30, 0xfff80080
	s_addc_u32 s35, s31, -1
	s_cmp_eq_u32 s28, s19
	s_cselect_b32 s37, s21, s35
	s_cselect_b32 s36, s20, s34
	s_cselect_b32 s35, s23, s17
	s_cselect_b32 s34, s22, s15
	s_add_i32 m0, s27, 0xc000
	ds_read_b128 v[184:187], v150
	ds_read_b128 v[188:191], v150 offset:1024
	ds_read_b128 v[198:201], v150 offset:2048
	ds_read_b128 v[210:213], v150 offset:3072
	ds_read_b128 v[214:217], v150 offset:4096
	ds_read_b128 v[218:221], v150 offset:5120
	ds_read_b128 v[222:225], v150 offset:6144
	ds_read_b128 v[226:229], v150 offset:7168
	global_load_lds_dwordx4 v140, s[30:31]
	s_add_i32 m0, s27, 0xe000
	s_nop 0
	global_load_lds_dwordx4 v142, s[30:31]
	s_waitcnt vmcnt(8)
	s_waitcnt lgkmcnt(0)
	s_barrier
	s_setprio 1
	s_waitcnt lgkmcnt(0)
	v_mfma_f32_16x16x32_bf16 v[126:129], v[152:155], v[184:187], v[126:129]
	v_mfma_f32_16x16x32_bf16 v[122:125], v[160:163], v[184:187], v[122:125]
	v_mfma_f32_16x16x32_bf16 v[110:113], v[152:155], v[198:201], v[110:113]
	v_mfma_f32_16x16x32_bf16 v[106:109], v[160:163], v[198:201], v[106:109]
	v_mfma_f32_16x16x32_bf16 v[94:97], v[152:155], v[214:217], v[94:97]
	v_mfma_f32_16x16x32_bf16 v[90:93], v[160:163], v[214:217], v[90:93]
	v_mfma_f32_16x16x32_bf16 v[78:81], v[152:155], v[222:225], v[78:81]
	v_mfma_f32_16x16x32_bf16 v[74:77], v[160:163], v[222:225], v[74:77]
	v_mfma_f32_16x16x32_bf16 v[126:129], v[156:159], v[188:191], v[126:129]
	v_mfma_f32_16x16x32_bf16 v[122:125], v[164:167], v[188:191], v[122:125]
	v_mfma_f32_16x16x32_bf16 v[110:113], v[156:159], v[210:213], v[110:113]
	v_mfma_f32_16x16x32_bf16 v[106:109], v[164:167], v[210:213], v[106:109]
	v_mfma_f32_16x16x32_bf16 v[94:97], v[156:159], v[218:221], v[94:97]
	v_mfma_f32_16x16x32_bf16 v[90:93], v[164:167], v[218:221], v[90:93]
	v_mfma_f32_16x16x32_bf16 v[78:81], v[156:159], v[226:229], v[78:81]
	v_mfma_f32_16x16x32_bf16 v[74:77], v[164:167], v[226:229], v[74:77]
	v_mfma_f32_16x16x32_bf16 v[118:121], v[168:171], v[184:187], v[118:121]
	v_mfma_f32_16x16x32_bf16 v[114:117], v[176:179], v[184:187], v[114:117]
	v_mfma_f32_16x16x32_bf16 v[102:105], v[168:171], v[198:201], v[102:105]
	v_mfma_f32_16x16x32_bf16 v[98:101], v[176:179], v[198:201], v[98:101]
	v_mfma_f32_16x16x32_bf16 v[86:89], v[168:171], v[214:217], v[86:89]
	v_mfma_f32_16x16x32_bf16 v[82:85], v[176:179], v[214:217], v[82:85]
	v_mfma_f32_16x16x32_bf16 v[70:73], v[168:171], v[222:225], v[70:73]
	v_mfma_f32_16x16x32_bf16 v[66:69], v[176:179], v[222:225], v[66:69]
	v_mfma_f32_16x16x32_bf16 v[118:121], v[172:175], v[188:191], v[118:121]
	v_mfma_f32_16x16x32_bf16 v[114:117], v[180:183], v[188:191], v[114:117]
	v_mfma_f32_16x16x32_bf16 v[102:105], v[172:175], v[210:213], v[102:105]
	v_mfma_f32_16x16x32_bf16 v[98:101], v[180:183], v[210:213], v[98:101]
	v_mfma_f32_16x16x32_bf16 v[86:89], v[172:175], v[218:221], v[86:89]
	v_mfma_f32_16x16x32_bf16 v[82:85], v[180:183], v[218:221], v[82:85]
	v_mfma_f32_16x16x32_bf16 v[70:73], v[172:175], v[226:229], v[70:73]
	s_barrier
	v_mfma_f32_16x16x32_bf16 v[66:69], v[180:183], v[226:229], v[66:69]
	s_setprio 2
	s_add_i32 s19, s60, s33
	v_lshl_add_u64 v[144:145], s[34:35], 0, v[132:133]
	s_mov_b32 m0, s19
	ds_read_b128 v[184:187], v150 offset:16384
	ds_read_b128 v[188:191], v150 offset:17408
	ds_read_b128 v[198:201], v150 offset:18432
	ds_read_b128 v[210:213], v150 offset:19456
	ds_read_b128 v[214:217], v150 offset:20480
	ds_read_b128 v[218:221], v150 offset:21504
	ds_read_b128 v[222:225], v150 offset:22528
	ds_read_b128 v[226:229], v150 offset:23552
	global_load_lds_dwordx4 v132, s[34:35]
	s_add_i32 m0, s19, 0x2000
	s_add_u32 s38, s34, 0x80000
	v_lshl_add_u64 v[192:193], s[34:35], 0, v[136:137]
	s_addc_u32 s39, s35, 0
	s_add_i32 s19, s61, s33
	global_load_lds_dwordx4 v136, s[34:35]
	s_mov_b32 m0, s19
	v_lshl_add_u64 v[206:207], s[36:37], 0, v[134:135]
	global_load_lds_dwordx4 v132, s[38:39]
	s_add_i32 m0, s19, 0x2000
	s_nop 0
	global_load_lds_dwordx4 v136, s[38:39]
	v_lshl_add_u64 v[202:203], s[36:37], 0, v[130:131]
	s_mov_b32 m0, s27
	s_nop 0
	global_load_lds_dwordx4 v130, s[36:37]
	s_mov_b32 m0, s41
	s_nop 0
	global_load_lds_dwordx4 v134, s[36:37]
	s_waitcnt vmcnt(8)
	s_waitcnt lgkmcnt(0)
	s_barrier
	s_setprio 1
	s_waitcnt lgkmcnt(0)
	v_mfma_f32_16x16x32_bf16 v[62:65], v[152:155], v[184:187], v[62:65]
	v_mfma_f32_16x16x32_bf16 v[58:61], v[160:163], v[184:187], v[58:61]
	v_mfma_f32_16x16x32_bf16 v[46:49], v[152:155], v[198:201], v[46:49]
	v_mfma_f32_16x16x32_bf16 v[42:45], v[160:163], v[198:201], v[42:45]
	v_mfma_f32_16x16x32_bf16 v[30:33], v[152:155], v[214:217], v[30:33]
	v_mfma_f32_16x16x32_bf16 v[26:29], v[160:163], v[214:217], v[26:29]
	v_mfma_f32_16x16x32_bf16 v[14:17], v[152:155], v[222:225], v[14:17]
	v_mfma_f32_16x16x32_bf16 v[10:13], v[160:163], v[222:225], v[10:13]
	v_mfma_f32_16x16x32_bf16 v[62:65], v[156:159], v[188:191], v[62:65]
	v_mfma_f32_16x16x32_bf16 v[58:61], v[164:167], v[188:191], v[58:61]
	v_mfma_f32_16x16x32_bf16 v[46:49], v[156:159], v[210:213], v[46:49]
	v_mfma_f32_16x16x32_bf16 v[42:45], v[164:167], v[210:213], v[42:45]
	v_mfma_f32_16x16x32_bf16 v[30:33], v[156:159], v[218:221], v[30:33]
	v_mfma_f32_16x16x32_bf16 v[26:29], v[164:167], v[218:221], v[26:29]
	v_mfma_f32_16x16x32_bf16 v[14:17], v[156:159], v[226:229], v[14:17]
	v_mfma_f32_16x16x32_bf16 v[10:13], v[164:167], v[226:229], v[10:13]
	v_mfma_f32_16x16x32_bf16 v[54:57], v[168:171], v[184:187], v[54:57]
	v_mfma_f32_16x16x32_bf16 v[50:53], v[176:179], v[184:187], v[50:53]
	v_mfma_f32_16x16x32_bf16 v[38:41], v[168:171], v[198:201], v[38:41]
	v_mfma_f32_16x16x32_bf16 v[34:37], v[176:179], v[198:201], v[34:37]
	v_mfma_f32_16x16x32_bf16 v[22:25], v[168:171], v[214:217], v[22:25]
	v_mfma_f32_16x16x32_bf16 v[18:21], v[176:179], v[214:217], v[18:21]
	v_mfma_f32_16x16x32_bf16 v[6:9], v[168:171], v[222:225], v[6:9]
	v_mfma_f32_16x16x32_bf16 v[2:5], v[176:179], v[222:225], v[2:5]
	v_mfma_f32_16x16x32_bf16 v[54:57], v[172:175], v[188:191], v[54:57]
	v_mfma_f32_16x16x32_bf16 v[50:53], v[180:183], v[188:191], v[50:53]
	v_mfma_f32_16x16x32_bf16 v[38:41], v[172:175], v[210:213], v[38:41]
	v_mfma_f32_16x16x32_bf16 v[34:37], v[180:183], v[210:213], v[34:37]
	v_mfma_f32_16x16x32_bf16 v[22:25], v[172:175], v[218:221], v[22:25]
	v_mfma_f32_16x16x32_bf16 v[18:21], v[180:183], v[218:221], v[18:21]
	v_mfma_f32_16x16x32_bf16 v[6:9], v[172:175], v[226:229], v[6:9]
	s_barrier
	v_mfma_f32_16x16x32_bf16 v[2:5], v[180:183], v[226:229], v[2:5]
	s_setprio 2
	s_add_i32 s19, 0, 0x18000
	s_add_i32 s38, 0, 0x1c000
	ds_read_b128 v[152:155], v250
	ds_read_b128 v[156:159], v250 offset:1024
	ds_read_b128 v[160:163], v250 offset:2048
	ds_read_b128 v[164:167], v250 offset:3072
	ds_read_b128 v[168:171], v250 offset:16384
	ds_read_b128 v[172:175], v250 offset:17408
	ds_read_b128 v[176:179], v250 offset:18432
	ds_read_b128 v[180:183], v250 offset:19456
	v_add_u32_e32 v151, s38, v146
	s_add_u32 s36, s36, 0x80000
	s_addc_u32 s37, s37, 0
	s_mov_b32 m0, s42
	ds_read_b128 v[184:187], v150 offset:32768
	ds_read_b128 v[188:191], v150 offset:33792
	ds_read_b128 v[198:201], v150 offset:34816
	ds_read_b128 v[210:213], v150 offset:35840
	ds_read_b128 v[214:217], v150 offset:36864
	ds_read_b128 v[218:221], v150 offset:37888
	ds_read_b128 v[222:225], v150 offset:38912
	ds_read_b128 v[226:229], v150 offset:39936
	global_load_lds_dwordx4 v130, s[36:37]
	v_lshl_add_u64 v[230:231], s[36:37], 0, v[134:135]
	s_mov_b32 m0, s43
	s_nop 0
	global_load_lds_dwordx4 v134, s[36:37]
	s_waitcnt vmcnt(8)
	s_waitcnt lgkmcnt(0)
	s_barrier
	s_setprio 1
	s_waitcnt lgkmcnt(0)
	v_mfma_f32_16x16x32_bf16 v[126:129], v[152:155], v[184:187], v[126:129]
	v_mfma_f32_16x16x32_bf16 v[122:125], v[160:163], v[184:187], v[122:125]
	v_mfma_f32_16x16x32_bf16 v[110:113], v[152:155], v[198:201], v[110:113]
	v_mfma_f32_16x16x32_bf16 v[106:109], v[160:163], v[198:201], v[106:109]
	v_mfma_f32_16x16x32_bf16 v[94:97], v[152:155], v[214:217], v[94:97]
	v_mfma_f32_16x16x32_bf16 v[90:93], v[160:163], v[214:217], v[90:93]
	v_mfma_f32_16x16x32_bf16 v[78:81], v[152:155], v[222:225], v[78:81]
	v_mfma_f32_16x16x32_bf16 v[74:77], v[160:163], v[222:225], v[74:77]
	v_mfma_f32_16x16x32_bf16 v[126:129], v[156:159], v[188:191], v[126:129]
	v_mfma_f32_16x16x32_bf16 v[122:125], v[164:167], v[188:191], v[122:125]
	v_mfma_f32_16x16x32_bf16 v[110:113], v[156:159], v[210:213], v[110:113]
	v_mfma_f32_16x16x32_bf16 v[106:109], v[164:167], v[210:213], v[106:109]
	v_mfma_f32_16x16x32_bf16 v[94:97], v[156:159], v[218:221], v[94:97]
	v_mfma_f32_16x16x32_bf16 v[90:93], v[164:167], v[218:221], v[90:93]
	v_mfma_f32_16x16x32_bf16 v[78:81], v[156:159], v[226:229], v[78:81]
	v_mfma_f32_16x16x32_bf16 v[74:77], v[164:167], v[226:229], v[74:77]
	v_mfma_f32_16x16x32_bf16 v[118:121], v[168:171], v[184:187], v[118:121]
	v_mfma_f32_16x16x32_bf16 v[114:117], v[176:179], v[184:187], v[114:117]
	v_mfma_f32_16x16x32_bf16 v[102:105], v[168:171], v[198:201], v[102:105]
	v_mfma_f32_16x16x32_bf16 v[98:101], v[176:179], v[198:201], v[98:101]
	v_mfma_f32_16x16x32_bf16 v[86:89], v[168:171], v[214:217], v[86:89]
	v_mfma_f32_16x16x32_bf16 v[82:85], v[176:179], v[214:217], v[82:85]
	v_mfma_f32_16x16x32_bf16 v[70:73], v[168:171], v[222:225], v[70:73]
	v_mfma_f32_16x16x32_bf16 v[66:69], v[176:179], v[222:225], v[66:69]
	v_mfma_f32_16x16x32_bf16 v[118:121], v[172:175], v[188:191], v[118:121]
	v_mfma_f32_16x16x32_bf16 v[114:117], v[180:183], v[188:191], v[114:117]
	v_mfma_f32_16x16x32_bf16 v[102:105], v[172:175], v[210:213], v[102:105]
	v_mfma_f32_16x16x32_bf16 v[98:101], v[180:183], v[210:213], v[98:101]
	v_mfma_f32_16x16x32_bf16 v[86:89], v[172:175], v[218:221], v[86:89]
	v_mfma_f32_16x16x32_bf16 v[82:85], v[180:183], v[218:221], v[82:85]
	v_mfma_f32_16x16x32_bf16 v[70:73], v[172:175], v[226:229], v[70:73]
	s_barrier
	v_mfma_f32_16x16x32_bf16 v[66:69], v[180:183], v[226:229], v[66:69]
	s_setprio 2
	s_add_i32 s19, s19, s33
	v_lshl_add_u64 v[144:145], v[144:145], 0, s[10:11]
	s_mov_b32 m0, s19
	ds_read_b128 v[184:187], v150 offset:49152
	ds_read_b128 v[188:191], v150 offset:50176
	ds_read_b128 v[198:201], v150 offset:51200
	ds_read_b128 v[210:213], v150 offset:52224
	ds_read_b128 v[214:217], v150 offset:53248
	ds_read_b128 v[218:221], v150 offset:54272
	ds_read_b128 v[222:225], v150 offset:55296
	ds_read_b128 v[226:229], v150 offset:56320
	global_load_lds_dwordx4 v[144:145], off
	s_add_i32 m0, s19, 0x2000
	s_add_u32 s34, s34, 0x80080
	v_lshl_add_u64 v[144:145], v[192:193], 0, s[10:11]
	s_addc_u32 s35, s35, 0
	s_add_i32 s19, s38, s33
	global_load_lds_dwordx4 v[144:145], off
	s_mov_b32 m0, s19
	s_nop 0
	global_load_lds_dwordx4 v132, s[34:35]
	s_add_i32 m0, s19, 0x2000
	s_nop 0
	global_load_lds_dwordx4 v136, s[34:35]
	v_lshl_add_u64 v[144:145], v[202:203], 0, s[10:11]
	s_mov_b32 m0, s51
	s_nop 0
	global_load_lds_dwordx4 v[144:145], off
	v_lshl_add_u64 v[144:145], v[206:207], 0, s[10:11]
	s_mov_b32 m0, s52
	s_nop 0
	global_load_lds_dwordx4 v[144:145], off
	s_waitcnt vmcnt(8)
	s_waitcnt lgkmcnt(0)
	s_barrier
	s_setprio 1
	s_waitcnt lgkmcnt(0)
	v_mfma_f32_16x16x32_bf16 v[62:65], v[152:155], v[184:187], v[62:65]
	v_mfma_f32_16x16x32_bf16 v[58:61], v[160:163], v[184:187], v[58:61]
	v_mfma_f32_16x16x32_bf16 v[46:49], v[152:155], v[198:201], v[46:49]
	v_mfma_f32_16x16x32_bf16 v[42:45], v[160:163], v[198:201], v[42:45]
	v_mfma_f32_16x16x32_bf16 v[30:33], v[152:155], v[214:217], v[30:33]
	v_mfma_f32_16x16x32_bf16 v[26:29], v[160:163], v[214:217], v[26:29]
	v_mfma_f32_16x16x32_bf16 v[14:17], v[152:155], v[222:225], v[14:17]
	v_mfma_f32_16x16x32_bf16 v[10:13], v[160:163], v[222:225], v[10:13]
	v_mfma_f32_16x16x32_bf16 v[62:65], v[156:159], v[188:191], v[62:65]
	v_mfma_f32_16x16x32_bf16 v[58:61], v[164:167], v[188:191], v[58:61]
	v_mfma_f32_16x16x32_bf16 v[46:49], v[156:159], v[210:213], v[46:49]
	v_mfma_f32_16x16x32_bf16 v[42:45], v[164:167], v[210:213], v[42:45]
	v_mfma_f32_16x16x32_bf16 v[30:33], v[156:159], v[218:221], v[30:33]
	v_mfma_f32_16x16x32_bf16 v[26:29], v[164:167], v[218:221], v[26:29]
	v_mfma_f32_16x16x32_bf16 v[14:17], v[156:159], v[226:229], v[14:17]
	v_mfma_f32_16x16x32_bf16 v[10:13], v[164:167], v[226:229], v[10:13]
	v_mfma_f32_16x16x32_bf16 v[54:57], v[168:171], v[184:187], v[54:57]
	v_mfma_f32_16x16x32_bf16 v[50:53], v[176:179], v[184:187], v[50:53]
	v_mfma_f32_16x16x32_bf16 v[38:41], v[168:171], v[198:201], v[38:41]
	v_mfma_f32_16x16x32_bf16 v[34:37], v[176:179], v[198:201], v[34:37]
	v_mfma_f32_16x16x32_bf16 v[22:25], v[168:171], v[214:217], v[22:25]
	v_mfma_f32_16x16x32_bf16 v[18:21], v[176:179], v[214:217], v[18:21]
	v_mfma_f32_16x16x32_bf16 v[6:9], v[168:171], v[222:225], v[6:9]
	v_mfma_f32_16x16x32_bf16 v[2:5], v[176:179], v[222:225], v[2:5]
	v_mfma_f32_16x16x32_bf16 v[54:57], v[172:175], v[188:191], v[54:57]
	v_mfma_f32_16x16x32_bf16 v[50:53], v[180:183], v[188:191], v[50:53]
	v_mfma_f32_16x16x32_bf16 v[38:41], v[172:175], v[210:213], v[38:41]
	v_mfma_f32_16x16x32_bf16 v[34:37], v[180:183], v[210:213], v[34:37]
	v_mfma_f32_16x16x32_bf16 v[22:25], v[172:175], v[218:221], v[22:25]
	v_mfma_f32_16x16x32_bf16 v[18:21], v[180:183], v[218:221], v[18:21]
	v_mfma_f32_16x16x32_bf16 v[6:9], v[172:175], v[226:229], v[6:9]
	s_barrier
	v_mfma_f32_16x16x32_bf16 v[2:5], v[180:183], v[226:229], v[2:5]
	s_setprio 2
	s_add_u32 s30, s30, 0x100
	s_addc_u32 s31, s31, 0
	s_add_u32 s15, s15, 0x100
	s_addc_u32 s17, s17, 0
	s_cmp_ge_i32 s29, s68
	s_mov_b32 s19, s29
	s_cbranch_scc0 .LBB0_1315

.Lpeel_6:
	v_add_u32_e32 v250, 0x18000, v164
	ds_read_b128 v[144:147], v166
	ds_read_b128 v[148:151], v166 offset:1024
	ds_read_b128 v[152:155], v166 offset:2048
	ds_read_b128 v[156:159], v166 offset:3072
	ds_read_b128 v[160:163], v167
	ds_read_b128 v[170:173], v167 offset:1024
	ds_read_b128 v[174:177], v167 offset:2048
	ds_read_b128 v[178:181], v167 offset:3072
	s_add_i32 s30, s26, 2
	s_add_u32 s27, s24, 0xffea0080
	s_addc_u32 s28, s25, -1
	s_cmp_eq_u32 s22, s26
	s_cselect_b32 s26, s20, s17
	s_cselect_b32 s29, s19, s28
	s_cselect_b32 s28, s18, s27
	s_cselect_b32 s27, s21, s23
	s_add_i32 m0, s34, 0xc000
	ds_read_b128 v[182:185], v168
	ds_read_b128 v[186:189], v168 offset:1024
	ds_read_b128 v[190:193], v168 offset:2048
	ds_read_b128 v[198:201], v168 offset:3072
	ds_read_b128 v[210:213], v168 offset:4096
	ds_read_b128 v[214:217], v168 offset:5120
	ds_read_b128 v[218:221], v168 offset:6144
	ds_read_b128 v[222:225], v168 offset:7168
	global_load_lds_dwordx4 v140, s[24:25]
	s_add_i32 m0, s34, 0xe000
	s_nop 0
	global_load_lds_dwordx4 v142, s[24:25]
	s_waitcnt vmcnt(8)
	s_waitcnt lgkmcnt(0)
	s_barrier
	s_setprio 1
	s_waitcnt lgkmcnt(0)
	v_mfma_f32_16x16x32_bf16 v[126:129], v[144:147], v[182:185], 0
	v_mfma_f32_16x16x32_bf16 v[122:125], v[152:155], v[182:185], 0
	v_mfma_f32_16x16x32_bf16 v[114:117], v[144:147], v[190:193], 0
	v_mfma_f32_16x16x32_bf16 v[106:109], v[152:155], v[190:193], 0
	v_mfma_f32_16x16x32_bf16 v[94:97], v[144:147], v[210:213], 0
	v_mfma_f32_16x16x32_bf16 v[90:93], v[152:155], v[210:213], 0
	v_mfma_f32_16x16x32_bf16 v[78:81], v[144:147], v[218:221], 0
	v_mfma_f32_16x16x32_bf16 v[74:77], v[152:155], v[218:221], 0
	v_mfma_f32_16x16x32_bf16 v[126:129], v[148:151], v[186:189], v[126:129]
	v_mfma_f32_16x16x32_bf16 v[122:125], v[156:159], v[186:189], v[122:125]
	v_mfma_f32_16x16x32_bf16 v[114:117], v[148:151], v[198:201], v[114:117]
	v_mfma_f32_16x16x32_bf16 v[106:109], v[156:159], v[198:201], v[106:109]
	v_mfma_f32_16x16x32_bf16 v[94:97], v[148:151], v[214:217], v[94:97]
	v_mfma_f32_16x16x32_bf16 v[90:93], v[156:159], v[214:217], v[90:93]
	v_mfma_f32_16x16x32_bf16 v[78:81], v[148:151], v[222:225], v[78:81]
	v_mfma_f32_16x16x32_bf16 v[74:77], v[156:159], v[222:225], v[74:77]
	v_mfma_f32_16x16x32_bf16 v[118:121], v[160:163], v[182:185], 0
	v_mfma_f32_16x16x32_bf16 v[110:113], v[174:177], v[182:185], 0
	v_mfma_f32_16x16x32_bf16 v[102:105], v[160:163], v[190:193], 0
	v_mfma_f32_16x16x32_bf16 v[98:101], v[174:177], v[190:193], 0
	v_mfma_f32_16x16x32_bf16 v[86:89], v[160:163], v[210:213], 0
	v_mfma_f32_16x16x32_bf16 v[82:85], v[174:177], v[210:213], 0
	v_mfma_f32_16x16x32_bf16 v[70:73], v[160:163], v[218:221], 0
	v_mfma_f32_16x16x32_bf16 v[66:69], v[174:177], v[218:221], 0
	v_mfma_f32_16x16x32_bf16 v[118:121], v[170:173], v[186:189], v[118:121]
	v_mfma_f32_16x16x32_bf16 v[110:113], v[178:181], v[186:189], v[110:113]
	v_mfma_f32_16x16x32_bf16 v[102:105], v[170:173], v[198:201], v[102:105]
	v_mfma_f32_16x16x32_bf16 v[98:101], v[178:181], v[198:201], v[98:101]
	v_mfma_f32_16x16x32_bf16 v[86:89], v[170:173], v[214:217], v[86:89]
	v_mfma_f32_16x16x32_bf16 v[82:85], v[178:181], v[214:217], v[82:85]
	v_mfma_f32_16x16x32_bf16 v[70:73], v[170:173], v[222:225], v[70:73]
	s_barrier
	v_mfma_f32_16x16x32_bf16 v[66:69], v[178:181], v[222:225], v[66:69]
	s_setprio 2
	s_add_i32 s31, s57, s33
	v_lshl_add_u64 v[202:203], s[26:27], 0, v[132:133]
	s_mov_b32 m0, s31
	ds_read_b128 v[182:185], v168 offset:16384
	ds_read_b128 v[186:189], v168 offset:17408
	ds_read_b128 v[190:193], v168 offset:18432
	ds_read_b128 v[198:201], v168 offset:19456
	ds_read_b128 v[210:213], v168 offset:20480
	ds_read_b128 v[214:217], v168 offset:21504
	ds_read_b128 v[218:221], v168 offset:22528
	ds_read_b128 v[222:225], v168 offset:23552
	global_load_lds_dwordx4 v132, s[26:27]
	s_add_i32 m0, s31, 0x2000
	s_add_u32 s68, s26, 0x160000
	v_lshl_add_u64 v[206:207], s[26:27], 0, v[136:137]
	s_addc_u32 s69, s27, 0
	s_add_i32 s31, s58, s33
	global_load_lds_dwordx4 v136, s[26:27]
	s_mov_b32 m0, s31
	v_lshl_add_u64 v[228:229], s[28:29], 0, v[134:135]
	global_load_lds_dwordx4 v132, s[68:69]
	s_add_i32 m0, s31, 0x2000
	s_nop 0
	global_load_lds_dwordx4 v136, s[68:69]
	v_lshl_add_u64 v[226:227], s[28:29], 0, v[130:131]
	s_mov_b32 m0, s34
	s_nop 0
	global_load_lds_dwordx4 v130, s[28:29]
	s_mov_b32 m0, s35
	s_nop 0
	global_load_lds_dwordx4 v134, s[28:29]
	s_waitcnt vmcnt(8)
	s_waitcnt lgkmcnt(0)
	s_barrier
	s_setprio 1
	s_waitcnt lgkmcnt(0)
	v_mfma_f32_16x16x32_bf16 v[62:65], v[144:147], v[182:185], 0
	v_mfma_f32_16x16x32_bf16 v[58:61], v[152:155], v[182:185], 0
	v_mfma_f32_16x16x32_bf16 v[46:49], v[144:147], v[190:193], 0
	v_mfma_f32_16x16x32_bf16 v[42:45], v[152:155], v[190:193], 0
	v_mfma_f32_16x16x32_bf16 v[30:33], v[144:147], v[210:213], 0
	v_mfma_f32_16x16x32_bf16 v[26:29], v[152:155], v[210:213], 0
	v_mfma_f32_16x16x32_bf16 v[14:17], v[144:147], v[218:221], 0
	v_mfma_f32_16x16x32_bf16 v[10:13], v[152:155], v[218:221], 0
	v_mfma_f32_16x16x32_bf16 v[62:65], v[148:151], v[186:189], v[62:65]
	v_mfma_f32_16x16x32_bf16 v[58:61], v[156:159], v[186:189], v[58:61]
	v_mfma_f32_16x16x32_bf16 v[46:49], v[148:151], v[198:201], v[46:49]
	v_mfma_f32_16x16x32_bf16 v[42:45], v[156:159], v[198:201], v[42:45]
	v_mfma_f32_16x16x32_bf16 v[30:33], v[148:151], v[214:217], v[30:33]
	v_mfma_f32_16x16x32_bf16 v[26:29], v[156:159], v[214:217], v[26:29]
	v_mfma_f32_16x16x32_bf16 v[14:17], v[148:151], v[222:225], v[14:17]
	v_mfma_f32_16x16x32_bf16 v[10:13], v[156:159], v[222:225], v[10:13]
	v_mfma_f32_16x16x32_bf16 v[54:57], v[160:163], v[182:185], 0
	v_mfma_f32_16x16x32_bf16 v[50:53], v[174:177], v[182:185], 0
	v_mfma_f32_16x16x32_bf16 v[38:41], v[160:163], v[190:193], 0
	v_mfma_f32_16x16x32_bf16 v[34:37], v[174:177], v[190:193], 0
	v_mfma_f32_16x16x32_bf16 v[22:25], v[160:163], v[210:213], 0
	v_mfma_f32_16x16x32_bf16 v[18:21], v[174:177], v[210:213], 0
	v_mfma_f32_16x16x32_bf16 v[6:9], v[160:163], v[218:221], 0
	v_mfma_f32_16x16x32_bf16 v[2:5], v[174:177], v[218:221], 0
	v_mfma_f32_16x16x32_bf16 v[54:57], v[170:173], v[186:189], v[54:57]
	v_mfma_f32_16x16x32_bf16 v[50:53], v[178:181], v[186:189], v[50:53]
	v_mfma_f32_16x16x32_bf16 v[38:41], v[170:173], v[198:201], v[38:41]
	v_mfma_f32_16x16x32_bf16 v[34:37], v[178:181], v[198:201], v[34:37]
	v_mfma_f32_16x16x32_bf16 v[22:25], v[170:173], v[214:217], v[22:25]
	v_mfma_f32_16x16x32_bf16 v[18:21], v[178:181], v[214:217], v[18:21]
	v_mfma_f32_16x16x32_bf16 v[6:9], v[170:173], v[222:225], v[6:9]
	s_barrier
	v_mfma_f32_16x16x32_bf16 v[2:5], v[178:181], v[222:225], v[2:5]
	s_setprio 2
	s_add_i32 s31, 0, 0x18000
	s_add_i32 s68, 0, 0x1c000
	ds_read_b128 v[144:147], v250
	ds_read_b128 v[148:151], v250 offset:1024
	ds_read_b128 v[152:155], v250 offset:2048
	ds_read_b128 v[156:159], v250 offset:3072
	ds_read_b128 v[160:163], v250 offset:16384
	ds_read_b128 v[170:173], v250 offset:17408
	ds_read_b128 v[174:177], v250 offset:18432
	ds_read_b128 v[178:181], v250 offset:19456
	v_add_u32_e32 v169, s68, v164
	s_add_u32 s28, s28, 0x160000
	s_addc_u32 s29, s29, 0
	s_mov_b32 m0, s36
	ds_read_b128 v[182:185], v168 offset:32768
	ds_read_b128 v[186:189], v168 offset:33792
	ds_read_b128 v[190:193], v168 offset:34816
	ds_read_b128 v[198:201], v168 offset:35840
	ds_read_b128 v[210:213], v168 offset:36864
	ds_read_b128 v[214:217], v168 offset:37888
	ds_read_b128 v[218:221], v168 offset:38912
	ds_read_b128 v[222:225], v168 offset:39936
	global_load_lds_dwordx4 v130, s[28:29]
	v_lshl_add_u64 v[230:231], s[28:29], 0, v[134:135]
	s_mov_b32 m0, s37
	s_nop 0
	global_load_lds_dwordx4 v134, s[28:29]
	s_waitcnt vmcnt(8)
	s_waitcnt lgkmcnt(0)
	s_barrier
	s_setprio 1
	s_waitcnt lgkmcnt(0)
	v_mfma_f32_16x16x32_bf16 v[126:129], v[144:147], v[182:185], v[126:129]
	v_mfma_f32_16x16x32_bf16 v[122:125], v[152:155], v[182:185], v[122:125]
	v_mfma_f32_16x16x32_bf16 v[114:117], v[144:147], v[190:193], v[114:117]
	v_mfma_f32_16x16x32_bf16 v[106:109], v[152:155], v[190:193], v[106:109]
	v_mfma_f32_16x16x32_bf16 v[94:97], v[144:147], v[210:213], v[94:97]
	v_mfma_f32_16x16x32_bf16 v[90:93], v[152:155], v[210:213], v[90:93]
	v_mfma_f32_16x16x32_bf16 v[78:81], v[144:147], v[218:221], v[78:81]
	v_mfma_f32_16x16x32_bf16 v[74:77], v[152:155], v[218:221], v[74:77]
	v_mfma_f32_16x16x32_bf16 v[126:129], v[148:151], v[186:189], v[126:129]
	v_mfma_f32_16x16x32_bf16 v[122:125], v[156:159], v[186:189], v[122:125]
	v_mfma_f32_16x16x32_bf16 v[114:117], v[148:151], v[198:201], v[114:117]
	v_mfma_f32_16x16x32_bf16 v[106:109], v[156:159], v[198:201], v[106:109]
	v_mfma_f32_16x16x32_bf16 v[94:97], v[148:151], v[214:217], v[94:97]
	v_mfma_f32_16x16x32_bf16 v[90:93], v[156:159], v[214:217], v[90:93]
	v_mfma_f32_16x16x32_bf16 v[78:81], v[148:151], v[222:225], v[78:81]
	v_mfma_f32_16x16x32_bf16 v[74:77], v[156:159], v[222:225], v[74:77]
	v_mfma_f32_16x16x32_bf16 v[118:121], v[160:163], v[182:185], v[118:121]
	v_mfma_f32_16x16x32_bf16 v[110:113], v[174:177], v[182:185], v[110:113]
	v_mfma_f32_16x16x32_bf16 v[102:105], v[160:163], v[190:193], v[102:105]
	v_mfma_f32_16x16x32_bf16 v[98:101], v[174:177], v[190:193], v[98:101]
	v_mfma_f32_16x16x32_bf16 v[86:89], v[160:163], v[210:213], v[86:89]
	v_mfma_f32_16x16x32_bf16 v[82:85], v[174:177], v[210:213], v[82:85]
	v_mfma_f32_16x16x32_bf16 v[70:73], v[160:163], v[218:221], v[70:73]
	v_mfma_f32_16x16x32_bf16 v[66:69], v[174:177], v[218:221], v[66:69]
	v_mfma_f32_16x16x32_bf16 v[118:121], v[170:173], v[186:189], v[118:121]
	v_mfma_f32_16x16x32_bf16 v[110:113], v[178:181], v[186:189], v[110:113]
	v_mfma_f32_16x16x32_bf16 v[102:105], v[170:173], v[198:201], v[102:105]
	v_mfma_f32_16x16x32_bf16 v[98:101], v[178:181], v[198:201], v[98:101]
	v_mfma_f32_16x16x32_bf16 v[86:89], v[170:173], v[214:217], v[86:89]
	v_mfma_f32_16x16x32_bf16 v[82:85], v[178:181], v[214:217], v[82:85]
	v_mfma_f32_16x16x32_bf16 v[70:73], v[170:173], v[222:225], v[70:73]
	s_barrier
	v_mfma_f32_16x16x32_bf16 v[66:69], v[178:181], v[222:225], v[66:69]
	s_setprio 2
	s_add_i32 s28, s31, s33
	v_lshl_add_u64 v[202:203], v[202:203], 0, s[12:13]
	s_mov_b32 m0, s28
	ds_read_b128 v[182:185], v168 offset:49152
	ds_read_b128 v[186:189], v168 offset:50176
	ds_read_b128 v[190:193], v168 offset:51200
	ds_read_b128 v[198:201], v168 offset:52224
	ds_read_b128 v[210:213], v168 offset:53248
	ds_read_b128 v[214:217], v168 offset:54272
	ds_read_b128 v[218:221], v168 offset:55296
	ds_read_b128 v[222:225], v168 offset:56320
	global_load_lds_dwordx4 v[202:203], off
	s_add_i32 m0, s28, 0x2000
	s_add_u32 s26, s26, 0x160080
	v_lshl_add_u64 v[202:203], v[206:207], 0, s[12:13]
	s_addc_u32 s27, s27, 0
	s_add_i32 s28, s68, s33
	global_load_lds_dwordx4 v[202:203], off
	s_mov_b32 m0, s28
	s_nop 0
	global_load_lds_dwordx4 v132, s[26:27]
	s_add_i32 m0, s28, 0x2000
	s_nop 0
	global_load_lds_dwordx4 v136, s[26:27]
	v_lshl_add_u64 v[202:203], v[226:227], 0, s[12:13]
	s_mov_b32 m0, s47
	s_nop 0
	global_load_lds_dwordx4 v[202:203], off
	v_lshl_add_u64 v[202:203], v[228:229], 0, s[12:13]
	s_mov_b32 m0, s48
	s_nop 0
	global_load_lds_dwordx4 v[202:203], off
	s_waitcnt vmcnt(8)
	s_waitcnt lgkmcnt(0)
	s_barrier
	s_setprio 1
	s_waitcnt lgkmcnt(0)
	v_mfma_f32_16x16x32_bf16 v[62:65], v[144:147], v[182:185], v[62:65]
	v_mfma_f32_16x16x32_bf16 v[58:61], v[152:155], v[182:185], v[58:61]
	v_mfma_f32_16x16x32_bf16 v[46:49], v[144:147], v[190:193], v[46:49]
	v_mfma_f32_16x16x32_bf16 v[42:45], v[152:155], v[190:193], v[42:45]
	v_mfma_f32_16x16x32_bf16 v[30:33], v[144:147], v[210:213], v[30:33]
	v_mfma_f32_16x16x32_bf16 v[26:29], v[152:155], v[210:213], v[26:29]
	v_mfma_f32_16x16x32_bf16 v[14:17], v[144:147], v[218:221], v[14:17]
	v_mfma_f32_16x16x32_bf16 v[10:13], v[152:155], v[218:221], v[10:13]
	v_mfma_f32_16x16x32_bf16 v[62:65], v[148:151], v[186:189], v[62:65]
	v_mfma_f32_16x16x32_bf16 v[58:61], v[156:159], v[186:189], v[58:61]
	v_mfma_f32_16x16x32_bf16 v[46:49], v[148:151], v[198:201], v[46:49]
	v_mfma_f32_16x16x32_bf16 v[42:45], v[156:159], v[198:201], v[42:45]
	v_mfma_f32_16x16x32_bf16 v[30:33], v[148:151], v[214:217], v[30:33]
	v_mfma_f32_16x16x32_bf16 v[26:29], v[156:159], v[214:217], v[26:29]
	v_mfma_f32_16x16x32_bf16 v[14:17], v[148:151], v[222:225], v[14:17]
	v_mfma_f32_16x16x32_bf16 v[10:13], v[156:159], v[222:225], v[10:13]
	v_mfma_f32_16x16x32_bf16 v[54:57], v[160:163], v[182:185], v[54:57]
	v_mfma_f32_16x16x32_bf16 v[50:53], v[174:177], v[182:185], v[50:53]
	v_mfma_f32_16x16x32_bf16 v[38:41], v[160:163], v[190:193], v[38:41]
	v_mfma_f32_16x16x32_bf16 v[34:37], v[174:177], v[190:193], v[34:37]
	v_mfma_f32_16x16x32_bf16 v[22:25], v[160:163], v[210:213], v[22:25]
	v_mfma_f32_16x16x32_bf16 v[18:21], v[174:177], v[210:213], v[18:21]
	v_mfma_f32_16x16x32_bf16 v[6:9], v[160:163], v[218:221], v[6:9]
	v_mfma_f32_16x16x32_bf16 v[2:5], v[174:177], v[218:221], v[2:5]
	v_mfma_f32_16x16x32_bf16 v[54:57], v[170:173], v[186:189], v[54:57]
	v_mfma_f32_16x16x32_bf16 v[50:53], v[178:181], v[186:189], v[50:53]
	v_mfma_f32_16x16x32_bf16 v[38:41], v[170:173], v[198:201], v[38:41]
	v_mfma_f32_16x16x32_bf16 v[34:37], v[178:181], v[198:201], v[34:37]
	v_mfma_f32_16x16x32_bf16 v[22:25], v[170:173], v[214:217], v[22:25]
	v_mfma_f32_16x16x32_bf16 v[18:21], v[178:181], v[214:217], v[18:21]
	v_mfma_f32_16x16x32_bf16 v[6:9], v[170:173], v[222:225], v[6:9]
	s_barrier
	v_mfma_f32_16x16x32_bf16 v[2:5], v[178:181], v[222:225], v[2:5]
	s_setprio 2
	s_add_u32 s24, s24, 0x100
	s_addc_u32 s25, s25, 0
	s_add_u32 s17, s17, 0x100
	s_addc_u32 s23, s23, 0
	s_cmp_ge_i32 s30, s67
	s_mov_b32 s26, s30
	s_cbranch_scc0 .LBB0_1451
	s_branch .Lpeeldone_6
.LBB0_1451:
	ds_read_b128 v[144:147], v166
	ds_read_b128 v[148:151], v166 offset:1024
	ds_read_b128 v[152:155], v166 offset:2048
	ds_read_b128 v[156:159], v166 offset:3072
	ds_read_b128 v[160:163], v167
	ds_read_b128 v[170:173], v167 offset:1024
	ds_read_b128 v[174:177], v167 offset:2048
	ds_read_b128 v[178:181], v167 offset:3072
	s_add_i32 s30, s26, 2
	s_add_u32 s27, s24, 0xffea0080
	s_addc_u32 s28, s25, -1
	s_cmp_eq_u32 s22, s26
	s_cselect_b32 s26, s20, s17
	s_cselect_b32 s29, s19, s28
	s_cselect_b32 s28, s18, s27
	s_cselect_b32 s27, s21, s23
	s_add_i32 m0, s34, 0xc000
	ds_read_b128 v[182:185], v168
	ds_read_b128 v[186:189], v168 offset:1024
	ds_read_b128 v[190:193], v168 offset:2048
	ds_read_b128 v[198:201], v168 offset:3072
	ds_read_b128 v[210:213], v168 offset:4096
	ds_read_b128 v[214:217], v168 offset:5120
	ds_read_b128 v[218:221], v168 offset:6144
	ds_read_b128 v[222:225], v168 offset:7168
	global_load_lds_dwordx4 v140, s[24:25]
	s_add_i32 m0, s34, 0xe000
	s_nop 0
	global_load_lds_dwordx4 v142, s[24:25]
	s_waitcnt vmcnt(8)
	s_waitcnt lgkmcnt(0)
	s_barrier
	s_setprio 1
	s_waitcnt lgkmcnt(0)
	v_mfma_f32_16x16x32_bf16 v[126:129], v[144:147], v[182:185], v[126:129]
	v_mfma_f32_16x16x32_bf16 v[122:125], v[152:155], v[182:185], v[122:125]
	v_mfma_f32_16x16x32_bf16 v[114:117], v[144:147], v[190:193], v[114:117]
	v_mfma_f32_16x16x32_bf16 v[106:109], v[152:155], v[190:193], v[106:109]
	v_mfma_f32_16x16x32_bf16 v[94:97], v[144:147], v[210:213], v[94:97]
	v_mfma_f32_16x16x32_bf16 v[90:93], v[152:155], v[210:213], v[90:93]
	v_mfma_f32_16x16x32_bf16 v[78:81], v[144:147], v[218:221], v[78:81]
	v_mfma_f32_16x16x32_bf16 v[74:77], v[152:155], v[218:221], v[74:77]
	v_mfma_f32_16x16x32_bf16 v[126:129], v[148:151], v[186:189], v[126:129]
	v_mfma_f32_16x16x32_bf16 v[122:125], v[156:159], v[186:189], v[122:125]
	v_mfma_f32_16x16x32_bf16 v[114:117], v[148:151], v[198:201], v[114:117]
	v_mfma_f32_16x16x32_bf16 v[106:109], v[156:159], v[198:201], v[106:109]
	v_mfma_f32_16x16x32_bf16 v[94:97], v[148:151], v[214:217], v[94:97]
	v_mfma_f32_16x16x32_bf16 v[90:93], v[156:159], v[214:217], v[90:93]
	v_mfma_f32_16x16x32_bf16 v[78:81], v[148:151], v[222:225], v[78:81]
	v_mfma_f32_16x16x32_bf16 v[74:77], v[156:159], v[222:225], v[74:77]
	v_mfma_f32_16x16x32_bf16 v[118:121], v[160:163], v[182:185], v[118:121]
	v_mfma_f32_16x16x32_bf16 v[110:113], v[174:177], v[182:185], v[110:113]
	v_mfma_f32_16x16x32_bf16 v[102:105], v[160:163], v[190:193], v[102:105]
	v_mfma_f32_16x16x32_bf16 v[98:101], v[174:177], v[190:193], v[98:101]
	v_mfma_f32_16x16x32_bf16 v[86:89], v[160:163], v[210:213], v[86:89]
	v_mfma_f32_16x16x32_bf16 v[82:85], v[174:177], v[210:213], v[82:85]
	v_mfma_f32_16x16x32_bf16 v[70:73], v[160:163], v[218:221], v[70:73]
	v_mfma_f32_16x16x32_bf16 v[66:69], v[174:177], v[218:221], v[66:69]
	v_mfma_f32_16x16x32_bf16 v[118:121], v[170:173], v[186:189], v[118:121]
	v_mfma_f32_16x16x32_bf16 v[110:113], v[178:181], v[186:189], v[110:113]
	v_mfma_f32_16x16x32_bf16 v[102:105], v[170:173], v[198:201], v[102:105]
	v_mfma_f32_16x16x32_bf16 v[98:101], v[178:181], v[198:201], v[98:101]
	v_mfma_f32_16x16x32_bf16 v[86:89], v[170:173], v[214:217], v[86:89]
	v_mfma_f32_16x16x32_bf16 v[82:85], v[178:181], v[214:217], v[82:85]
	v_mfma_f32_16x16x32_bf16 v[70:73], v[170:173], v[222:225], v[70:73]
	s_barrier
	v_mfma_f32_16x16x32_bf16 v[66:69], v[178:181], v[222:225], v[66:69]
	s_setprio 2
	s_add_i32 s31, s57, s33
	v_lshl_add_u64 v[202:203], s[26:27], 0, v[132:133]
	s_mov_b32 m0, s31
	ds_read_b128 v[182:185], v168 offset:16384
	ds_read_b128 v[186:189], v168 offset:17408
	ds_read_b128 v[190:193], v168 offset:18432
	ds_read_b128 v[198:201], v168 offset:19456
	ds_read_b128 v[210:213], v168 offset:20480
	ds_read_b128 v[214:217], v168 offset:21504
	ds_read_b128 v[218:221], v168 offset:22528
	ds_read_b128 v[222:225], v168 offset:23552
	global_load_lds_dwordx4 v132, s[26:27]
	s_add_i32 m0, s31, 0x2000
	s_add_u32 s68, s26, 0x160000
	v_lshl_add_u64 v[206:207], s[26:27], 0, v[136:137]
	s_addc_u32 s69, s27, 0
	s_add_i32 s31, s58, s33
	global_load_lds_dwordx4 v136, s[26:27]
	s_mov_b32 m0, s31
	v_lshl_add_u64 v[228:229], s[28:29], 0, v[134:135]
	global_load_lds_dwordx4 v132, s[68:69]
	s_add_i32 m0, s31, 0x2000
	s_nop 0
	global_load_lds_dwordx4 v136, s[68:69]
	v_lshl_add_u64 v[226:227], s[28:29], 0, v[130:131]
	s_mov_b32 m0, s34
	s_nop 0
	global_load_lds_dwordx4 v130, s[28:29]
	s_mov_b32 m0, s35
	s_nop 0
	global_load_lds_dwordx4 v134, s[28:29]
	s_waitcnt vmcnt(8)
	s_waitcnt lgkmcnt(0)
	s_barrier
	s_setprio 1
	s_waitcnt lgkmcnt(0)
	v_mfma_f32_16x16x32_bf16 v[62:65], v[144:147], v[182:185], v[62:65]
	v_mfma_f32_16x16x32_bf16 v[58:61], v[152:155], v[182:185], v[58:61]
	v_mfma_f32_16x16x32_bf16 v[46:49], v[144:147], v[190:193], v[46:49]
	v_mfma_f32_16x16x32_bf16 v[42:45], v[152:155], v[190:193], v[42:45]
	v_mfma_f32_16x16x32_bf16 v[30:33], v[144:147], v[210:213], v[30:33]
	v_mfma_f32_16x16x32_bf16 v[26:29], v[152:155], v[210:213], v[26:29]
	v_mfma_f32_16x16x32_bf16 v[14:17], v[144:147], v[218:221], v[14:17]
	v_mfma_f32_16x16x32_bf16 v[10:13], v[152:155], v[218:221], v[10:13]
	v_mfma_f32_16x16x32_bf16 v[62:65], v[148:151], v[186:189], v[62:65]
	v_mfma_f32_16x16x32_bf16 v[58:61], v[156:159], v[186:189], v[58:61]
	v_mfma_f32_16x16x32_bf16 v[46:49], v[148:151], v[198:201], v[46:49]
	v_mfma_f32_16x16x32_bf16 v[42:45], v[156:159], v[198:201], v[42:45]
	v_mfma_f32_16x16x32_bf16 v[30:33], v[148:151], v[214:217], v[30:33]
	v_mfma_f32_16x16x32_bf16 v[26:29], v[156:159], v[214:217], v[26:29]
	v_mfma_f32_16x16x32_bf16 v[14:17], v[148:151], v[222:225], v[14:17]
	v_mfma_f32_16x16x32_bf16 v[10:13], v[156:159], v[222:225], v[10:13]
	v_mfma_f32_16x16x32_bf16 v[54:57], v[160:163], v[182:185], v[54:57]
	v_mfma_f32_16x16x32_bf16 v[50:53], v[174:177], v[182:185], v[50:53]
	v_mfma_f32_16x16x32_bf16 v[38:41], v[160:163], v[190:193], v[38:41]
	v_mfma_f32_16x16x32_bf16 v[34:37], v[174:177], v[190:193], v[34:37]
	v_mfma_f32_16x16x32_bf16 v[22:25], v[160:163], v[210:213], v[22:25]
	v_mfma_f32_16x16x32_bf16 v[18:21], v[174:177], v[210:213], v[18:21]
	v_mfma_f32_16x16x32_bf16 v[6:9], v[160:163], v[218:221], v[6:9]
	v_mfma_f32_16x16x32_bf16 v[2:5], v[174:177], v[218:221], v[2:5]
	v_mfma_f32_16x16x32_bf16 v[54:57], v[170:173], v[186:189], v[54:57]
	v_mfma_f32_16x16x32_bf16 v[50:53], v[178:181], v[186:189], v[50:53]
	v_mfma_f32_16x16x32_bf16 v[38:41], v[170:173], v[198:201], v[38:41]
	v_mfma_f32_16x16x32_bf16 v[34:37], v[178:181], v[198:201], v[34:37]
	v_mfma_f32_16x16x32_bf16 v[22:25], v[170:173], v[214:217], v[22:25]
	v_mfma_f32_16x16x32_bf16 v[18:21], v[178:181], v[214:217], v[18:21]
	v_mfma_f32_16x16x32_bf16 v[6:9], v[170:173], v[222:225], v[6:9]
	s_barrier
	v_mfma_f32_16x16x32_bf16 v[2:5], v[178:181], v[222:225], v[2:5]
	s_setprio 2
	s_add_i32 s31, 0, 0x18000
	s_add_i32 s68, 0, 0x1c000
	ds_read_b128 v[144:147], v250
	ds_read_b128 v[148:151], v250 offset:1024
	ds_read_b128 v[152:155], v250 offset:2048
	ds_read_b128 v[156:159], v250 offset:3072
	ds_read_b128 v[160:163], v250 offset:16384
	ds_read_b128 v[170:173], v250 offset:17408
	ds_read_b128 v[174:177], v250 offset:18432
	ds_read_b128 v[178:181], v250 offset:19456
	v_add_u32_e32 v169, s68, v164
	s_add_u32 s28, s28, 0x160000
	s_addc_u32 s29, s29, 0
	s_mov_b32 m0, s36
	ds_read_b128 v[182:185], v168 offset:32768
	ds_read_b128 v[186:189], v168 offset:33792
	ds_read_b128 v[190:193], v168 offset:34816
	ds_read_b128 v[198:201], v168 offset:35840
	ds_read_b128 v[210:213], v168 offset:36864
	ds_read_b128 v[214:217], v168 offset:37888
	ds_read_b128 v[218:221], v168 offset:38912
	ds_read_b128 v[222:225], v168 offset:39936
	global_load_lds_dwordx4 v130, s[28:29]
	v_lshl_add_u64 v[230:231], s[28:29], 0, v[134:135]
	s_mov_b32 m0, s37
	s_nop 0
	global_load_lds_dwordx4 v134, s[28:29]
	s_waitcnt vmcnt(8)
	s_waitcnt lgkmcnt(0)
	s_barrier
	s_setprio 1
	s_waitcnt lgkmcnt(0)
	v_mfma_f32_16x16x32_bf16 v[126:129], v[144:147], v[182:185], v[126:129]
	v_mfma_f32_16x16x32_bf16 v[122:125], v[152:155], v[182:185], v[122:125]
	v_mfma_f32_16x16x32_bf16 v[114:117], v[144:147], v[190:193], v[114:117]
	v_mfma_f32_16x16x32_bf16 v[106:109], v[152:155], v[190:193], v[106:109]
	v_mfma_f32_16x16x32_bf16 v[94:97], v[144:147], v[210:213], v[94:97]
	v_mfma_f32_16x16x32_bf16 v[90:93], v[152:155], v[210:213], v[90:93]
	v_mfma_f32_16x16x32_bf16 v[78:81], v[144:147], v[218:221], v[78:81]
	v_mfma_f32_16x16x32_bf16 v[74:77], v[152:155], v[218:221], v[74:77]
	v_mfma_f32_16x16x32_bf16 v[126:129], v[148:151], v[186:189], v[126:129]
	v_mfma_f32_16x16x32_bf16 v[122:125], v[156:159], v[186:189], v[122:125]
	v_mfma_f32_16x16x32_bf16 v[114:117], v[148:151], v[198:201], v[114:117]
	v_mfma_f32_16x16x32_bf16 v[106:109], v[156:159], v[198:201], v[106:109]
	v_mfma_f32_16x16x32_bf16 v[94:97], v[148:151], v[214:217], v[94:97]
	v_mfma_f32_16x16x32_bf16 v[90:93], v[156:159], v[214:217], v[90:93]
	v_mfma_f32_16x16x32_bf16 v[78:81], v[148:151], v[222:225], v[78:81]
	v_mfma_f32_16x16x32_bf16 v[74:77], v[156:159], v[222:225], v[74:77]
	v_mfma_f32_16x16x32_bf16 v[118:121], v[160:163], v[182:185], v[118:121]
	v_mfma_f32_16x16x32_bf16 v[110:113], v[174:177], v[182:185], v[110:113]
	v_mfma_f32_16x16x32_bf16 v[102:105], v[160:163], v[190:193], v[102:105]
	v_mfma_f32_16x16x32_bf16 v[98:101], v[174:177], v[190:193], v[98:101]
	v_mfma_f32_16x16x32_bf16 v[86:89], v[160:163], v[210:213], v[86:89]
	v_mfma_f32_16x16x32_bf16 v[82:85], v[174:177], v[210:213], v[82:85]
	v_mfma_f32_16x16x32_bf16 v[70:73], v[160:163], v[218:221], v[70:73]
	v_mfma_f32_16x16x32_bf16 v[66:69], v[174:177], v[218:221], v[66:69]
	v_mfma_f32_16x16x32_bf16 v[118:121], v[170:173], v[186:189], v[118:121]
	v_mfma_f32_16x16x32_bf16 v[110:113], v[178:181], v[186:189], v[110:113]
	v_mfma_f32_16x16x32_bf16 v[102:105], v[170:173], v[198:201], v[102:105]
	v_mfma_f32_16x16x32_bf16 v[98:101], v[178:181], v[198:201], v[98:101]
	v_mfma_f32_16x16x32_bf16 v[86:89], v[170:173], v[214:217], v[86:89]
	v_mfma_f32_16x16x32_bf16 v[82:85], v[178:181], v[214:217], v[82:85]
	v_mfma_f32_16x16x32_bf16 v[70:73], v[170:173], v[222:225], v[70:73]
	s_barrier
	v_mfma_f32_16x16x32_bf16 v[66:69], v[178:181], v[222:225], v[66:69]
	s_setprio 2
	s_add_i32 s28, s31, s33
	v_lshl_add_u64 v[202:203], v[202:203], 0, s[12:13]
	s_mov_b32 m0, s28
	ds_read_b128 v[182:185], v168 offset:49152
	ds_read_b128 v[186:189], v168 offset:50176
	ds_read_b128 v[190:193], v168 offset:51200
	ds_read_b128 v[198:201], v168 offset:52224
	ds_read_b128 v[210:213], v168 offset:53248
	ds_read_b128 v[214:217], v168 offset:54272
	ds_read_b128 v[218:221], v168 offset:55296
	ds_read_b128 v[222:225], v168 offset:56320
	global_load_lds_dwordx4 v[202:203], off
	s_add_i32 m0, s28, 0x2000
	s_add_u32 s26, s26, 0x160080
	v_lshl_add_u64 v[202:203], v[206:207], 0, s[12:13]
	s_addc_u32 s27, s27, 0
	s_add_i32 s28, s68, s33
	global_load_lds_dwordx4 v[202:203], off
	s_mov_b32 m0, s28
	s_nop 0
	global_load_lds_dwordx4 v132, s[26:27]
	s_add_i32 m0, s28, 0x2000
	s_nop 0
	global_load_lds_dwordx4 v136, s[26:27]
	v_lshl_add_u64 v[202:203], v[226:227], 0, s[12:13]
	s_mov_b32 m0, s47
	s_nop 0
	global_load_lds_dwordx4 v[202:203], off
	v_lshl_add_u64 v[202:203], v[228:229], 0, s[12:13]
	s_mov_b32 m0, s48
	s_nop 0
	global_load_lds_dwordx4 v[202:203], off
	s_waitcnt vmcnt(8)
	s_waitcnt lgkmcnt(0)
	s_barrier
	s_setprio 1
	s_waitcnt lgkmcnt(0)
	v_mfma_f32_16x16x32_bf16 v[62:65], v[144:147], v[182:185], v[62:65]
	v_mfma_f32_16x16x32_bf16 v[58:61], v[152:155], v[182:185], v[58:61]
	v_mfma_f32_16x16x32_bf16 v[46:49], v[144:147], v[190:193], v[46:49]
	v_mfma_f32_16x16x32_bf16 v[42:45], v[152:155], v[190:193], v[42:45]
	v_mfma_f32_16x16x32_bf16 v[30:33], v[144:147], v[210:213], v[30:33]
	v_mfma_f32_16x16x32_bf16 v[26:29], v[152:155], v[210:213], v[26:29]
	v_mfma_f32_16x16x32_bf16 v[14:17], v[144:147], v[218:221], v[14:17]
	v_mfma_f32_16x16x32_bf16 v[10:13], v[152:155], v[218:221], v[10:13]
	v_mfma_f32_16x16x32_bf16 v[62:65], v[148:151], v[186:189], v[62:65]
	v_mfma_f32_16x16x32_bf16 v[58:61], v[156:159], v[186:189], v[58:61]
	v_mfma_f32_16x16x32_bf16 v[46:49], v[148:151], v[198:201], v[46:49]
	v_mfma_f32_16x16x32_bf16 v[42:45], v[156:159], v[198:201], v[42:45]
	v_mfma_f32_16x16x32_bf16 v[30:33], v[148:151], v[214:217], v[30:33]
	v_mfma_f32_16x16x32_bf16 v[26:29], v[156:159], v[214:217], v[26:29]
	v_mfma_f32_16x16x32_bf16 v[14:17], v[148:151], v[222:225], v[14:17]
	v_mfma_f32_16x16x32_bf16 v[10:13], v[156:159], v[222:225], v[10:13]
	v_mfma_f32_16x16x32_bf16 v[54:57], v[160:163], v[182:185], v[54:57]
	v_mfma_f32_16x16x32_bf16 v[50:53], v[174:177], v[182:185], v[50:53]
	v_mfma_f32_16x16x32_bf16 v[38:41], v[160:163], v[190:193], v[38:41]
	v_mfma_f32_16x16x32_bf16 v[34:37], v[174:177], v[190:193], v[34:37]
	v_mfma_f32_16x16x32_bf16 v[22:25], v[160:163], v[210:213], v[22:25]
	v_mfma_f32_16x16x32_bf16 v[18:21], v[174:177], v[210:213], v[18:21]
	v_mfma_f32_16x16x32_bf16 v[6:9], v[160:163], v[218:221], v[6:9]
	v_mfma_f32_16x16x32_bf16 v[2:5], v[174:177], v[218:221], v[2:5]
	v_mfma_f32_16x16x32_bf16 v[54:57], v[170:173], v[186:189], v[54:57]
	v_mfma_f32_16x16x32_bf16 v[50:53], v[178:181], v[186:189], v[50:53]
	v_mfma_f32_16x16x32_bf16 v[38:41], v[170:173], v[198:201], v[38:41]
	v_mfma_f32_16x16x32_bf16 v[34:37], v[178:181], v[198:201], v[34:37]
	v_mfma_f32_16x16x32_bf16 v[22:25], v[170:173], v[214:217], v[22:25]
	v_mfma_f32_16x16x32_bf16 v[18:21], v[178:181], v[214:217], v[18:21]
	v_mfma_f32_16x16x32_bf16 v[6:9], v[170:173], v[222:225], v[6:9]
	s_barrier
	v_mfma_f32_16x16x32_bf16 v[2:5], v[178:181], v[222:225], v[2:5]
	s_setprio 2
	s_add_u32 s24, s24, 0x100
	s_addc_u32 s25, s25, 0
	s_add_u32 s17, s17, 0x100
	s_addc_u32 s23, s23, 0
	s_cmp_ge_i32 s30, s67
	s_mov_b32 s26, s30
	s_cbranch_scc0 .LBB0_1451

.Lpeel_3:
	v_add_u32_e32 v250, 0x18000, v144
	s_add_i32 s29, s23, 2
	s_add_u32 s34, s30, 0xfff80080
	s_addc_u32 s35, s31, -1
	s_cmp_eq_u32 s28, s23
	s_cselect_b32 s37, s25, s35
	s_cselect_b32 s36, s24, s34
	s_cselect_b32 s35, s27, s21
	s_cselect_b32 s34, s26, s19
	s_add_i32 m0, s15, 0xc000
	global_load_lds_dwordx4 v140, s[30:31]
	s_add_i32 m0, s15, 0xe000
	s_nop 0
	global_load_lds_dwordx4 v142, s[30:31]
	s_waitcnt vmcnt(8)
	s_waitcnt lgkmcnt(0)
	s_barrier
	s_setprio 1
	s_waitcnt lgkmcnt(0)
	v_mfma_f32_16x16x32_bf16 v[126:129], v[150:153], v[182:185], 0
	v_mfma_f32_16x16x32_bf16 v[122:125], v[158:161], v[182:185], 0
	v_mfma_f32_16x16x32_bf16 v[118:121], v[150:153], v[190:193], 0
	v_mfma_f32_16x16x32_bf16 v[114:117], v[158:161], v[190:193], 0
	v_mfma_f32_16x16x32_bf16 v[110:113], v[150:153], v[210:213], 0
	v_mfma_f32_16x16x32_bf16 v[106:109], v[158:161], v[210:213], 0
	v_mfma_f32_16x16x32_bf16 v[102:105], v[150:153], v[218:221], 0
	v_mfma_f32_16x16x32_bf16 v[98:101], v[158:161], v[218:221], 0
	v_mfma_f32_16x16x32_bf16 v[126:129], v[154:157], v[186:189], v[126:129]
	v_mfma_f32_16x16x32_bf16 v[122:125], v[162:165], v[186:189], v[122:125]
	v_mfma_f32_16x16x32_bf16 v[118:121], v[154:157], v[198:201], v[118:121]
	v_mfma_f32_16x16x32_bf16 v[114:117], v[162:165], v[198:201], v[114:117]
	v_mfma_f32_16x16x32_bf16 v[110:113], v[154:157], v[214:217], v[110:113]
	v_mfma_f32_16x16x32_bf16 v[106:109], v[162:165], v[214:217], v[106:109]
	v_mfma_f32_16x16x32_bf16 v[102:105], v[154:157], v[222:225], v[102:105]
	v_mfma_f32_16x16x32_bf16 v[98:101], v[162:165], v[222:225], v[98:101]
	v_mfma_f32_16x16x32_bf16 v[94:97], v[166:169], v[182:185], 0
	v_mfma_f32_16x16x32_bf16 v[90:93], v[174:177], v[182:185], 0
	v_mfma_f32_16x16x32_bf16 v[86:89], v[166:169], v[190:193], 0
	v_mfma_f32_16x16x32_bf16 v[82:85], v[174:177], v[190:193], 0
	v_mfma_f32_16x16x32_bf16 v[78:81], v[166:169], v[210:213], 0
	v_mfma_f32_16x16x32_bf16 v[74:77], v[174:177], v[210:213], 0
	v_mfma_f32_16x16x32_bf16 v[70:73], v[166:169], v[218:221], 0
	v_mfma_f32_16x16x32_bf16 v[66:69], v[174:177], v[218:221], 0
	v_mfma_f32_16x16x32_bf16 v[94:97], v[170:173], v[186:189], v[94:97]
	v_mfma_f32_16x16x32_bf16 v[90:93], v[178:181], v[186:189], v[90:93]
	v_mfma_f32_16x16x32_bf16 v[86:89], v[170:173], v[198:201], v[86:89]
	v_mfma_f32_16x16x32_bf16 v[82:85], v[178:181], v[198:201], v[82:85]
	v_mfma_f32_16x16x32_bf16 v[78:81], v[170:173], v[214:217], v[78:81]
	v_mfma_f32_16x16x32_bf16 v[74:77], v[178:181], v[214:217], v[74:77]
	v_mfma_f32_16x16x32_bf16 v[70:73], v[170:173], v[222:225], v[70:73]
	s_barrier
	v_mfma_f32_16x16x32_bf16 v[66:69], v[178:181], v[222:225], v[66:69]
	s_setprio 2
	s_add_i32 s23, s60, s33
	v_lshl_add_u64 v[202:203], s[34:35], 0, v[132:133]
	s_mov_b32 m0, s23
	ds_read_b128 v[182:185], v148 offset:16384
	ds_read_b128 v[186:189], v148 offset:17408
	ds_read_b128 v[190:193], v148 offset:18432
	ds_read_b128 v[198:201], v148 offset:19456
	ds_read_b128 v[210:213], v148 offset:20480
	ds_read_b128 v[214:217], v148 offset:21504
	ds_read_b128 v[218:221], v148 offset:22528
	ds_read_b128 v[222:225], v148 offset:23552
	global_load_lds_dwordx4 v132, s[34:35]
	s_add_i32 m0, s23, 0x2000
	s_add_u32 s38, s34, 0x80000
	v_lshl_add_u64 v[206:207], s[34:35], 0, v[136:137]
	s_addc_u32 s39, s35, 0
	s_add_i32 s23, s61, s33
	global_load_lds_dwordx4 v136, s[34:35]
	s_mov_b32 m0, s23
	v_lshl_add_u64 v[228:229], s[36:37], 0, v[134:135]
	global_load_lds_dwordx4 v132, s[38:39]
	s_add_i32 m0, s23, 0x2000
	s_nop 0
	global_load_lds_dwordx4 v136, s[38:39]
	v_lshl_add_u64 v[226:227], s[36:37], 0, v[130:131]
	s_mov_b32 m0, s15
	s_nop 0
	global_load_lds_dwordx4 v130, s[36:37]
	s_mov_b32 m0, s41
	s_nop 0
	global_load_lds_dwordx4 v134, s[36:37]
	s_waitcnt vmcnt(8)
	s_waitcnt lgkmcnt(0)
	s_barrier
	s_setprio 1
	s_waitcnt lgkmcnt(0)
	v_mfma_f32_16x16x32_bf16 v[62:65], v[150:153], v[182:185], 0
	v_mfma_f32_16x16x32_bf16 v[58:61], v[158:161], v[182:185], 0
	v_mfma_f32_16x16x32_bf16 v[54:57], v[150:153], v[190:193], 0
	v_mfma_f32_16x16x32_bf16 v[50:53], v[158:161], v[190:193], 0
	v_mfma_f32_16x16x32_bf16 v[46:49], v[150:153], v[210:213], 0
	v_mfma_f32_16x16x32_bf16 v[42:45], v[158:161], v[210:213], 0
	v_mfma_f32_16x16x32_bf16 v[38:41], v[150:153], v[218:221], 0
	v_mfma_f32_16x16x32_bf16 v[34:37], v[158:161], v[218:221], 0
	v_mfma_f32_16x16x32_bf16 v[62:65], v[154:157], v[186:189], v[62:65]
	v_mfma_f32_16x16x32_bf16 v[58:61], v[162:165], v[186:189], v[58:61]
	v_mfma_f32_16x16x32_bf16 v[54:57], v[154:157], v[198:201], v[54:57]
	v_mfma_f32_16x16x32_bf16 v[50:53], v[162:165], v[198:201], v[50:53]
	v_mfma_f32_16x16x32_bf16 v[46:49], v[154:157], v[214:217], v[46:49]
	v_mfma_f32_16x16x32_bf16 v[42:45], v[162:165], v[214:217], v[42:45]
	v_mfma_f32_16x16x32_bf16 v[38:41], v[154:157], v[222:225], v[38:41]
	v_mfma_f32_16x16x32_bf16 v[34:37], v[162:165], v[222:225], v[34:37]
	v_mfma_f32_16x16x32_bf16 v[30:33], v[166:169], v[182:185], 0
	v_mfma_f32_16x16x32_bf16 v[26:29], v[174:177], v[182:185], 0
	v_mfma_f32_16x16x32_bf16 v[22:25], v[166:169], v[190:193], 0
	v_mfma_f32_16x16x32_bf16 v[18:21], v[174:177], v[190:193], 0
	v_mfma_f32_16x16x32_bf16 v[14:17], v[166:169], v[210:213], 0
	v_mfma_f32_16x16x32_bf16 v[10:13], v[174:177], v[210:213], 0
	v_mfma_f32_16x16x32_bf16 v[6:9], v[166:169], v[218:221], 0
	v_mfma_f32_16x16x32_bf16 v[2:5], v[174:177], v[218:221], 0
	v_mfma_f32_16x16x32_bf16 v[30:33], v[170:173], v[186:189], v[30:33]
	v_mfma_f32_16x16x32_bf16 v[26:29], v[178:181], v[186:189], v[26:29]
	v_mfma_f32_16x16x32_bf16 v[22:25], v[170:173], v[198:201], v[22:25]
	v_mfma_f32_16x16x32_bf16 v[18:21], v[178:181], v[198:201], v[18:21]
	v_mfma_f32_16x16x32_bf16 v[14:17], v[170:173], v[214:217], v[14:17]
	v_mfma_f32_16x16x32_bf16 v[10:13], v[178:181], v[214:217], v[10:13]
	v_mfma_f32_16x16x32_bf16 v[6:9], v[170:173], v[222:225], v[6:9]
	s_barrier
	v_mfma_f32_16x16x32_bf16 v[2:5], v[178:181], v[222:225], v[2:5]
	s_setprio 2
	s_add_i32 s23, 0, 0x18000
	s_add_i32 s38, 0, 0x1c000
	ds_read_b128 v[150:153], v250
	ds_read_b128 v[154:157], v250 offset:1024
	ds_read_b128 v[158:161], v250 offset:2048
	ds_read_b128 v[162:165], v250 offset:3072
	ds_read_b128 v[166:169], v250 offset:16384
	ds_read_b128 v[170:173], v250 offset:17408
	ds_read_b128 v[174:177], v250 offset:18432
	ds_read_b128 v[178:181], v250 offset:19456
	v_add_u32_e32 v149, s38, v144
	s_add_u32 s36, s36, 0x80000
	s_addc_u32 s37, s37, 0
	s_mov_b32 m0, s42
	ds_read_b128 v[182:185], v148 offset:32768
	ds_read_b128 v[186:189], v148 offset:33792
	ds_read_b128 v[190:193], v148 offset:34816
	ds_read_b128 v[198:201], v148 offset:35840
	ds_read_b128 v[210:213], v148 offset:36864
	ds_read_b128 v[214:217], v148 offset:37888
	ds_read_b128 v[218:221], v148 offset:38912
	ds_read_b128 v[222:225], v148 offset:39936
	global_load_lds_dwordx4 v130, s[36:37]
	v_lshl_add_u64 v[230:231], s[36:37], 0, v[134:135]
	s_mov_b32 m0, s43
	s_nop 0
	global_load_lds_dwordx4 v134, s[36:37]
	s_waitcnt vmcnt(8)
	s_waitcnt lgkmcnt(0)
	s_barrier
	s_setprio 1
	s_waitcnt lgkmcnt(0)
	v_mfma_f32_16x16x32_bf16 v[126:129], v[150:153], v[182:185], v[126:129]
	v_mfma_f32_16x16x32_bf16 v[122:125], v[158:161], v[182:185], v[122:125]
	v_mfma_f32_16x16x32_bf16 v[118:121], v[150:153], v[190:193], v[118:121]
	v_mfma_f32_16x16x32_bf16 v[114:117], v[158:161], v[190:193], v[114:117]
	v_mfma_f32_16x16x32_bf16 v[110:113], v[150:153], v[210:213], v[110:113]
	v_mfma_f32_16x16x32_bf16 v[106:109], v[158:161], v[210:213], v[106:109]
	v_mfma_f32_16x16x32_bf16 v[102:105], v[150:153], v[218:221], v[102:105]
	v_mfma_f32_16x16x32_bf16 v[98:101], v[158:161], v[218:221], v[98:101]
	v_mfma_f32_16x16x32_bf16 v[126:129], v[154:157], v[186:189], v[126:129]
	v_mfma_f32_16x16x32_bf16 v[122:125], v[162:165], v[186:189], v[122:125]
	v_mfma_f32_16x16x32_bf16 v[118:121], v[154:157], v[198:201], v[118:121]
	v_mfma_f32_16x16x32_bf16 v[114:117], v[162:165], v[198:201], v[114:117]
	v_mfma_f32_16x16x32_bf16 v[110:113], v[154:157], v[214:217], v[110:113]
	v_mfma_f32_16x16x32_bf16 v[106:109], v[162:165], v[214:217], v[106:109]
	v_mfma_f32_16x16x32_bf16 v[102:105], v[154:157], v[222:225], v[102:105]
	v_mfma_f32_16x16x32_bf16 v[98:101], v[162:165], v[222:225], v[98:101]
	v_mfma_f32_16x16x32_bf16 v[94:97], v[166:169], v[182:185], v[94:97]
	v_mfma_f32_16x16x32_bf16 v[90:93], v[174:177], v[182:185], v[90:93]
	v_mfma_f32_16x16x32_bf16 v[86:89], v[166:169], v[190:193], v[86:89]
	v_mfma_f32_16x16x32_bf16 v[82:85], v[174:177], v[190:193], v[82:85]
	v_mfma_f32_16x16x32_bf16 v[78:81], v[166:169], v[210:213], v[78:81]
	v_mfma_f32_16x16x32_bf16 v[74:77], v[174:177], v[210:213], v[74:77]
	v_mfma_f32_16x16x32_bf16 v[70:73], v[166:169], v[218:221], v[70:73]
	v_mfma_f32_16x16x32_bf16 v[66:69], v[174:177], v[218:221], v[66:69]
	v_mfma_f32_16x16x32_bf16 v[94:97], v[170:173], v[186:189], v[94:97]
	v_mfma_f32_16x16x32_bf16 v[90:93], v[178:181], v[186:189], v[90:93]
	v_mfma_f32_16x16x32_bf16 v[86:89], v[170:173], v[198:201], v[86:89]
	v_mfma_f32_16x16x32_bf16 v[82:85], v[178:181], v[198:201], v[82:85]
	v_mfma_f32_16x16x32_bf16 v[78:81], v[170:173], v[214:217], v[78:81]
	v_mfma_f32_16x16x32_bf16 v[74:77], v[178:181], v[214:217], v[74:77]
	v_mfma_f32_16x16x32_bf16 v[70:73], v[170:173], v[222:225], v[70:73]
	s_barrier
	v_mfma_f32_16x16x32_bf16 v[66:69], v[178:181], v[222:225], v[66:69]
	s_setprio 2
	s_add_i32 s23, s23, s33
	v_lshl_add_u64 v[202:203], v[202:203], 0, s[10:11]
	s_mov_b32 m0, s23
	ds_read_b128 v[182:185], v148 offset:49152
	ds_read_b128 v[186:189], v148 offset:50176
	ds_read_b128 v[190:193], v148 offset:51200
	ds_read_b128 v[198:201], v148 offset:52224
	ds_read_b128 v[210:213], v148 offset:53248
	ds_read_b128 v[214:217], v148 offset:54272
	ds_read_b128 v[218:221], v148 offset:55296
	ds_read_b128 v[222:225], v148 offset:56320
	global_load_lds_dwordx4 v[202:203], off
	s_add_i32 m0, s23, 0x2000
	s_add_u32 s34, s34, 0x80080
	v_lshl_add_u64 v[202:203], v[206:207], 0, s[10:11]
	s_addc_u32 s35, s35, 0
	s_add_i32 s23, s38, s33
	global_load_lds_dwordx4 v[202:203], off
	s_mov_b32 m0, s23
	s_nop 0
	global_load_lds_dwordx4 v132, s[34:35]
	s_add_i32 m0, s23, 0x2000
	s_nop 0
	global_load_lds_dwordx4 v136, s[34:35]
	v_lshl_add_u64 v[202:203], v[226:227], 0, s[10:11]
	s_mov_b32 m0, s51
	s_nop 0
	global_load_lds_dwordx4 v[202:203], off
	v_lshl_add_u64 v[202:203], v[228:229], 0, s[10:11]
	s_mov_b32 m0, s52
	s_nop 0
	global_load_lds_dwordx4 v[202:203], off
	s_waitcnt vmcnt(8)
	s_waitcnt lgkmcnt(0)
	s_barrier
	s_setprio 1
	s_waitcnt lgkmcnt(0)
	v_mfma_f32_16x16x32_bf16 v[62:65], v[150:153], v[182:185], v[62:65]
	v_mfma_f32_16x16x32_bf16 v[58:61], v[158:161], v[182:185], v[58:61]
	v_mfma_f32_16x16x32_bf16 v[54:57], v[150:153], v[190:193], v[54:57]
	v_mfma_f32_16x16x32_bf16 v[50:53], v[158:161], v[190:193], v[50:53]
	v_mfma_f32_16x16x32_bf16 v[46:49], v[150:153], v[210:213], v[46:49]
	v_mfma_f32_16x16x32_bf16 v[42:45], v[158:161], v[210:213], v[42:45]
	v_mfma_f32_16x16x32_bf16 v[38:41], v[150:153], v[218:221], v[38:41]
	v_mfma_f32_16x16x32_bf16 v[34:37], v[158:161], v[218:221], v[34:37]
	v_mfma_f32_16x16x32_bf16 v[62:65], v[154:157], v[186:189], v[62:65]
	v_mfma_f32_16x16x32_bf16 v[58:61], v[162:165], v[186:189], v[58:61]
	v_mfma_f32_16x16x32_bf16 v[54:57], v[154:157], v[198:201], v[54:57]
	v_mfma_f32_16x16x32_bf16 v[50:53], v[162:165], v[198:201], v[50:53]
	v_mfma_f32_16x16x32_bf16 v[46:49], v[154:157], v[214:217], v[46:49]
	v_mfma_f32_16x16x32_bf16 v[42:45], v[162:165], v[214:217], v[42:45]
	v_mfma_f32_16x16x32_bf16 v[38:41], v[154:157], v[222:225], v[38:41]
	v_mfma_f32_16x16x32_bf16 v[34:37], v[162:165], v[222:225], v[34:37]
	v_mfma_f32_16x16x32_bf16 v[30:33], v[166:169], v[182:185], v[30:33]
	v_mfma_f32_16x16x32_bf16 v[26:29], v[174:177], v[182:185], v[26:29]
	v_mfma_f32_16x16x32_bf16 v[22:25], v[166:169], v[190:193], v[22:25]
	v_mfma_f32_16x16x32_bf16 v[18:21], v[174:177], v[190:193], v[18:21]
	v_mfma_f32_16x16x32_bf16 v[14:17], v[166:169], v[210:213], v[14:17]
	v_mfma_f32_16x16x32_bf16 v[10:13], v[174:177], v[210:213], v[10:13]
	v_mfma_f32_16x16x32_bf16 v[6:9], v[166:169], v[218:221], v[6:9]
	v_mfma_f32_16x16x32_bf16 v[2:5], v[174:177], v[218:221], v[2:5]
	v_mfma_f32_16x16x32_bf16 v[30:33], v[170:173], v[186:189], v[30:33]
	v_mfma_f32_16x16x32_bf16 v[26:29], v[178:181], v[186:189], v[26:29]
	v_mfma_f32_16x16x32_bf16 v[22:25], v[170:173], v[198:201], v[22:25]
	v_mfma_f32_16x16x32_bf16 v[18:21], v[178:181], v[198:201], v[18:21]
	v_mfma_f32_16x16x32_bf16 v[14:17], v[170:173], v[214:217], v[14:17]
	v_mfma_f32_16x16x32_bf16 v[10:13], v[178:181], v[214:217], v[10:13]
	v_mfma_f32_16x16x32_bf16 v[6:9], v[170:173], v[222:225], v[6:9]
	s_barrier
	v_mfma_f32_16x16x32_bf16 v[2:5], v[178:181], v[222:225], v[2:5]
	s_setprio 2
	s_add_u32 s30, s30, 0x100
	s_addc_u32 s31, s31, 0
	s_add_u32 s19, s19, 0x100
	s_addc_u32 s21, s21, 0
	s_cmp_ge_i32 s29, s68
	s_mov_b32 s23, s29
	s_cbranch_scc0 .LBB0_1973
	s_branch .Lpeeldone_3
.LBB0_1973:
	ds_read_b128 v[150:153], v146
	ds_read_b128 v[154:157], v146 offset:1024
	ds_read_b128 v[158:161], v146 offset:2048
	ds_read_b128 v[162:165], v146 offset:3072
	ds_read_b128 v[166:169], v147
	ds_read_b128 v[170:173], v147 offset:1024
	ds_read_b128 v[174:177], v147 offset:2048
	ds_read_b128 v[178:181], v147 offset:3072
	s_add_i32 s29, s23, 2
	s_add_u32 s34, s30, 0xfff80080
	s_addc_u32 s35, s31, -1
	s_cmp_eq_u32 s28, s23
	s_cselect_b32 s37, s25, s35
	s_cselect_b32 s36, s24, s34
	s_cselect_b32 s35, s27, s21
	s_cselect_b32 s34, s26, s19
	s_add_i32 m0, s15, 0xc000
	ds_read_b128 v[182:185], v148
	ds_read_b128 v[186:189], v148 offset:1024
	ds_read_b128 v[190:193], v148 offset:2048
	ds_read_b128 v[198:201], v148 offset:3072
	ds_read_b128 v[210:213], v148 offset:4096
	ds_read_b128 v[214:217], v148 offset:5120
	ds_read_b128 v[218:221], v148 offset:6144
	ds_read_b128 v[222:225], v148 offset:7168
	global_load_lds_dwordx4 v140, s[30:31]
	s_add_i32 m0, s15, 0xe000
	s_nop 0
	global_load_lds_dwordx4 v142, s[30:31]
	s_waitcnt vmcnt(8)
	s_waitcnt lgkmcnt(0)
	s_barrier
	s_setprio 1
	s_waitcnt lgkmcnt(0)
	v_mfma_f32_16x16x32_bf16 v[126:129], v[150:153], v[182:185], v[126:129]
	v_mfma_f32_16x16x32_bf16 v[122:125], v[158:161], v[182:185], v[122:125]
	v_mfma_f32_16x16x32_bf16 v[118:121], v[150:153], v[190:193], v[118:121]
	v_mfma_f32_16x16x32_bf16 v[114:117], v[158:161], v[190:193], v[114:117]
	v_mfma_f32_16x16x32_bf16 v[110:113], v[150:153], v[210:213], v[110:113]
	v_mfma_f32_16x16x32_bf16 v[106:109], v[158:161], v[210:213], v[106:109]
	v_mfma_f32_16x16x32_bf16 v[102:105], v[150:153], v[218:221], v[102:105]
	v_mfma_f32_16x16x32_bf16 v[98:101], v[158:161], v[218:221], v[98:101]
	v_mfma_f32_16x16x32_bf16 v[126:129], v[154:157], v[186:189], v[126:129]
	v_mfma_f32_16x16x32_bf16 v[122:125], v[162:165], v[186:189], v[122:125]
	v_mfma_f32_16x16x32_bf16 v[118:121], v[154:157], v[198:201], v[118:121]
	v_mfma_f32_16x16x32_bf16 v[114:117], v[162:165], v[198:201], v[114:117]
	v_mfma_f32_16x16x32_bf16 v[110:113], v[154:157], v[214:217], v[110:113]
	v_mfma_f32_16x16x32_bf16 v[106:109], v[162:165], v[214:217], v[106:109]
	v_mfma_f32_16x16x32_bf16 v[102:105], v[154:157], v[222:225], v[102:105]
	v_mfma_f32_16x16x32_bf16 v[98:101], v[162:165], v[222:225], v[98:101]
	v_mfma_f32_16x16x32_bf16 v[94:97], v[166:169], v[182:185], v[94:97]
	v_mfma_f32_16x16x32_bf16 v[90:93], v[174:177], v[182:185], v[90:93]
	v_mfma_f32_16x16x32_bf16 v[86:89], v[166:169], v[190:193], v[86:89]
	v_mfma_f32_16x16x32_bf16 v[82:85], v[174:177], v[190:193], v[82:85]
	v_mfma_f32_16x16x32_bf16 v[78:81], v[166:169], v[210:213], v[78:81]
	v_mfma_f32_16x16x32_bf16 v[74:77], v[174:177], v[210:213], v[74:77]
	v_mfma_f32_16x16x32_bf16 v[70:73], v[166:169], v[218:221], v[70:73]
	v_mfma_f32_16x16x32_bf16 v[66:69], v[174:177], v[218:221], v[66:69]
	v_mfma_f32_16x16x32_bf16 v[94:97], v[170:173], v[186:189], v[94:97]
	v_mfma_f32_16x16x32_bf16 v[90:93], v[178:181], v[186:189], v[90:93]
	v_mfma_f32_16x16x32_bf16 v[86:89], v[170:173], v[198:201], v[86:89]
	v_mfma_f32_16x16x32_bf16 v[82:85], v[178:181], v[198:201], v[82:85]
	v_mfma_f32_16x16x32_bf16 v[78:81], v[170:173], v[214:217], v[78:81]
	v_mfma_f32_16x16x32_bf16 v[74:77], v[178:181], v[214:217], v[74:77]
	v_mfma_f32_16x16x32_bf16 v[70:73], v[170:173], v[222:225], v[70:73]
	s_barrier
	v_mfma_f32_16x16x32_bf16 v[66:69], v[178:181], v[222:225], v[66:69]
	s_setprio 2
	s_add_i32 s23, s60, s33
	v_lshl_add_u64 v[202:203], s[34:35], 0, v[132:133]
	s_mov_b32 m0, s23
	ds_read_b128 v[182:185], v148 offset:16384
	ds_read_b128 v[186:189], v148 offset:17408
	ds_read_b128 v[190:193], v148 offset:18432
	ds_read_b128 v[198:201], v148 offset:19456
	ds_read_b128 v[210:213], v148 offset:20480
	ds_read_b128 v[214:217], v148 offset:21504
	ds_read_b128 v[218:221], v148 offset:22528
	ds_read_b128 v[222:225], v148 offset:23552
	global_load_lds_dwordx4 v132, s[34:35]
	s_add_i32 m0, s23, 0x2000
	s_add_u32 s38, s34, 0x80000
	v_lshl_add_u64 v[206:207], s[34:35], 0, v[136:137]
	s_addc_u32 s39, s35, 0
	s_add_i32 s23, s61, s33
	global_load_lds_dwordx4 v136, s[34:35]
	s_mov_b32 m0, s23
	v_lshl_add_u64 v[228:229], s[36:37], 0, v[134:135]
	global_load_lds_dwordx4 v132, s[38:39]
	s_add_i32 m0, s23, 0x2000
	s_nop 0
	global_load_lds_dwordx4 v136, s[38:39]
	v_lshl_add_u64 v[226:227], s[36:37], 0, v[130:131]
	s_mov_b32 m0, s15
	s_nop 0
	global_load_lds_dwordx4 v130, s[36:37]
	s_mov_b32 m0, s41
	s_nop 0
	global_load_lds_dwordx4 v134, s[36:37]
	s_waitcnt vmcnt(8)
	s_waitcnt lgkmcnt(0)
	s_barrier
	s_setprio 1
	s_waitcnt lgkmcnt(0)
	v_mfma_f32_16x16x32_bf16 v[62:65], v[150:153], v[182:185], v[62:65]
	v_mfma_f32_16x16x32_bf16 v[58:61], v[158:161], v[182:185], v[58:61]
	v_mfma_f32_16x16x32_bf16 v[54:57], v[150:153], v[190:193], v[54:57]
	v_mfma_f32_16x16x32_bf16 v[50:53], v[158:161], v[190:193], v[50:53]
	v_mfma_f32_16x16x32_bf16 v[46:49], v[150:153], v[210:213], v[46:49]
	v_mfma_f32_16x16x32_bf16 v[42:45], v[158:161], v[210:213], v[42:45]
	v_mfma_f32_16x16x32_bf16 v[38:41], v[150:153], v[218:221], v[38:41]
	v_mfma_f32_16x16x32_bf16 v[34:37], v[158:161], v[218:221], v[34:37]
	v_mfma_f32_16x16x32_bf16 v[62:65], v[154:157], v[186:189], v[62:65]
	v_mfma_f32_16x16x32_bf16 v[58:61], v[162:165], v[186:189], v[58:61]
	v_mfma_f32_16x16x32_bf16 v[54:57], v[154:157], v[198:201], v[54:57]
	v_mfma_f32_16x16x32_bf16 v[50:53], v[162:165], v[198:201], v[50:53]
	v_mfma_f32_16x16x32_bf16 v[46:49], v[154:157], v[214:217], v[46:49]
	v_mfma_f32_16x16x32_bf16 v[42:45], v[162:165], v[214:217], v[42:45]
	v_mfma_f32_16x16x32_bf16 v[38:41], v[154:157], v[222:225], v[38:41]
	v_mfma_f32_16x16x32_bf16 v[34:37], v[162:165], v[222:225], v[34:37]
	v_mfma_f32_16x16x32_bf16 v[30:33], v[166:169], v[182:185], v[30:33]
	v_mfma_f32_16x16x32_bf16 v[26:29], v[174:177], v[182:185], v[26:29]
	v_mfma_f32_16x16x32_bf16 v[22:25], v[166:169], v[190:193], v[22:25]
	v_mfma_f32_16x16x32_bf16 v[18:21], v[174:177], v[190:193], v[18:21]
	v_mfma_f32_16x16x32_bf16 v[14:17], v[166:169], v[210:213], v[14:17]
	v_mfma_f32_16x16x32_bf16 v[10:13], v[174:177], v[210:213], v[10:13]
	v_mfma_f32_16x16x32_bf16 v[6:9], v[166:169], v[218:221], v[6:9]
	v_mfma_f32_16x16x32_bf16 v[2:5], v[174:177], v[218:221], v[2:5]
	v_mfma_f32_16x16x32_bf16 v[30:33], v[170:173], v[186:189], v[30:33]
	v_mfma_f32_16x16x32_bf16 v[26:29], v[178:181], v[186:189], v[26:29]
	v_mfma_f32_16x16x32_bf16 v[22:25], v[170:173], v[198:201], v[22:25]
	v_mfma_f32_16x16x32_bf16 v[18:21], v[178:181], v[198:201], v[18:21]
	v_mfma_f32_16x16x32_bf16 v[14:17], v[170:173], v[214:217], v[14:17]
	v_mfma_f32_16x16x32_bf16 v[10:13], v[178:181], v[214:217], v[10:13]
	v_mfma_f32_16x16x32_bf16 v[6:9], v[170:173], v[222:225], v[6:9]
	s_barrier
	v_mfma_f32_16x16x32_bf16 v[2:5], v[178:181], v[222:225], v[2:5]
	s_setprio 2
	s_add_i32 s23, 0, 0x18000
	s_add_i32 s38, 0, 0x1c000
	ds_read_b128 v[150:153], v250
	ds_read_b128 v[154:157], v250 offset:1024
	ds_read_b128 v[158:161], v250 offset:2048
	ds_read_b128 v[162:165], v250 offset:3072
	ds_read_b128 v[166:169], v250 offset:16384
	ds_read_b128 v[170:173], v250 offset:17408
	ds_read_b128 v[174:177], v250 offset:18432
	ds_read_b128 v[178:181], v250 offset:19456
	v_add_u32_e32 v149, s38, v144
	s_add_u32 s36, s36, 0x80000
	s_addc_u32 s37, s37, 0
	s_mov_b32 m0, s42
	ds_read_b128 v[182:185], v148 offset:32768
	ds_read_b128 v[186:189], v148 offset:33792
	ds_read_b128 v[190:193], v148 offset:34816
	ds_read_b128 v[198:201], v148 offset:35840
	ds_read_b128 v[210:213], v148 offset:36864
	ds_read_b128 v[214:217], v148 offset:37888
	ds_read_b128 v[218:221], v148 offset:38912
	ds_read_b128 v[222:225], v148 offset:39936
	global_load_lds_dwordx4 v130, s[36:37]
	v_lshl_add_u64 v[230:231], s[36:37], 0, v[134:135]
	s_mov_b32 m0, s43
	s_nop 0
	global_load_lds_dwordx4 v134, s[36:37]
	s_waitcnt vmcnt(8)
	s_waitcnt lgkmcnt(0)
	s_barrier
	s_setprio 1
	s_waitcnt lgkmcnt(0)
	v_mfma_f32_16x16x32_bf16 v[126:129], v[150:153], v[182:185], v[126:129]
	v_mfma_f32_16x16x32_bf16 v[122:125], v[158:161], v[182:185], v[122:125]
	v_mfma_f32_16x16x32_bf16 v[118:121], v[150:153], v[190:193], v[118:121]
	v_mfma_f32_16x16x32_bf16 v[114:117], v[158:161], v[190:193], v[114:117]
	v_mfma_f32_16x16x32_bf16 v[110:113], v[150:153], v[210:213], v[110:113]
	v_mfma_f32_16x16x32_bf16 v[106:109], v[158:161], v[210:213], v[106:109]
	v_mfma_f32_16x16x32_bf16 v[102:105], v[150:153], v[218:221], v[102:105]
	v_mfma_f32_16x16x32_bf16 v[98:101], v[158:161], v[218:221], v[98:101]
	v_mfma_f32_16x16x32_bf16 v[126:129], v[154:157], v[186:189], v[126:129]
	v_mfma_f32_16x16x32_bf16 v[122:125], v[162:165], v[186:189], v[122:125]
	v_mfma_f32_16x16x32_bf16 v[118:121], v[154:157], v[198:201], v[118:121]
	v_mfma_f32_16x16x32_bf16 v[114:117], v[162:165], v[198:201], v[114:117]
	v_mfma_f32_16x16x32_bf16 v[110:113], v[154:157], v[214:217], v[110:113]
	v_mfma_f32_16x16x32_bf16 v[106:109], v[162:165], v[214:217], v[106:109]
	v_mfma_f32_16x16x32_bf16 v[102:105], v[154:157], v[222:225], v[102:105]
	v_mfma_f32_16x16x32_bf16 v[98:101], v[162:165], v[222:225], v[98:101]
	v_mfma_f32_16x16x32_bf16 v[94:97], v[166:169], v[182:185], v[94:97]
	v_mfma_f32_16x16x32_bf16 v[90:93], v[174:177], v[182:185], v[90:93]
	v_mfma_f32_16x16x32_bf16 v[86:89], v[166:169], v[190:193], v[86:89]
	v_mfma_f32_16x16x32_bf16 v[82:85], v[174:177], v[190:193], v[82:85]
	v_mfma_f32_16x16x32_bf16 v[78:81], v[166:169], v[210:213], v[78:81]
	v_mfma_f32_16x16x32_bf16 v[74:77], v[174:177], v[210:213], v[74:77]
	v_mfma_f32_16x16x32_bf16 v[70:73], v[166:169], v[218:221], v[70:73]
	v_mfma_f32_16x16x32_bf16 v[66:69], v[174:177], v[218:221], v[66:69]
	v_mfma_f32_16x16x32_bf16 v[94:97], v[170:173], v[186:189], v[94:97]
	v_mfma_f32_16x16x32_bf16 v[90:93], v[178:181], v[186:189], v[90:93]
	v_mfma_f32_16x16x32_bf16 v[86:89], v[170:173], v[198:201], v[86:89]
	v_mfma_f32_16x16x32_bf16 v[82:85], v[178:181], v[198:201], v[82:85]
	v_mfma_f32_16x16x32_bf16 v[78:81], v[170:173], v[214:217], v[78:81]
	v_mfma_f32_16x16x32_bf16 v[74:77], v[178:181], v[214:217], v[74:77]
	v_mfma_f32_16x16x32_bf16 v[70:73], v[170:173], v[222:225], v[70:73]
	s_barrier
	v_mfma_f32_16x16x32_bf16 v[66:69], v[178:181], v[222:225], v[66:69]
	s_setprio 2
	s_add_i32 s23, s23, s33
	v_lshl_add_u64 v[202:203], v[202:203], 0, s[10:11]
	s_mov_b32 m0, s23
	ds_read_b128 v[182:185], v148 offset:49152
	ds_read_b128 v[186:189], v148 offset:50176
	ds_read_b128 v[190:193], v148 offset:51200
	ds_read_b128 v[198:201], v148 offset:52224
	ds_read_b128 v[210:213], v148 offset:53248
	ds_read_b128 v[214:217], v148 offset:54272
	ds_read_b128 v[218:221], v148 offset:55296
	ds_read_b128 v[222:225], v148 offset:56320
	global_load_lds_dwordx4 v[202:203], off
	s_add_i32 m0, s23, 0x2000
	s_add_u32 s34, s34, 0x80080
	v_lshl_add_u64 v[202:203], v[206:207], 0, s[10:11]
	s_addc_u32 s35, s35, 0
	s_add_i32 s23, s38, s33
	global_load_lds_dwordx4 v[202:203], off
	s_mov_b32 m0, s23
	s_nop 0
	global_load_lds_dwordx4 v132, s[34:35]
	s_add_i32 m0, s23, 0x2000
	s_nop 0
	global_load_lds_dwordx4 v136, s[34:35]
	v_lshl_add_u64 v[202:203], v[226:227], 0, s[10:11]
	s_mov_b32 m0, s51
	s_nop 0
	global_load_lds_dwordx4 v[202:203], off
	v_lshl_add_u64 v[202:203], v[228:229], 0, s[10:11]
	s_mov_b32 m0, s52
	s_nop 0
	global_load_lds_dwordx4 v[202:203], off
	s_waitcnt vmcnt(8)
	s_waitcnt lgkmcnt(0)
	s_barrier
	s_setprio 1
	s_waitcnt lgkmcnt(0)
	v_mfma_f32_16x16x32_bf16 v[62:65], v[150:153], v[182:185], v[62:65]
	v_mfma_f32_16x16x32_bf16 v[58:61], v[158:161], v[182:185], v[58:61]
	v_mfma_f32_16x16x32_bf16 v[54:57], v[150:153], v[190:193], v[54:57]
	v_mfma_f32_16x16x32_bf16 v[50:53], v[158:161], v[190:193], v[50:53]
	v_mfma_f32_16x16x32_bf16 v[46:49], v[150:153], v[210:213], v[46:49]
	v_mfma_f32_16x16x32_bf16 v[42:45], v[158:161], v[210:213], v[42:45]
	v_mfma_f32_16x16x32_bf16 v[38:41], v[150:153], v[218:221], v[38:41]
	v_mfma_f32_16x16x32_bf16 v[34:37], v[158:161], v[218:221], v[34:37]
	v_mfma_f32_16x16x32_bf16 v[62:65], v[154:157], v[186:189], v[62:65]
	v_mfma_f32_16x16x32_bf16 v[58:61], v[162:165], v[186:189], v[58:61]
	v_mfma_f32_16x16x32_bf16 v[54:57], v[154:157], v[198:201], v[54:57]
	v_mfma_f32_16x16x32_bf16 v[50:53], v[162:165], v[198:201], v[50:53]
	v_mfma_f32_16x16x32_bf16 v[46:49], v[154:157], v[214:217], v[46:49]
	v_mfma_f32_16x16x32_bf16 v[42:45], v[162:165], v[214:217], v[42:45]
	v_mfma_f32_16x16x32_bf16 v[38:41], v[154:157], v[222:225], v[38:41]
	v_mfma_f32_16x16x32_bf16 v[34:37], v[162:165], v[222:225], v[34:37]
	v_mfma_f32_16x16x32_bf16 v[30:33], v[166:169], v[182:185], v[30:33]
	v_mfma_f32_16x16x32_bf16 v[26:29], v[174:177], v[182:185], v[26:29]
	v_mfma_f32_16x16x32_bf16 v[22:25], v[166:169], v[190:193], v[22:25]
	v_mfma_f32_16x16x32_bf16 v[18:21], v[174:177], v[190:193], v[18:21]
	v_mfma_f32_16x16x32_bf16 v[14:17], v[166:169], v[210:213], v[14:17]
	v_mfma_f32_16x16x32_bf16 v[10:13], v[174:177], v[210:213], v[10:13]
	v_mfma_f32_16x16x32_bf16 v[6:9], v[166:169], v[218:221], v[6:9]
	v_mfma_f32_16x16x32_bf16 v[2:5], v[174:177], v[218:221], v[2:5]
	v_mfma_f32_16x16x32_bf16 v[30:33], v[170:173], v[186:189], v[30:33]
	v_mfma_f32_16x16x32_bf16 v[26:29], v[178:181], v[186:189], v[26:29]
	v_mfma_f32_16x16x32_bf16 v[22:25], v[170:173], v[198:201], v[22:25]
	v_mfma_f32_16x16x32_bf16 v[18:21], v[178:181], v[198:201], v[18:21]
	v_mfma_f32_16x16x32_bf16 v[14:17], v[170:173], v[214:217], v[14:17]
	v_mfma_f32_16x16x32_bf16 v[10:13], v[178:181], v[214:217], v[10:13]
	v_mfma_f32_16x16x32_bf16 v[6:9], v[170:173], v[222:225], v[6:9]
	s_barrier
	v_mfma_f32_16x16x32_bf16 v[2:5], v[178:181], v[222:225], v[2:5]
	s_setprio 2
	s_add_u32 s30, s30, 0x100
	s_addc_u32 s31, s31, 0
	s_add_u32 s19, s19, 0x100
	s_addc_u32 s21, s21, 0
	s_cmp_ge_i32 s29, s68
	s_mov_b32 s23, s29
	s_cbranch_scc0 .LBB0_1973

.Lpeel_1:
	v_add_u32_e32 v250, 0x18000, v146
	ds_read_b128 v[152:155], v148
	ds_read_b128 v[156:159], v148 offset:1024
	s_add_i32 s29, s19, 2
	s_add_u32 s34, s30, 0xfff80080
	s_addc_u32 s35, s31, -1
	s_cmp_eq_u32 s28, s19
	s_cselect_b32 s37, s21, s35
	s_cselect_b32 s36, s20, s34
	s_cselect_b32 s35, s23, s17
	s_cselect_b32 s34, s22, s15
	s_add_i32 m0, s27, 0xc000
	global_load_lds_dwordx4 v140, s[30:31]
	s_add_i32 m0, s27, 0xe000
	s_nop 0
	global_load_lds_dwordx4 v142, s[30:31]
	s_waitcnt vmcnt(8)
	s_waitcnt lgkmcnt(0)
	s_barrier
	s_setprio 1
	s_waitcnt lgkmcnt(0)
	v_mfma_f32_16x16x32_bf16 v[126:129], v[152:155], v[184:187], 0
	v_mfma_f32_16x16x32_bf16 v[122:125], v[160:163], v[184:187], 0
	v_mfma_f32_16x16x32_bf16 v[110:113], v[152:155], v[192:195], 0
	v_mfma_f32_16x16x32_bf16 v[106:109], v[160:163], v[192:195], 0
	v_mfma_f32_16x16x32_bf16 v[94:97], v[152:155], v[210:213], 0
	v_mfma_f32_16x16x32_bf16 v[90:93], v[160:163], v[210:213], 0
	v_mfma_f32_16x16x32_bf16 v[78:81], v[152:155], v[218:221], 0
	v_mfma_f32_16x16x32_bf16 v[74:77], v[160:163], v[218:221], 0
	v_mfma_f32_16x16x32_bf16 v[126:129], v[156:159], v[188:191], v[126:129]
	v_mfma_f32_16x16x32_bf16 v[122:125], v[164:167], v[188:191], v[122:125]
	v_mfma_f32_16x16x32_bf16 v[110:113], v[156:159], v[198:201], v[110:113]
	v_mfma_f32_16x16x32_bf16 v[106:109], v[164:167], v[198:201], v[106:109]
	v_mfma_f32_16x16x32_bf16 v[94:97], v[156:159], v[214:217], v[94:97]
	v_mfma_f32_16x16x32_bf16 v[90:93], v[164:167], v[214:217], v[90:93]
	v_mfma_f32_16x16x32_bf16 v[78:81], v[156:159], v[222:225], v[78:81]
	v_mfma_f32_16x16x32_bf16 v[74:77], v[164:167], v[222:225], v[74:77]
	v_mfma_f32_16x16x32_bf16 v[118:121], v[168:171], v[184:187], 0
	v_mfma_f32_16x16x32_bf16 v[114:117], v[176:179], v[184:187], 0
	v_mfma_f32_16x16x32_bf16 v[102:105], v[168:171], v[192:195], 0
	v_mfma_f32_16x16x32_bf16 v[98:101], v[176:179], v[192:195], 0
	v_mfma_f32_16x16x32_bf16 v[86:89], v[168:171], v[210:213], 0
	v_mfma_f32_16x16x32_bf16 v[82:85], v[176:179], v[210:213], 0
	v_mfma_f32_16x16x32_bf16 v[70:73], v[168:171], v[218:221], 0
	v_mfma_f32_16x16x32_bf16 v[66:69], v[176:179], v[218:221], 0
	v_mfma_f32_16x16x32_bf16 v[118:121], v[172:175], v[188:191], v[118:121]
	v_mfma_f32_16x16x32_bf16 v[114:117], v[180:183], v[188:191], v[114:117]
	v_mfma_f32_16x16x32_bf16 v[102:105], v[172:175], v[198:201], v[102:105]
	v_mfma_f32_16x16x32_bf16 v[98:101], v[180:183], v[198:201], v[98:101]
	v_mfma_f32_16x16x32_bf16 v[86:89], v[172:175], v[214:217], v[86:89]
	v_mfma_f32_16x16x32_bf16 v[82:85], v[180:183], v[214:217], v[82:85]
	v_mfma_f32_16x16x32_bf16 v[70:73], v[172:175], v[222:225], v[70:73]
	s_barrier
	v_mfma_f32_16x16x32_bf16 v[66:69], v[180:183], v[222:225], v[66:69]
	s_setprio 2
	s_add_i32 s19, s60, s33
	v_lshl_add_u64 v[144:145], s[34:35], 0, v[132:133]
	s_mov_b32 m0, s19
	ds_read_b128 v[184:187], v150 offset:16384
	ds_read_b128 v[188:191], v150 offset:17408
	ds_read_b128 v[192:195], v150 offset:18432
	ds_read_b128 v[198:201], v150 offset:19456
	ds_read_b128 v[210:213], v150 offset:20480
	ds_read_b128 v[214:217], v150 offset:21504
	ds_read_b128 v[218:221], v150 offset:22528
	ds_read_b128 v[222:225], v150 offset:23552
	global_load_lds_dwordx4 v132, s[34:35]
	s_add_i32 m0, s19, 0x2000
	s_add_u32 s38, s34, 0x80000
	v_lshl_add_u64 v[202:203], s[34:35], 0, v[136:137]
	s_addc_u32 s39, s35, 0
	s_add_i32 s19, s61, s33
	global_load_lds_dwordx4 v136, s[34:35]
	s_mov_b32 m0, s19
	v_lshl_add_u64 v[226:227], s[36:37], 0, v[134:135]
	global_load_lds_dwordx4 v132, s[38:39]
	s_add_i32 m0, s19, 0x2000
	s_nop 0
	global_load_lds_dwordx4 v136, s[38:39]
	v_lshl_add_u64 v[206:207], s[36:37], 0, v[130:131]
	s_mov_b32 m0, s27
	s_nop 0
	global_load_lds_dwordx4 v130, s[36:37]
	s_mov_b32 m0, s41
	s_nop 0
	global_load_lds_dwordx4 v134, s[36:37]
	s_waitcnt vmcnt(8)
	s_waitcnt lgkmcnt(0)
	s_barrier
	s_setprio 1
	s_waitcnt lgkmcnt(0)
	v_mfma_f32_16x16x32_bf16 v[62:65], v[152:155], v[184:187], 0
	v_mfma_f32_16x16x32_bf16 v[58:61], v[160:163], v[184:187], 0
	v_mfma_f32_16x16x32_bf16 v[46:49], v[152:155], v[192:195], 0
	v_mfma_f32_16x16x32_bf16 v[42:45], v[160:163], v[192:195], 0
	v_mfma_f32_16x16x32_bf16 v[30:33], v[152:155], v[210:213], 0
	v_mfma_f32_16x16x32_bf16 v[26:29], v[160:163], v[210:213], 0
	v_mfma_f32_16x16x32_bf16 v[14:17], v[152:155], v[218:221], 0
	v_mfma_f32_16x16x32_bf16 v[10:13], v[160:163], v[218:221], 0
	v_mfma_f32_16x16x32_bf16 v[62:65], v[156:159], v[188:191], v[62:65]
	v_mfma_f32_16x16x32_bf16 v[58:61], v[164:167], v[188:191], v[58:61]
	v_mfma_f32_16x16x32_bf16 v[46:49], v[156:159], v[198:201], v[46:49]
	v_mfma_f32_16x16x32_bf16 v[42:45], v[164:167], v[198:201], v[42:45]
	v_mfma_f32_16x16x32_bf16 v[30:33], v[156:159], v[214:217], v[30:33]
	v_mfma_f32_16x16x32_bf16 v[26:29], v[164:167], v[214:217], v[26:29]
	v_mfma_f32_16x16x32_bf16 v[14:17], v[156:159], v[222:225], v[14:17]
	v_mfma_f32_16x16x32_bf16 v[10:13], v[164:167], v[222:225], v[10:13]
	v_mfma_f32_16x16x32_bf16 v[54:57], v[168:171], v[184:187], 0
	v_mfma_f32_16x16x32_bf16 v[50:53], v[176:179], v[184:187], 0
	v_mfma_f32_16x16x32_bf16 v[38:41], v[168:171], v[192:195], 0
	v_mfma_f32_16x16x32_bf16 v[34:37], v[176:179], v[192:195], 0
	v_mfma_f32_16x16x32_bf16 v[22:25], v[168:171], v[210:213], 0
	v_mfma_f32_16x16x32_bf16 v[18:21], v[176:179], v[210:213], 0
	v_mfma_f32_16x16x32_bf16 v[6:9], v[168:171], v[218:221], 0
	v_mfma_f32_16x16x32_bf16 v[2:5], v[176:179], v[218:221], 0
	v_mfma_f32_16x16x32_bf16 v[54:57], v[172:175], v[188:191], v[54:57]
	v_mfma_f32_16x16x32_bf16 v[50:53], v[180:183], v[188:191], v[50:53]
	v_mfma_f32_16x16x32_bf16 v[38:41], v[172:175], v[198:201], v[38:41]
	v_mfma_f32_16x16x32_bf16 v[34:37], v[180:183], v[198:201], v[34:37]
	v_mfma_f32_16x16x32_bf16 v[22:25], v[172:175], v[214:217], v[22:25]
	v_mfma_f32_16x16x32_bf16 v[18:21], v[180:183], v[214:217], v[18:21]
	v_mfma_f32_16x16x32_bf16 v[6:9], v[172:175], v[222:225], v[6:9]
	s_barrier
	v_mfma_f32_16x16x32_bf16 v[2:5], v[180:183], v[222:225], v[2:5]
	s_setprio 2
	s_add_i32 s19, 0, 0x18000
	s_add_i32 s38, 0, 0x1c000
	ds_read_b128 v[152:155], v250
	ds_read_b128 v[156:159], v250 offset:1024
	ds_read_b128 v[160:163], v250 offset:2048
	ds_read_b128 v[164:167], v250 offset:3072
	ds_read_b128 v[168:171], v250 offset:16384
	ds_read_b128 v[172:175], v250 offset:17408
	ds_read_b128 v[176:179], v250 offset:18432
	ds_read_b128 v[180:183], v250 offset:19456
	v_add_u32_e32 v151, s38, v146
	s_add_u32 s36, s36, 0x80000
	s_addc_u32 s37, s37, 0
	s_mov_b32 m0, s42
	ds_read_b128 v[184:187], v150 offset:32768
	ds_read_b128 v[188:191], v150 offset:33792
	ds_read_b128 v[192:195], v150 offset:34816
	ds_read_b128 v[198:201], v150 offset:35840
	ds_read_b128 v[210:213], v150 offset:36864
	ds_read_b128 v[214:217], v150 offset:37888
	ds_read_b128 v[218:221], v150 offset:38912
	ds_read_b128 v[222:225], v150 offset:39936
	global_load_lds_dwordx4 v130, s[36:37]
	v_lshl_add_u64 v[228:229], s[36:37], 0, v[134:135]
	s_mov_b32 m0, s43
	s_nop 0
	global_load_lds_dwordx4 v134, s[36:37]
	s_waitcnt vmcnt(8)
	s_waitcnt lgkmcnt(0)
	s_barrier
	s_setprio 1
	s_waitcnt lgkmcnt(0)
	v_mfma_f32_16x16x32_bf16 v[126:129], v[152:155], v[184:187], v[126:129]
	v_mfma_f32_16x16x32_bf16 v[122:125], v[160:163], v[184:187], v[122:125]
	v_mfma_f32_16x16x32_bf16 v[110:113], v[152:155], v[192:195], v[110:113]
	v_mfma_f32_16x16x32_bf16 v[106:109], v[160:163], v[192:195], v[106:109]
	v_mfma_f32_16x16x32_bf16 v[94:97], v[152:155], v[210:213], v[94:97]
	v_mfma_f32_16x16x32_bf16 v[90:93], v[160:163], v[210:213], v[90:93]
	v_mfma_f32_16x16x32_bf16 v[78:81], v[152:155], v[218:221], v[78:81]
	v_mfma_f32_16x16x32_bf16 v[74:77], v[160:163], v[218:221], v[74:77]
	v_mfma_f32_16x16x32_bf16 v[126:129], v[156:159], v[188:191], v[126:129]
	v_mfma_f32_16x16x32_bf16 v[122:125], v[164:167], v[188:191], v[122:125]
	v_mfma_f32_16x16x32_bf16 v[110:113], v[156:159], v[198:201], v[110:113]
	v_mfma_f32_16x16x32_bf16 v[106:109], v[164:167], v[198:201], v[106:109]
	v_mfma_f32_16x16x32_bf16 v[94:97], v[156:159], v[214:217], v[94:97]
	v_mfma_f32_16x16x32_bf16 v[90:93], v[164:167], v[214:217], v[90:93]
	v_mfma_f32_16x16x32_bf16 v[78:81], v[156:159], v[222:225], v[78:81]
	v_mfma_f32_16x16x32_bf16 v[74:77], v[164:167], v[222:225], v[74:77]
	v_mfma_f32_16x16x32_bf16 v[118:121], v[168:171], v[184:187], v[118:121]
	v_mfma_f32_16x16x32_bf16 v[114:117], v[176:179], v[184:187], v[114:117]
	v_mfma_f32_16x16x32_bf16 v[102:105], v[168:171], v[192:195], v[102:105]
	v_mfma_f32_16x16x32_bf16 v[98:101], v[176:179], v[192:195], v[98:101]
	v_mfma_f32_16x16x32_bf16 v[86:89], v[168:171], v[210:213], v[86:89]
	v_mfma_f32_16x16x32_bf16 v[82:85], v[176:179], v[210:213], v[82:85]
	v_mfma_f32_16x16x32_bf16 v[70:73], v[168:171], v[218:221], v[70:73]
	v_mfma_f32_16x16x32_bf16 v[66:69], v[176:179], v[218:221], v[66:69]
	v_mfma_f32_16x16x32_bf16 v[118:121], v[172:175], v[188:191], v[118:121]
	v_mfma_f32_16x16x32_bf16 v[114:117], v[180:183], v[188:191], v[114:117]
	v_mfma_f32_16x16x32_bf16 v[102:105], v[172:175], v[198:201], v[102:105]
	v_mfma_f32_16x16x32_bf16 v[98:101], v[180:183], v[198:201], v[98:101]
	v_mfma_f32_16x16x32_bf16 v[86:89], v[172:175], v[214:217], v[86:89]
	v_mfma_f32_16x16x32_bf16 v[82:85], v[180:183], v[214:217], v[82:85]
	v_mfma_f32_16x16x32_bf16 v[70:73], v[172:175], v[222:225], v[70:73]
	s_barrier
	v_mfma_f32_16x16x32_bf16 v[66:69], v[180:183], v[222:225], v[66:69]
	s_setprio 2
	s_add_i32 s19, s19, s33
	v_lshl_add_u64 v[144:145], v[144:145], 0, s[10:11]
	s_mov_b32 m0, s19
	ds_read_b128 v[184:187], v150 offset:49152
	ds_read_b128 v[188:191], v150 offset:50176
	ds_read_b128 v[192:195], v150 offset:51200
	ds_read_b128 v[198:201], v150 offset:52224
	ds_read_b128 v[210:213], v150 offset:53248
	ds_read_b128 v[214:217], v150 offset:54272
	ds_read_b128 v[218:221], v150 offset:55296
	ds_read_b128 v[222:225], v150 offset:56320
	global_load_lds_dwordx4 v[144:145], off
	s_add_i32 m0, s19, 0x2000
	s_add_u32 s34, s34, 0x80080
	v_lshl_add_u64 v[144:145], v[202:203], 0, s[10:11]
	s_addc_u32 s35, s35, 0
	s_add_i32 s19, s38, s33
	global_load_lds_dwordx4 v[144:145], off
	s_mov_b32 m0, s19
	s_nop 0
	global_load_lds_dwordx4 v132, s[34:35]
	s_add_i32 m0, s19, 0x2000
	s_nop 0
	global_load_lds_dwordx4 v136, s[34:35]
	v_lshl_add_u64 v[144:145], v[206:207], 0, s[10:11]
	s_mov_b32 m0, s51
	s_nop 0
	global_load_lds_dwordx4 v[144:145], off
	v_lshl_add_u64 v[144:145], v[226:227], 0, s[10:11]
	s_mov_b32 m0, s52
	s_nop 0
	global_load_lds_dwordx4 v[144:145], off
	s_waitcnt vmcnt(8)
	s_waitcnt lgkmcnt(0)
	s_barrier
	s_setprio 1
	s_waitcnt lgkmcnt(0)
	v_mfma_f32_16x16x32_bf16 v[62:65], v[152:155], v[184:187], v[62:65]
	v_mfma_f32_16x16x32_bf16 v[58:61], v[160:163], v[184:187], v[58:61]
	v_mfma_f32_16x16x32_bf16 v[46:49], v[152:155], v[192:195], v[46:49]
	v_mfma_f32_16x16x32_bf16 v[42:45], v[160:163], v[192:195], v[42:45]
	v_mfma_f32_16x16x32_bf16 v[30:33], v[152:155], v[210:213], v[30:33]
	v_mfma_f32_16x16x32_bf16 v[26:29], v[160:163], v[210:213], v[26:29]
	v_mfma_f32_16x16x32_bf16 v[14:17], v[152:155], v[218:221], v[14:17]
	v_mfma_f32_16x16x32_bf16 v[10:13], v[160:163], v[218:221], v[10:13]
	v_mfma_f32_16x16x32_bf16 v[62:65], v[156:159], v[188:191], v[62:65]
	v_mfma_f32_16x16x32_bf16 v[58:61], v[164:167], v[188:191], v[58:61]
	v_mfma_f32_16x16x32_bf16 v[46:49], v[156:159], v[198:201], v[46:49]
	v_mfma_f32_16x16x32_bf16 v[42:45], v[164:167], v[198:201], v[42:45]
	v_mfma_f32_16x16x32_bf16 v[30:33], v[156:159], v[214:217], v[30:33]
	v_mfma_f32_16x16x32_bf16 v[26:29], v[164:167], v[214:217], v[26:29]
	v_mfma_f32_16x16x32_bf16 v[14:17], v[156:159], v[222:225], v[14:17]
	v_mfma_f32_16x16x32_bf16 v[10:13], v[164:167], v[222:225], v[10:13]
	v_mfma_f32_16x16x32_bf16 v[54:57], v[168:171], v[184:187], v[54:57]
	v_mfma_f32_16x16x32_bf16 v[50:53], v[176:179], v[184:187], v[50:53]
	v_mfma_f32_16x16x32_bf16 v[38:41], v[168:171], v[192:195], v[38:41]
	v_mfma_f32_16x16x32_bf16 v[34:37], v[176:179], v[192:195], v[34:37]
	v_mfma_f32_16x16x32_bf16 v[22:25], v[168:171], v[210:213], v[22:25]
	v_mfma_f32_16x16x32_bf16 v[18:21], v[176:179], v[210:213], v[18:21]
	v_mfma_f32_16x16x32_bf16 v[6:9], v[168:171], v[218:221], v[6:9]
	v_mfma_f32_16x16x32_bf16 v[2:5], v[176:179], v[218:221], v[2:5]
	v_mfma_f32_16x16x32_bf16 v[54:57], v[172:175], v[188:191], v[54:57]
	v_mfma_f32_16x16x32_bf16 v[50:53], v[180:183], v[188:191], v[50:53]
	v_mfma_f32_16x16x32_bf16 v[38:41], v[172:175], v[198:201], v[38:41]
	v_mfma_f32_16x16x32_bf16 v[34:37], v[180:183], v[198:201], v[34:37]
	v_mfma_f32_16x16x32_bf16 v[22:25], v[172:175], v[214:217], v[22:25]
	v_mfma_f32_16x16x32_bf16 v[18:21], v[180:183], v[214:217], v[18:21]
	v_mfma_f32_16x16x32_bf16 v[6:9], v[172:175], v[222:225], v[6:9]
	s_barrier
	v_mfma_f32_16x16x32_bf16 v[2:5], v[180:183], v[222:225], v[2:5]
	s_setprio 2
	s_add_u32 s30, s30, 0x100
	s_addc_u32 s31, s31, 0
	s_add_u32 s15, s15, 0x100
	s_addc_u32 s17, s17, 0
	s_cmp_ge_i32 s29, s68
	s_mov_b32 s19, s29
	s_cbranch_scc0 .LBB0_2547
	s_branch .Lpeeldone_1
.LBB0_2547:
	ds_read_b128 v[152:155], v148
	ds_read_b128 v[156:159], v148 offset:1024
	ds_read_b128 v[160:163], v148 offset:2048
	ds_read_b128 v[164:167], v148 offset:3072
	ds_read_b128 v[168:171], v149
	ds_read_b128 v[172:175], v149 offset:1024
	ds_read_b128 v[176:179], v149 offset:2048
	ds_read_b128 v[180:183], v149 offset:3072
	s_add_i32 s29, s19, 2
	s_add_u32 s34, s30, 0xfff80080
	s_addc_u32 s35, s31, -1
	s_cmp_eq_u32 s28, s19
	s_cselect_b32 s37, s21, s35
	s_cselect_b32 s36, s20, s34
	s_cselect_b32 s35, s23, s17
	s_cselect_b32 s34, s22, s15
	s_add_i32 m0, s27, 0xc000
	ds_read_b128 v[184:187], v150
	ds_read_b128 v[188:191], v150 offset:1024
	ds_read_b128 v[192:195], v150 offset:2048
	ds_read_b128 v[198:201], v150 offset:3072
	ds_read_b128 v[210:213], v150 offset:4096
	ds_read_b128 v[214:217], v150 offset:5120
	ds_read_b128 v[218:221], v150 offset:6144
	ds_read_b128 v[222:225], v150 offset:7168
	global_load_lds_dwordx4 v140, s[30:31]
	s_add_i32 m0, s27, 0xe000
	s_nop 0
	global_load_lds_dwordx4 v142, s[30:31]
	s_waitcnt vmcnt(8)
	s_waitcnt lgkmcnt(0)
	s_barrier
	s_setprio 1
	s_waitcnt lgkmcnt(0)
	v_mfma_f32_16x16x32_bf16 v[126:129], v[152:155], v[184:187], v[126:129]
	v_mfma_f32_16x16x32_bf16 v[122:125], v[160:163], v[184:187], v[122:125]
	v_mfma_f32_16x16x32_bf16 v[110:113], v[152:155], v[192:195], v[110:113]
	v_mfma_f32_16x16x32_bf16 v[106:109], v[160:163], v[192:195], v[106:109]
	v_mfma_f32_16x16x32_bf16 v[94:97], v[152:155], v[210:213], v[94:97]
	v_mfma_f32_16x16x32_bf16 v[90:93], v[160:163], v[210:213], v[90:93]
	v_mfma_f32_16x16x32_bf16 v[78:81], v[152:155], v[218:221], v[78:81]
	v_mfma_f32_16x16x32_bf16 v[74:77], v[160:163], v[218:221], v[74:77]
	v_mfma_f32_16x16x32_bf16 v[126:129], v[156:159], v[188:191], v[126:129]
	v_mfma_f32_16x16x32_bf16 v[122:125], v[164:167], v[188:191], v[122:125]
	v_mfma_f32_16x16x32_bf16 v[110:113], v[156:159], v[198:201], v[110:113]
	v_mfma_f32_16x16x32_bf16 v[106:109], v[164:167], v[198:201], v[106:109]
	v_mfma_f32_16x16x32_bf16 v[94:97], v[156:159], v[214:217], v[94:97]
	v_mfma_f32_16x16x32_bf16 v[90:93], v[164:167], v[214:217], v[90:93]
	v_mfma_f32_16x16x32_bf16 v[78:81], v[156:159], v[222:225], v[78:81]
	v_mfma_f32_16x16x32_bf16 v[74:77], v[164:167], v[222:225], v[74:77]
	v_mfma_f32_16x16x32_bf16 v[118:121], v[168:171], v[184:187], v[118:121]
	v_mfma_f32_16x16x32_bf16 v[114:117], v[176:179], v[184:187], v[114:117]
	v_mfma_f32_16x16x32_bf16 v[102:105], v[168:171], v[192:195], v[102:105]
	v_mfma_f32_16x16x32_bf16 v[98:101], v[176:179], v[192:195], v[98:101]
	v_mfma_f32_16x16x32_bf16 v[86:89], v[168:171], v[210:213], v[86:89]
	v_mfma_f32_16x16x32_bf16 v[82:85], v[176:179], v[210:213], v[82:85]
	v_mfma_f32_16x16x32_bf16 v[70:73], v[168:171], v[218:221], v[70:73]
	v_mfma_f32_16x16x32_bf16 v[66:69], v[176:179], v[218:221], v[66:69]
	v_mfma_f32_16x16x32_bf16 v[118:121], v[172:175], v[188:191], v[118:121]
	v_mfma_f32_16x16x32_bf16 v[114:117], v[180:183], v[188:191], v[114:117]
	v_mfma_f32_16x16x32_bf16 v[102:105], v[172:175], v[198:201], v[102:105]
	v_mfma_f32_16x16x32_bf16 v[98:101], v[180:183], v[198:201], v[98:101]
	v_mfma_f32_16x16x32_bf16 v[86:89], v[172:175], v[214:217], v[86:89]
	v_mfma_f32_16x16x32_bf16 v[82:85], v[180:183], v[214:217], v[82:85]
	v_mfma_f32_16x16x32_bf16 v[70:73], v[172:175], v[222:225], v[70:73]
	s_barrier
	v_mfma_f32_16x16x32_bf16 v[66:69], v[180:183], v[222:225], v[66:69]
	s_setprio 2
	s_add_i32 s19, s60, s33
	v_lshl_add_u64 v[144:145], s[34:35], 0, v[132:133]
	s_mov_b32 m0, s19
	ds_read_b128 v[184:187], v150 offset:16384
	ds_read_b128 v[188:191], v150 offset:17408
	ds_read_b128 v[192:195], v150 offset:18432
	ds_read_b128 v[198:201], v150 offset:19456
	ds_read_b128 v[210:213], v150 offset:20480
	ds_read_b128 v[214:217], v150 offset:21504
	ds_read_b128 v[218:221], v150 offset:22528
	ds_read_b128 v[222:225], v150 offset:23552
	global_load_lds_dwordx4 v132, s[34:35]
	s_add_i32 m0, s19, 0x2000
	s_add_u32 s38, s34, 0x80000
	v_lshl_add_u64 v[202:203], s[34:35], 0, v[136:137]
	s_addc_u32 s39, s35, 0
	s_add_i32 s19, s61, s33
	global_load_lds_dwordx4 v136, s[34:35]
	s_mov_b32 m0, s19
	v_lshl_add_u64 v[226:227], s[36:37], 0, v[134:135]
	global_load_lds_dwordx4 v132, s[38:39]
	s_add_i32 m0, s19, 0x2000
	s_nop 0
	global_load_lds_dwordx4 v136, s[38:39]
	v_lshl_add_u64 v[206:207], s[36:37], 0, v[130:131]
	s_mov_b32 m0, s27
	s_nop 0
	global_load_lds_dwordx4 v130, s[36:37]
	s_mov_b32 m0, s41
	s_nop 0
	global_load_lds_dwordx4 v134, s[36:37]
	s_waitcnt vmcnt(8)
	s_waitcnt lgkmcnt(0)
	s_barrier
	s_setprio 1
	s_waitcnt lgkmcnt(0)
	v_mfma_f32_16x16x32_bf16 v[62:65], v[152:155], v[184:187], v[62:65]
	v_mfma_f32_16x16x32_bf16 v[58:61], v[160:163], v[184:187], v[58:61]
	v_mfma_f32_16x16x32_bf16 v[46:49], v[152:155], v[192:195], v[46:49]
	v_mfma_f32_16x16x32_bf16 v[42:45], v[160:163], v[192:195], v[42:45]
	v_mfma_f32_16x16x32_bf16 v[30:33], v[152:155], v[210:213], v[30:33]
	v_mfma_f32_16x16x32_bf16 v[26:29], v[160:163], v[210:213], v[26:29]
	v_mfma_f32_16x16x32_bf16 v[14:17], v[152:155], v[218:221], v[14:17]
	v_mfma_f32_16x16x32_bf16 v[10:13], v[160:163], v[218:221], v[10:13]
	v_mfma_f32_16x16x32_bf16 v[62:65], v[156:159], v[188:191], v[62:65]
	v_mfma_f32_16x16x32_bf16 v[58:61], v[164:167], v[188:191], v[58:61]
	v_mfma_f32_16x16x32_bf16 v[46:49], v[156:159], v[198:201], v[46:49]
	v_mfma_f32_16x16x32_bf16 v[42:45], v[164:167], v[198:201], v[42:45]
	v_mfma_f32_16x16x32_bf16 v[30:33], v[156:159], v[214:217], v[30:33]
	v_mfma_f32_16x16x32_bf16 v[26:29], v[164:167], v[214:217], v[26:29]
	v_mfma_f32_16x16x32_bf16 v[14:17], v[156:159], v[222:225], v[14:17]
	v_mfma_f32_16x16x32_bf16 v[10:13], v[164:167], v[222:225], v[10:13]
	v_mfma_f32_16x16x32_bf16 v[54:57], v[168:171], v[184:187], v[54:57]
	v_mfma_f32_16x16x32_bf16 v[50:53], v[176:179], v[184:187], v[50:53]
	v_mfma_f32_16x16x32_bf16 v[38:41], v[168:171], v[192:195], v[38:41]
	v_mfma_f32_16x16x32_bf16 v[34:37], v[176:179], v[192:195], v[34:37]
	v_mfma_f32_16x16x32_bf16 v[22:25], v[168:171], v[210:213], v[22:25]
	v_mfma_f32_16x16x32_bf16 v[18:21], v[176:179], v[210:213], v[18:21]
	v_mfma_f32_16x16x32_bf16 v[6:9], v[168:171], v[218:221], v[6:9]
	v_mfma_f32_16x16x32_bf16 v[2:5], v[176:179], v[218:221], v[2:5]
	v_mfma_f32_16x16x32_bf16 v[54:57], v[172:175], v[188:191], v[54:57]
	v_mfma_f32_16x16x32_bf16 v[50:53], v[180:183], v[188:191], v[50:53]
	v_mfma_f32_16x16x32_bf16 v[38:41], v[172:175], v[198:201], v[38:41]
	v_mfma_f32_16x16x32_bf16 v[34:37], v[180:183], v[198:201], v[34:37]
	v_mfma_f32_16x16x32_bf16 v[22:25], v[172:175], v[214:217], v[22:25]
	v_mfma_f32_16x16x32_bf16 v[18:21], v[180:183], v[214:217], v[18:21]
	v_mfma_f32_16x16x32_bf16 v[6:9], v[172:175], v[222:225], v[6:9]
	s_barrier
	v_mfma_f32_16x16x32_bf16 v[2:5], v[180:183], v[222:225], v[2:5]
	s_setprio 2
	s_add_i32 s19, 0, 0x18000
	s_add_i32 s38, 0, 0x1c000
	ds_read_b128 v[152:155], v250
	ds_read_b128 v[156:159], v250 offset:1024
	ds_read_b128 v[160:163], v250 offset:2048
	ds_read_b128 v[164:167], v250 offset:3072
	ds_read_b128 v[168:171], v250 offset:16384
	ds_read_b128 v[172:175], v250 offset:17408
	ds_read_b128 v[176:179], v250 offset:18432
	ds_read_b128 v[180:183], v250 offset:19456
	v_add_u32_e32 v151, s38, v146
	s_add_u32 s36, s36, 0x80000
	s_addc_u32 s37, s37, 0
	s_mov_b32 m0, s42
	ds_read_b128 v[184:187], v150 offset:32768
	ds_read_b128 v[188:191], v150 offset:33792
	ds_read_b128 v[192:195], v150 offset:34816
	ds_read_b128 v[198:201], v150 offset:35840
	ds_read_b128 v[210:213], v150 offset:36864
	ds_read_b128 v[214:217], v150 offset:37888
	ds_read_b128 v[218:221], v150 offset:38912
	ds_read_b128 v[222:225], v150 offset:39936
	global_load_lds_dwordx4 v130, s[36:37]
	v_lshl_add_u64 v[228:229], s[36:37], 0, v[134:135]
	s_mov_b32 m0, s43
	s_nop 0
	global_load_lds_dwordx4 v134, s[36:37]
	s_waitcnt vmcnt(8)
	s_waitcnt lgkmcnt(0)
	s_barrier
	s_setprio 1
	s_waitcnt lgkmcnt(0)
	v_mfma_f32_16x16x32_bf16 v[126:129], v[152:155], v[184:187], v[126:129]
	v_mfma_f32_16x16x32_bf16 v[122:125], v[160:163], v[184:187], v[122:125]
	v_mfma_f32_16x16x32_bf16 v[110:113], v[152:155], v[192:195], v[110:113]
	v_mfma_f32_16x16x32_bf16 v[106:109], v[160:163], v[192:195], v[106:109]
	v_mfma_f32_16x16x32_bf16 v[94:97], v[152:155], v[210:213], v[94:97]
	v_mfma_f32_16x16x32_bf16 v[90:93], v[160:163], v[210:213], v[90:93]
	v_mfma_f32_16x16x32_bf16 v[78:81], v[152:155], v[218:221], v[78:81]
	v_mfma_f32_16x16x32_bf16 v[74:77], v[160:163], v[218:221], v[74:77]
	v_mfma_f32_16x16x32_bf16 v[126:129], v[156:159], v[188:191], v[126:129]
	v_mfma_f32_16x16x32_bf16 v[122:125], v[164:167], v[188:191], v[122:125]
	v_mfma_f32_16x16x32_bf16 v[110:113], v[156:159], v[198:201], v[110:113]
	v_mfma_f32_16x16x32_bf16 v[106:109], v[164:167], v[198:201], v[106:109]
	v_mfma_f32_16x16x32_bf16 v[94:97], v[156:159], v[214:217], v[94:97]
	v_mfma_f32_16x16x32_bf16 v[90:93], v[164:167], v[214:217], v[90:93]
	v_mfma_f32_16x16x32_bf16 v[78:81], v[156:159], v[222:225], v[78:81]
	v_mfma_f32_16x16x32_bf16 v[74:77], v[164:167], v[222:225], v[74:77]
	v_mfma_f32_16x16x32_bf16 v[118:121], v[168:171], v[184:187], v[118:121]
	v_mfma_f32_16x16x32_bf16 v[114:117], v[176:179], v[184:187], v[114:117]
	v_mfma_f32_16x16x32_bf16 v[102:105], v[168:171], v[192:195], v[102:105]
	v_mfma_f32_16x16x32_bf16 v[98:101], v[176:179], v[192:195], v[98:101]
	v_mfma_f32_16x16x32_bf16 v[86:89], v[168:171], v[210:213], v[86:89]
	v_mfma_f32_16x16x32_bf16 v[82:85], v[176:179], v[210:213], v[82:85]
	v_mfma_f32_16x16x32_bf16 v[70:73], v[168:171], v[218:221], v[70:73]
	v_mfma_f32_16x16x32_bf16 v[66:69], v[176:179], v[218:221], v[66:69]
	v_mfma_f32_16x16x32_bf16 v[118:121], v[172:175], v[188:191], v[118:121]
	v_mfma_f32_16x16x32_bf16 v[114:117], v[180:183], v[188:191], v[114:117]
	v_mfma_f32_16x16x32_bf16 v[102:105], v[172:175], v[198:201], v[102:105]
	v_mfma_f32_16x16x32_bf16 v[98:101], v[180:183], v[198:201], v[98:101]
	v_mfma_f32_16x16x32_bf16 v[86:89], v[172:175], v[214:217], v[86:89]
	v_mfma_f32_16x16x32_bf16 v[82:85], v[180:183], v[214:217], v[82:85]
	v_mfma_f32_16x16x32_bf16 v[70:73], v[172:175], v[222:225], v[70:73]
	s_barrier
	v_mfma_f32_16x16x32_bf16 v[66:69], v[180:183], v[222:225], v[66:69]
	s_setprio 2
	s_add_i32 s19, s19, s33
	v_lshl_add_u64 v[144:145], v[144:145], 0, s[10:11]
	s_mov_b32 m0, s19
	ds_read_b128 v[184:187], v150 offset:49152
	ds_read_b128 v[188:191], v150 offset:50176
	ds_read_b128 v[192:195], v150 offset:51200
	ds_read_b128 v[198:201], v150 offset:52224
	ds_read_b128 v[210:213], v150 offset:53248
	ds_read_b128 v[214:217], v150 offset:54272
	ds_read_b128 v[218:221], v150 offset:55296
	ds_read_b128 v[222:225], v150 offset:56320
	global_load_lds_dwordx4 v[144:145], off
	s_add_i32 m0, s19, 0x2000
	s_add_u32 s34, s34, 0x80080
	v_lshl_add_u64 v[144:145], v[202:203], 0, s[10:11]
	s_addc_u32 s35, s35, 0
	s_add_i32 s19, s38, s33
	global_load_lds_dwordx4 v[144:145], off
	s_mov_b32 m0, s19
	s_nop 0
	global_load_lds_dwordx4 v132, s[34:35]
	s_add_i32 m0, s19, 0x2000
	s_nop 0
	global_load_lds_dwordx4 v136, s[34:35]
	v_lshl_add_u64 v[144:145], v[206:207], 0, s[10:11]
	s_mov_b32 m0, s51
	s_nop 0
	global_load_lds_dwordx4 v[144:145], off
	v_lshl_add_u64 v[144:145], v[226:227], 0, s[10:11]
	s_mov_b32 m0, s52
	s_nop 0
	global_load_lds_dwordx4 v[144:145], off
	s_waitcnt vmcnt(8)
	s_waitcnt lgkmcnt(0)
	s_barrier
	s_setprio 1
	s_waitcnt lgkmcnt(0)
	v_mfma_f32_16x16x32_bf16 v[62:65], v[152:155], v[184:187], v[62:65]
	v_mfma_f32_16x16x32_bf16 v[58:61], v[160:163], v[184:187], v[58:61]
	v_mfma_f32_16x16x32_bf16 v[46:49], v[152:155], v[192:195], v[46:49]
	v_mfma_f32_16x16x32_bf16 v[42:45], v[160:163], v[192:195], v[42:45]
	v_mfma_f32_16x16x32_bf16 v[30:33], v[152:155], v[210:213], v[30:33]
	v_mfma_f32_16x16x32_bf16 v[26:29], v[160:163], v[210:213], v[26:29]
	v_mfma_f32_16x16x32_bf16 v[14:17], v[152:155], v[218:221], v[14:17]
	v_mfma_f32_16x16x32_bf16 v[10:13], v[160:163], v[218:221], v[10:13]
	v_mfma_f32_16x16x32_bf16 v[62:65], v[156:159], v[188:191], v[62:65]
	v_mfma_f32_16x16x32_bf16 v[58:61], v[164:167], v[188:191], v[58:61]
	v_mfma_f32_16x16x32_bf16 v[46:49], v[156:159], v[198:201], v[46:49]
	v_mfma_f32_16x16x32_bf16 v[42:45], v[164:167], v[198:201], v[42:45]
	v_mfma_f32_16x16x32_bf16 v[30:33], v[156:159], v[214:217], v[30:33]
	v_mfma_f32_16x16x32_bf16 v[26:29], v[164:167], v[214:217], v[26:29]
	v_mfma_f32_16x16x32_bf16 v[14:17], v[156:159], v[222:225], v[14:17]
	v_mfma_f32_16x16x32_bf16 v[10:13], v[164:167], v[222:225], v[10:13]
	v_mfma_f32_16x16x32_bf16 v[54:57], v[168:171], v[184:187], v[54:57]
	v_mfma_f32_16x16x32_bf16 v[50:53], v[176:179], v[184:187], v[50:53]
	v_mfma_f32_16x16x32_bf16 v[38:41], v[168:171], v[192:195], v[38:41]
	v_mfma_f32_16x16x32_bf16 v[34:37], v[176:179], v[192:195], v[34:37]
	v_mfma_f32_16x16x32_bf16 v[22:25], v[168:171], v[210:213], v[22:25]
	v_mfma_f32_16x16x32_bf16 v[18:21], v[176:179], v[210:213], v[18:21]
	v_mfma_f32_16x16x32_bf16 v[6:9], v[168:171], v[218:221], v[6:9]
	v_mfma_f32_16x16x32_bf16 v[2:5], v[176:179], v[218:221], v[2:5]
	v_mfma_f32_16x16x32_bf16 v[54:57], v[172:175], v[188:191], v[54:57]
	v_mfma_f32_16x16x32_bf16 v[50:53], v[180:183], v[188:191], v[50:53]
	v_mfma_f32_16x16x32_bf16 v[38:41], v[172:175], v[198:201], v[38:41]
	v_mfma_f32_16x16x32_bf16 v[34:37], v[180:183], v[198:201], v[34:37]
	v_mfma_f32_16x16x32_bf16 v[22:25], v[172:175], v[214:217], v[22:25]
	v_mfma_f32_16x16x32_bf16 v[18:21], v[180:183], v[214:217], v[18:21]
	v_mfma_f32_16x16x32_bf16 v[6:9], v[172:175], v[222:225], v[6:9]
	s_barrier
	v_mfma_f32_16x16x32_bf16 v[2:5], v[180:183], v[222:225], v[2:5]
	s_setprio 2
	s_add_u32 s30, s30, 0x100
	s_addc_u32 s31, s31, 0
	s_add_u32 s15, s15, 0x100
	s_addc_u32 s17, s17, 0
	s_cmp_ge_i32 s29, s68
	s_mov_b32 s19, s29
	s_cbranch_scc0 .LBB0_2547

.Lpeel_0:
	v_add_u32_e32 v250, 0x18000, v168
	ds_read_b128 v[144:147], v170
	ds_read_b128 v[148:151], v170 offset:1024
	ds_read_b128 v[152:155], v170 offset:2048
	ds_read_b128 v[156:159], v170 offset:3072
	ds_read_b128 v[160:163], v171
	ds_read_b128 v[164:167], v171 offset:1024
	ds_read_b128 v[174:177], v171 offset:2048
	ds_read_b128 v[178:181], v171 offset:3072
	s_add_i32 s30, s26, 2
	s_add_u32 s27, s24, 0xffea0080
	s_addc_u32 s28, s25, -1
	s_cmp_eq_u32 s22, s26
	s_cselect_b32 s26, s20, s17
	s_cselect_b32 s29, s19, s28
	s_cselect_b32 s28, s18, s27
	s_cselect_b32 s27, s21, s23
	s_add_i32 m0, s34, 0xc000
	ds_read_b128 v[182:185], v172
	ds_read_b128 v[186:189], v172 offset:1024
	ds_read_b128 v[190:193], v172 offset:2048
	ds_read_b128 v[194:197], v172 offset:3072
	ds_read_b128 v[198:201], v172 offset:4096
	ds_read_b128 v[202:205], v172 offset:5120
	ds_read_b128 v[206:209], v172 offset:6144
	ds_read_b128 v[210:213], v172 offset:7168
	global_load_lds_dwordx4 v140, s[24:25]
	s_add_i32 m0, s34, 0xe000
	s_nop 0
	global_load_lds_dwordx4 v142, s[24:25]
	s_waitcnt vmcnt(8)
	s_waitcnt lgkmcnt(0)
	s_barrier
	s_setprio 1
	s_waitcnt lgkmcnt(0)
	v_mfma_f32_16x16x32_bf16 v[126:129], v[144:147], v[182:185], 0
	v_mfma_f32_16x16x32_bf16 v[122:125], v[152:155], v[182:185], 0
	v_mfma_f32_16x16x32_bf16 v[118:121], v[144:147], v[190:193], 0
	v_mfma_f32_16x16x32_bf16 v[110:113], v[152:155], v[190:193], 0
	v_mfma_f32_16x16x32_bf16 v[94:97], v[144:147], v[198:201], 0
	v_mfma_f32_16x16x32_bf16 v[90:93], v[152:155], v[198:201], 0
	v_mfma_f32_16x16x32_bf16 v[82:85], v[144:147], v[206:209], 0
	v_mfma_f32_16x16x32_bf16 v[74:77], v[152:155], v[206:209], 0
	v_mfma_f32_16x16x32_bf16 v[126:129], v[148:151], v[186:189], v[126:129]
	v_mfma_f32_16x16x32_bf16 v[122:125], v[156:159], v[186:189], v[122:125]
	v_mfma_f32_16x16x32_bf16 v[118:121], v[148:151], v[194:197], v[118:121]
	v_mfma_f32_16x16x32_bf16 v[110:113], v[156:159], v[194:197], v[110:113]
	v_mfma_f32_16x16x32_bf16 v[94:97], v[148:151], v[202:205], v[94:97]
	v_mfma_f32_16x16x32_bf16 v[90:93], v[156:159], v[202:205], v[90:93]
	v_mfma_f32_16x16x32_bf16 v[82:85], v[148:151], v[210:213], v[82:85]
	v_mfma_f32_16x16x32_bf16 v[74:77], v[156:159], v[210:213], v[74:77]
	v_mfma_f32_16x16x32_bf16 v[114:117], v[160:163], v[182:185], 0
	v_mfma_f32_16x16x32_bf16 v[106:109], v[174:177], v[182:185], 0
	v_mfma_f32_16x16x32_bf16 v[102:105], v[160:163], v[190:193], 0
	v_mfma_f32_16x16x32_bf16 v[98:101], v[174:177], v[190:193], 0
	v_mfma_f32_16x16x32_bf16 v[86:89], v[160:163], v[198:201], 0
	v_mfma_f32_16x16x32_bf16 v[78:81], v[174:177], v[198:201], 0
	v_mfma_f32_16x16x32_bf16 v[70:73], v[160:163], v[206:209], 0
	v_mfma_f32_16x16x32_bf16 v[66:69], v[174:177], v[206:209], 0
	v_mfma_f32_16x16x32_bf16 v[114:117], v[164:167], v[186:189], v[114:117]
	v_mfma_f32_16x16x32_bf16 v[106:109], v[178:181], v[186:189], v[106:109]
	v_mfma_f32_16x16x32_bf16 v[102:105], v[164:167], v[194:197], v[102:105]
	v_mfma_f32_16x16x32_bf16 v[98:101], v[178:181], v[194:197], v[98:101]
	v_mfma_f32_16x16x32_bf16 v[86:89], v[164:167], v[202:205], v[86:89]
	v_mfma_f32_16x16x32_bf16 v[78:81], v[178:181], v[202:205], v[78:81]
	v_mfma_f32_16x16x32_bf16 v[70:73], v[164:167], v[210:213], v[70:73]
	s_barrier
	v_mfma_f32_16x16x32_bf16 v[66:69], v[178:181], v[210:213], v[66:69]
	s_setprio 2
	s_add_i32 s31, s57, s33
	v_lshl_add_u64 v[214:215], s[26:27], 0, v[132:133]
	s_mov_b32 m0, s31
	ds_read_b128 v[182:185], v172 offset:16384
	ds_read_b128 v[186:189], v172 offset:17408
	ds_read_b128 v[190:193], v172 offset:18432
	ds_read_b128 v[194:197], v172 offset:19456
	ds_read_b128 v[198:201], v172 offset:20480
	ds_read_b128 v[202:205], v172 offset:21504
	ds_read_b128 v[206:209], v172 offset:22528
	ds_read_b128 v[210:213], v172 offset:23552
	global_load_lds_dwordx4 v132, s[26:27]
	s_add_i32 m0, s31, 0x2000
	s_add_u32 s68, s26, 0x160000
	v_lshl_add_u64 v[216:217], s[26:27], 0, v[136:137]
	s_addc_u32 s69, s27, 0
	s_add_i32 s31, s58, s33
	global_load_lds_dwordx4 v136, s[26:27]
	s_mov_b32 m0, s31
	v_lshl_add_u64 v[220:221], s[28:29], 0, v[134:135]
	global_load_lds_dwordx4 v132, s[68:69]
	s_add_i32 m0, s31, 0x2000
	s_nop 0
	global_load_lds_dwordx4 v136, s[68:69]
	v_lshl_add_u64 v[218:219], s[28:29], 0, v[130:131]
	s_mov_b32 m0, s34
	s_nop 0
	global_load_lds_dwordx4 v130, s[28:29]
	s_mov_b32 m0, s35
	s_nop 0
	global_load_lds_dwordx4 v134, s[28:29]
	s_waitcnt vmcnt(8)
	s_waitcnt lgkmcnt(0)
	s_barrier
	s_setprio 1
	s_waitcnt lgkmcnt(0)
	v_mfma_f32_16x16x32_bf16 v[62:65], v[144:147], v[182:185], 0
	v_mfma_f32_16x16x32_bf16 v[58:61], v[152:155], v[182:185], 0
	v_mfma_f32_16x16x32_bf16 v[50:53], v[144:147], v[190:193], 0
	v_mfma_f32_16x16x32_bf16 v[42:45], v[152:155], v[190:193], 0
	v_mfma_f32_16x16x32_bf16 v[30:33], v[144:147], v[198:201], 0
	v_mfma_f32_16x16x32_bf16 v[26:29], v[152:155], v[198:201], 0
	v_mfma_f32_16x16x32_bf16 v[18:21], v[144:147], v[206:209], 0
	v_mfma_f32_16x16x32_bf16 v[10:13], v[152:155], v[206:209], 0
	v_mfma_f32_16x16x32_bf16 v[62:65], v[148:151], v[186:189], v[62:65]
	v_mfma_f32_16x16x32_bf16 v[58:61], v[156:159], v[186:189], v[58:61]
	v_mfma_f32_16x16x32_bf16 v[50:53], v[148:151], v[194:197], v[50:53]
	v_mfma_f32_16x16x32_bf16 v[42:45], v[156:159], v[194:197], v[42:45]
	v_mfma_f32_16x16x32_bf16 v[30:33], v[148:151], v[202:205], v[30:33]
	v_mfma_f32_16x16x32_bf16 v[26:29], v[156:159], v[202:205], v[26:29]
	v_mfma_f32_16x16x32_bf16 v[18:21], v[148:151], v[210:213], v[18:21]
	v_mfma_f32_16x16x32_bf16 v[10:13], v[156:159], v[210:213], v[10:13]
	v_mfma_f32_16x16x32_bf16 v[54:57], v[160:163], v[182:185], 0
	v_mfma_f32_16x16x32_bf16 v[46:49], v[174:177], v[182:185], 0
	v_mfma_f32_16x16x32_bf16 v[38:41], v[160:163], v[190:193], 0
	v_mfma_f32_16x16x32_bf16 v[34:37], v[174:177], v[190:193], 0
	v_mfma_f32_16x16x32_bf16 v[22:25], v[160:163], v[198:201], 0
	v_mfma_f32_16x16x32_bf16 v[14:17], v[174:177], v[198:201], 0
	v_mfma_f32_16x16x32_bf16 v[6:9], v[160:163], v[206:209], 0
	v_mfma_f32_16x16x32_bf16 v[2:5], v[174:177], v[206:209], 0
	v_mfma_f32_16x16x32_bf16 v[54:57], v[164:167], v[186:189], v[54:57]
	v_mfma_f32_16x16x32_bf16 v[46:49], v[178:181], v[186:189], v[46:49]
	v_mfma_f32_16x16x32_bf16 v[38:41], v[164:167], v[194:197], v[38:41]
	v_mfma_f32_16x16x32_bf16 v[34:37], v[178:181], v[194:197], v[34:37]
	v_mfma_f32_16x16x32_bf16 v[22:25], v[164:167], v[202:205], v[22:25]
	v_mfma_f32_16x16x32_bf16 v[14:17], v[178:181], v[202:205], v[14:17]
	v_mfma_f32_16x16x32_bf16 v[6:9], v[164:167], v[210:213], v[6:9]
	s_barrier
	v_mfma_f32_16x16x32_bf16 v[2:5], v[178:181], v[210:213], v[2:5]
	s_setprio 2
	s_add_i32 s31, 0, 0x18000
	s_add_i32 s68, 0, 0x1c000
	ds_read_b128 v[144:147], v250
	ds_read_b128 v[148:151], v250 offset:1024
	ds_read_b128 v[152:155], v250 offset:2048
	ds_read_b128 v[156:159], v250 offset:3072
	ds_read_b128 v[160:163], v250 offset:16384
	ds_read_b128 v[164:167], v250 offset:17408
	ds_read_b128 v[174:177], v250 offset:18432
	ds_read_b128 v[178:181], v250 offset:19456
	v_add_u32_e32 v173, s68, v168
	s_add_u32 s28, s28, 0x160000
	s_addc_u32 s29, s29, 0
	s_mov_b32 m0, s36
	ds_read_b128 v[182:185], v172 offset:32768
	ds_read_b128 v[186:189], v172 offset:33792
	ds_read_b128 v[190:193], v172 offset:34816
	ds_read_b128 v[194:197], v172 offset:35840
	ds_read_b128 v[198:201], v172 offset:36864
	ds_read_b128 v[202:205], v172 offset:37888
	ds_read_b128 v[206:209], v172 offset:38912
	ds_read_b128 v[210:213], v172 offset:39936
	global_load_lds_dwordx4 v130, s[28:29]
	v_lshl_add_u64 v[222:223], s[28:29], 0, v[134:135]
	s_mov_b32 m0, s37
	s_nop 0
	global_load_lds_dwordx4 v134, s[28:29]
	s_waitcnt vmcnt(8)
	s_waitcnt lgkmcnt(0)
	s_barrier
	s_setprio 1
	s_waitcnt lgkmcnt(0)
	v_mfma_f32_16x16x32_bf16 v[126:129], v[144:147], v[182:185], v[126:129]
	v_mfma_f32_16x16x32_bf16 v[122:125], v[152:155], v[182:185], v[122:125]
	v_mfma_f32_16x16x32_bf16 v[118:121], v[144:147], v[190:193], v[118:121]
	v_mfma_f32_16x16x32_bf16 v[110:113], v[152:155], v[190:193], v[110:113]
	v_mfma_f32_16x16x32_bf16 v[94:97], v[144:147], v[198:201], v[94:97]
	v_mfma_f32_16x16x32_bf16 v[90:93], v[152:155], v[198:201], v[90:93]
	v_mfma_f32_16x16x32_bf16 v[82:85], v[144:147], v[206:209], v[82:85]
	v_mfma_f32_16x16x32_bf16 v[74:77], v[152:155], v[206:209], v[74:77]
	v_mfma_f32_16x16x32_bf16 v[126:129], v[148:151], v[186:189], v[126:129]
	v_mfma_f32_16x16x32_bf16 v[122:125], v[156:159], v[186:189], v[122:125]
	v_mfma_f32_16x16x32_bf16 v[118:121], v[148:151], v[194:197], v[118:121]
	v_mfma_f32_16x16x32_bf16 v[110:113], v[156:159], v[194:197], v[110:113]
	v_mfma_f32_16x16x32_bf16 v[94:97], v[148:151], v[202:205], v[94:97]
	v_mfma_f32_16x16x32_bf16 v[90:93], v[156:159], v[202:205], v[90:93]
	v_mfma_f32_16x16x32_bf16 v[82:85], v[148:151], v[210:213], v[82:85]
	v_mfma_f32_16x16x32_bf16 v[74:77], v[156:159], v[210:213], v[74:77]
	v_mfma_f32_16x16x32_bf16 v[114:117], v[160:163], v[182:185], v[114:117]
	v_mfma_f32_16x16x32_bf16 v[106:109], v[174:177], v[182:185], v[106:109]
	v_mfma_f32_16x16x32_bf16 v[102:105], v[160:163], v[190:193], v[102:105]
	v_mfma_f32_16x16x32_bf16 v[98:101], v[174:177], v[190:193], v[98:101]
	v_mfma_f32_16x16x32_bf16 v[86:89], v[160:163], v[198:201], v[86:89]
	v_mfma_f32_16x16x32_bf16 v[78:81], v[174:177], v[198:201], v[78:81]
	v_mfma_f32_16x16x32_bf16 v[70:73], v[160:163], v[206:209], v[70:73]
	v_mfma_f32_16x16x32_bf16 v[66:69], v[174:177], v[206:209], v[66:69]
	v_mfma_f32_16x16x32_bf16 v[114:117], v[164:167], v[186:189], v[114:117]
	v_mfma_f32_16x16x32_bf16 v[106:109], v[178:181], v[186:189], v[106:109]
	v_mfma_f32_16x16x32_bf16 v[102:105], v[164:167], v[194:197], v[102:105]
	v_mfma_f32_16x16x32_bf16 v[98:101], v[178:181], v[194:197], v[98:101]
	v_mfma_f32_16x16x32_bf16 v[86:89], v[164:167], v[202:205], v[86:89]
	v_mfma_f32_16x16x32_bf16 v[78:81], v[178:181], v[202:205], v[78:81]
	v_mfma_f32_16x16x32_bf16 v[70:73], v[164:167], v[210:213], v[70:73]
	s_barrier
	v_mfma_f32_16x16x32_bf16 v[66:69], v[178:181], v[210:213], v[66:69]
	s_setprio 2
	s_add_i32 s28, s31, s33
	v_lshl_add_u64 v[214:215], v[214:215], 0, s[12:13]
	s_mov_b32 m0, s28
	ds_read_b128 v[182:185], v172 offset:49152
	ds_read_b128 v[186:189], v172 offset:50176
	ds_read_b128 v[190:193], v172 offset:51200
	ds_read_b128 v[194:197], v172 offset:52224
	ds_read_b128 v[198:201], v172 offset:53248
	ds_read_b128 v[202:205], v172 offset:54272
	ds_read_b128 v[206:209], v172 offset:55296
	ds_read_b128 v[210:213], v172 offset:56320
	global_load_lds_dwordx4 v[214:215], off
	s_add_i32 m0, s28, 0x2000
	s_add_u32 s26, s26, 0x160080
	v_lshl_add_u64 v[214:215], v[216:217], 0, s[12:13]
	s_addc_u32 s27, s27, 0
	s_add_i32 s28, s68, s33
	global_load_lds_dwordx4 v[214:215], off
	s_mov_b32 m0, s28
	s_nop 0
	global_load_lds_dwordx4 v132, s[26:27]
	s_add_i32 m0, s28, 0x2000
	s_nop 0
	global_load_lds_dwordx4 v136, s[26:27]
	v_lshl_add_u64 v[214:215], v[218:219], 0, s[12:13]
	s_mov_b32 m0, s47
	s_nop 0
	global_load_lds_dwordx4 v[214:215], off
	v_lshl_add_u64 v[214:215], v[220:221], 0, s[12:13]
	s_mov_b32 m0, s48
	s_nop 0
	global_load_lds_dwordx4 v[214:215], off
	s_waitcnt vmcnt(8)
	s_waitcnt lgkmcnt(0)
	s_barrier
	s_setprio 1
	s_waitcnt lgkmcnt(0)
	v_mfma_f32_16x16x32_bf16 v[62:65], v[144:147], v[182:185], v[62:65]
	v_mfma_f32_16x16x32_bf16 v[58:61], v[152:155], v[182:185], v[58:61]
	v_mfma_f32_16x16x32_bf16 v[50:53], v[144:147], v[190:193], v[50:53]
	v_mfma_f32_16x16x32_bf16 v[42:45], v[152:155], v[190:193], v[42:45]
	v_mfma_f32_16x16x32_bf16 v[30:33], v[144:147], v[198:201], v[30:33]
	v_mfma_f32_16x16x32_bf16 v[26:29], v[152:155], v[198:201], v[26:29]
	v_mfma_f32_16x16x32_bf16 v[18:21], v[144:147], v[206:209], v[18:21]
	v_mfma_f32_16x16x32_bf16 v[10:13], v[152:155], v[206:209], v[10:13]
	v_mfma_f32_16x16x32_bf16 v[62:65], v[148:151], v[186:189], v[62:65]
	v_mfma_f32_16x16x32_bf16 v[58:61], v[156:159], v[186:189], v[58:61]
	v_mfma_f32_16x16x32_bf16 v[50:53], v[148:151], v[194:197], v[50:53]
	v_mfma_f32_16x16x32_bf16 v[42:45], v[156:159], v[194:197], v[42:45]
	v_mfma_f32_16x16x32_bf16 v[30:33], v[148:151], v[202:205], v[30:33]
	v_mfma_f32_16x16x32_bf16 v[26:29], v[156:159], v[202:205], v[26:29]
	v_mfma_f32_16x16x32_bf16 v[18:21], v[148:151], v[210:213], v[18:21]
	v_mfma_f32_16x16x32_bf16 v[10:13], v[156:159], v[210:213], v[10:13]
	v_mfma_f32_16x16x32_bf16 v[54:57], v[160:163], v[182:185], v[54:57]
	v_mfma_f32_16x16x32_bf16 v[46:49], v[174:177], v[182:185], v[46:49]
	v_mfma_f32_16x16x32_bf16 v[38:41], v[160:163], v[190:193], v[38:41]
	v_mfma_f32_16x16x32_bf16 v[34:37], v[174:177], v[190:193], v[34:37]
	v_mfma_f32_16x16x32_bf16 v[22:25], v[160:163], v[198:201], v[22:25]
	v_mfma_f32_16x16x32_bf16 v[14:17], v[174:177], v[198:201], v[14:17]
	v_mfma_f32_16x16x32_bf16 v[6:9], v[160:163], v[206:209], v[6:9]
	v_mfma_f32_16x16x32_bf16 v[2:5], v[174:177], v[206:209], v[2:5]
	v_mfma_f32_16x16x32_bf16 v[54:57], v[164:167], v[186:189], v[54:57]
	v_mfma_f32_16x16x32_bf16 v[46:49], v[178:181], v[186:189], v[46:49]
	v_mfma_f32_16x16x32_bf16 v[38:41], v[164:167], v[194:197], v[38:41]
	v_mfma_f32_16x16x32_bf16 v[34:37], v[178:181], v[194:197], v[34:37]
	v_mfma_f32_16x16x32_bf16 v[22:25], v[164:167], v[202:205], v[22:25]
	v_mfma_f32_16x16x32_bf16 v[14:17], v[178:181], v[202:205], v[14:17]
	v_mfma_f32_16x16x32_bf16 v[6:9], v[164:167], v[210:213], v[6:9]
	s_barrier
	v_mfma_f32_16x16x32_bf16 v[2:5], v[178:181], v[210:213], v[2:5]
	s_setprio 2
	s_add_u32 s24, s24, 0x100
	s_addc_u32 s25, s25, 0
	s_add_u32 s17, s17, 0x100
	s_addc_u32 s23, s23, 0
	s_cmp_ge_i32 s30, s67
	s_mov_b32 s26, s30
	s_cbranch_scc0 .LBB0_2683
	s_branch .Lpeeldone_0
.LBB0_2683:
	ds_read_b128 v[144:147], v170
	ds_read_b128 v[148:151], v170 offset:1024
	ds_read_b128 v[152:155], v170 offset:2048
	ds_read_b128 v[156:159], v170 offset:3072
	ds_read_b128 v[160:163], v171
	ds_read_b128 v[164:167], v171 offset:1024
	ds_read_b128 v[174:177], v171 offset:2048
	ds_read_b128 v[178:181], v171 offset:3072
	s_add_i32 s30, s26, 2
	s_add_u32 s27, s24, 0xffea0080
	s_addc_u32 s28, s25, -1
	s_cmp_eq_u32 s22, s26
	s_cselect_b32 s26, s20, s17
	s_cselect_b32 s29, s19, s28
	s_cselect_b32 s28, s18, s27
	s_cselect_b32 s27, s21, s23
	s_add_i32 m0, s34, 0xc000
	ds_read_b128 v[182:185], v172
	ds_read_b128 v[186:189], v172 offset:1024
	ds_read_b128 v[190:193], v172 offset:2048
	ds_read_b128 v[194:197], v172 offset:3072
	ds_read_b128 v[198:201], v172 offset:4096
	ds_read_b128 v[202:205], v172 offset:5120
	ds_read_b128 v[206:209], v172 offset:6144
	ds_read_b128 v[210:213], v172 offset:7168
	global_load_lds_dwordx4 v140, s[24:25]
	s_add_i32 m0, s34, 0xe000
	s_nop 0
	global_load_lds_dwordx4 v142, s[24:25]
	s_waitcnt vmcnt(8)
	s_waitcnt lgkmcnt(0)
	s_barrier
	s_setprio 1
	s_waitcnt lgkmcnt(0)
	v_mfma_f32_16x16x32_bf16 v[126:129], v[144:147], v[182:185], v[126:129]
	v_mfma_f32_16x16x32_bf16 v[122:125], v[152:155], v[182:185], v[122:125]
	v_mfma_f32_16x16x32_bf16 v[118:121], v[144:147], v[190:193], v[118:121]
	v_mfma_f32_16x16x32_bf16 v[110:113], v[152:155], v[190:193], v[110:113]
	v_mfma_f32_16x16x32_bf16 v[94:97], v[144:147], v[198:201], v[94:97]
	v_mfma_f32_16x16x32_bf16 v[90:93], v[152:155], v[198:201], v[90:93]
	v_mfma_f32_16x16x32_bf16 v[82:85], v[144:147], v[206:209], v[82:85]
	v_mfma_f32_16x16x32_bf16 v[74:77], v[152:155], v[206:209], v[74:77]
	v_mfma_f32_16x16x32_bf16 v[126:129], v[148:151], v[186:189], v[126:129]
	v_mfma_f32_16x16x32_bf16 v[122:125], v[156:159], v[186:189], v[122:125]
	v_mfma_f32_16x16x32_bf16 v[118:121], v[148:151], v[194:197], v[118:121]
	v_mfma_f32_16x16x32_bf16 v[110:113], v[156:159], v[194:197], v[110:113]
	v_mfma_f32_16x16x32_bf16 v[94:97], v[148:151], v[202:205], v[94:97]
	v_mfma_f32_16x16x32_bf16 v[90:93], v[156:159], v[202:205], v[90:93]
	v_mfma_f32_16x16x32_bf16 v[82:85], v[148:151], v[210:213], v[82:85]
	v_mfma_f32_16x16x32_bf16 v[74:77], v[156:159], v[210:213], v[74:77]
	v_mfma_f32_16x16x32_bf16 v[114:117], v[160:163], v[182:185], v[114:117]
	v_mfma_f32_16x16x32_bf16 v[106:109], v[174:177], v[182:185], v[106:109]
	v_mfma_f32_16x16x32_bf16 v[102:105], v[160:163], v[190:193], v[102:105]
	v_mfma_f32_16x16x32_bf16 v[98:101], v[174:177], v[190:193], v[98:101]
	v_mfma_f32_16x16x32_bf16 v[86:89], v[160:163], v[198:201], v[86:89]
	v_mfma_f32_16x16x32_bf16 v[78:81], v[174:177], v[198:201], v[78:81]
	v_mfma_f32_16x16x32_bf16 v[70:73], v[160:163], v[206:209], v[70:73]
	v_mfma_f32_16x16x32_bf16 v[66:69], v[174:177], v[206:209], v[66:69]
	v_mfma_f32_16x16x32_bf16 v[114:117], v[164:167], v[186:189], v[114:117]
	v_mfma_f32_16x16x32_bf16 v[106:109], v[178:181], v[186:189], v[106:109]
	v_mfma_f32_16x16x32_bf16 v[102:105], v[164:167], v[194:197], v[102:105]
	v_mfma_f32_16x16x32_bf16 v[98:101], v[178:181], v[194:197], v[98:101]
	v_mfma_f32_16x16x32_bf16 v[86:89], v[164:167], v[202:205], v[86:89]
	v_mfma_f32_16x16x32_bf16 v[78:81], v[178:181], v[202:205], v[78:81]
	v_mfma_f32_16x16x32_bf16 v[70:73], v[164:167], v[210:213], v[70:73]
	s_barrier
	v_mfma_f32_16x16x32_bf16 v[66:69], v[178:181], v[210:213], v[66:69]
	s_setprio 2
	s_add_i32 s31, s57, s33
	v_lshl_add_u64 v[214:215], s[26:27], 0, v[132:133]
	s_mov_b32 m0, s31
	ds_read_b128 v[182:185], v172 offset:16384
	ds_read_b128 v[186:189], v172 offset:17408
	ds_read_b128 v[190:193], v172 offset:18432
	ds_read_b128 v[194:197], v172 offset:19456
	ds_read_b128 v[198:201], v172 offset:20480
	ds_read_b128 v[202:205], v172 offset:21504
	ds_read_b128 v[206:209], v172 offset:22528
	ds_read_b128 v[210:213], v172 offset:23552
	global_load_lds_dwordx4 v132, s[26:27]
	s_add_i32 m0, s31, 0x2000
	s_add_u32 s68, s26, 0x160000
	v_lshl_add_u64 v[216:217], s[26:27], 0, v[136:137]
	s_addc_u32 s69, s27, 0
	s_add_i32 s31, s58, s33
	global_load_lds_dwordx4 v136, s[26:27]
	s_mov_b32 m0, s31
	v_lshl_add_u64 v[220:221], s[28:29], 0, v[134:135]
	global_load_lds_dwordx4 v132, s[68:69]
	s_add_i32 m0, s31, 0x2000
	s_nop 0
	global_load_lds_dwordx4 v136, s[68:69]
	v_lshl_add_u64 v[218:219], s[28:29], 0, v[130:131]
	s_mov_b32 m0, s34
	s_nop 0
	global_load_lds_dwordx4 v130, s[28:29]
	s_mov_b32 m0, s35
	s_nop 0
	global_load_lds_dwordx4 v134, s[28:29]
	s_waitcnt vmcnt(8)
	s_waitcnt lgkmcnt(0)
	s_barrier
	s_setprio 1
	s_waitcnt lgkmcnt(0)
	v_mfma_f32_16x16x32_bf16 v[62:65], v[144:147], v[182:185], v[62:65]
	v_mfma_f32_16x16x32_bf16 v[58:61], v[152:155], v[182:185], v[58:61]
	v_mfma_f32_16x16x32_bf16 v[50:53], v[144:147], v[190:193], v[50:53]
	v_mfma_f32_16x16x32_bf16 v[42:45], v[152:155], v[190:193], v[42:45]
	v_mfma_f32_16x16x32_bf16 v[30:33], v[144:147], v[198:201], v[30:33]
	v_mfma_f32_16x16x32_bf16 v[26:29], v[152:155], v[198:201], v[26:29]
	v_mfma_f32_16x16x32_bf16 v[18:21], v[144:147], v[206:209], v[18:21]
	v_mfma_f32_16x16x32_bf16 v[10:13], v[152:155], v[206:209], v[10:13]
	v_mfma_f32_16x16x32_bf16 v[62:65], v[148:151], v[186:189], v[62:65]
	v_mfma_f32_16x16x32_bf16 v[58:61], v[156:159], v[186:189], v[58:61]
	v_mfma_f32_16x16x32_bf16 v[50:53], v[148:151], v[194:197], v[50:53]
	v_mfma_f32_16x16x32_bf16 v[42:45], v[156:159], v[194:197], v[42:45]
	v_mfma_f32_16x16x32_bf16 v[30:33], v[148:151], v[202:205], v[30:33]
	v_mfma_f32_16x16x32_bf16 v[26:29], v[156:159], v[202:205], v[26:29]
	v_mfma_f32_16x16x32_bf16 v[18:21], v[148:151], v[210:213], v[18:21]
	v_mfma_f32_16x16x32_bf16 v[10:13], v[156:159], v[210:213], v[10:13]
	v_mfma_f32_16x16x32_bf16 v[54:57], v[160:163], v[182:185], v[54:57]
	v_mfma_f32_16x16x32_bf16 v[46:49], v[174:177], v[182:185], v[46:49]
	v_mfma_f32_16x16x32_bf16 v[38:41], v[160:163], v[190:193], v[38:41]
	v_mfma_f32_16x16x32_bf16 v[34:37], v[174:177], v[190:193], v[34:37]
	v_mfma_f32_16x16x32_bf16 v[22:25], v[160:163], v[198:201], v[22:25]
	v_mfma_f32_16x16x32_bf16 v[14:17], v[174:177], v[198:201], v[14:17]
	v_mfma_f32_16x16x32_bf16 v[6:9], v[160:163], v[206:209], v[6:9]
	v_mfma_f32_16x16x32_bf16 v[2:5], v[174:177], v[206:209], v[2:5]
	v_mfma_f32_16x16x32_bf16 v[54:57], v[164:167], v[186:189], v[54:57]
	v_mfma_f32_16x16x32_bf16 v[46:49], v[178:181], v[186:189], v[46:49]
	v_mfma_f32_16x16x32_bf16 v[38:41], v[164:167], v[194:197], v[38:41]
	v_mfma_f32_16x16x32_bf16 v[34:37], v[178:181], v[194:197], v[34:37]
	v_mfma_f32_16x16x32_bf16 v[22:25], v[164:167], v[202:205], v[22:25]
	v_mfma_f32_16x16x32_bf16 v[14:17], v[178:181], v[202:205], v[14:17]
	v_mfma_f32_16x16x32_bf16 v[6:9], v[164:167], v[210:213], v[6:9]
	s_barrier
	v_mfma_f32_16x16x32_bf16 v[2:5], v[178:181], v[210:213], v[2:5]
	s_setprio 2
	s_add_i32 s31, 0, 0x18000
	s_add_i32 s68, 0, 0x1c000
	ds_read_b128 v[144:147], v250
	ds_read_b128 v[148:151], v250 offset:1024
	ds_read_b128 v[152:155], v250 offset:2048
	ds_read_b128 v[156:159], v250 offset:3072
	ds_read_b128 v[160:163], v250 offset:16384
	ds_read_b128 v[164:167], v250 offset:17408
	ds_read_b128 v[174:177], v250 offset:18432
	ds_read_b128 v[178:181], v250 offset:19456
	v_add_u32_e32 v173, s68, v168
	s_add_u32 s28, s28, 0x160000
	s_addc_u32 s29, s29, 0
	s_mov_b32 m0, s36
	ds_read_b128 v[182:185], v172 offset:32768
	ds_read_b128 v[186:189], v172 offset:33792
	ds_read_b128 v[190:193], v172 offset:34816
	ds_read_b128 v[194:197], v172 offset:35840
	ds_read_b128 v[198:201], v172 offset:36864
	ds_read_b128 v[202:205], v172 offset:37888
	ds_read_b128 v[206:209], v172 offset:38912
	ds_read_b128 v[210:213], v172 offset:39936
	global_load_lds_dwordx4 v130, s[28:29]
	v_lshl_add_u64 v[222:223], s[28:29], 0, v[134:135]
	s_mov_b32 m0, s37
	s_nop 0
	global_load_lds_dwordx4 v134, s[28:29]
	s_waitcnt vmcnt(8)
	s_waitcnt lgkmcnt(0)
	s_barrier
	s_setprio 1
	s_waitcnt lgkmcnt(0)
	v_mfma_f32_16x16x32_bf16 v[126:129], v[144:147], v[182:185], v[126:129]
	v_mfma_f32_16x16x32_bf16 v[122:125], v[152:155], v[182:185], v[122:125]
	v_mfma_f32_16x16x32_bf16 v[118:121], v[144:147], v[190:193], v[118:121]
	v_mfma_f32_16x16x32_bf16 v[110:113], v[152:155], v[190:193], v[110:113]
	v_mfma_f32_16x16x32_bf16 v[94:97], v[144:147], v[198:201], v[94:97]
	v_mfma_f32_16x16x32_bf16 v[90:93], v[152:155], v[198:201], v[90:93]
	v_mfma_f32_16x16x32_bf16 v[82:85], v[144:147], v[206:209], v[82:85]
	v_mfma_f32_16x16x32_bf16 v[74:77], v[152:155], v[206:209], v[74:77]
	v_mfma_f32_16x16x32_bf16 v[126:129], v[148:151], v[186:189], v[126:129]
	v_mfma_f32_16x16x32_bf16 v[122:125], v[156:159], v[186:189], v[122:125]
	v_mfma_f32_16x16x32_bf16 v[118:121], v[148:151], v[194:197], v[118:121]
	v_mfma_f32_16x16x32_bf16 v[110:113], v[156:159], v[194:197], v[110:113]
	v_mfma_f32_16x16x32_bf16 v[94:97], v[148:151], v[202:205], v[94:97]
	v_mfma_f32_16x16x32_bf16 v[90:93], v[156:159], v[202:205], v[90:93]
	v_mfma_f32_16x16x32_bf16 v[82:85], v[148:151], v[210:213], v[82:85]
	v_mfma_f32_16x16x32_bf16 v[74:77], v[156:159], v[210:213], v[74:77]
	v_mfma_f32_16x16x32_bf16 v[114:117], v[160:163], v[182:185], v[114:117]
	v_mfma_f32_16x16x32_bf16 v[106:109], v[174:177], v[182:185], v[106:109]
	v_mfma_f32_16x16x32_bf16 v[102:105], v[160:163], v[190:193], v[102:105]
	v_mfma_f32_16x16x32_bf16 v[98:101], v[174:177], v[190:193], v[98:101]
	v_mfma_f32_16x16x32_bf16 v[86:89], v[160:163], v[198:201], v[86:89]
	v_mfma_f32_16x16x32_bf16 v[78:81], v[174:177], v[198:201], v[78:81]
	v_mfma_f32_16x16x32_bf16 v[70:73], v[160:163], v[206:209], v[70:73]
	v_mfma_f32_16x16x32_bf16 v[66:69], v[174:177], v[206:209], v[66:69]
	v_mfma_f32_16x16x32_bf16 v[114:117], v[164:167], v[186:189], v[114:117]
	v_mfma_f32_16x16x32_bf16 v[106:109], v[178:181], v[186:189], v[106:109]
	v_mfma_f32_16x16x32_bf16 v[102:105], v[164:167], v[194:197], v[102:105]
	v_mfma_f32_16x16x32_bf16 v[98:101], v[178:181], v[194:197], v[98:101]
	v_mfma_f32_16x16x32_bf16 v[86:89], v[164:167], v[202:205], v[86:89]
	v_mfma_f32_16x16x32_bf16 v[78:81], v[178:181], v[202:205], v[78:81]
	v_mfma_f32_16x16x32_bf16 v[70:73], v[164:167], v[210:213], v[70:73]
	s_barrier
	v_mfma_f32_16x16x32_bf16 v[66:69], v[178:181], v[210:213], v[66:69]
	s_setprio 2
	s_add_i32 s28, s31, s33
	v_lshl_add_u64 v[214:215], v[214:215], 0, s[12:13]
	s_mov_b32 m0, s28
	ds_read_b128 v[182:185], v172 offset:49152
	ds_read_b128 v[186:189], v172 offset:50176
	ds_read_b128 v[190:193], v172 offset:51200
	ds_read_b128 v[194:197], v172 offset:52224
	ds_read_b128 v[198:201], v172 offset:53248
	ds_read_b128 v[202:205], v172 offset:54272
	ds_read_b128 v[206:209], v172 offset:55296
	ds_read_b128 v[210:213], v172 offset:56320
	global_load_lds_dwordx4 v[214:215], off
	s_add_i32 m0, s28, 0x2000
	s_add_u32 s26, s26, 0x160080
	v_lshl_add_u64 v[214:215], v[216:217], 0, s[12:13]
	s_addc_u32 s27, s27, 0
	s_add_i32 s28, s68, s33
	global_load_lds_dwordx4 v[214:215], off
	s_mov_b32 m0, s28
	s_nop 0
	global_load_lds_dwordx4 v132, s[26:27]
	s_add_i32 m0, s28, 0x2000
	s_nop 0
	global_load_lds_dwordx4 v136, s[26:27]
	v_lshl_add_u64 v[214:215], v[218:219], 0, s[12:13]
	s_mov_b32 m0, s47
	s_nop 0
	global_load_lds_dwordx4 v[214:215], off
	v_lshl_add_u64 v[214:215], v[220:221], 0, s[12:13]
	s_mov_b32 m0, s48
	s_nop 0
	global_load_lds_dwordx4 v[214:215], off
	s_waitcnt vmcnt(8)
	s_waitcnt lgkmcnt(0)
	s_barrier
	s_setprio 1
	s_waitcnt lgkmcnt(0)
	v_mfma_f32_16x16x32_bf16 v[62:65], v[144:147], v[182:185], v[62:65]
	v_mfma_f32_16x16x32_bf16 v[58:61], v[152:155], v[182:185], v[58:61]
	v_mfma_f32_16x16x32_bf16 v[50:53], v[144:147], v[190:193], v[50:53]
	v_mfma_f32_16x16x32_bf16 v[42:45], v[152:155], v[190:193], v[42:45]
	v_mfma_f32_16x16x32_bf16 v[30:33], v[144:147], v[198:201], v[30:33]
	v_mfma_f32_16x16x32_bf16 v[26:29], v[152:155], v[198:201], v[26:29]
	v_mfma_f32_16x16x32_bf16 v[18:21], v[144:147], v[206:209], v[18:21]
	v_mfma_f32_16x16x32_bf16 v[10:13], v[152:155], v[206:209], v[10:13]
	v_mfma_f32_16x16x32_bf16 v[62:65], v[148:151], v[186:189], v[62:65]
	v_mfma_f32_16x16x32_bf16 v[58:61], v[156:159], v[186:189], v[58:61]
	v_mfma_f32_16x16x32_bf16 v[50:53], v[148:151], v[194:197], v[50:53]
	v_mfma_f32_16x16x32_bf16 v[42:45], v[156:159], v[194:197], v[42:45]
	v_mfma_f32_16x16x32_bf16 v[30:33], v[148:151], v[202:205], v[30:33]
	v_mfma_f32_16x16x32_bf16 v[26:29], v[156:159], v[202:205], v[26:29]
	v_mfma_f32_16x16x32_bf16 v[18:21], v[148:151], v[210:213], v[18:21]
	v_mfma_f32_16x16x32_bf16 v[10:13], v[156:159], v[210:213], v[10:13]
	v_mfma_f32_16x16x32_bf16 v[54:57], v[160:163], v[182:185], v[54:57]
	v_mfma_f32_16x16x32_bf16 v[46:49], v[174:177], v[182:185], v[46:49]
	v_mfma_f32_16x16x32_bf16 v[38:41], v[160:163], v[190:193], v[38:41]
	v_mfma_f32_16x16x32_bf16 v[34:37], v[174:177], v[190:193], v[34:37]
	v_mfma_f32_16x16x32_bf16 v[22:25], v[160:163], v[198:201], v[22:25]
	v_mfma_f32_16x16x32_bf16 v[14:17], v[174:177], v[198:201], v[14:17]
	v_mfma_f32_16x16x32_bf16 v[6:9], v[160:163], v[206:209], v[6:9]
	v_mfma_f32_16x16x32_bf16 v[2:5], v[174:177], v[206:209], v[2:5]
	v_mfma_f32_16x16x32_bf16 v[54:57], v[164:167], v[186:189], v[54:57]
	v_mfma_f32_16x16x32_bf16 v[46:49], v[178:181], v[186:189], v[46:49]
	v_mfma_f32_16x16x32_bf16 v[38:41], v[164:167], v[194:197], v[38:41]
	v_mfma_f32_16x16x32_bf16 v[34:37], v[178:181], v[194:197], v[34:37]
	v_mfma_f32_16x16x32_bf16 v[22:25], v[164:167], v[202:205], v[22:25]
	v_mfma_f32_16x16x32_bf16 v[14:17], v[178:181], v[202:205], v[14:17]
	v_mfma_f32_16x16x32_bf16 v[6:9], v[164:167], v[210:213], v[6:9]
	s_barrier
	v_mfma_f32_16x16x32_bf16 v[2:5], v[178:181], v[210:213], v[2:5]
	s_setprio 2
	s_add_u32 s24, s24, 0x100
	s_addc_u32 s25, s25, 0
	s_add_u32 s17, s17, 0x100
	s_addc_u32 s23, s23, 0
	s_cmp_ge_i32 s30, s67
	s_mov_b32 s26, s30
	s_cbranch_scc0 .LBB0_2683
